# write-through epilogue stores in the GEMM phases on top of: hoisted scale and colmax loads, W_ffn2_out conversion in the P11 tail slot, no unit-transition drains
# baseline (speedup 1.0000x reference)
; #define PG8_STAGE(bufoff, gbase, voff) do { _Pragma("unroll") for (int _i = 0; _i < 2; ++_i) \
;         __builtin_amdgcn_global_load_lds((const unsigned*)((const char*)(gbase) + (voff)[_i]), (LAS unsigned*)(lds + (bufoff) + ldsw + _i * 8192), 16, 0, 0); } while (0)
; #define PG8_LDA(dst, b, h) do { _Pragma("unroll") for (int m = 0; m < 4; ++m) _Pragma("unroll") for (int k = 0; k < 2; ++k) dst[m][k] = *(const LAS bf16x8*)(lds + PG8_SA(b, h) + aoff + m * 2048 + k * 1024); } while (0)
; #define PG8_LDB(dst, b, h) do { _Pragma("unroll") for (int n = 0; n < 2; ++n) _Pragma("unroll") for (int k = 0; k < 2; ++k) dst[n][k] = *(const LAS bf16x8*)(lds + PG8_SB(b, h) + boff + n * 2048 + k * 1024); } while (0)
; #define PG8_MMA(ai, bj, At, Bt) do { __builtin_amdgcn_s_setprio(1); _Pragma("unroll") for (int m = 0; m < 4; ++m) _Pragma("unroll") for (int n = 0; n < 2; ++n) _Pragma("unroll") for (int k = 0; k < 2; ++k) \
;         acc[ai][bj][m][n] = MmaOp<Epi::I8>::run(Bt[n][k], At[m][k], acc[ai][bj][m][n]); __builtin_amdgcn_s_setprio(0); } while (0)
; #define PG8_WAIT_L(n) asm volatile("s_waitcnt lgkmcnt(" #n ")" ::: "memory")
; #define PG8_BAR __builtin_amdgcn_s_barrier()
; #define PG8_SCHED __builtin_amdgcn_sched_barrier(0)
; template <class Epi, class Sched>
; __device__ __forceinline__ void gemm_phase(LAS unsigned char* lds, const Gemm g, const Sched& S, const Epi& E) {
;     ...
;             PG8_LDB(B0, 0, 0); PG8_SCHED; PG8_LDA(At, 0, 0); PG8_STAGE(PG8_SA(1, 1), a1 + hstepA, voffA);
;             PG8_WAIT_L(8); PG8_BAR; PG8_WAIT_L(0); PG8_MMA(0, 0, At, B0); PG8_BAR; PG8_SCHED;
;             PG8_LDB(B1, 0, 1); PG8_STAGE(PG8_SB(0, 0), b2, voffB);
;             PG8_BAR; PG8_WAIT_L(0); PG8_MMA(0, 1, At, B1); PG8_BAR;
;             PG8_LDA(At, 0, 1); PG8_STAGE(PG8_SA(0, 0), a2, voffA);
;             PG8_BAR; PG8_WAIT_L(0); PG8_MMA(1, 0, At, B0); PG8_BAR; PG8_SCHED;
.LBB0_115:
	ds_read_b128 v[40:43], v167
	ds_read_b128 v[52:55], v167 offset:1024
	ds_read_b128 v[136:139], v167 offset:2048
	ds_read_b128 v[172:175], v167 offset:3072
	s_add_u32 s28, s26, 0xfffc0080
	s_addc_u32 s29, s27, -1
	s_cmp_eq_u32 s53, 12
	s_cselect_b32 s31, s19, s29
	s_cselect_b32 s30, s48, s28
	s_cselect_b32 s29, s17, s51
	s_cselect_b32 s28, s49, s50
	v_lshl_add_u64 v[156:157], s[26:27], 0, v[148:149]
	s_add_i32 m0, s25, 0xc000
	ds_read_b128 v[178:181], v169
	ds_read_b128 v[182:185], v169 offset:1024
	ds_read_b128 v[186:189], v169 offset:2048
	ds_read_b128 v[190:193], v169 offset:3072
	ds_read_b128 v[194:197], v169 offset:4096
	ds_read_b128 v[198:201], v169 offset:5120
	ds_read_b128 v[202:205], v169 offset:6144
	ds_read_b128 v[206:209], v169 offset:7168
	global_load_lds_dwordx4 v[156:157], off
	v_lshl_add_u64 v[156:157], s[26:27], 0, v[150:151]
	s_add_i32 m0, s25, 0xe000
	s_nop 0
	global_load_lds_dwordx4 v[156:157], off
	s_waitcnt lgkmcnt(8)
	s_barrier
	s_waitcnt lgkmcnt(0)
	s_setprio 1
	s_waitcnt lgkmcnt(0)
	v_mfma_i32_16x16x64_i8 v[132:135], v[40:43], v[178:181], v[132:135]
	v_mfma_i32_16x16x64_i8 v[124:127], v[136:139], v[178:181], v[124:127]
	v_mfma_i32_16x16x64_i8 v[116:119], v[40:43], v[186:189], v[116:119]
	v_mfma_i32_16x16x64_i8 v[108:111], v[136:139], v[186:189], v[108:111]
	v_mfma_i32_16x16x64_i8 v[100:103], v[40:43], v[194:197], v[100:103]
	v_mfma_i32_16x16x64_i8 v[92:95], v[136:139], v[194:197], v[92:95]
	v_mfma_i32_16x16x64_i8 v[84:87], v[40:43], v[202:205], v[84:87]
	v_mfma_i32_16x16x64_i8 v[76:79], v[136:139], v[202:205], v[76:79]
	v_mfma_i32_16x16x64_i8 v[132:135], v[52:55], v[182:185], v[132:135]
	v_mfma_i32_16x16x64_i8 v[124:127], v[172:175], v[182:185], v[124:127]
	v_mfma_i32_16x16x64_i8 v[116:119], v[52:55], v[190:193], v[116:119]
	v_mfma_i32_16x16x64_i8 v[108:111], v[172:175], v[190:193], v[108:111]
	v_mfma_i32_16x16x64_i8 v[100:103], v[52:55], v[198:201], v[100:103]
	v_mfma_i32_16x16x64_i8 v[92:95], v[172:175], v[198:201], v[92:95]
	v_mfma_i32_16x16x64_i8 v[84:87], v[52:55], v[206:209], v[84:87]
	v_mfma_i32_16x16x64_i8 v[76:79], v[172:175], v[206:209], v[76:79]
	s_setprio 0
	s_barrier
	s_add_i32 s54, s44, s34
	v_lshl_add_u64 v[156:157], s[28:29], 0, v[144:145]
	s_mov_b32 m0, s54
	ds_read_b128 v[210:213], v171
	ds_read_b128 v[214:217], v171 offset:1024
	ds_read_b128 v[218:221], v171 offset:2048
	ds_read_b128 v[222:225], v171 offset:3072
	global_load_lds_dwordx4 v[156:157], off
	v_lshl_add_u64 v[160:161], s[28:29], 0, v[140:141]
	s_add_i32 m0, s54, 0x2000
	s_nop 0
	global_load_lds_dwordx4 v[160:161], off
	s_barrier
	s_waitcnt lgkmcnt(0)
	s_setprio 1
	s_waitcnt lgkmcnt(0)
	v_mfma_i32_16x16x64_i8 v[128:131], v[210:213], v[178:181], v[128:131]
	v_mfma_i32_16x16x64_i8 v[120:123], v[218:221], v[178:181], v[120:123]
	v_mfma_i32_16x16x64_i8 v[112:115], v[210:213], v[186:189], v[112:115]
	v_mfma_i32_16x16x64_i8 v[104:107], v[218:221], v[186:189], v[104:107]
	v_mfma_i32_16x16x64_i8 v[96:99], v[210:213], v[194:197], v[96:99]
	v_mfma_i32_16x16x64_i8 v[88:91], v[218:221], v[194:197], v[88:91]
	v_mfma_i32_16x16x64_i8 v[80:83], v[210:213], v[202:205], v[80:83]
	v_mfma_i32_16x16x64_i8 v[72:75], v[218:221], v[202:205], v[72:75]
	v_mfma_i32_16x16x64_i8 v[128:131], v[214:217], v[182:185], v[128:131]
	v_mfma_i32_16x16x64_i8 v[120:123], v[222:225], v[182:185], v[120:123]
	v_mfma_i32_16x16x64_i8 v[112:115], v[214:217], v[190:193], v[112:115]
	v_mfma_i32_16x16x64_i8 v[104:107], v[222:225], v[190:193], v[104:107]
	v_mfma_i32_16x16x64_i8 v[96:99], v[214:217], v[198:201], v[96:99]
	v_mfma_i32_16x16x64_i8 v[88:91], v[222:225], v[198:201], v[88:91]
	v_mfma_i32_16x16x64_i8 v[80:83], v[214:217], v[206:209], v[80:83]
	v_mfma_i32_16x16x64_i8 v[72:75], v[222:225], v[206:209], v[72:75]
	s_setprio 0
	s_mov_b32 m0, s25
	v_lshl_add_u64 v[226:227], s[30:31], 0, v[146:147]
	s_barrier
	ds_read_b128 v[178:181], v169 offset:16384
	ds_read_b128 v[182:185], v169 offset:17408
	ds_read_b128 v[186:189], v169 offset:18432
	ds_read_b128 v[190:193], v169 offset:19456
	ds_read_b128 v[194:197], v169 offset:20480
	ds_read_b128 v[198:201], v169 offset:21504
	ds_read_b128 v[202:205], v169 offset:22528
	ds_read_b128 v[206:209], v169 offset:23552
	global_load_lds_dwordx4 v[226:227], off
	v_lshl_add_u64 v[228:229], s[30:31], 0, v[142:143]
	s_mov_b32 m0, s37
	s_nop 0
	global_load_lds_dwordx4 v[228:229], off
	s_barrier
	s_waitcnt lgkmcnt(0)
	s_setprio 1
	s_waitcnt lgkmcnt(0)
	v_mfma_i32_16x16x64_i8 v[68:71], v[40:43], v[178:181], v[68:71]
	v_mfma_i32_16x16x64_i8 v[60:63], v[136:139], v[178:181], v[60:63]
	v_mfma_i32_16x16x64_i8 v[48:51], v[40:43], v[186:189], v[48:51]
	v_mfma_i32_16x16x64_i8 v[36:39], v[136:139], v[186:189], v[36:39]
	v_mfma_i32_16x16x64_i8 v[28:31], v[40:43], v[194:197], v[28:31]
	v_mfma_i32_16x16x64_i8 v[20:23], v[136:139], v[194:197], v[20:23]
	v_mfma_i32_16x16x64_i8 v[12:15], v[40:43], v[202:205], v[12:15]
	v_mfma_i32_16x16x64_i8 v[4:7], v[136:139], v[202:205], v[4:7]
	v_mfma_i32_16x16x64_i8 v[68:71], v[52:55], v[182:185], v[68:71]
	v_mfma_i32_16x16x64_i8 v[60:63], v[172:175], v[182:185], v[60:63]
	v_mfma_i32_16x16x64_i8 v[48:51], v[52:55], v[190:193], v[48:51]
	v_mfma_i32_16x16x64_i8 v[36:39], v[172:175], v[190:193], v[36:39]
	v_mfma_i32_16x16x64_i8 v[28:31], v[52:55], v[198:201], v[28:31]
	v_mfma_i32_16x16x64_i8 v[20:23], v[172:175], v[198:201], v[20:23]
	v_mfma_i32_16x16x64_i8 v[12:15], v[52:55], v[206:209], v[12:15]
	v_mfma_i32_16x16x64_i8 v[4:7], v[172:175], v[206:209], v[4:7]
	s_setprio 0
	s_barrier
; #define PG8_STAGE(bufoff, gbase, voff) do { _Pragma("unroll") for (int _i = 0; _i < 2; ++_i) \
;         __builtin_amdgcn_global_load_lds((const unsigned*)((const char*)(gbase) + (voff)[_i]), (LAS unsigned*)(lds + (bufoff) + ldsw + _i * 8192), 16, 0, 0); } while (0)
; #define PG8_LDA(dst, b, h) do { _Pragma("unroll") for (int m = 0; m < 4; ++m) _Pragma("unroll") for (int k = 0; k < 2; ++k) dst[m][k] = *(const LAS bf16x8*)(lds + PG8_SA(b, h) + aoff + m * 2048 + k * 1024); } while (0)
; #define PG8_LDB(dst, b, h) do { _Pragma("unroll") for (int n = 0; n < 2; ++n) _Pragma("unroll") for (int k = 0; k < 2; ++k) dst[n][k] = *(const LAS bf16x8*)(lds + PG8_SB(b, h) + boff + n * 2048 + k * 1024); } while (0)
; #define PG8_MMA(ai, bj, At, Bt) do { __builtin_amdgcn_s_setprio(1); _Pragma("unroll") for (int m = 0; m < 4; ++m) _Pragma("unroll") for (int n = 0; n < 2; ++n) _Pragma("unroll") for (int k = 0; k < 2; ++k) \
;         acc[ai][bj][m][n] = MmaOp<Epi::I8>::run(Bt[n][k], At[m][k], acc[ai][bj][m][n]); __builtin_amdgcn_s_setprio(0); } while (0)
; #define PG8_WAIT_V(n) asm volatile("s_waitcnt vmcnt(" #n ")" ::: "memory")
; #define PG8_WAIT_L(n) asm volatile("s_waitcnt lgkmcnt(" #n ")" ::: "memory")
; #define PG8_BAR __builtin_amdgcn_s_barrier()
; #define PG8_SCHED __builtin_amdgcn_sched_barrier(0)
; template <class Epi, class Sched>
; __device__ __forceinline__ void gemm_phase(LAS unsigned char* lds, const Gemm g, const Sched& S, const Epi& E) {
;     ...
;             PG8_STAGE(PG8_SB(0, 1), b2 + hstepB, voffB);
;             PG8_WAIT_V(6); PG8_BAR; PG8_MMA(1, 1, At, B1); PG8_BAR;
;             PG8_LDB(B0, 1, 0); PG8_SCHED; PG8_LDA(At, 1, 0); PG8_STAGE(PG8_SA(0, 1), a2 + hstepA, voffA);
;             PG8_WAIT_L(8); PG8_BAR; PG8_WAIT_L(0); PG8_MMA(0, 0, At, B0); PG8_BAR; PG8_SCHED;
;             PG8_LDB(B1, 1, 1); PG8_STAGE(PG8_SB(1, 0), b3, voffB);
;             PG8_BAR; PG8_WAIT_L(0); PG8_MMA(0, 1, At, B1); PG8_BAR;
;             PG8_LDA(At, 1, 1); PG8_STAGE(PG8_SA(1, 0), a3, voffA);
	s_add_u32 s54, s28, 0x40000
	s_addc_u32 s55, s29, 0
	s_add_i32 s56, s45, s34
	v_lshl_add_u64 v[40:41], s[54:55], 0, v[144:145]
	s_mov_b32 m0, s56
	s_nop 0
	global_load_lds_dwordx4 v[40:41], off
	v_lshl_add_u64 v[40:41], s[54:55], 0, v[140:141]
	s_add_i32 m0, s56, 0x2000
	s_nop 0
	global_load_lds_dwordx4 v[40:41], off
	s_waitcnt vmcnt(6)
	s_barrier
	s_setprio 1
	v_mfma_i32_16x16x64_i8 v[44:47], v[210:213], v[186:189], v[44:47]
	v_mfma_i32_16x16x64_i8 v[32:35], v[218:221], v[186:189], v[32:35]
	v_mfma_i32_16x16x64_i8 v[24:27], v[210:213], v[194:197], v[24:27]
	v_mfma_i32_16x16x64_i8 v[16:19], v[218:221], v[194:197], v[16:19]
	v_mfma_i32_16x16x64_i8 v[8:11], v[210:213], v[202:205], v[8:11]
	v_mfma_i32_16x16x64_i8 v[0:3], v[218:221], v[202:205], v[0:3]
	v_mfma_i32_16x16x64_i8 v[40:43], v[210:213], v[178:181], v[64:67]
	v_mfma_i32_16x16x64_i8 v[52:55], v[218:221], v[178:181], v[56:59]
	v_mfma_i32_16x16x64_i8 v[44:47], v[214:217], v[190:193], v[44:47]
	v_mfma_i32_16x16x64_i8 v[32:35], v[222:225], v[190:193], v[32:35]
	v_mfma_i32_16x16x64_i8 v[24:27], v[214:217], v[198:201], v[24:27]
	v_mfma_i32_16x16x64_i8 v[16:19], v[222:225], v[198:201], v[16:19]
	v_mfma_i32_16x16x64_i8 v[8:11], v[214:217], v[206:209], v[8:11]
	v_mfma_i32_16x16x64_i8 v[0:3], v[222:225], v[206:209], v[0:3]
	v_mfma_i32_16x16x64_i8 v[40:43], v[214:217], v[182:185], v[40:43]
	v_mfma_i32_16x16x64_i8 v[52:55], v[222:225], v[182:185], v[52:55]
	s_setprio 0
	s_add_i32 s54, 0, 0x18000
	v_add_u32_e32 v158, s54, v163
	s_barrier
	ds_read_b128 v[56:59], v158
	ds_read_b128 v[64:67], v158 offset:1024
	ds_read_b128 v[136:139], v158 offset:2048
	ds_read_b128 v[172:175], v158 offset:3072
	s_add_u32 s30, s30, 0x40000
	s_addc_u32 s31, s31, 0
	s_mov_b32 m0, s38
	v_lshl_add_u64 v[210:211], s[30:31], 0, v[146:147]
	ds_read_b128 v[178:181], v169 offset:32768
	ds_read_b128 v[182:185], v169 offset:33792
	ds_read_b128 v[186:189], v169 offset:34816
	ds_read_b128 v[190:193], v169 offset:35840
	ds_read_b128 v[194:197], v169 offset:36864
	ds_read_b128 v[198:201], v169 offset:37888
	ds_read_b128 v[202:205], v169 offset:38912
	ds_read_b128 v[206:209], v169 offset:39936
	global_load_lds_dwordx4 v[210:211], off
	v_lshl_add_u64 v[210:211], s[30:31], 0, v[142:143]
	s_mov_b32 m0, s39
	s_nop 0
	global_load_lds_dwordx4 v[210:211], off
	s_waitcnt lgkmcnt(8)
	s_barrier
	s_waitcnt lgkmcnt(0)
	s_setprio 1
	s_waitcnt lgkmcnt(0)
	v_mfma_i32_16x16x64_i8 v[132:135], v[56:59], v[178:181], v[132:135]
	v_mfma_i32_16x16x64_i8 v[124:127], v[136:139], v[178:181], v[124:127]
	v_mfma_i32_16x16x64_i8 v[116:119], v[56:59], v[186:189], v[116:119]
	v_mfma_i32_16x16x64_i8 v[108:111], v[136:139], v[186:189], v[108:111]
	v_mfma_i32_16x16x64_i8 v[100:103], v[56:59], v[194:197], v[100:103]
	v_mfma_i32_16x16x64_i8 v[92:95], v[136:139], v[194:197], v[92:95]
	v_mfma_i32_16x16x64_i8 v[84:87], v[56:59], v[202:205], v[84:87]
	v_mfma_i32_16x16x64_i8 v[76:79], v[136:139], v[202:205], v[76:79]
	v_mfma_i32_16x16x64_i8 v[132:135], v[64:67], v[182:185], v[132:135]
	v_mfma_i32_16x16x64_i8 v[124:127], v[172:175], v[182:185], v[124:127]
	v_mfma_i32_16x16x64_i8 v[116:119], v[64:67], v[190:193], v[116:119]
	v_mfma_i32_16x16x64_i8 v[108:111], v[172:175], v[190:193], v[108:111]
	v_mfma_i32_16x16x64_i8 v[100:103], v[64:67], v[198:201], v[100:103]
	v_mfma_i32_16x16x64_i8 v[92:95], v[172:175], v[198:201], v[92:95]
	v_mfma_i32_16x16x64_i8 v[84:87], v[64:67], v[206:209], v[84:87]
	v_mfma_i32_16x16x64_i8 v[76:79], v[172:175], v[206:209], v[76:79]
	s_setprio 0
	s_barrier
	s_add_i32 s30, 0, 0x1c000
	s_add_i32 s31, s54, s34
	v_add_u32_e32 v158, s30, v163
	v_lshl_add_u64 v[156:157], v[156:157], 0, s[14:15]
	s_mov_b32 m0, s31
	ds_read_b128 v[210:213], v158
	ds_read_b128 v[214:217], v158 offset:1024
	ds_read_b128 v[218:221], v158 offset:2048
	ds_read_b128 v[222:225], v158 offset:3072
	global_load_lds_dwordx4 v[156:157], off
	v_lshl_add_u64 v[156:157], v[160:161], 0, s[14:15]
	s_add_i32 m0, s31, 0x2000
	s_nop 0
	global_load_lds_dwordx4 v[156:157], off
	s_barrier
	s_waitcnt lgkmcnt(0)
	s_setprio 1
	s_waitcnt lgkmcnt(0)
	v_mfma_i32_16x16x64_i8 v[128:131], v[210:213], v[178:181], v[128:131]
	v_mfma_i32_16x16x64_i8 v[120:123], v[218:221], v[178:181], v[120:123]
	v_mfma_i32_16x16x64_i8 v[112:115], v[210:213], v[186:189], v[112:115]
	v_mfma_i32_16x16x64_i8 v[104:107], v[218:221], v[186:189], v[104:107]
	v_mfma_i32_16x16x64_i8 v[96:99], v[210:213], v[194:197], v[96:99]
	v_mfma_i32_16x16x64_i8 v[88:91], v[218:221], v[194:197], v[88:91]
	v_mfma_i32_16x16x64_i8 v[80:83], v[210:213], v[202:205], v[80:83]
	v_mfma_i32_16x16x64_i8 v[72:75], v[218:221], v[202:205], v[72:75]
	v_mfma_i32_16x16x64_i8 v[128:131], v[214:217], v[182:185], v[128:131]
	v_mfma_i32_16x16x64_i8 v[120:123], v[222:225], v[182:185], v[120:123]
	v_mfma_i32_16x16x64_i8 v[112:115], v[214:217], v[190:193], v[112:115]
	v_mfma_i32_16x16x64_i8 v[104:107], v[222:225], v[190:193], v[104:107]
	v_mfma_i32_16x16x64_i8 v[96:99], v[214:217], v[198:201], v[96:99]
	v_mfma_i32_16x16x64_i8 v[88:91], v[222:225], v[198:201], v[88:91]
	v_mfma_i32_16x16x64_i8 v[80:83], v[214:217], v[206:209], v[80:83]
	v_mfma_i32_16x16x64_i8 v[72:75], v[222:225], v[206:209], v[72:75]
	s_setprio 0
	s_mov_b32 m0, s41
	v_lshl_add_u64 v[156:157], v[226:227], 0, s[14:15]
	s_barrier
	ds_read_b128 v[178:181], v169 offset:49152
	ds_read_b128 v[182:185], v169 offset:50176
	ds_read_b128 v[186:189], v169 offset:51200
	ds_read_b128 v[190:193], v169 offset:52224
	ds_read_b128 v[194:197], v169 offset:53248
	ds_read_b128 v[198:201], v169 offset:54272
	ds_read_b128 v[202:205], v169 offset:55296
	ds_read_b128 v[206:209], v169 offset:56320
	global_load_lds_dwordx4 v[156:157], off
	v_lshl_add_u64 v[156:157], v[228:229], 0, s[14:15]
	s_mov_b32 m0, s42
	s_nop 0
	global_load_lds_dwordx4 v[156:157], off
	s_barrier
; __device__ __forceinline__ float ld_agent(const float* p) { return __hip_atomic_load(p, __ATOMIC_RELAXED, __HIP_MEMORY_SCOPE_AGENT); }
; #define PG8_STAGE(bufoff, gbase, voff) do { _Pragma("unroll") for (int _i = 0; _i < 2; ++_i) \
;         __builtin_amdgcn_global_load_lds((const unsigned*)((const char*)(gbase) + (voff)[_i]), (LAS unsigned*)(lds + (bufoff) + ldsw + _i * 8192), 16, 0, 0); } while (0)
; #define PG8_MMA(ai, bj, At, Bt) do { __builtin_amdgcn_s_setprio(1); _Pragma("unroll") for (int m = 0; m < 4; ++m) _Pragma("unroll") for (int n = 0; n < 2; ++n) _Pragma("unroll") for (int k = 0; k < 2; ++k) \
;         acc[ai][bj][m][n] = MmaOp<Epi::I8>::run(Bt[n][k], At[m][k], acc[ai][bj][m][n]); __builtin_amdgcn_s_setprio(0); } while (0)
; #define PG8_WAIT_V(n) asm volatile("s_waitcnt vmcnt(" #n ")" ::: "memory")
; #define PG8_WAIT_L(n) asm volatile("s_waitcnt lgkmcnt(" #n ")" ::: "memory")
; #define PG8_BAR __builtin_amdgcn_s_barrier()
; #define PG8_SCHED __builtin_amdgcn_sched_barrier(0)
;     __device__ __forceinline__ void operator()(const i32x4 (&acc)[2][2][4][2], const Unit& u, int wr, int wc, int fr, int fq) const {
;         const int row0 = u.pm * BM + wr * 64 + fr, col0 = u.pn * HALF + wc * 32 + 8 * fq, scol = u.pn * BM + wc * 32 + 8 * fq;
;         float sq[8];
; #pragma unroll
;         for (int g = 0; g < 8; ++g) sq[g] = ld_agent(frs + row0 + (g >> 2) * HALF + (g & 3) * 16);
;         f32x4 sg[2], su[2];
; #pragma unroll
;         for (int n = 0; n < 2; ++n) { sg[n] = *(const f32x4*)(swinv + scol + 4 * n); su[n] = *(const f32x4*)(swinv + scol + HALF + 4 * n); }
; template <class Epi, class Sched>
; __device__ __forceinline__ void gemm_phase(LAS unsigned char* lds, const Gemm g, const Sched& S, const Epi& E) {
;     ...
;             PG8_BAR; PG8_WAIT_L(0); PG8_MMA(1, 0, At, B0); PG8_BAR; PG8_SCHED;
;             PG8_STAGE(PG8_SB(1, 1), b3 + hstepB, voffB);
;             PG8_WAIT_V(6); PG8_BAR; PG8_MMA(1, 1, At, B1); PG8_BAR;
	s_waitcnt lgkmcnt(0)
	s_setprio 1
	s_waitcnt lgkmcnt(0)
	v_mfma_i32_16x16x64_i8 v[68:71], v[56:59], v[178:181], v[68:71]
	v_mfma_i32_16x16x64_i8 v[60:63], v[136:139], v[178:181], v[60:63]
	v_mfma_i32_16x16x64_i8 v[48:51], v[56:59], v[186:189], v[48:51]
	v_mfma_i32_16x16x64_i8 v[36:39], v[136:139], v[186:189], v[36:39]
	v_mfma_i32_16x16x64_i8 v[28:31], v[56:59], v[194:197], v[28:31]
	v_mfma_i32_16x16x64_i8 v[20:23], v[136:139], v[194:197], v[20:23]
	v_mfma_i32_16x16x64_i8 v[12:15], v[56:59], v[202:205], v[12:15]
	v_mfma_i32_16x16x64_i8 v[4:7], v[136:139], v[202:205], v[4:7]
	v_mfma_i32_16x16x64_i8 v[68:71], v[64:67], v[182:185], v[68:71]
	v_mfma_i32_16x16x64_i8 v[60:63], v[172:175], v[182:185], v[60:63]
	v_mfma_i32_16x16x64_i8 v[48:51], v[64:67], v[190:193], v[48:51]
	v_mfma_i32_16x16x64_i8 v[36:39], v[172:175], v[190:193], v[36:39]
	v_mfma_i32_16x16x64_i8 v[28:31], v[64:67], v[198:201], v[28:31]
	v_mfma_i32_16x16x64_i8 v[20:23], v[172:175], v[198:201], v[20:23]
	v_mfma_i32_16x16x64_i8 v[12:15], v[64:67], v[206:209], v[12:15]
	v_mfma_i32_16x16x64_i8 v[4:7], v[172:175], v[206:209], v[4:7]
	s_setprio 0
	s_barrier
	s_add_u32 s28, s28, 0x40080
	s_addc_u32 s29, s29, 0
	s_add_i32 s30, s30, s34
	v_lshl_add_u64 v[56:57], s[28:29], 0, v[144:145]
	s_mov_b32 m0, s30
	s_nop 0
	global_load_lds_dwordx4 v[56:57], off
	v_lshl_add_u64 v[56:57], s[28:29], 0, v[140:141]
	s_add_i32 m0, s30, 0x2000
	s_nop 0
	global_load_lds_dwordx4 v[56:57], off
	s_waitcnt vmcnt(6)
	s_barrier
	s_setprio 1
	v_mfma_i32_16x16x64_i8 v[40:43], v[210:213], v[178:181], v[40:43]
	v_mfma_i32_16x16x64_i8 v[64:67], v[214:217], v[182:185], v[40:43]
	v_mfma_i32_16x16x64_i8 v[40:43], v[218:221], v[178:181], v[52:55]
	v_mfma_i32_16x16x64_i8 v[56:59], v[222:225], v[182:185], v[40:43]
	v_mfma_i32_16x16x64_i8 v[40:43], v[210:213], v[186:189], v[44:47]
	v_mfma_i32_16x16x64_i8 v[32:35], v[218:221], v[186:189], v[32:35]
	v_mfma_i32_16x16x64_i8 v[24:27], v[210:213], v[194:197], v[24:27]
	v_mfma_i32_16x16x64_i8 v[16:19], v[218:221], v[194:197], v[16:19]
	v_mfma_i32_16x16x64_i8 v[8:11], v[210:213], v[202:205], v[8:11]
	v_mfma_i32_16x16x64_i8 v[0:3], v[218:221], v[202:205], v[0:3]
	v_mfma_i32_16x16x64_i8 v[44:47], v[214:217], v[190:193], v[40:43]
	v_mfma_i32_16x16x64_i8 v[32:35], v[222:225], v[190:193], v[32:35]
	v_mfma_i32_16x16x64_i8 v[24:27], v[214:217], v[198:201], v[24:27]
	v_mfma_i32_16x16x64_i8 v[16:19], v[222:225], v[198:201], v[16:19]
	v_mfma_i32_16x16x64_i8 v[8:11], v[214:217], v[206:209], v[8:11]
	v_mfma_i32_16x16x64_i8 v[0:3], v[222:225], v[206:209], v[0:3]
	s_setprio 0
	s_add_i32 s53, s53, 2
	s_add_u32 s26, s26, 0x100
	s_addc_u32 s27, s27, 0
	s_add_u32 s50, s50, 0x100
	s_addc_u32 s51, s51, 0
	s_cmp_gt_u32 s53, 13
	s_barrier
	s_cbranch_scc0 .LBB0_115
	v_lshl_add_u32 v156, s24, 8, v159
	v_ashrrev_i32_e32 v157, 31, v156
	v_lshl_add_u64 v[40:41], v[156:157], 2, s[2:3]
	global_load_dword v178, v[40:41], off sc1
	global_load_dword v172, v[40:41], off offset:64 sc1
	global_load_dword v170, v[40:41], off offset:128 sc1
	global_load_dword v168, v[40:41], off offset:192 sc1
	global_load_dword v166, v[40:41], off offset:512 sc1
	global_load_dword v164, v[40:41], off offset:576 sc1
	global_load_dword v162, v[40:41], off offset:640 sc1
	global_load_dword v158, v[40:41], off offset:704 sc1
	v_lshl_or_b32 v40, s47, 8, v165
	v_ashrrev_i32_e32 v41, 31, v40
	v_lshl_add_u64 v[160:161], v[40:41], 2, s[12:13]
	global_load_dwordx4 v[40:43], v[160:161], off offset:16
	global_load_dwordx4 v[52:55], v[160:161], off
	global_load_dwordx4 v[136:139], v[160:161], off offset:528
	global_load_dwordx4 v[180:183], v[160:161], off offset:512
	v_cvt_f32_i32_e32 v161, v132
	v_cvt_f32_i32_e32 v160, v128
	v_cvt_f32_i32_e32 v135, v135
	v_cvt_f32_i32_e32 v125, v125
	v_readlane_b32 s54, v239, 46
	v_lshl_or_b32 v174, s47, 7, v165
	v_readlane_b32 s55, v239, 47
	v_ashrrev_i32_e32 v175, 31, v174
	v_cvt_f32_i32_e32 v117, v117
	v_cvt_f32_i32_e32 v109, v109
	v_cvt_f32_i32_e32 v101, v101
	v_cvt_f32_i32_e32 v93, v93
	v_cvt_f32_i32_e32 v85, v85
	v_cvt_f32_i32_e32 v77, v77
	v_cvt_f32_i32_e32 v69, v69
	v_cvt_f32_i32_e32 v61, v61
	v_cvt_f32_i32_e32 v49, v49
	v_cvt_f32_i32_e32 v37, v37
	v_cvt_f32_i32_e32 v29, v29
	v_cvt_f32_i32_e32 v21, v21
	v_cvt_f32_i32_e32 v13, v13
	v_cvt_f32_i32_e32 v5, v5
	s_and_b64 vcc, exec, s[0:1]
	s_mov_b32 s47, s16
	s_mov_b32 s24, s18
	s_mov_b64 s[28:29], s[22:23]
	s_waitcnt vmcnt(0)
; __device__ __forceinline__ unsigned cvt_pk_bf16(float lo, float hi) { unsigned r; asm volatile("v_cvt_pk_bf16_f32 %0, %1, %2" : "=v"(r) : "v"(lo), "v"(hi)); return r; }
; __device__ __forceinline__ float sigm(float x) { return __builtin_amdgcn_rcpf(1.f + __builtin_amdgcn_exp2f(-LOG2E * x)); }
;     __device__ __forceinline__ void operator()(const i32x4 (&acc)[2][2][4][2], const Unit& u, int wr, int wc, int fr, int fq) const {
;     ...
;         for (int ai = 0; ai < 2; ++ai)
; #pragma unroll
;             for (int m = 0; m < 4; ++m) {
;                 const int r = row0 + ai * HALF + m * 16; const float rs = sq[ai * 4 + m];
;                 float v[8];
; #pragma unroll
;                 for (int n = 0; n < 2; ++n)
; #pragma unroll
;                     for (int j = 0; j < 4; ++j) { const float g = (float)acc[ai][0][m][n][j] * rs * sg[n][j], up = (float)acc[ai][1][m][n][j] * rs * su[n][j]; v[n * 4 + j] = g * sigm(g) * up; }
;                 u32x4 w; w.x = cvt_pk_bf16(v[0], v[1]); w.y = cvt_pk_bf16(v[2], v[3]); w.z = cvt_pk_bf16(v[4], v[5]); w.w = cvt_pk_bf16(v[6], v[7]);
;                 *(u32x4*)(O + (size_t)r * FF + col0) = w;
	v_pk_mul_f32 v[184:185], v[178:179], v[160:161] op_sel_hi:[0,1]
	v_mov_b32_e32 v161, v52
	v_mov_b32_e32 v160, v180
	v_pk_mul_f32 v[184:185], v[184:185], v[160:161]
	s_nop 0
	v_mul_f32_e32 v52, 0xbfb8aa3b, v185
	v_exp_f32_e32 v52, v52
	s_nop 0
	v_add_f32_e32 v52, 1.0, v52
	v_rcp_f32_e32 v52, v52
	s_nop 0
	v_mul_f32_e32 v52, v185, v52
	v_mul_f32_e32 v132, v184, v52
	v_cvt_f32_i32_e32 v185, v133
	v_cvt_f32_i32_e32 v184, v129
	v_mov_b32_e32 v52, v181
	v_pk_mul_f32 v[128:129], v[178:179], v[184:185] op_sel_hi:[0,1]
	v_pk_mul_f32 v[128:129], v[128:129], v[52:53]
	s_nop 0
	v_mul_f32_e32 v133, 0xbfb8aa3b, v129
	v_exp_f32_e32 v133, v133
	s_nop 0
	v_add_f32_e32 v133, 1.0, v133
	v_rcp_f32_e32 v133, v133
	s_nop 0
	v_mul_f32_e32 v129, v129, v133
	v_mul_f32_e32 v133, v128, v129
	v_cvt_f32_i32_e32 v129, v134
	v_cvt_f32_i32_e32 v128, v130
	v_cvt_f32_i32_e32 v134, v131
	v_cvt_pk_bf16_f32 v132, v132, v133
	v_pk_mul_f32 v[180:181], v[178:179], v[128:129] op_sel_hi:[0,1]
	v_mov_b32_e32 v128, v182
	v_mov_b32_e32 v129, v54
	v_pk_mul_f32 v[180:181], v[180:181], v[128:129]
	v_pk_mul_f32 v[130:131], v[178:179], v[134:135] op_sel_hi:[0,1]
	v_mul_f32_e32 v54, 0xbfb8aa3b, v181
	v_exp_f32_e32 v54, v54
	s_nop 0
	v_add_f32_e32 v54, 1.0, v54
	v_rcp_f32_e32 v54, v54
	s_nop 0
	v_mul_f32_e32 v54, v181, v54
	v_mul_f32_e32 v157, v180, v54
	v_mov_b32_e32 v54, v183
	v_pk_mul_f32 v[130:131], v[130:131], v[54:55]
	s_nop 0
	v_mul_f32_e32 v134, 0xbfb8aa3b, v131
	v_exp_f32_e32 v134, v134
	s_nop 0
	v_add_f32_e32 v134, 1.0, v134
	v_rcp_f32_e32 v134, v134
	s_nop 0
	v_mul_f32_e32 v131, v131, v134
	v_mul_f32_e32 v173, v130, v131
	v_cvt_f32_i32_e32 v131, v124
	v_cvt_f32_i32_e32 v130, v120
	v_cvt_f32_i32_e32 v124, v121
	v_cvt_pk_bf16_f32 v133, v157, v173
	v_pk_mul_f32 v[134:135], v[178:179], v[130:131] op_sel_hi:[0,1]
	v_mov_b32_e32 v130, v136
	v_mov_b32_e32 v131, v40
	v_pk_mul_f32 v[134:135], v[134:135], v[130:131]
	v_pk_mul_f32 v[120:121], v[178:179], v[124:125] op_sel_hi:[0,1]
	v_mul_f32_e32 v40, 0xbfb8aa3b, v135
	v_exp_f32_e32 v40, v40
	s_nop 0
	v_add_f32_e32 v40, 1.0, v40
	v_rcp_f32_e32 v40, v40
	s_nop 0
	v_mul_f32_e32 v40, v135, v40
	v_mul_f32_e32 v134, v134, v40
	v_mov_b32_e32 v40, v137
	v_pk_mul_f32 v[120:121], v[120:121], v[40:41]
	s_nop 0
	v_mul_f32_e32 v124, 0xbfb8aa3b, v121
	v_exp_f32_e32 v124, v124
	s_nop 0
	v_add_f32_e32 v124, 1.0, v124
	v_rcp_f32_e32 v124, v124
	s_nop 0
	v_mul_f32_e32 v121, v121, v124
	v_mul_f32_e32 v135, v120, v121
	v_cvt_f32_i32_e32 v121, v126
	v_cvt_f32_i32_e32 v120, v122
	v_cvt_pk_bf16_f32 v134, v134, v135
	v_pk_mul_f32 v[124:125], v[178:179], v[120:121] op_sel_hi:[0,1]
	v_mov_b32_e32 v120, v138
	v_mov_b32_e32 v121, v42
	v_pk_mul_f32 v[124:125], v[124:125], v[120:121]
	s_nop 0
	v_mul_f32_e32 v42, 0xbfb8aa3b, v125
	v_exp_f32_e32 v42, v42
	s_nop 0
	v_add_f32_e32 v42, 1.0, v42
	v_rcp_f32_e32 v42, v42
	s_nop 0
	v_mul_f32_e32 v42, v125, v42
	v_mul_f32_e32 v126, v124, v42
	v_cvt_f32_i32_e32 v125, v127
	v_cvt_f32_i32_e32 v124, v123
	v_mov_b32_e32 v42, v139
	v_pk_mul_f32 v[122:123], v[178:179], v[124:125] op_sel_hi:[0,1]
	v_pk_mul_f32 v[122:123], v[122:123], v[42:43]
	s_nop 0
	v_mul_f32_e32 v124, 0xbfb8aa3b, v123
	v_exp_f32_e32 v124, v124
	s_nop 0
	v_add_f32_e32 v124, 1.0, v124
	v_rcp_f32_e32 v124, v124
	s_nop 0
	v_mul_f32_e32 v123, v123, v124
	v_mul_f32_e32 v122, v122, v123
	v_cvt_pk_bf16_f32 v135, v126, v122
	v_mov_b64_e32 v[122:123], s[54:55]
	v_mad_i64_i32 v[126:127], s[26:27], v156, s46, v[122:123]
	v_lshlrev_b64 v[124:125], 1, v[174:175]
	v_lshl_add_u64 v[126:127], v[126:127], 0, v[124:125]
	global_store_dwordx4 v[126:127], v[132:135], off sc0 sc1
	v_cvt_f32_i32_e32 v127, v116
	v_cvt_f32_i32_e32 v126, v112
	v_cvt_f32_i32_e32 v116, v113
	v_pk_mul_f32 v[126:127], v[172:173], v[126:127] op_sel_hi:[0,1]
	v_pk_mul_f32 v[126:127], v[126:127], v[160:161]
	s_nop 0
	v_mul_f32_e32 v112, 0xbfb8aa3b, v127
	v_exp_f32_e32 v112, v112
	s_nop 0
	v_add_f32_e32 v112, 1.0, v112
	v_rcp_f32_e32 v112, v112
	s_nop 0
	v_mul_f32_e32 v112, v127, v112
	v_mul_f32_e32 v126, v126, v112
	v_pk_mul_f32 v[112:113], v[172:173], v[116:117] op_sel_hi:[0,1]
	v_pk_mul_f32 v[112:113], v[112:113], v[52:53]
	s_nop 0
	v_mul_f32_e32 v116, 0xbfb8aa3b, v113
	v_exp_f32_e32 v116, v116
	s_nop 0
	v_add_f32_e32 v116, 1.0, v116
	v_rcp_f32_e32 v116, v116
	s_nop 0
	v_mul_f32_e32 v113, v113, v116
	v_mul_f32_e32 v116, v112, v113
	v_cvt_f32_i32_e32 v113, v118
	v_cvt_f32_i32_e32 v112, v114
	v_pk_mul_f32 v[112:113], v[172:173], v[112:113] op_sel_hi:[0,1]
	v_pk_mul_f32 v[112:113], v[112:113], v[128:129]
	s_nop 0
	v_mul_f32_e32 v114, 0xbfb8aa3b, v113
	v_exp_f32_e32 v114, v114
	s_nop 0
	v_add_f32_e32 v114, 1.0, v114
	v_rcp_f32_e32 v114, v114
	s_nop 0
	v_mul_f32_e32 v113, v113, v114
	v_mul_f32_e32 v114, v112, v113
	v_cvt_f32_i32_e32 v113, v119
	v_cvt_f32_i32_e32 v112, v115
	v_pk_mul_f32 v[112:113], v[172:173], v[112:113] op_sel_hi:[0,1]
	v_pk_mul_f32 v[112:113], v[112:113], v[54:55]
	s_nop 0
	v_mul_f32_e32 v115, 0xbfb8aa3b, v113
	v_exp_f32_e32 v115, v115
	s_nop 0
	v_add_f32_e32 v115, 1.0, v115
	v_rcp_f32_e32 v115, v115
	s_nop 0
	v_mul_f32_e32 v113, v113, v115
	v_mul_f32_e32 v115, v112, v113
	v_cvt_f32_i32_e32 v113, v108
	v_cvt_f32_i32_e32 v112, v104
	v_cvt_f32_i32_e32 v108, v105
	v_pk_mul_f32 v[112:113], v[172:173], v[112:113] op_sel_hi:[0,1]
	v_pk_mul_f32 v[112:113], v[112:113], v[130:131]
	s_nop 0
	v_mul_f32_e32 v104, 0xbfb8aa3b, v113
	v_exp_f32_e32 v104, v104
	s_nop 0
	v_add_f32_e32 v104, 1.0, v104
	v_rcp_f32_e32 v104, v104
	s_nop 0
	v_mul_f32_e32 v104, v113, v104
	v_mul_f32_e32 v112, v112, v104
	v_pk_mul_f32 v[104:105], v[172:173], v[108:109] op_sel_hi:[0,1]
	v_pk_mul_f32 v[104:105], v[104:105], v[40:41]
; __device__ __forceinline__ unsigned cvt_pk_bf16(float lo, float hi) { unsigned r; asm volatile("v_cvt_pk_bf16_f32 %0, %1, %2" : "=v"(r) : "v"(lo), "v"(hi)); return r; }
; __device__ __forceinline__ float sigm(float x) { return __builtin_amdgcn_rcpf(1.f + __builtin_amdgcn_exp2f(-LOG2E * x)); }
;     __device__ __forceinline__ void operator()(const i32x4 (&acc)[2][2][4][2], const Unit& u, int wr, int wc, int fr, int fq) const {
;     ...
;         for (int ai = 0; ai < 2; ++ai)
; #pragma unroll
;             for (int m = 0; m < 4; ++m) {
;                 const int r = row0 + ai * HALF + m * 16; const float rs = sq[ai * 4 + m];
;                 float v[8];
; #pragma unroll
;                 for (int n = 0; n < 2; ++n)
; #pragma unroll
;                     for (int j = 0; j < 4; ++j) { const float g = (float)acc[ai][0][m][n][j] * rs * sg[n][j], up = (float)acc[ai][1][m][n][j] * rs * su[n][j]; v[n * 4 + j] = g * sigm(g) * up; }
;                 u32x4 w; w.x = cvt_pk_bf16(v[0], v[1]); w.y = cvt_pk_bf16(v[2], v[3]); w.z = cvt_pk_bf16(v[4], v[5]); w.w = cvt_pk_bf16(v[6], v[7]);
;                 *(u32x4*)(O + (size_t)r * FF + col0) = w;
	s_nop 0
	v_mul_f32_e32 v108, 0xbfb8aa3b, v105
	v_exp_f32_e32 v108, v108
	s_nop 0
	v_add_f32_e32 v108, 1.0, v108
	v_rcp_f32_e32 v108, v108
	s_nop 0
	v_mul_f32_e32 v105, v105, v108
	v_mul_f32_e32 v108, v104, v105
	v_cvt_f32_i32_e32 v105, v110
	v_cvt_f32_i32_e32 v104, v106
	v_or_b32_e32 v110, 16, v156
	v_pk_mul_f32 v[104:105], v[172:173], v[104:105] op_sel_hi:[0,1]
	v_pk_mul_f32 v[104:105], v[104:105], v[120:121]
	s_nop 0
	v_mul_f32_e32 v106, 0xbfb8aa3b, v105
	v_exp_f32_e32 v106, v106
	s_nop 0
	v_add_f32_e32 v106, 1.0, v106
	v_rcp_f32_e32 v106, v106
	s_nop 0
	v_mul_f32_e32 v105, v105, v106
	v_mul_f32_e32 v109, v104, v105
	v_cvt_f32_i32_e32 v105, v111
	v_cvt_f32_i32_e32 v104, v107
	v_pk_mul_f32 v[104:105], v[172:173], v[104:105] op_sel_hi:[0,1]
	v_pk_mul_f32 v[104:105], v[104:105], v[42:43]
	s_nop 0
	v_mul_f32_e32 v106, 0xbfb8aa3b, v105
	v_exp_f32_e32 v106, v106
	s_nop 0
	v_add_f32_e32 v106, 1.0, v106
	v_rcp_f32_e32 v106, v106
	s_nop 0
	v_mul_f32_e32 v105, v105, v106
	v_mul_f32_e32 v107, v104, v105
	v_cvt_pk_bf16_f32 v104, v126, v116
	v_cvt_pk_bf16_f32 v105, v114, v115
	v_cvt_pk_bf16_f32 v106, v112, v108
	v_cvt_pk_bf16_f32 v107, v109, v107
	v_mad_i64_i32 v[108:109], s[26:27], v110, s46, v[122:123]
	v_lshl_add_u64 v[108:109], v[108:109], 0, v[124:125]
	global_store_dwordx4 v[108:109], v[104:107], off sc0 sc1
	s_nop 1
	v_cvt_f32_i32_e32 v105, v100
	v_cvt_f32_i32_e32 v104, v96
	v_cvt_f32_i32_e32 v100, v97
	v_pk_mul_f32 v[104:105], v[170:171], v[104:105] op_sel_hi:[0,1]
	v_pk_mul_f32 v[104:105], v[104:105], v[160:161]
	s_nop 0
	v_mul_f32_e32 v96, 0xbfb8aa3b, v105
	v_exp_f32_e32 v96, v96
	s_nop 0
	v_add_f32_e32 v96, 1.0, v96
	v_rcp_f32_e32 v96, v96
	s_nop 0
	v_mul_f32_e32 v96, v105, v96
	v_mul_f32_e32 v104, v104, v96
	v_pk_mul_f32 v[96:97], v[170:171], v[100:101] op_sel_hi:[0,1]
	v_pk_mul_f32 v[96:97], v[96:97], v[52:53]
	s_nop 0
	v_mul_f32_e32 v100, 0xbfb8aa3b, v97
	v_exp_f32_e32 v100, v100
	s_nop 0
	v_add_f32_e32 v100, 1.0, v100
	v_rcp_f32_e32 v100, v100
	s_nop 0
	v_mul_f32_e32 v97, v97, v100
	v_mul_f32_e32 v100, v96, v97
	v_cvt_f32_i32_e32 v97, v102
	v_cvt_f32_i32_e32 v96, v98
	v_pk_mul_f32 v[96:97], v[170:171], v[96:97] op_sel_hi:[0,1]
	v_pk_mul_f32 v[96:97], v[96:97], v[128:129]
	s_nop 0
	v_mul_f32_e32 v98, 0xbfb8aa3b, v97
	v_exp_f32_e32 v98, v98
	s_nop 0
	v_add_f32_e32 v98, 1.0, v98
	v_rcp_f32_e32 v98, v98
	s_nop 0
	v_mul_f32_e32 v97, v97, v98
	v_mul_f32_e32 v98, v96, v97
	v_cvt_f32_i32_e32 v97, v103
	v_cvt_f32_i32_e32 v96, v99
	v_pk_mul_f32 v[96:97], v[170:171], v[96:97] op_sel_hi:[0,1]
	v_pk_mul_f32 v[96:97], v[96:97], v[54:55]
	s_nop 0
	v_mul_f32_e32 v99, 0xbfb8aa3b, v97
	v_exp_f32_e32 v99, v99
	s_nop 0
	v_add_f32_e32 v99, 1.0, v99
	v_rcp_f32_e32 v99, v99
	s_nop 0
	v_mul_f32_e32 v97, v97, v99
	v_mul_f32_e32 v99, v96, v97
	v_cvt_f32_i32_e32 v97, v92
	v_cvt_f32_i32_e32 v96, v88
	v_cvt_f32_i32_e32 v92, v89
	v_pk_mul_f32 v[96:97], v[170:171], v[96:97] op_sel_hi:[0,1]
	v_pk_mul_f32 v[96:97], v[96:97], v[130:131]
	s_nop 0
	v_mul_f32_e32 v88, 0xbfb8aa3b, v97
	v_exp_f32_e32 v88, v88
	s_nop 0
	v_add_f32_e32 v88, 1.0, v88
	v_rcp_f32_e32 v88, v88
	s_nop 0
	v_mul_f32_e32 v88, v97, v88
	v_mul_f32_e32 v96, v96, v88
	v_pk_mul_f32 v[88:89], v[170:171], v[92:93] op_sel_hi:[0,1]
	v_pk_mul_f32 v[88:89], v[88:89], v[40:41]
	s_nop 0
	v_mul_f32_e32 v92, 0xbfb8aa3b, v89
	v_exp_f32_e32 v92, v92
	s_nop 0
	v_add_f32_e32 v92, 1.0, v92
	v_rcp_f32_e32 v92, v92
	s_nop 0
	v_mul_f32_e32 v89, v89, v92
	v_mul_f32_e32 v92, v88, v89
	v_cvt_f32_i32_e32 v89, v94
	v_cvt_f32_i32_e32 v88, v90
	v_or_b32_e32 v94, 32, v156
	v_pk_mul_f32 v[88:89], v[170:171], v[88:89] op_sel_hi:[0,1]
	v_pk_mul_f32 v[88:89], v[88:89], v[120:121]
	s_nop 0
	v_mul_f32_e32 v90, 0xbfb8aa3b, v89
	v_exp_f32_e32 v90, v90
	s_nop 0
	v_add_f32_e32 v90, 1.0, v90
	v_rcp_f32_e32 v90, v90
	s_nop 0
	v_mul_f32_e32 v89, v89, v90
	v_mul_f32_e32 v93, v88, v89
	v_cvt_f32_i32_e32 v89, v95
	v_cvt_f32_i32_e32 v88, v91
	v_pk_mul_f32 v[88:89], v[170:171], v[88:89] op_sel_hi:[0,1]
	v_pk_mul_f32 v[88:89], v[88:89], v[42:43]
	s_nop 0
	v_mul_f32_e32 v90, 0xbfb8aa3b, v89
	v_exp_f32_e32 v90, v90
	s_nop 0
	v_add_f32_e32 v90, 1.0, v90
	v_rcp_f32_e32 v90, v90
	s_nop 0
	v_mul_f32_e32 v89, v89, v90
	v_mul_f32_e32 v91, v88, v89
	v_cvt_pk_bf16_f32 v88, v104, v100
	v_cvt_pk_bf16_f32 v89, v98, v99
	v_cvt_pk_bf16_f32 v90, v96, v92
	v_cvt_pk_bf16_f32 v91, v93, v91
	v_mad_i64_i32 v[92:93], s[26:27], v94, s46, v[122:123]
	v_lshl_add_u64 v[92:93], v[92:93], 0, v[124:125]
	global_store_dwordx4 v[92:93], v[88:91], off sc0 sc1
	s_nop 1
	v_cvt_f32_i32_e32 v89, v84
	v_cvt_f32_i32_e32 v88, v80
	v_cvt_f32_i32_e32 v84, v81
	v_pk_mul_f32 v[88:89], v[168:169], v[88:89] op_sel_hi:[0,1]
	v_pk_mul_f32 v[88:89], v[88:89], v[160:161]
	s_nop 0
	v_mul_f32_e32 v80, 0xbfb8aa3b, v89
	v_exp_f32_e32 v80, v80
	s_nop 0
	v_add_f32_e32 v80, 1.0, v80
	v_rcp_f32_e32 v80, v80
	s_nop 0
	v_mul_f32_e32 v80, v89, v80
	v_mul_f32_e32 v88, v88, v80
	v_pk_mul_f32 v[80:81], v[168:169], v[84:85] op_sel_hi:[0,1]
	v_pk_mul_f32 v[80:81], v[80:81], v[52:53]
	s_nop 0
	v_mul_f32_e32 v84, 0xbfb8aa3b, v81
	v_exp_f32_e32 v84, v84
	s_nop 0
	v_add_f32_e32 v84, 1.0, v84
	v_rcp_f32_e32 v84, v84
	s_nop 0
	v_mul_f32_e32 v81, v81, v84
	v_mul_f32_e32 v84, v80, v81
	v_cvt_f32_i32_e32 v81, v86
	v_cvt_f32_i32_e32 v80, v82
	v_pk_mul_f32 v[80:81], v[168:169], v[80:81] op_sel_hi:[0,1]
	v_pk_mul_f32 v[80:81], v[80:81], v[128:129]
	s_nop 0
	v_mul_f32_e32 v82, 0xbfb8aa3b, v81
	v_exp_f32_e32 v82, v82
	s_nop 0
	v_add_f32_e32 v82, 1.0, v82
	v_rcp_f32_e32 v82, v82
	s_nop 0
	v_mul_f32_e32 v81, v81, v82
	v_mul_f32_e32 v82, v80, v81
	v_cvt_f32_i32_e32 v81, v87
	v_cvt_f32_i32_e32 v80, v83
; __device__ __forceinline__ unsigned cvt_pk_bf16(float lo, float hi) { unsigned r; asm volatile("v_cvt_pk_bf16_f32 %0, %1, %2" : "=v"(r) : "v"(lo), "v"(hi)); return r; }
; __device__ __forceinline__ float sigm(float x) { return __builtin_amdgcn_rcpf(1.f + __builtin_amdgcn_exp2f(-LOG2E * x)); }
;     __device__ __forceinline__ void operator()(const i32x4 (&acc)[2][2][4][2], const Unit& u, int wr, int wc, int fr, int fq) const {
;     ...
;         for (int ai = 0; ai < 2; ++ai)
; #pragma unroll
;             for (int m = 0; m < 4; ++m) {
;                 const int r = row0 + ai * HALF + m * 16; const float rs = sq[ai * 4 + m];
;                 float v[8];
; #pragma unroll
;                 for (int n = 0; n < 2; ++n)
; #pragma unroll
;                     for (int j = 0; j < 4; ++j) { const float g = (float)acc[ai][0][m][n][j] * rs * sg[n][j], up = (float)acc[ai][1][m][n][j] * rs * su[n][j]; v[n * 4 + j] = g * sigm(g) * up; }
;                 u32x4 w; w.x = cvt_pk_bf16(v[0], v[1]); w.y = cvt_pk_bf16(v[2], v[3]); w.z = cvt_pk_bf16(v[4], v[5]); w.w = cvt_pk_bf16(v[6], v[7]);
;                 *(u32x4*)(O + (size_t)r * FF + col0) = w;
	v_pk_mul_f32 v[80:81], v[168:169], v[80:81] op_sel_hi:[0,1]
	v_pk_mul_f32 v[80:81], v[80:81], v[54:55]
	s_nop 0
	v_mul_f32_e32 v83, 0xbfb8aa3b, v81
	v_exp_f32_e32 v83, v83
	s_nop 0
	v_add_f32_e32 v83, 1.0, v83
	v_rcp_f32_e32 v83, v83
	s_nop 0
	v_mul_f32_e32 v81, v81, v83
	v_mul_f32_e32 v83, v80, v81
	v_cvt_f32_i32_e32 v81, v76
	v_cvt_f32_i32_e32 v80, v72
	v_cvt_f32_i32_e32 v76, v73
	v_pk_mul_f32 v[80:81], v[168:169], v[80:81] op_sel_hi:[0,1]
	v_pk_mul_f32 v[80:81], v[80:81], v[130:131]
	s_nop 0
	v_mul_f32_e32 v72, 0xbfb8aa3b, v81
	v_exp_f32_e32 v72, v72
	s_nop 0
	v_add_f32_e32 v72, 1.0, v72
	v_rcp_f32_e32 v72, v72
	s_nop 0
	v_mul_f32_e32 v72, v81, v72
	v_mul_f32_e32 v80, v80, v72
	v_pk_mul_f32 v[72:73], v[168:169], v[76:77] op_sel_hi:[0,1]
	v_pk_mul_f32 v[72:73], v[72:73], v[40:41]
	s_nop 0
	v_mul_f32_e32 v76, 0xbfb8aa3b, v73
	v_exp_f32_e32 v76, v76
	s_nop 0
	v_add_f32_e32 v76, 1.0, v76
	v_rcp_f32_e32 v76, v76
	s_nop 0
	v_mul_f32_e32 v73, v73, v76
	v_mul_f32_e32 v76, v72, v73
	v_cvt_f32_i32_e32 v73, v78
	v_cvt_f32_i32_e32 v72, v74
	v_or_b32_e32 v78, 48, v156
	v_pk_mul_f32 v[72:73], v[168:169], v[72:73] op_sel_hi:[0,1]
	v_pk_mul_f32 v[72:73], v[72:73], v[120:121]
	s_nop 0
	v_mul_f32_e32 v74, 0xbfb8aa3b, v73
	v_exp_f32_e32 v74, v74
	s_nop 0
	v_add_f32_e32 v74, 1.0, v74
	v_rcp_f32_e32 v74, v74
	s_nop 0
	v_mul_f32_e32 v73, v73, v74
	v_mul_f32_e32 v77, v72, v73
	v_cvt_f32_i32_e32 v73, v79
	v_cvt_f32_i32_e32 v72, v75
	v_pk_mul_f32 v[72:73], v[168:169], v[72:73] op_sel_hi:[0,1]
	v_pk_mul_f32 v[72:73], v[72:73], v[42:43]
	s_nop 0
	v_mul_f32_e32 v74, 0xbfb8aa3b, v73
	v_exp_f32_e32 v74, v74
	s_nop 0
	v_add_f32_e32 v74, 1.0, v74
	v_rcp_f32_e32 v74, v74
	s_nop 0
	v_mul_f32_e32 v73, v73, v74
	v_mul_f32_e32 v75, v72, v73
	v_cvt_pk_bf16_f32 v72, v88, v84
	v_cvt_pk_bf16_f32 v73, v82, v83
	v_cvt_pk_bf16_f32 v74, v80, v76
	v_cvt_pk_bf16_f32 v75, v77, v75
	v_mad_i64_i32 v[76:77], s[26:27], v78, s46, v[122:123]
	v_lshl_add_u64 v[76:77], v[76:77], 0, v[124:125]
	global_store_dwordx4 v[76:77], v[72:75], off sc0 sc1
	s_nop 1
	v_cvt_f32_i32_e32 v73, v68
	v_cvt_f32_i32_e32 v72, v64
	v_cvt_f32_i32_e32 v68, v65
	v_add_u32_e32 v74, 0x80, v156
	v_pk_mul_f32 v[72:73], v[166:167], v[72:73] op_sel_hi:[0,1]
	v_pk_mul_f32 v[72:73], v[72:73], v[160:161]
	s_nop 0
	v_mul_f32_e32 v64, 0xbfb8aa3b, v73
	v_exp_f32_e32 v64, v64
	s_nop 0
	v_add_f32_e32 v64, 1.0, v64
	v_rcp_f32_e32 v64, v64
	s_nop 0
	v_mul_f32_e32 v64, v73, v64
	v_mul_f32_e32 v72, v72, v64
	v_pk_mul_f32 v[64:65], v[166:167], v[68:69] op_sel_hi:[0,1]
	v_pk_mul_f32 v[64:65], v[64:65], v[52:53]
	s_nop 0
	v_mul_f32_e32 v68, 0xbfb8aa3b, v65
	v_exp_f32_e32 v68, v68
	s_nop 0
	v_add_f32_e32 v68, 1.0, v68
	v_rcp_f32_e32 v68, v68
	s_nop 0
	v_mul_f32_e32 v65, v65, v68
	v_mul_f32_e32 v68, v64, v65
	v_cvt_f32_i32_e32 v65, v70
	v_cvt_f32_i32_e32 v64, v66
	v_pk_mul_f32 v[64:65], v[166:167], v[64:65] op_sel_hi:[0,1]
	v_pk_mul_f32 v[64:65], v[64:65], v[128:129]
	s_nop 0
	v_mul_f32_e32 v66, 0xbfb8aa3b, v65
	v_exp_f32_e32 v66, v66
	s_nop 0
	v_add_f32_e32 v66, 1.0, v66
	v_rcp_f32_e32 v66, v66
	s_nop 0
	v_mul_f32_e32 v65, v65, v66
	v_mul_f32_e32 v66, v64, v65
	v_cvt_f32_i32_e32 v65, v71
	v_cvt_f32_i32_e32 v64, v67
	v_pk_mul_f32 v[64:65], v[166:167], v[64:65] op_sel_hi:[0,1]
	v_pk_mul_f32 v[64:65], v[64:65], v[54:55]
	s_nop 0
	v_mul_f32_e32 v67, 0xbfb8aa3b, v65
	v_exp_f32_e32 v67, v67
	s_nop 0
	v_add_f32_e32 v67, 1.0, v67
	v_rcp_f32_e32 v67, v67
	s_nop 0
	v_mul_f32_e32 v65, v65, v67
	v_mul_f32_e32 v67, v64, v65
	v_cvt_f32_i32_e32 v65, v60
	v_cvt_f32_i32_e32 v64, v56
	v_cvt_f32_i32_e32 v60, v57
	v_pk_mul_f32 v[64:65], v[166:167], v[64:65] op_sel_hi:[0,1]
	v_pk_mul_f32 v[64:65], v[64:65], v[130:131]
	s_nop 0
	v_mul_f32_e32 v56, 0xbfb8aa3b, v65
	v_exp_f32_e32 v56, v56
	s_nop 0
	v_add_f32_e32 v56, 1.0, v56
	v_rcp_f32_e32 v56, v56
	s_nop 0
	v_mul_f32_e32 v56, v65, v56
	v_mul_f32_e32 v64, v64, v56
	v_pk_mul_f32 v[56:57], v[166:167], v[60:61] op_sel_hi:[0,1]
	v_pk_mul_f32 v[56:57], v[56:57], v[40:41]
	s_nop 0
	v_mul_f32_e32 v60, 0xbfb8aa3b, v57
	v_exp_f32_e32 v60, v60
	s_nop 0
	v_add_f32_e32 v60, 1.0, v60
	v_rcp_f32_e32 v60, v60
	s_nop 0
	v_mul_f32_e32 v57, v57, v60
	v_mul_f32_e32 v60, v56, v57
	v_cvt_f32_i32_e32 v57, v62
	v_cvt_f32_i32_e32 v56, v58
	v_pk_mul_f32 v[56:57], v[166:167], v[56:57] op_sel_hi:[0,1]
	v_pk_mul_f32 v[56:57], v[56:57], v[120:121]
	s_nop 0
	v_mul_f32_e32 v58, 0xbfb8aa3b, v57
	v_exp_f32_e32 v58, v58
	s_nop 0
	v_add_f32_e32 v58, 1.0, v58
	v_rcp_f32_e32 v58, v58
	s_nop 0
	v_mul_f32_e32 v57, v57, v58
	v_mul_f32_e32 v61, v56, v57
	v_cvt_f32_i32_e32 v57, v63
	v_cvt_f32_i32_e32 v56, v59
	v_pk_mul_f32 v[56:57], v[166:167], v[56:57] op_sel_hi:[0,1]
	v_pk_mul_f32 v[56:57], v[56:57], v[42:43]
	s_nop 0
	v_mul_f32_e32 v58, 0xbfb8aa3b, v57
	v_exp_f32_e32 v58, v58
	s_nop 0
	v_add_f32_e32 v58, 1.0, v58
	v_rcp_f32_e32 v58, v58
	s_nop 0
	v_mul_f32_e32 v57, v57, v58
	v_mul_f32_e32 v59, v56, v57
	v_cvt_pk_bf16_f32 v56, v72, v68
	v_cvt_pk_bf16_f32 v57, v66, v67
	v_cvt_pk_bf16_f32 v58, v64, v60
	v_cvt_pk_bf16_f32 v59, v61, v59
	v_mad_i64_i32 v[60:61], s[26:27], v74, s46, v[122:123]
	v_lshl_add_u64 v[60:61], v[60:61], 0, v[124:125]
	global_store_dwordx4 v[60:61], v[56:59], off sc0 sc1
	s_nop 1
	v_cvt_f32_i32_e32 v57, v48
	v_cvt_f32_i32_e32 v56, v44
	v_cvt_f32_i32_e32 v48, v45
	v_pk_mul_f32 v[56:57], v[164:165], v[56:57] op_sel_hi:[0,1]
	v_pk_mul_f32 v[56:57], v[56:57], v[160:161]
	s_nop 0
	v_mul_f32_e32 v44, 0xbfb8aa3b, v57
	v_exp_f32_e32 v44, v44
	s_nop 0
	v_add_f32_e32 v44, 1.0, v44
	v_rcp_f32_e32 v44, v44
	s_nop 0
	v_mul_f32_e32 v44, v57, v44
	v_mul_f32_e32 v56, v56, v44
	v_pk_mul_f32 v[44:45], v[164:165], v[48:49] op_sel_hi:[0,1]
; __device__ __forceinline__ unsigned cvt_pk_bf16(float lo, float hi) { unsigned r; asm volatile("v_cvt_pk_bf16_f32 %0, %1, %2" : "=v"(r) : "v"(lo), "v"(hi)); return r; }
; __device__ __forceinline__ float sigm(float x) { return __builtin_amdgcn_rcpf(1.f + __builtin_amdgcn_exp2f(-LOG2E * x)); }
;     __device__ __forceinline__ void operator()(const i32x4 (&acc)[2][2][4][2], const Unit& u, int wr, int wc, int fr, int fq) const {
;     ...
;         for (int ai = 0; ai < 2; ++ai)
; #pragma unroll
;             for (int m = 0; m < 4; ++m) {
;                 const int r = row0 + ai * HALF + m * 16; const float rs = sq[ai * 4 + m];
;                 float v[8];
; #pragma unroll
;                 for (int n = 0; n < 2; ++n)
; #pragma unroll
;                     for (int j = 0; j < 4; ++j) { const float g = (float)acc[ai][0][m][n][j] * rs * sg[n][j], up = (float)acc[ai][1][m][n][j] * rs * su[n][j]; v[n * 4 + j] = g * sigm(g) * up; }
;                 u32x4 w; w.x = cvt_pk_bf16(v[0], v[1]); w.y = cvt_pk_bf16(v[2], v[3]); w.z = cvt_pk_bf16(v[4], v[5]); w.w = cvt_pk_bf16(v[6], v[7]);
;                 *(u32x4*)(O + (size_t)r * FF + col0) = w;
	v_pk_mul_f32 v[44:45], v[44:45], v[52:53]
	s_nop 0
	v_mul_f32_e32 v48, 0xbfb8aa3b, v45
	v_exp_f32_e32 v48, v48
	s_nop 0
	v_add_f32_e32 v48, 1.0, v48
	v_rcp_f32_e32 v48, v48
	s_nop 0
	v_mul_f32_e32 v45, v45, v48
	v_mul_f32_e32 v48, v44, v45
	v_cvt_f32_i32_e32 v45, v50
	v_cvt_f32_i32_e32 v44, v46
	v_pk_mul_f32 v[44:45], v[164:165], v[44:45] op_sel_hi:[0,1]
	v_pk_mul_f32 v[44:45], v[44:45], v[128:129]
	s_nop 0
	v_mul_f32_e32 v46, 0xbfb8aa3b, v45
	v_exp_f32_e32 v46, v46
	s_nop 0
	v_add_f32_e32 v46, 1.0, v46
	v_rcp_f32_e32 v46, v46
	s_nop 0
	v_mul_f32_e32 v45, v45, v46
	v_mul_f32_e32 v46, v44, v45
	v_cvt_f32_i32_e32 v45, v51
	v_cvt_f32_i32_e32 v44, v47
	v_pk_mul_f32 v[44:45], v[164:165], v[44:45] op_sel_hi:[0,1]
	v_pk_mul_f32 v[44:45], v[44:45], v[54:55]
	s_nop 0
	v_mul_f32_e32 v47, 0xbfb8aa3b, v45
	v_exp_f32_e32 v47, v47
	s_nop 0
	v_add_f32_e32 v47, 1.0, v47
	v_rcp_f32_e32 v47, v47
	s_nop 0
	v_mul_f32_e32 v45, v45, v47
	v_mul_f32_e32 v47, v44, v45
	v_cvt_f32_i32_e32 v45, v36
	v_cvt_f32_i32_e32 v44, v32
	v_cvt_f32_i32_e32 v36, v33
	v_pk_mul_f32 v[44:45], v[164:165], v[44:45] op_sel_hi:[0,1]
	v_pk_mul_f32 v[44:45], v[44:45], v[130:131]
	s_nop 0
	v_mul_f32_e32 v32, 0xbfb8aa3b, v45
	v_exp_f32_e32 v32, v32
	s_nop 0
	v_add_f32_e32 v32, 1.0, v32
	v_rcp_f32_e32 v32, v32
	s_nop 0
	v_mul_f32_e32 v32, v45, v32
	v_mul_f32_e32 v44, v44, v32
	v_pk_mul_f32 v[32:33], v[164:165], v[36:37] op_sel_hi:[0,1]
	v_pk_mul_f32 v[32:33], v[32:33], v[40:41]
	s_nop 0
	v_mul_f32_e32 v36, 0xbfb8aa3b, v33
	v_exp_f32_e32 v36, v36
	s_nop 0
	v_add_f32_e32 v36, 1.0, v36
	v_rcp_f32_e32 v36, v36
	s_nop 0
	v_mul_f32_e32 v33, v33, v36
	v_mul_f32_e32 v36, v32, v33
	v_cvt_f32_i32_e32 v33, v38
	v_cvt_f32_i32_e32 v32, v34
	v_add_u32_e32 v38, 0x90, v156
	v_pk_mul_f32 v[32:33], v[164:165], v[32:33] op_sel_hi:[0,1]
	v_pk_mul_f32 v[32:33], v[32:33], v[120:121]
	s_nop 0
	v_mul_f32_e32 v34, 0xbfb8aa3b, v33
	v_exp_f32_e32 v34, v34
	s_nop 0
	v_add_f32_e32 v34, 1.0, v34
	v_rcp_f32_e32 v34, v34
	s_nop 0
	v_mul_f32_e32 v33, v33, v34
	v_mul_f32_e32 v37, v32, v33
	v_cvt_f32_i32_e32 v33, v39
	v_cvt_f32_i32_e32 v32, v35
	v_pk_mul_f32 v[32:33], v[164:165], v[32:33] op_sel_hi:[0,1]
	v_pk_mul_f32 v[32:33], v[32:33], v[42:43]
	s_nop 0
	v_mul_f32_e32 v34, 0xbfb8aa3b, v33
	v_exp_f32_e32 v34, v34
	s_nop 0
	v_add_f32_e32 v34, 1.0, v34
	v_rcp_f32_e32 v34, v34
	s_nop 0
	v_mul_f32_e32 v33, v33, v34
	v_mul_f32_e32 v35, v32, v33
	v_cvt_pk_bf16_f32 v32, v56, v48
	v_cvt_pk_bf16_f32 v33, v46, v47
	v_cvt_pk_bf16_f32 v34, v44, v36
	v_cvt_pk_bf16_f32 v35, v37, v35
	v_mad_i64_i32 v[36:37], s[26:27], v38, s46, v[122:123]
	v_lshl_add_u64 v[36:37], v[36:37], 0, v[124:125]
	global_store_dwordx4 v[36:37], v[32:35], off sc0 sc1
	s_nop 1
	v_cvt_f32_i32_e32 v33, v28
	v_cvt_f32_i32_e32 v32, v24
	v_cvt_f32_i32_e32 v28, v25
	v_pk_mul_f32 v[32:33], v[162:163], v[32:33] op_sel_hi:[0,1]
	v_pk_mul_f32 v[32:33], v[32:33], v[160:161]
	s_nop 0
	v_mul_f32_e32 v24, 0xbfb8aa3b, v33
	v_exp_f32_e32 v24, v24
	s_nop 0
	v_add_f32_e32 v24, 1.0, v24
	v_rcp_f32_e32 v24, v24
	s_nop 0
	v_mul_f32_e32 v24, v33, v24
	v_mul_f32_e32 v32, v32, v24
	v_pk_mul_f32 v[24:25], v[162:163], v[28:29] op_sel_hi:[0,1]
	v_pk_mul_f32 v[24:25], v[24:25], v[52:53]
	s_nop 0
	v_mul_f32_e32 v28, 0xbfb8aa3b, v25
	v_exp_f32_e32 v28, v28
	s_nop 0
	v_add_f32_e32 v28, 1.0, v28
	v_rcp_f32_e32 v28, v28
	s_nop 0
	v_mul_f32_e32 v25, v25, v28
	v_mul_f32_e32 v28, v24, v25
	v_cvt_f32_i32_e32 v25, v30
	v_cvt_f32_i32_e32 v24, v26
	v_pk_mul_f32 v[24:25], v[162:163], v[24:25] op_sel_hi:[0,1]
	v_pk_mul_f32 v[24:25], v[24:25], v[128:129]
	s_nop 0
	v_mul_f32_e32 v26, 0xbfb8aa3b, v25
	v_exp_f32_e32 v26, v26
	s_nop 0
	v_add_f32_e32 v26, 1.0, v26
	v_rcp_f32_e32 v26, v26
	s_nop 0
	v_mul_f32_e32 v25, v25, v26
	v_mul_f32_e32 v26, v24, v25
	v_cvt_f32_i32_e32 v25, v31
	v_cvt_f32_i32_e32 v24, v27
	v_pk_mul_f32 v[24:25], v[162:163], v[24:25] op_sel_hi:[0,1]
	v_pk_mul_f32 v[24:25], v[24:25], v[54:55]
	s_nop 0
	v_mul_f32_e32 v27, 0xbfb8aa3b, v25
	v_exp_f32_e32 v27, v27
	s_nop 0
	v_add_f32_e32 v27, 1.0, v27
	v_rcp_f32_e32 v27, v27
	s_nop 0
	v_mul_f32_e32 v25, v25, v27
	v_mul_f32_e32 v27, v24, v25
	v_cvt_f32_i32_e32 v25, v20
	v_cvt_f32_i32_e32 v24, v16
	v_cvt_f32_i32_e32 v20, v17
	v_pk_mul_f32 v[24:25], v[162:163], v[24:25] op_sel_hi:[0,1]
	v_pk_mul_f32 v[24:25], v[24:25], v[130:131]
	s_nop 0
	v_mul_f32_e32 v16, 0xbfb8aa3b, v25
	v_exp_f32_e32 v16, v16
	s_nop 0
	v_add_f32_e32 v16, 1.0, v16
	v_rcp_f32_e32 v16, v16
	s_nop 0
	v_mul_f32_e32 v16, v25, v16
; __device__ __forceinline__ unsigned cvt_pk_bf16(float lo, float hi) { unsigned r; asm volatile("v_cvt_pk_bf16_f32 %0, %1, %2" : "=v"(r) : "v"(lo), "v"(hi)); return r; }
; __device__ __forceinline__ float sigm(float x) { return __builtin_amdgcn_rcpf(1.f + __builtin_amdgcn_exp2f(-LOG2E * x)); }
; #define PG8_WAIT_V(n) asm volatile("s_waitcnt vmcnt(" #n ")" ::: "memory")
; #define PG8_BAR __builtin_amdgcn_s_barrier()
;     __device__ __forceinline__ void operator()(const i32x4 (&acc)[2][2][4][2], const Unit& u, int wr, int wc, int fr, int fq) const {
;     ...
;         for (int ai = 0; ai < 2; ++ai)
; #pragma unroll
;             for (int m = 0; m < 4; ++m) {
;                 const int r = row0 + ai * HALF + m * 16; const float rs = sq[ai * 4 + m];
;                 float v[8];
; #pragma unroll
;                 for (int n = 0; n < 2; ++n)
; #pragma unroll
;                     for (int j = 0; j < 4; ++j) { const float g = (float)acc[ai][0][m][n][j] * rs * sg[n][j], up = (float)acc[ai][1][m][n][j] * rs * su[n][j]; v[n * 4 + j] = g * sigm(g) * up; }
;                 u32x4 w; w.x = cvt_pk_bf16(v[0], v[1]); w.y = cvt_pk_bf16(v[2], v[3]); w.z = cvt_pk_bf16(v[4], v[5]); w.w = cvt_pk_bf16(v[6], v[7]);
;                 *(u32x4*)(O + (size_t)r * FF + col0) = w;
; template <class Epi, class Sched>
; __device__ __forceinline__ void gemm_phase(LAS unsigned char* lds, const Gemm g, const Sched& S, const Epi& E) {
;     ...
;         E(acc, cur, wr, wc, fr, fq);
;         if (!has_next) break;
; #pragma unroll
;         for (int a = 0; a < 2; ++a)
; #pragma unroll
;             for (int b = 0; b < 2; ++b)
; #pragma unroll
;                 for (int m = 0; m < 4; ++m)
; #pragma unroll
;                     for (int n = 0; n < 2; ++n) acc[a][b][m][n] = (acc_t){0, 0, 0, 0};
;         cur = nxt; cA = nA; cB = nB; ++ui;
;     }
;     PG8_WAIT_V(0);
;     if (wr == 0) PG8_BAR;
;     PG8_BAR;
	v_mul_f32_e32 v24, v24, v16
	v_pk_mul_f32 v[16:17], v[162:163], v[20:21] op_sel_hi:[0,1]
	v_pk_mul_f32 v[16:17], v[16:17], v[40:41]
	s_nop 0
	v_mul_f32_e32 v20, 0xbfb8aa3b, v17
	v_exp_f32_e32 v20, v20
	s_nop 0
	v_add_f32_e32 v20, 1.0, v20
	v_rcp_f32_e32 v20, v20
	s_nop 0
	v_mul_f32_e32 v17, v17, v20
	v_mul_f32_e32 v20, v16, v17
	v_cvt_f32_i32_e32 v17, v22
	v_cvt_f32_i32_e32 v16, v18
	v_add_u32_e32 v22, 0xa0, v156
	v_pk_mul_f32 v[16:17], v[162:163], v[16:17] op_sel_hi:[0,1]
	v_pk_mul_f32 v[16:17], v[16:17], v[120:121]
	s_nop 0
	v_mul_f32_e32 v18, 0xbfb8aa3b, v17
	v_exp_f32_e32 v18, v18
	s_nop 0
	v_add_f32_e32 v18, 1.0, v18
	v_rcp_f32_e32 v18, v18
	s_nop 0
	v_mul_f32_e32 v17, v17, v18
	v_mul_f32_e32 v21, v16, v17
	v_cvt_f32_i32_e32 v17, v23
	v_cvt_f32_i32_e32 v16, v19
	v_pk_mul_f32 v[16:17], v[162:163], v[16:17] op_sel_hi:[0,1]
	v_pk_mul_f32 v[16:17], v[16:17], v[42:43]
	s_nop 0
	v_mul_f32_e32 v18, 0xbfb8aa3b, v17
	v_exp_f32_e32 v18, v18
	s_nop 0
	v_add_f32_e32 v18, 1.0, v18
	v_rcp_f32_e32 v18, v18
	s_nop 0
	v_mul_f32_e32 v17, v17, v18
	v_mul_f32_e32 v19, v16, v17
	v_cvt_pk_bf16_f32 v16, v32, v28
	v_cvt_pk_bf16_f32 v17, v26, v27
	v_cvt_pk_bf16_f32 v18, v24, v20
	v_cvt_pk_bf16_f32 v19, v21, v19
	v_mad_i64_i32 v[20:21], s[26:27], v22, s46, v[122:123]
	v_lshl_add_u64 v[20:21], v[20:21], 0, v[124:125]
	global_store_dwordx4 v[20:21], v[16:19], off sc0 sc1
	s_nop 1
	v_cvt_f32_i32_e32 v17, v12
	v_cvt_f32_i32_e32 v16, v8
	v_cvt_f32_i32_e32 v12, v9
	v_pk_mul_f32 v[16:17], v[158:159], v[16:17] op_sel_hi:[0,1]
	v_pk_mul_f32 v[16:17], v[16:17], v[160:161]
	s_nop 0
	v_mul_f32_e32 v8, 0xbfb8aa3b, v17
	v_exp_f32_e32 v8, v8
	s_nop 0
	v_add_f32_e32 v8, 1.0, v8
	v_rcp_f32_e32 v8, v8
	s_nop 0
	v_mul_f32_e32 v8, v17, v8
	v_mul_f32_e32 v16, v16, v8
	v_pk_mul_f32 v[8:9], v[158:159], v[12:13] op_sel_hi:[0,1]
	v_pk_mul_f32 v[8:9], v[8:9], v[52:53]
	s_nop 0
	v_mul_f32_e32 v12, 0xbfb8aa3b, v9
	v_exp_f32_e32 v12, v12
	s_nop 0
	v_add_f32_e32 v12, 1.0, v12
	v_rcp_f32_e32 v12, v12
	s_nop 0
	v_mul_f32_e32 v9, v9, v12
	v_mul_f32_e32 v12, v8, v9
	v_cvt_f32_i32_e32 v9, v14
	v_cvt_f32_i32_e32 v8, v10
	v_pk_mul_f32 v[8:9], v[158:159], v[8:9] op_sel_hi:[0,1]
	v_pk_mul_f32 v[8:9], v[8:9], v[128:129]
	s_nop 0
	v_mul_f32_e32 v10, 0xbfb8aa3b, v9
	v_exp_f32_e32 v10, v10
	s_nop 0
	v_add_f32_e32 v10, 1.0, v10
	v_rcp_f32_e32 v10, v10
	s_nop 0
	v_mul_f32_e32 v9, v9, v10
	v_mul_f32_e32 v10, v8, v9
	v_cvt_f32_i32_e32 v9, v15
	v_cvt_f32_i32_e32 v8, v11
	v_pk_mul_f32 v[8:9], v[158:159], v[8:9] op_sel_hi:[0,1]
	v_pk_mul_f32 v[8:9], v[8:9], v[54:55]
	s_nop 0
	v_mul_f32_e32 v11, 0xbfb8aa3b, v9
	v_exp_f32_e32 v11, v11
	s_nop 0
	v_add_f32_e32 v11, 1.0, v11
	v_rcp_f32_e32 v11, v11
	s_nop 0
	v_mul_f32_e32 v9, v9, v11
	v_mul_f32_e32 v11, v8, v9
	v_cvt_f32_i32_e32 v9, v4
	v_cvt_f32_i32_e32 v8, v0
	v_cvt_f32_i32_e32 v4, v1
	v_pk_mul_f32 v[8:9], v[158:159], v[8:9] op_sel_hi:[0,1]
	v_pk_mul_f32 v[8:9], v[8:9], v[130:131]
	s_nop 0
	v_mul_f32_e32 v0, 0xbfb8aa3b, v9
	v_exp_f32_e32 v0, v0
	s_nop 0
	v_add_f32_e32 v0, 1.0, v0
	v_rcp_f32_e32 v0, v0
	s_nop 0
	v_mul_f32_e32 v0, v9, v0
	v_mul_f32_e32 v8, v8, v0
	v_pk_mul_f32 v[0:1], v[158:159], v[4:5] op_sel_hi:[0,1]
	v_pk_mul_f32 v[0:1], v[0:1], v[40:41]
	s_nop 0
	v_mul_f32_e32 v4, 0xbfb8aa3b, v1
	v_exp_f32_e32 v4, v4
	s_nop 0
	v_add_f32_e32 v4, 1.0, v4
	v_rcp_f32_e32 v4, v4
	s_nop 0
	v_mul_f32_e32 v1, v1, v4
	v_mul_f32_e32 v4, v0, v1
	v_cvt_f32_i32_e32 v1, v6
	v_cvt_f32_i32_e32 v0, v2
	v_add_u32_e32 v6, 0xb0, v156
	v_pk_mul_f32 v[0:1], v[158:159], v[0:1] op_sel_hi:[0,1]
	v_pk_mul_f32 v[0:1], v[0:1], v[120:121]
	s_nop 0
	v_mul_f32_e32 v2, 0xbfb8aa3b, v1
	v_exp_f32_e32 v2, v2
	s_nop 0
	v_add_f32_e32 v2, 1.0, v2
	v_rcp_f32_e32 v2, v2
	s_nop 0
	v_mul_f32_e32 v1, v1, v2
	v_mul_f32_e32 v5, v0, v1
	v_cvt_f32_i32_e32 v1, v7
	v_cvt_f32_i32_e32 v0, v3
	v_pk_mul_f32 v[0:1], v[158:159], v[0:1] op_sel_hi:[0,1]
	v_pk_mul_f32 v[0:1], v[0:1], v[42:43]
	s_nop 0
	v_mul_f32_e32 v2, 0xbfb8aa3b, v1
	v_exp_f32_e32 v2, v2
	s_nop 0
	v_add_f32_e32 v2, 1.0, v2
	v_rcp_f32_e32 v2, v2
	s_nop 0
	v_mul_f32_e32 v1, v1, v2
	v_mul_f32_e32 v3, v0, v1
	v_cvt_pk_bf16_f32 v0, v16, v12
	v_cvt_pk_bf16_f32 v1, v10, v11
	v_cvt_pk_bf16_f32 v2, v8, v4
	v_cvt_pk_bf16_f32 v3, v5, v3
	v_mad_i64_i32 v[4:5], s[26:27], v6, s46, v[122:123]
	v_lshl_add_u64 v[4:5], v[4:5], 0, v[124:125]
	s_mov_b64 s[26:27], s[20:21]
	global_store_dwordx4 v[4:5], v[0:3], off sc0 sc1
	s_cbranch_vccz .LBB0_112
	s_waitcnt vmcnt(0)
	s_cmpk_gt_u32 s33, 0xff
	s_cbranch_scc1 .LBB0_119
	s_barrier

; #define PG8_STAGE(bufoff, gbase, voff) do { _Pragma("unroll") for (int _i = 0; _i < 2; ++_i) \
;         __builtin_amdgcn_global_load_lds((const unsigned*)((const char*)(gbase) + (voff)[_i]), (LAS unsigned*)(lds + (bufoff) + ldsw + _i * 8192), 16, 0, 0); } while (0)
; #define PG8_LDA(dst, b, h) do { _Pragma("unroll") for (int m = 0; m < 4; ++m) _Pragma("unroll") for (int k = 0; k < 2; ++k) dst[m][k] = *(const LAS bf16x8*)(lds + PG8_SA(b, h) + aoff + m * 2048 + k * 1024); } while (0)
; #define PG8_LDB(dst, b, h) do { _Pragma("unroll") for (int n = 0; n < 2; ++n) _Pragma("unroll") for (int k = 0; k < 2; ++k) dst[n][k] = *(const LAS bf16x8*)(lds + PG8_SB(b, h) + boff + n * 2048 + k * 1024); } while (0)
; #define PG8_MMA(ai, bj, At, Bt) do { __builtin_amdgcn_s_setprio(1); _Pragma("unroll") for (int m = 0; m < 4; ++m) _Pragma("unroll") for (int n = 0; n < 2; ++n) _Pragma("unroll") for (int k = 0; k < 2; ++k) \
;         acc[ai][bj][m][n] = MmaOp<Epi::I8>::run(Bt[n][k], At[m][k], acc[ai][bj][m][n]); __builtin_amdgcn_s_setprio(0); } while (0)
; #define PG8_WAIT_V(n) asm volatile("s_waitcnt vmcnt(" #n ")" ::: "memory")
; #define PG8_WAIT_L(n) asm volatile("s_waitcnt lgkmcnt(" #n ")" ::: "memory")
; #define PG8_BAR __builtin_amdgcn_s_barrier()
; template <class Epi, class Sched>
; __device__ __forceinline__ void gemm_phase(LAS unsigned char* lds, const Gemm g, const Sched& S, const Epi& E) {
;     ...
;             PG8_LDB(B0, 0, 0); PG8_SCHED; PG8_LDA(At, 0, 0); PG8_STAGE(PG8_SA(1, 1), a1 + hstepA, voffA);
;             PG8_WAIT_L(8); PG8_BAR; PG8_WAIT_L(0); PG8_MMA(0, 0, At, B0); PG8_BAR; PG8_SCHED;
;             PG8_LDB(B1, 0, 1); PG8_STAGE(PG8_SB(0, 0), b2, voffB);
;             PG8_BAR; PG8_WAIT_L(0); PG8_MMA(0, 1, At, B1); PG8_BAR;
;             PG8_LDA(At, 0, 1); PG8_STAGE(PG8_SA(0, 0), a2, voffA);
;             PG8_BAR; PG8_WAIT_L(0); PG8_MMA(1, 0, At, B0); PG8_BAR; PG8_SCHED;
;             PG8_STAGE(PG8_SB(0, 1), b2 + hstepB, voffB);
;             PG8_WAIT_V(6); PG8_BAR; PG8_MMA(1, 1, At, B1); PG8_BAR;
;             PG8_LDB(B0, 1, 0); PG8_SCHED; PG8_LDA(At, 1, 0); PG8_STAGE(PG8_SA(0, 1), a2 + hstepA, voffA);
;             PG8_WAIT_L(8); PG8_BAR; PG8_WAIT_L(0); PG8_MMA(0, 0, At, B0); PG8_BAR; PG8_SCHED;
;             PG8_LDB(B1, 1, 1); PG8_STAGE(PG8_SB(1, 0), b3, voffB);
;             PG8_BAR; PG8_WAIT_L(0); PG8_MMA(0, 1, At, B1); PG8_BAR;
.LBB0_238:
	ds_read_b128 v[128:131], v155
	ds_read_b128 v[144:147], v155 offset:1024
	ds_read_b128 v[148:151], v155 offset:2048
	ds_read_b128 v[158:161], v155 offset:3072
	s_add_u32 s18, s16, 0xffea8080
	s_addc_u32 s19, s17, -1
	s_cmpk_eq_i32 s49, 0x52
	s_cselect_b32 s21, s5, s19
	s_cselect_b32 s20, s4, s18
	s_cselect_b32 s19, s7, s48
	s_cselect_b32 s18, s6, s47
	v_lshl_add_u64 v[174:175], s[16:17], 0, v[136:137]
	s_add_i32 m0, s26, 0xc000
	ds_read_b128 v[162:165], v156
	ds_read_b128 v[166:169], v156 offset:1024
	ds_read_b128 v[170:173], v156 offset:2048
	ds_read_b128 v[178:181], v156 offset:3072
	ds_read_b128 v[182:185], v156 offset:4096
	ds_read_b128 v[186:189], v156 offset:5120
	ds_read_b128 v[190:193], v156 offset:6144
	ds_read_b128 v[194:197], v156 offset:7168
	global_load_lds_dwordx4 v[174:175], off
	v_lshl_add_u64 v[174:175], s[16:17], 0, v[138:139]
	s_add_i32 m0, s26, 0xe000
	s_nop 0
	global_load_lds_dwordx4 v[174:175], off
	s_waitcnt lgkmcnt(8)
	s_barrier
	s_waitcnt lgkmcnt(0)
	s_setprio 1
	s_waitcnt lgkmcnt(0)
	v_mfma_f32_16x16x32_bf16 v[124:127], v[128:131], v[162:165], v[124:127]
	v_mfma_f32_16x16x32_bf16 v[120:123], v[148:151], v[162:165], v[120:123]
	v_mfma_f32_16x16x32_bf16 v[116:119], v[128:131], v[170:173], v[116:119]
	v_mfma_f32_16x16x32_bf16 v[112:115], v[148:151], v[170:173], v[112:115]
	v_mfma_f32_16x16x32_bf16 v[92:95], v[128:131], v[182:185], v[92:95]
	v_mfma_f32_16x16x32_bf16 v[88:91], v[148:151], v[182:185], v[88:91]
	v_mfma_f32_16x16x32_bf16 v[84:87], v[128:131], v[190:193], v[84:87]
	v_mfma_f32_16x16x32_bf16 v[76:79], v[148:151], v[190:193], v[76:79]
	v_mfma_f32_16x16x32_bf16 v[124:127], v[144:147], v[166:169], v[124:127]
	v_mfma_f32_16x16x32_bf16 v[120:123], v[158:161], v[166:169], v[120:123]
	v_mfma_f32_16x16x32_bf16 v[116:119], v[144:147], v[178:181], v[116:119]
	v_mfma_f32_16x16x32_bf16 v[112:115], v[158:161], v[178:181], v[112:115]
	v_mfma_f32_16x16x32_bf16 v[92:95], v[144:147], v[186:189], v[92:95]
	v_mfma_f32_16x16x32_bf16 v[88:91], v[158:161], v[186:189], v[88:91]
	v_mfma_f32_16x16x32_bf16 v[84:87], v[144:147], v[194:197], v[84:87]
	v_mfma_f32_16x16x32_bf16 v[76:79], v[158:161], v[194:197], v[76:79]
	s_setprio 0
	s_barrier
	s_add_i32 s50, s37, s23
	v_lshl_add_u64 v[174:175], s[18:19], 0, v[134:135]
	s_mov_b32 m0, s50
	ds_read_b128 v[198:201], v157
	ds_read_b128 v[202:205], v157 offset:1024
	ds_read_b128 v[206:209], v157 offset:2048
	ds_read_b128 v[210:213], v157 offset:3072
	global_load_lds_dwordx4 v[174:175], off
	v_lshl_add_u64 v[214:215], s[18:19], 0, v[132:133]
	s_add_i32 m0, s50, 0x2000
	s_nop 0
	global_load_lds_dwordx4 v[214:215], off
	s_barrier
	s_waitcnt lgkmcnt(0)
	s_setprio 1
	s_waitcnt lgkmcnt(0)
	v_mfma_f32_16x16x32_bf16 v[108:111], v[198:201], v[162:165], v[108:111]
	v_mfma_f32_16x16x32_bf16 v[104:107], v[206:209], v[162:165], v[104:107]
	v_mfma_f32_16x16x32_bf16 v[100:103], v[198:201], v[170:173], v[100:103]
	v_mfma_f32_16x16x32_bf16 v[96:99], v[206:209], v[170:173], v[96:99]
	v_mfma_f32_16x16x32_bf16 v[80:83], v[198:201], v[182:185], v[80:83]
	v_mfma_f32_16x16x32_bf16 v[72:75], v[206:209], v[182:185], v[72:75]
	v_mfma_f32_16x16x32_bf16 v[68:71], v[198:201], v[190:193], v[68:71]
	v_mfma_f32_16x16x32_bf16 v[64:67], v[206:209], v[190:193], v[64:67]
	v_mfma_f32_16x16x32_bf16 v[108:111], v[202:205], v[166:169], v[108:111]
	v_mfma_f32_16x16x32_bf16 v[104:107], v[210:213], v[166:169], v[104:107]
	v_mfma_f32_16x16x32_bf16 v[100:103], v[202:205], v[178:181], v[100:103]
	v_mfma_f32_16x16x32_bf16 v[96:99], v[210:213], v[178:181], v[96:99]
	v_mfma_f32_16x16x32_bf16 v[80:83], v[202:205], v[186:189], v[80:83]
	v_mfma_f32_16x16x32_bf16 v[72:75], v[210:213], v[186:189], v[72:75]
	v_mfma_f32_16x16x32_bf16 v[68:71], v[202:205], v[194:197], v[68:71]
	v_mfma_f32_16x16x32_bf16 v[64:67], v[210:213], v[194:197], v[64:67]
	s_setprio 0
	s_mov_b32 m0, s26
	v_lshl_add_u64 v[216:217], s[20:21], 0, v[134:135]
	s_barrier
	ds_read_b128 v[162:165], v156 offset:16384
	ds_read_b128 v[166:169], v156 offset:17408
	ds_read_b128 v[170:173], v156 offset:18432
	ds_read_b128 v[178:181], v156 offset:19456
	ds_read_b128 v[182:185], v156 offset:20480
	ds_read_b128 v[186:189], v156 offset:21504
	ds_read_b128 v[190:193], v156 offset:22528
	ds_read_b128 v[194:197], v156 offset:23552
	global_load_lds_dwordx4 v[216:217], off
	v_lshl_add_u64 v[218:219], s[20:21], 0, v[132:133]
	s_mov_b32 m0, s27
	s_nop 0
	global_load_lds_dwordx4 v[218:219], off
	s_barrier
	s_waitcnt lgkmcnt(0)
	s_setprio 1
	s_waitcnt lgkmcnt(0)
	v_mfma_f32_16x16x32_bf16 v[60:63], v[128:131], v[162:165], v[60:63]
	v_mfma_f32_16x16x32_bf16 v[56:59], v[148:151], v[162:165], v[56:59]
	v_mfma_f32_16x16x32_bf16 v[52:55], v[128:131], v[170:173], v[52:55]
	v_mfma_f32_16x16x32_bf16 v[44:47], v[148:151], v[170:173], v[44:47]
	v_mfma_f32_16x16x32_bf16 v[28:31], v[128:131], v[182:185], v[28:31]
	v_mfma_f32_16x16x32_bf16 v[24:27], v[148:151], v[182:185], v[24:27]
	v_mfma_f32_16x16x32_bf16 v[20:23], v[128:131], v[190:193], v[20:23]
	v_mfma_f32_16x16x32_bf16 v[12:15], v[148:151], v[190:193], v[12:15]
	v_mfma_f32_16x16x32_bf16 v[60:63], v[144:147], v[166:169], v[60:63]
	v_mfma_f32_16x16x32_bf16 v[56:59], v[158:161], v[166:169], v[56:59]
	v_mfma_f32_16x16x32_bf16 v[52:55], v[144:147], v[178:181], v[52:55]
	v_mfma_f32_16x16x32_bf16 v[44:47], v[158:161], v[178:181], v[44:47]
	v_mfma_f32_16x16x32_bf16 v[28:31], v[144:147], v[186:189], v[28:31]
	v_mfma_f32_16x16x32_bf16 v[24:27], v[158:161], v[186:189], v[24:27]
	v_mfma_f32_16x16x32_bf16 v[20:23], v[144:147], v[194:197], v[20:23]
	v_mfma_f32_16x16x32_bf16 v[12:15], v[158:161], v[194:197], v[12:15]
	s_setprio 0
	s_barrier
; #define PG8_STAGE(bufoff, gbase, voff) do { _Pragma("unroll") for (int _i = 0; _i < 2; ++_i) \
;         __builtin_amdgcn_global_load_lds((const unsigned*)((const char*)(gbase) + (voff)[_i]), (LAS unsigned*)(lds + (bufoff) + ldsw + _i * 8192), 16, 0, 0); } while (0)
; #define PG8_LDA(dst, b, h) do { _Pragma("unroll") for (int m = 0; m < 4; ++m) _Pragma("unroll") for (int k = 0; k < 2; ++k) dst[m][k] = *(const LAS bf16x8*)(lds + PG8_SA(b, h) + aoff + m * 2048 + k * 1024); } while (0)
; #define PG8_LDB(dst, b, h) do { _Pragma("unroll") for (int n = 0; n < 2; ++n) _Pragma("unroll") for (int k = 0; k < 2; ++k) dst[n][k] = *(const LAS bf16x8*)(lds + PG8_SB(b, h) + boff + n * 2048 + k * 1024); } while (0)
; #define PG8_MMA(ai, bj, At, Bt) do { __builtin_amdgcn_s_setprio(1); _Pragma("unroll") for (int m = 0; m < 4; ++m) _Pragma("unroll") for (int n = 0; n < 2; ++n) _Pragma("unroll") for (int k = 0; k < 2; ++k) \
;         acc[ai][bj][m][n] = MmaOp<Epi::I8>::run(Bt[n][k], At[m][k], acc[ai][bj][m][n]); __builtin_amdgcn_s_setprio(0); } while (0)
; #define PG8_WAIT_V(n) asm volatile("s_waitcnt vmcnt(" #n ")" ::: "memory")
; #define PG8_WAIT_L(n) asm volatile("s_waitcnt lgkmcnt(" #n ")" ::: "memory")
; #define PG8_BAR __builtin_amdgcn_s_barrier()
; #define PG8_SCHED __builtin_amdgcn_sched_barrier(0)
; template <class Epi, class Sched>
; __device__ __forceinline__ void gemm_phase(LAS unsigned char* lds, const Gemm g, const Sched& S, const Epi& E) {
;     ...
;             PG8_STAGE(PG8_SB(0, 1), b2 + hstepB, voffB);
;             PG8_WAIT_V(6); PG8_BAR; PG8_MMA(1, 1, At, B1); PG8_BAR;
;             PG8_LDB(B0, 1, 0); PG8_SCHED; PG8_LDA(At, 1, 0); PG8_STAGE(PG8_SA(0, 1), a2 + hstepA, voffA);
;             PG8_WAIT_L(8); PG8_BAR; PG8_WAIT_L(0); PG8_MMA(0, 0, At, B0); PG8_BAR; PG8_SCHED;
;             PG8_LDB(B1, 1, 1); PG8_STAGE(PG8_SB(1, 0), b3, voffB);
;             PG8_BAR; PG8_WAIT_L(0); PG8_MMA(0, 1, At, B1); PG8_BAR;
;             PG8_LDA(At, 1, 1); PG8_STAGE(PG8_SA(1, 0), a3, voffA);
;             PG8_BAR; PG8_WAIT_L(0); PG8_MMA(1, 0, At, B0); PG8_BAR; PG8_SCHED;
	s_add_u32 s50, s18, 0x158000
	s_addc_u32 s51, s19, 0
	s_add_i32 s53, s38, s23
	v_lshl_add_u64 v[128:129], s[50:51], 0, v[134:135]
	s_mov_b32 m0, s53
	s_nop 0
	global_load_lds_dwordx4 v[128:129], off
	v_lshl_add_u64 v[128:129], s[50:51], 0, v[132:133]
	s_add_i32 m0, s53, 0x2000
	s_nop 0
	global_load_lds_dwordx4 v[128:129], off
	s_waitcnt vmcnt(6)
	s_barrier
	s_setprio 1
	v_mfma_f32_16x16x32_bf16 v[48:51], v[198:201], v[162:165], v[48:51]
	v_mfma_f32_16x16x32_bf16 v[40:43], v[206:209], v[162:165], v[40:43]
	v_mfma_f32_16x16x32_bf16 v[36:39], v[198:201], v[170:173], v[36:39]
	v_mfma_f32_16x16x32_bf16 v[32:35], v[206:209], v[170:173], v[32:35]
	v_mfma_f32_16x16x32_bf16 v[16:19], v[198:201], v[182:185], v[16:19]
	v_mfma_f32_16x16x32_bf16 v[8:11], v[206:209], v[182:185], v[8:11]
	v_mfma_f32_16x16x32_bf16 v[4:7], v[198:201], v[190:193], v[4:7]
	v_mfma_f32_16x16x32_bf16 v[0:3], v[206:209], v[190:193], v[0:3]
	v_mfma_f32_16x16x32_bf16 v[48:51], v[202:205], v[166:169], v[48:51]
	v_mfma_f32_16x16x32_bf16 v[40:43], v[210:213], v[166:169], v[40:43]
	v_mfma_f32_16x16x32_bf16 v[36:39], v[202:205], v[178:181], v[36:39]
	v_mfma_f32_16x16x32_bf16 v[32:35], v[210:213], v[178:181], v[32:35]
	v_mfma_f32_16x16x32_bf16 v[16:19], v[202:205], v[186:189], v[16:19]
	v_mfma_f32_16x16x32_bf16 v[8:11], v[210:213], v[186:189], v[8:11]
	v_mfma_f32_16x16x32_bf16 v[4:7], v[202:205], v[194:197], v[4:7]
	v_mfma_f32_16x16x32_bf16 v[0:3], v[210:213], v[194:197], v[0:3]
	s_setprio 0
	s_add_i32 s50, 0, 0x18000
	v_add_u32_e32 v158, s50, v153
	s_barrier
	ds_read_b128 v[128:131], v158
	ds_read_b128 v[144:147], v158 offset:1024
	ds_read_b128 v[148:151], v158 offset:2048
	ds_read_b128 v[158:161], v158 offset:3072
	s_add_u32 s20, s20, 0x158000
	s_addc_u32 s21, s21, 0
	s_mov_b32 m0, s28
	v_lshl_add_u64 v[198:199], s[20:21], 0, v[134:135]
	ds_read_b128 v[162:165], v156 offset:32768
	ds_read_b128 v[166:169], v156 offset:33792
	ds_read_b128 v[170:173], v156 offset:34816
	ds_read_b128 v[178:181], v156 offset:35840
	ds_read_b128 v[182:185], v156 offset:36864
	ds_read_b128 v[186:189], v156 offset:37888
	ds_read_b128 v[190:193], v156 offset:38912
	ds_read_b128 v[194:197], v156 offset:39936
	global_load_lds_dwordx4 v[198:199], off
	v_lshl_add_u64 v[198:199], s[20:21], 0, v[132:133]
	s_mov_b32 m0, s29
	s_nop 0
	global_load_lds_dwordx4 v[198:199], off
	s_waitcnt lgkmcnt(8)
	s_barrier
	s_waitcnt lgkmcnt(0)
	s_setprio 1
	s_waitcnt lgkmcnt(0)
	v_mfma_f32_16x16x32_bf16 v[124:127], v[128:131], v[162:165], v[124:127]
	v_mfma_f32_16x16x32_bf16 v[120:123], v[148:151], v[162:165], v[120:123]
	v_mfma_f32_16x16x32_bf16 v[116:119], v[128:131], v[170:173], v[116:119]
	v_mfma_f32_16x16x32_bf16 v[112:115], v[148:151], v[170:173], v[112:115]
	v_mfma_f32_16x16x32_bf16 v[92:95], v[128:131], v[182:185], v[92:95]
	v_mfma_f32_16x16x32_bf16 v[88:91], v[148:151], v[182:185], v[88:91]
	v_mfma_f32_16x16x32_bf16 v[84:87], v[128:131], v[190:193], v[84:87]
	v_mfma_f32_16x16x32_bf16 v[76:79], v[148:151], v[190:193], v[76:79]
	v_mfma_f32_16x16x32_bf16 v[124:127], v[144:147], v[166:169], v[124:127]
	v_mfma_f32_16x16x32_bf16 v[120:123], v[158:161], v[166:169], v[120:123]
	v_mfma_f32_16x16x32_bf16 v[116:119], v[144:147], v[178:181], v[116:119]
	v_mfma_f32_16x16x32_bf16 v[112:115], v[158:161], v[178:181], v[112:115]
	v_mfma_f32_16x16x32_bf16 v[92:95], v[144:147], v[186:189], v[92:95]
	v_mfma_f32_16x16x32_bf16 v[88:91], v[158:161], v[186:189], v[88:91]
	v_mfma_f32_16x16x32_bf16 v[84:87], v[144:147], v[194:197], v[84:87]
	v_mfma_f32_16x16x32_bf16 v[76:79], v[158:161], v[194:197], v[76:79]
	s_setprio 0
	s_barrier
	s_add_i32 s20, 0, 0x1c000
	s_add_i32 s21, s50, s23
	v_add_u32_e32 v210, s20, v153
	v_lshl_add_u64 v[174:175], v[174:175], 0, s[12:13]
	s_mov_b32 m0, s21
	ds_read_b128 v[198:201], v210
	ds_read_b128 v[202:205], v210 offset:1024
	ds_read_b128 v[206:209], v210 offset:2048
	ds_read_b128 v[210:213], v210 offset:3072
	global_load_lds_dwordx4 v[174:175], off
	v_lshl_add_u64 v[174:175], v[214:215], 0, s[12:13]
	s_add_i32 m0, s21, 0x2000
	s_nop 0
	global_load_lds_dwordx4 v[174:175], off
	s_barrier
	s_waitcnt lgkmcnt(0)
	s_setprio 1
	s_waitcnt lgkmcnt(0)
	v_mfma_f32_16x16x32_bf16 v[108:111], v[198:201], v[162:165], v[108:111]
	v_mfma_f32_16x16x32_bf16 v[104:107], v[206:209], v[162:165], v[104:107]
	v_mfma_f32_16x16x32_bf16 v[100:103], v[198:201], v[170:173], v[100:103]
	v_mfma_f32_16x16x32_bf16 v[96:99], v[206:209], v[170:173], v[96:99]
	v_mfma_f32_16x16x32_bf16 v[80:83], v[198:201], v[182:185], v[80:83]
	v_mfma_f32_16x16x32_bf16 v[72:75], v[206:209], v[182:185], v[72:75]
	v_mfma_f32_16x16x32_bf16 v[68:71], v[198:201], v[190:193], v[68:71]
	v_mfma_f32_16x16x32_bf16 v[64:67], v[206:209], v[190:193], v[64:67]
	v_mfma_f32_16x16x32_bf16 v[108:111], v[202:205], v[166:169], v[108:111]
	v_mfma_f32_16x16x32_bf16 v[104:107], v[210:213], v[166:169], v[104:107]
	v_mfma_f32_16x16x32_bf16 v[100:103], v[202:205], v[178:181], v[100:103]
	v_mfma_f32_16x16x32_bf16 v[96:99], v[210:213], v[178:181], v[96:99]
	v_mfma_f32_16x16x32_bf16 v[80:83], v[202:205], v[186:189], v[80:83]
	v_mfma_f32_16x16x32_bf16 v[72:75], v[210:213], v[186:189], v[72:75]
	v_mfma_f32_16x16x32_bf16 v[68:71], v[202:205], v[194:197], v[68:71]
	v_mfma_f32_16x16x32_bf16 v[64:67], v[210:213], v[194:197], v[64:67]
	s_setprio 0
	s_mov_b32 m0, s31
	v_lshl_add_u64 v[174:175], v[216:217], 0, s[12:13]
	s_barrier
	ds_read_b128 v[162:165], v156 offset:49152
	ds_read_b128 v[166:169], v156 offset:50176
	ds_read_b128 v[170:173], v156 offset:51200
	ds_read_b128 v[178:181], v156 offset:52224
	ds_read_b128 v[182:185], v156 offset:53248
	ds_read_b128 v[186:189], v156 offset:54272
	ds_read_b128 v[190:193], v156 offset:55296
	ds_read_b128 v[194:197], v156 offset:56320
	global_load_lds_dwordx4 v[174:175], off
	v_lshl_add_u64 v[174:175], v[218:219], 0, s[12:13]
	s_mov_b32 m0, s33
	s_nop 0
	global_load_lds_dwordx4 v[174:175], off
	s_barrier
; #define PG8_STAGE(bufoff, gbase, voff) do { _Pragma("unroll") for (int _i = 0; _i < 2; ++_i) \
;         __builtin_amdgcn_global_load_lds((const unsigned*)((const char*)(gbase) + (voff)[_i]), (LAS unsigned*)(lds + (bufoff) + ldsw + _i * 8192), 16, 0, 0); } while (0)
; #define PG8_MMA(ai, bj, At, Bt) do { __builtin_amdgcn_s_setprio(1); _Pragma("unroll") for (int m = 0; m < 4; ++m) _Pragma("unroll") for (int n = 0; n < 2; ++n) _Pragma("unroll") for (int k = 0; k < 2; ++k) \
;         acc[ai][bj][m][n] = MmaOp<Epi::I8>::run(Bt[n][k], At[m][k], acc[ai][bj][m][n]); __builtin_amdgcn_s_setprio(0); } while (0)
; #define PG8_WAIT_V(n) asm volatile("s_waitcnt vmcnt(" #n ")" ::: "memory")
; #define PG8_WAIT_L(n) asm volatile("s_waitcnt lgkmcnt(" #n ")" ::: "memory")
; #define PG8_BAR __builtin_amdgcn_s_barrier()
; #define PG8_SCHED __builtin_amdgcn_sched_barrier(0)
;     __device__ __forceinline__ void operator()(const f32x4 (&acc)[2][2][4][2], const Unit& u, int wr, int wc, int fr, int fq) const {
;         const int row0 = u.pm * BM + wr * 64 + fr, col0 = u.pn * BM + wc * 32 + 4 * fq;
;         const float* base = ((u.pm < MP / BM) ? base_lo : base_hi - (size_t)MP * DM) + (size_t)row0 * DM + col0;
;         f32x4 b[2][2], nb[2][2];
; #pragma unroll
;         for (int bj = 0; bj < 2; ++bj)
; #pragma unroll
;             for (int n = 0; n < 2; ++n) b[bj][n] = *(const f32x4*)(base + bj * HALF + n * 16);
; template <class Epi, class Sched>
; __device__ __forceinline__ void gemm_phase(LAS unsigned char* lds, const Gemm g, const Sched& S, const Epi& E) {
;     ...
;             PG8_BAR; PG8_WAIT_L(0); PG8_MMA(1, 0, At, B0); PG8_BAR; PG8_SCHED;
;             PG8_STAGE(PG8_SB(1, 1), b3 + hstepB, voffB);
;             PG8_WAIT_V(6); PG8_BAR; PG8_MMA(1, 1, At, B1); PG8_BAR;
;         }
	s_waitcnt lgkmcnt(0)
	s_setprio 1
	s_waitcnt lgkmcnt(0)
	v_mfma_f32_16x16x32_bf16 v[60:63], v[128:131], v[162:165], v[60:63]
	v_mfma_f32_16x16x32_bf16 v[56:59], v[148:151], v[162:165], v[56:59]
	v_mfma_f32_16x16x32_bf16 v[52:55], v[128:131], v[170:173], v[52:55]
	v_mfma_f32_16x16x32_bf16 v[44:47], v[148:151], v[170:173], v[44:47]
	v_mfma_f32_16x16x32_bf16 v[28:31], v[128:131], v[182:185], v[28:31]
	v_mfma_f32_16x16x32_bf16 v[24:27], v[148:151], v[182:185], v[24:27]
	v_mfma_f32_16x16x32_bf16 v[20:23], v[128:131], v[190:193], v[20:23]
	v_mfma_f32_16x16x32_bf16 v[12:15], v[148:151], v[190:193], v[12:15]
	v_mfma_f32_16x16x32_bf16 v[60:63], v[144:147], v[166:169], v[60:63]
	v_mfma_f32_16x16x32_bf16 v[56:59], v[158:161], v[166:169], v[56:59]
	v_mfma_f32_16x16x32_bf16 v[52:55], v[144:147], v[178:181], v[52:55]
	v_mfma_f32_16x16x32_bf16 v[44:47], v[158:161], v[178:181], v[44:47]
	v_mfma_f32_16x16x32_bf16 v[28:31], v[144:147], v[186:189], v[28:31]
	v_mfma_f32_16x16x32_bf16 v[24:27], v[158:161], v[186:189], v[24:27]
	v_mfma_f32_16x16x32_bf16 v[20:23], v[144:147], v[194:197], v[20:23]
	v_mfma_f32_16x16x32_bf16 v[12:15], v[158:161], v[194:197], v[12:15]
	s_setprio 0
	s_barrier
	s_add_u32 s18, s18, 0x158080
	s_addc_u32 s19, s19, 0
	s_add_i32 s20, s20, s23
	v_lshl_add_u64 v[128:129], s[18:19], 0, v[134:135]
	s_mov_b32 m0, s20
	s_nop 0
	global_load_lds_dwordx4 v[128:129], off
	v_lshl_add_u64 v[128:129], s[18:19], 0, v[132:133]
	s_add_i32 m0, s20, 0x2000
	s_nop 0
	global_load_lds_dwordx4 v[128:129], off
	s_waitcnt vmcnt(6)
	s_barrier
	s_setprio 1
	v_mfma_f32_16x16x32_bf16 v[48:51], v[198:201], v[162:165], v[48:51]
	v_mfma_f32_16x16x32_bf16 v[40:43], v[206:209], v[162:165], v[40:43]
	v_mfma_f32_16x16x32_bf16 v[36:39], v[198:201], v[170:173], v[36:39]
	v_mfma_f32_16x16x32_bf16 v[32:35], v[206:209], v[170:173], v[32:35]
	v_mfma_f32_16x16x32_bf16 v[16:19], v[198:201], v[182:185], v[16:19]
	v_mfma_f32_16x16x32_bf16 v[8:11], v[206:209], v[182:185], v[8:11]
	v_mfma_f32_16x16x32_bf16 v[4:7], v[198:201], v[190:193], v[4:7]
	v_mfma_f32_16x16x32_bf16 v[0:3], v[206:209], v[190:193], v[0:3]
	v_mfma_f32_16x16x32_bf16 v[48:51], v[202:205], v[166:169], v[48:51]
	v_mfma_f32_16x16x32_bf16 v[40:43], v[210:213], v[166:169], v[40:43]
	v_mfma_f32_16x16x32_bf16 v[36:39], v[202:205], v[178:181], v[36:39]
	v_mfma_f32_16x16x32_bf16 v[32:35], v[210:213], v[178:181], v[32:35]
	v_mfma_f32_16x16x32_bf16 v[16:19], v[202:205], v[186:189], v[16:19]
	v_mfma_f32_16x16x32_bf16 v[8:11], v[210:213], v[186:189], v[8:11]
	v_mfma_f32_16x16x32_bf16 v[4:7], v[202:205], v[194:197], v[4:7]
	v_mfma_f32_16x16x32_bf16 v[0:3], v[210:213], v[194:197], v[0:3]
	s_setprio 0
	s_add_i32 s49, s49, 2
	s_add_u32 s16, s16, 0x100
	s_addc_u32 s17, s17, 0
	s_add_u32 s47, s47, 0x100
	s_addc_u32 s48, s48, 0
	s_cmpk_gt_u32 s49, 0x53
	s_barrier
	s_cbranch_scc0 .LBB0_238
	v_readlane_b32 s56, v239, 2
	v_lshl_add_u32 v146, s45, 8, v152
	v_readlane_b32 s57, v239, 3
	s_cmp_lt_i32 s45, 32
	s_mov_b64 s[48:49], s[56:57]
	v_ashrrev_i32_e32 v147, 31, v146
	v_lshl_or_b32 v144, s46, 8, v154
	s_cselect_b32 s17, s49, s36
	s_cselect_b32 s16, s48, s35
	v_lshlrev_b64 v[128:129], 13, v[146:147]
	v_lshl_add_u64 v[128:129], s[16:17], 0, v[128:129]
	v_ashrrev_i32_e32 v145, 31, v144
	v_lshl_add_u64 v[148:149], v[144:145], 2, v[128:129]
	global_load_dwordx4 v[158:161], v[148:149], off
	global_load_dwordx4 v[162:165], v[148:149], off offset:64
	global_load_dwordx4 v[166:169], v[148:149], off offset:512
	global_load_dwordx4 v[170:173], v[148:149], off offset:576
	s_mov_b32 s16, 0x20000
	v_add_co_u32_e32 v128, vcc, s16, v148
	v_lshlrev_b64 v[150:151], 11, v[146:147]
	s_nop 0
	v_addc_co_u32_e32 v129, vcc, 0, v149, vcc
	global_load_dwordx4 v[178:181], v[128:129], off
	global_load_dwordx4 v[182:185], v[128:129], off offset:64
	global_load_dwordx4 v[186:189], v[128:129], off offset:512
	s_nop 0
	global_load_dwordx4 v[128:131], v[128:129], off offset:576
	v_readlane_b32 s88, v239, 27
	v_lshl_add_u64 v[150:151], v[150:151], 0, v[144:145]
	v_readlane_b32 s92, v239, 31
	v_readlane_b32 s93, v239, 32
	v_readlane_b32 s18, v239, 25
	v_readlane_b32 s19, v239, 26
	v_lshl_add_u64 v[190:191], v[150:151], 2, s[92:93]
	s_mov_b32 s16, 0x40000
	v_lshl_add_u64 v[192:193], v[150:151], 1, s[18:19]
	v_add_co_u32_e32 v194, vcc, s16, v148
	v_or_b32_e32 v174, 16, v146
	s_nop 0
	v_addc_co_u32_e32 v195, vcc, 0, v149, vcc
	v_ashrrev_i32_e32 v175, 31, v174
	v_lshlrev_b64 v[174:175], 11, v[174:175]
	v_lshl_add_u64 v[174:175], v[174:175], 0, v[144:145]
	v_lshl_add_u64 v[196:197], v[174:175], 2, s[92:93]
	v_lshl_add_u64 v[174:175], v[174:175], 1, s[18:19]
	s_mov_b32 s17, 0x60000
	v_add_co_u32_e32 v198, vcc, s17, v148
	s_mov_b32 s46, s43
	s_nop 0
	v_addc_co_u32_e32 v199, vcc, 0, v149, vcc
	s_mov_b32 s45, s44
	s_mov_b64 s[16:17], s[4:5]
	v_readlane_b32 s58, v239, 4
	v_readlane_b32 s59, v239, 5
	v_readlane_b32 s60, v239, 6
	v_readlane_b32 s61, v239, 7
	v_readlane_b32 s62, v239, 8
	v_readlane_b32 s63, v239, 9
	v_readlane_b32 s64, v239, 10
	v_readlane_b32 s65, v239, 11
	v_readlane_b32 s66, v239, 12
	v_readlane_b32 s67, v239, 13
	v_readlane_b32 s68, v239, 14
	v_readlane_b32 s69, v239, 15
	v_readlane_b32 s70, v239, 16
	v_readlane_b32 s71, v239, 17
	v_readlane_b32 s89, v239, 28
	v_readlane_b32 s90, v239, 29
	v_readlane_b32 s91, v239, 30
	v_readlane_b32 s94, v239, 33
	v_readlane_b32 s95, v239, 34
	s_waitcnt vmcnt(0)
; __device__ __forceinline__ unsigned cvt_pk_bf16(float lo, float hi) { unsigned r; asm volatile("v_cvt_pk_bf16_f32 %0, %1, %2" : "=v"(r) : "v"(lo), "v"(hi)); return r; }
;     __device__ __forceinline__ void operator()(const f32x4 (&acc)[2][2][4][2], const Unit& u, int wr, int wc, int fr, int fq) const {
;     ...
;         for (int g = 0; g < 8; ++g) {
;             const int ai = g >> 2, m = g & 3;
;             const int r = row0 + ai * HALF + m * 16; const size_t off = (size_t)r * DM + col0; float s = 0.f;
;             if (g < 7) { const float* nrow = base + (size_t)(((g + 1) >> 2) * HALF + ((g + 1) & 3) * 16) * DM;
; #pragma unroll
;                 for (int bj = 0; bj < 2; ++bj)
; #pragma unroll
;                     for (int n = 0; n < 2; ++n) nb[bj][n] = *(const f32x4*)(nrow + bj * HALF + n * 16); }
; #pragma unroll
;             for (int bj = 0; bj < 2; ++bj)
; #pragma unroll
;                 for (int n = 0; n < 2; ++n) {
;                     const f32x4 o = b[bj][n] + acc[ai][bj][m][n] * alpha;
;                     *(f32x4*)(out + off + bj * HALF + n * 16) = o;
;                     if (WITH_SSQ) s += (o[0] * o[0] + o[1] * o[1]) + (o[2] * o[2] + o[3] * o[3]);
;                     if (WITH_HB) { u32x2 w; w.x = cvt_pk_bf16(o[0], o[1]); w.y = cvt_pk_bf16(o[2], o[3]); *(u32x2*)(hb + off + bj * HALF + n * 16) = w; }
;                 }
;             if (WITH_SSQ) { s += __shfl_xor(s, 16); s += __shfl_xor(s, 32); if (fq == 0) atomicAdd(ssq + r, s); }
;             asm volatile("" ::: "memory");
; #pragma unroll
;             for (int bj = 0; bj < 2; ++bj)
; #pragma unroll
;                 for (int n = 0; n < 2; ++n) b[bj][n] = nb[bj][n];
;         }
	v_pk_fma_f32 v[126:127], v[126:127], 0.5, v[160:161] op_sel_hi:[1,0,1]
	v_pk_fma_f32 v[124:125], v[124:125], 0.5, v[158:159] op_sel_hi:[1,0,1]
	v_pk_fma_f32 v[120:121], v[120:121], 0.5, v[162:163] op_sel_hi:[1,0,1]
	global_store_dwordx4 v[190:191], v[124:127], off sc0 sc1
	v_pk_fma_f32 v[122:123], v[122:123], 0.5, v[164:165] op_sel_hi:[1,0,1]
	v_pk_fma_f32 v[108:109], v[108:109], 0.5, v[166:167] op_sel_hi:[1,0,1]
	v_cvt_pk_bf16_f32 v124, v124, v125
	v_cvt_pk_bf16_f32 v125, v126, v127
	global_store_dwordx2 v[192:193], v[124:125], off sc0 sc1
	global_store_dwordx4 v[190:191], v[120:123], off offset:64 sc0 sc1
	v_pk_fma_f32 v[110:111], v[110:111], 0.5, v[168:169] op_sel_hi:[1,0,1]
	v_pk_fma_f32 v[104:105], v[104:105], 0.5, v[170:171] op_sel_hi:[1,0,1]
	v_cvt_pk_bf16_f32 v120, v120, v121
	v_cvt_pk_bf16_f32 v121, v122, v123
	global_store_dwordx2 v[192:193], v[120:121], off offset:32 sc0 sc1
	global_store_dwordx4 v[190:191], v[108:111], off offset:512 sc0 sc1
	v_pk_fma_f32 v[106:107], v[106:107], 0.5, v[172:173] op_sel_hi:[1,0,1]
	v_pk_fma_f32 v[118:119], v[118:119], 0.5, v[180:181] op_sel_hi:[1,0,1]
	v_cvt_pk_bf16_f32 v108, v108, v109
	v_cvt_pk_bf16_f32 v109, v110, v111
	global_store_dwordx2 v[192:193], v[108:109], off offset:256 sc0 sc1
	global_store_dwordx4 v[190:191], v[104:107], off offset:576 sc0 sc1
	v_pk_fma_f32 v[116:117], v[116:117], 0.5, v[178:179] op_sel_hi:[1,0,1]
	v_pk_fma_f32 v[112:113], v[112:113], 0.5, v[182:183] op_sel_hi:[1,0,1]
	v_cvt_pk_bf16_f32 v104, v104, v105
	v_cvt_pk_bf16_f32 v105, v106, v107
	global_store_dwordx2 v[192:193], v[104:105], off offset:288 sc0 sc1
	global_load_dwordx4 v[104:107], v[194:195], off
	global_load_dwordx4 v[108:111], v[194:195], off offset:64
	global_load_dwordx4 v[120:123], v[194:195], off offset:512
	global_load_dwordx4 v[124:127], v[194:195], off offset:576
	v_pk_fma_f32 v[114:115], v[114:115], 0.5, v[184:185] op_sel_hi:[1,0,1]
	global_store_dwordx4 v[196:197], v[116:119], off sc0 sc1
	v_pk_fma_f32 v[100:101], v[100:101], 0.5, v[186:187] op_sel_hi:[1,0,1]
	v_pk_fma_f32 v[102:103], v[102:103], 0.5, v[188:189] op_sel_hi:[1,0,1]
	v_cvt_pk_bf16_f32 v116, v116, v117
	v_cvt_pk_bf16_f32 v117, v118, v119
	global_store_dwordx2 v[174:175], v[116:117], off sc0 sc1
	global_store_dwordx4 v[196:197], v[112:115], off offset:64 sc0 sc1
	v_pk_fma_f32 v[96:97], v[96:97], 0.5, v[128:129] op_sel_hi:[1,0,1]
	v_pk_fma_f32 v[98:99], v[98:99], 0.5, v[130:131] op_sel_hi:[1,0,1]
	v_cvt_pk_bf16_f32 v112, v112, v113
	v_cvt_pk_bf16_f32 v113, v114, v115
	global_store_dwordx2 v[174:175], v[112:113], off offset:32 sc0 sc1
	global_store_dwordx4 v[196:197], v[100:103], off offset:512 sc0 sc1
	v_or_b32_e32 v128, 32, v146
	v_ashrrev_i32_e32 v129, 31, v128
	v_cvt_pk_bf16_f32 v100, v100, v101
	v_cvt_pk_bf16_f32 v101, v102, v103
	global_store_dwordx2 v[174:175], v[100:101], off offset:256 sc0 sc1
	global_store_dwordx4 v[196:197], v[96:99], off offset:576 sc0 sc1
	v_lshlrev_b64 v[128:129], 11, v[128:129]
	v_lshl_add_u64 v[128:129], v[128:129], 0, v[144:145]
	v_cvt_pk_bf16_f32 v96, v96, v97
	v_cvt_pk_bf16_f32 v97, v98, v99
	global_store_dwordx2 v[174:175], v[96:97], off offset:288 sc0 sc1
	global_load_dwordx4 v[96:99], v[198:199], off
	global_load_dwordx4 v[100:103], v[198:199], off offset:64
	global_load_dwordx4 v[112:115], v[198:199], off offset:512
	global_load_dwordx4 v[116:119], v[198:199], off offset:576
	v_lshl_add_u64 v[158:159], v[128:129], 2, s[92:93]
	v_lshl_add_u64 v[128:129], v[128:129], 1, s[18:19]
	v_add_co_u32_e32 v160, vcc, s39, v148
	v_or_b32_e32 v130, 48, v146
	s_nop 0
	v_addc_co_u32_e32 v161, vcc, 0, v149, vcc
	v_ashrrev_i32_e32 v131, 31, v130
	v_lshlrev_b64 v[130:131], 11, v[130:131]
	v_lshl_add_u64 v[130:131], v[130:131], 0, v[144:145]
	v_lshl_add_u64 v[162:163], v[130:131], 2, s[92:93]
	v_lshl_add_u64 v[130:131], v[130:131], 1, s[18:19]
	v_add_co_u32_e32 v164, vcc, s40, v148
	s_waitcnt vmcnt(0)
	v_pk_fma_f32 v[94:95], v[94:95], 0.5, v[106:107] op_sel_hi:[1,0,1]
	v_pk_fma_f32 v[92:93], v[92:93], 0.5, v[104:105] op_sel_hi:[1,0,1]
	v_pk_fma_f32 v[88:89], v[88:89], 0.5, v[108:109] op_sel_hi:[1,0,1]
	global_store_dwordx4 v[158:159], v[92:95], off sc0 sc1
	v_pk_fma_f32 v[90:91], v[90:91], 0.5, v[110:111] op_sel_hi:[1,0,1]
	v_pk_fma_f32 v[80:81], v[80:81], 0.5, v[120:121] op_sel_hi:[1,0,1]
	v_cvt_pk_bf16_f32 v92, v92, v93
	v_cvt_pk_bf16_f32 v93, v94, v95
	global_store_dwordx2 v[128:129], v[92:93], off sc0 sc1
	global_store_dwordx4 v[158:159], v[88:91], off offset:64 sc0 sc1
	v_pk_fma_f32 v[82:83], v[82:83], 0.5, v[122:123] op_sel_hi:[1,0,1]
	v_pk_fma_f32 v[72:73], v[72:73], 0.5, v[124:125] op_sel_hi:[1,0,1]
	v_cvt_pk_bf16_f32 v88, v88, v89
	v_cvt_pk_bf16_f32 v89, v90, v91
	global_store_dwordx2 v[128:129], v[88:89], off offset:32 sc0 sc1
	global_store_dwordx4 v[158:159], v[80:83], off offset:512 sc0 sc1
	v_pk_fma_f32 v[74:75], v[74:75], 0.5, v[126:127] op_sel_hi:[1,0,1]
	v_addc_co_u32_e32 v165, vcc, 0, v149, vcc
	v_cvt_pk_bf16_f32 v80, v80, v81
	v_cvt_pk_bf16_f32 v81, v82, v83
	global_store_dwordx2 v[128:129], v[80:81], off offset:256 sc0 sc1
	global_store_dwordx4 v[158:159], v[72:75], off offset:576 sc0 sc1
	v_pk_fma_f32 v[78:79], v[78:79], 0.5, v[102:103] op_sel_hi:[1,0,1]
	s_nop 0
	v_cvt_pk_bf16_f32 v72, v72, v73
	v_cvt_pk_bf16_f32 v73, v74, v75
	global_store_dwordx2 v[128:129], v[72:73], off offset:288 sc0 sc1
	global_load_dwordx4 v[80:83], v[160:161], off
	v_pk_fma_f32 v[74:75], v[86:87], 0.5, v[98:99] op_sel_hi:[1,0,1]
	v_pk_fma_f32 v[72:73], v[84:85], 0.5, v[96:97] op_sel_hi:[1,0,1]
	global_load_dwordx4 v[84:87], v[160:161], off offset:64
	global_load_dwordx4 v[88:91], v[160:161], off offset:512
; __device__ __forceinline__ unsigned cvt_pk_bf16(float lo, float hi) { unsigned r; asm volatile("v_cvt_pk_bf16_f32 %0, %1, %2" : "=v"(r) : "v"(lo), "v"(hi)); return r; }
;     __device__ __forceinline__ void operator()(const f32x4 (&acc)[2][2][4][2], const Unit& u, int wr, int wc, int fr, int fq) const {
;     ...
;         for (int g = 0; g < 8; ++g) {
;             const int ai = g >> 2, m = g & 3;
;             const int r = row0 + ai * HALF + m * 16; const size_t off = (size_t)r * DM + col0; float s = 0.f;
;             if (g < 7) { const float* nrow = base + (size_t)(((g + 1) >> 2) * HALF + ((g + 1) & 3) * 16) * DM;
; #pragma unroll
;                 for (int bj = 0; bj < 2; ++bj)
; #pragma unroll
;                     for (int n = 0; n < 2; ++n) nb[bj][n] = *(const f32x4*)(nrow + bj * HALF + n * 16); }
; #pragma unroll
;             for (int bj = 0; bj < 2; ++bj)
; #pragma unroll
;                 for (int n = 0; n < 2; ++n) {
;                     const f32x4 o = b[bj][n] + acc[ai][bj][m][n] * alpha;
;                     *(f32x4*)(out + off + bj * HALF + n * 16) = o;
;                     if (WITH_SSQ) s += (o[0] * o[0] + o[1] * o[1]) + (o[2] * o[2] + o[3] * o[3]);
;                     if (WITH_HB) { u32x2 w; w.x = cvt_pk_bf16(o[0], o[1]); w.y = cvt_pk_bf16(o[2], o[3]); *(u32x2*)(hb + off + bj * HALF + n * 16) = w; }
;                 }
;             if (WITH_SSQ) { s += __shfl_xor(s, 16); s += __shfl_xor(s, 32); if (fq == 0) atomicAdd(ssq + r, s); }
;             asm volatile("" ::: "memory");
; #pragma unroll
;             for (int bj = 0; bj < 2; ++bj)
; #pragma unroll
;                 for (int n = 0; n < 2; ++n) b[bj][n] = nb[bj][n];
;         }
	global_load_dwordx4 v[92:95], v[160:161], off offset:576
	v_pk_fma_f32 v[76:77], v[76:77], 0.5, v[100:101] op_sel_hi:[1,0,1]
	global_store_dwordx4 v[162:163], v[72:75], off sc0 sc1
	v_pk_fma_f32 v[68:69], v[68:69], 0.5, v[112:113] op_sel_hi:[1,0,1]
	v_pk_fma_f32 v[70:71], v[70:71], 0.5, v[114:115] op_sel_hi:[1,0,1]
	v_cvt_pk_bf16_f32 v72, v72, v73
	v_cvt_pk_bf16_f32 v73, v74, v75
	global_store_dwordx2 v[130:131], v[72:73], off sc0 sc1
	global_store_dwordx4 v[162:163], v[76:79], off offset:64 sc0 sc1
	v_cvt_pk_bf16_f32 v72, v76, v77
	v_cvt_pk_bf16_f32 v73, v78, v79
	v_pk_fma_f32 v[64:65], v[64:65], 0.5, v[116:117] op_sel_hi:[1,0,1]
	global_store_dwordx2 v[130:131], v[72:73], off offset:32 sc0 sc1
	global_store_dwordx4 v[162:163], v[68:71], off offset:512 sc0 sc1
	v_pk_fma_f32 v[66:67], v[66:67], 0.5, v[118:119] op_sel_hi:[1,0,1]
	v_lshl_add_u64 v[98:99], v[150:151], 0, s[14:15]
	v_cvt_pk_bf16_f32 v68, v68, v69
	v_cvt_pk_bf16_f32 v69, v70, v71
	global_store_dwordx2 v[130:131], v[68:69], off offset:256 sc0 sc1
	global_store_dwordx4 v[162:163], v[64:67], off offset:576 sc0 sc1
	v_lshl_add_u64 v[100:101], v[98:99], 2, s[92:93]
	v_lshl_add_u64 v[98:99], v[98:99], 1, s[18:19]
	v_cvt_pk_bf16_f32 v64, v64, v65
	v_cvt_pk_bf16_f32 v65, v66, v67
	global_store_dwordx2 v[130:131], v[64:65], off offset:288 sc0 sc1
	global_load_dwordx4 v[64:67], v[164:165], off
	global_load_dwordx4 v[68:71], v[164:165], off offset:64
	global_load_dwordx4 v[72:75], v[164:165], off offset:512
	global_load_dwordx4 v[76:79], v[164:165], off offset:576
	v_add_u32_e32 v96, 0x90, v146
	v_add_co_u32_e32 v102, vcc, s41, v148
	v_ashrrev_i32_e32 v97, 31, v96
	s_nop 0
	v_addc_co_u32_e32 v103, vcc, 0, v149, vcc
	v_lshlrev_b64 v[96:97], 11, v[96:97]
	v_lshl_add_u64 v[96:97], v[96:97], 0, v[144:145]
	v_lshl_add_u64 v[104:105], v[96:97], 2, s[92:93]
	v_lshl_add_u64 v[96:97], v[96:97], 1, s[18:19]
	v_add_co_u32_e32 v106, vcc, s42, v148
	s_waitcnt vmcnt(0)
	v_pk_fma_f32 v[62:63], v[62:63], 0.5, v[82:83] op_sel_hi:[1,0,1]
	v_pk_fma_f32 v[60:61], v[60:61], 0.5, v[80:81] op_sel_hi:[1,0,1]
	global_store_dwordx4 v[100:101], v[60:63], off sc0 sc1
	v_pk_fma_f32 v[56:57], v[56:57], 0.5, v[84:85] op_sel_hi:[1,0,1]
	v_pk_fma_f32 v[58:59], v[58:59], 0.5, v[86:87] op_sel_hi:[1,0,1]
	v_cvt_pk_bf16_f32 v60, v60, v61
	v_cvt_pk_bf16_f32 v61, v62, v63
	v_pk_fma_f32 v[48:49], v[48:49], 0.5, v[88:89] op_sel_hi:[1,0,1]
	global_store_dwordx2 v[98:99], v[60:61], off sc0 sc1
	global_store_dwordx4 v[100:101], v[56:59], off offset:64 sc0 sc1
	v_pk_fma_f32 v[50:51], v[50:51], 0.5, v[90:91] op_sel_hi:[1,0,1]
	v_pk_fma_f32 v[40:41], v[40:41], 0.5, v[92:93] op_sel_hi:[1,0,1]
	v_cvt_pk_bf16_f32 v56, v56, v57
	v_cvt_pk_bf16_f32 v57, v58, v59
	global_store_dwordx2 v[98:99], v[56:57], off offset:32 sc0 sc1
	global_store_dwordx4 v[100:101], v[48:51], off offset:512 sc0 sc1
	v_pk_fma_f32 v[42:43], v[42:43], 0.5, v[94:95] op_sel_hi:[1,0,1]
	v_addc_co_u32_e32 v107, vcc, 0, v149, vcc
	v_cvt_pk_bf16_f32 v48, v48, v49
	v_cvt_pk_bf16_f32 v49, v50, v51
	global_store_dwordx2 v[98:99], v[48:49], off offset:256 sc0 sc1
	global_store_dwordx4 v[100:101], v[40:43], off offset:576 sc0 sc1
	s_and_b64 vcc, exec, s[0:1]
	v_pk_fma_f32 v[46:47], v[46:47], 0.5, v[70:71] op_sel_hi:[1,0,1]
	v_cvt_pk_bf16_f32 v40, v40, v41
	v_cvt_pk_bf16_f32 v41, v42, v43
	global_store_dwordx2 v[98:99], v[40:41], off offset:288 sc0 sc1
	global_load_dwordx4 v[48:51], v[102:103], off
	v_pk_fma_f32 v[42:43], v[54:55], 0.5, v[66:67] op_sel_hi:[1,0,1]
	v_pk_fma_f32 v[40:41], v[52:53], 0.5, v[64:65] op_sel_hi:[1,0,1]
	global_load_dwordx4 v[52:55], v[102:103], off offset:64
	global_load_dwordx4 v[56:59], v[102:103], off offset:512
	global_load_dwordx4 v[60:63], v[102:103], off offset:576
	v_pk_fma_f32 v[44:45], v[44:45], 0.5, v[68:69] op_sel_hi:[1,0,1]
	global_store_dwordx4 v[104:105], v[40:43], off sc0 sc1
	v_pk_fma_f32 v[36:37], v[36:37], 0.5, v[72:73] op_sel_hi:[1,0,1]
	v_pk_fma_f32 v[38:39], v[38:39], 0.5, v[74:75] op_sel_hi:[1,0,1]
	v_cvt_pk_bf16_f32 v40, v40, v41
	v_cvt_pk_bf16_f32 v41, v42, v43
	global_store_dwordx2 v[96:97], v[40:41], off sc0 sc1
	global_store_dwordx4 v[104:105], v[44:47], off offset:64 sc0 sc1
	v_cvt_pk_bf16_f32 v40, v44, v45
	v_cvt_pk_bf16_f32 v41, v46, v47
	v_pk_fma_f32 v[32:33], v[32:33], 0.5, v[76:77] op_sel_hi:[1,0,1]
	global_store_dwordx2 v[96:97], v[40:41], off offset:32 sc0 sc1
	global_store_dwordx4 v[104:105], v[36:39], off offset:512 sc0 sc1
	v_pk_fma_f32 v[34:35], v[34:35], 0.5, v[78:79] op_sel_hi:[1,0,1]
	v_add_u32_e32 v64, 0xa0, v146
	v_cvt_pk_bf16_f32 v36, v36, v37
	v_cvt_pk_bf16_f32 v37, v38, v39
	global_store_dwordx2 v[96:97], v[36:37], off offset:256 sc0 sc1
	global_store_dwordx4 v[104:105], v[32:35], off offset:576 sc0 sc1
	v_ashrrev_i32_e32 v65, 31, v64
	v_lshlrev_b64 v[64:65], 11, v[64:65]
	v_cvt_pk_bf16_f32 v32, v32, v33
	v_cvt_pk_bf16_f32 v33, v34, v35
	global_store_dwordx2 v[96:97], v[32:33], off offset:288 sc0 sc1
	global_load_dwordx4 v[32:35], v[106:107], off
	global_load_dwordx4 v[36:39], v[106:107], off offset:64
	global_load_dwordx4 v[40:43], v[106:107], off offset:512
	global_load_dwordx4 v[44:47], v[106:107], off offset:576
	v_lshl_add_u64 v[64:65], v[64:65], 0, v[144:145]
	v_lshl_add_u64 v[68:69], v[64:65], 2, s[92:93]
	v_add_u32_e32 v66, 0xb0, v146
	v_lshl_add_u64 v[64:65], v[64:65], 1, s[18:19]
	v_ashrrev_i32_e32 v67, 31, v66
	v_lshlrev_b64 v[66:67], 11, v[66:67]
	v_lshl_add_u64 v[66:67], v[66:67], 0, v[144:145]
	v_lshl_add_u64 v[70:71], v[66:67], 2, s[92:93]
	v_lshl_add_u64 v[66:67], v[66:67], 1, s[18:19]
	s_mov_b64 s[18:19], s[6:7]
	s_waitcnt vmcnt(0)
; __device__ __forceinline__ unsigned cvt_pk_bf16(float lo, float hi) { unsigned r; asm volatile("v_cvt_pk_bf16_f32 %0, %1, %2" : "=v"(r) : "v"(lo), "v"(hi)); return r; }
; #define PG8_WAIT_V(n) asm volatile("s_waitcnt vmcnt(" #n ")" ::: "memory")
;     __device__ __forceinline__ void operator()(const f32x4 (&acc)[2][2][4][2], const Unit& u, int wr, int wc, int fr, int fq) const {
;     ...
;         for (int g = 0; g < 8; ++g) {
;             const int ai = g >> 2, m = g & 3;
;             const int r = row0 + ai * HALF + m * 16; const size_t off = (size_t)r * DM + col0; float s = 0.f;
;             if (g < 7) { const float* nrow = base + (size_t)(((g + 1) >> 2) * HALF + ((g + 1) & 3) * 16) * DM;
; #pragma unroll
;                 for (int bj = 0; bj < 2; ++bj)
; #pragma unroll
;                     for (int n = 0; n < 2; ++n) nb[bj][n] = *(const f32x4*)(nrow + bj * HALF + n * 16); }
; #pragma unroll
;             for (int bj = 0; bj < 2; ++bj)
; #pragma unroll
;                 for (int n = 0; n < 2; ++n) {
;                     const f32x4 o = b[bj][n] + acc[ai][bj][m][n] * alpha;
;                     *(f32x4*)(out + off + bj * HALF + n * 16) = o;
;                     if (WITH_SSQ) s += (o[0] * o[0] + o[1] * o[1]) + (o[2] * o[2] + o[3] * o[3]);
;                     if (WITH_HB) { u32x2 w; w.x = cvt_pk_bf16(o[0], o[1]); w.y = cvt_pk_bf16(o[2], o[3]); *(u32x2*)(hb + off + bj * HALF + n * 16) = w; }
;                 }
;             if (WITH_SSQ) { s += __shfl_xor(s, 16); s += __shfl_xor(s, 32); if (fq == 0) atomicAdd(ssq + r, s); }
;             asm volatile("" ::: "memory");
; #pragma unroll
;             for (int bj = 0; bj < 2; ++bj)
; #pragma unroll
;                 for (int n = 0; n < 2; ++n) b[bj][n] = nb[bj][n];
;         }
; template <class Epi, class Sched>
; __device__ __forceinline__ void gemm_phase(LAS unsigned char* lds, const Gemm g, const Sched& S, const Epi& E) {
;     ...
;         E(acc, cur, wr, wc, fr, fq);
;         if (!has_next) break;
; #pragma unroll
;         for (int a = 0; a < 2; ++a)
; #pragma unroll
;             for (int b = 0; b < 2; ++b)
; #pragma unroll
;                 for (int m = 0; m < 4; ++m)
; #pragma unroll
;                     for (int n = 0; n < 2; ++n) acc[a][b][m][n] = (acc_t){0, 0, 0, 0};
;         cur = nxt; cA = nA; cB = nB; ++ui;
;     }
;     PG8_WAIT_V(0);
;     if (wr == 0) PG8_BAR;
;     PG8_BAR;
	v_pk_fma_f32 v[30:31], v[30:31], 0.5, v[50:51] op_sel_hi:[1,0,1]
	v_pk_fma_f32 v[28:29], v[28:29], 0.5, v[48:49] op_sel_hi:[1,0,1]
	global_store_dwordx4 v[68:69], v[28:31], off sc0 sc1
	v_pk_fma_f32 v[24:25], v[24:25], 0.5, v[52:53] op_sel_hi:[1,0,1]
	v_pk_fma_f32 v[26:27], v[26:27], 0.5, v[54:55] op_sel_hi:[1,0,1]
	v_cvt_pk_bf16_f32 v28, v28, v29
	v_cvt_pk_bf16_f32 v29, v30, v31
	v_pk_fma_f32 v[16:17], v[16:17], 0.5, v[56:57] op_sel_hi:[1,0,1]
	global_store_dwordx2 v[64:65], v[28:29], off sc0 sc1
	global_store_dwordx4 v[68:69], v[24:27], off offset:64 sc0 sc1
	v_pk_fma_f32 v[18:19], v[18:19], 0.5, v[58:59] op_sel_hi:[1,0,1]
	v_pk_fma_f32 v[8:9], v[8:9], 0.5, v[60:61] op_sel_hi:[1,0,1]
	v_cvt_pk_bf16_f32 v24, v24, v25
	v_cvt_pk_bf16_f32 v25, v26, v27
	global_store_dwordx2 v[64:65], v[24:25], off offset:32 sc0 sc1
	global_store_dwordx4 v[68:69], v[16:19], off offset:512 sc0 sc1
	v_pk_fma_f32 v[10:11], v[10:11], 0.5, v[62:63] op_sel_hi:[1,0,1]
	v_pk_fma_f32 v[14:15], v[14:15], 0.5, v[38:39] op_sel_hi:[1,0,1]
	v_cvt_pk_bf16_f32 v16, v16, v17
	v_cvt_pk_bf16_f32 v17, v18, v19
	global_store_dwordx2 v[64:65], v[16:17], off offset:256 sc0 sc1
	global_store_dwordx4 v[68:69], v[8:11], off offset:576 sc0 sc1
	v_pk_fma_f32 v[12:13], v[12:13], 0.5, v[36:37] op_sel_hi:[1,0,1]
	v_pk_fma_f32 v[4:5], v[4:5], 0.5, v[40:41] op_sel_hi:[1,0,1]
	v_cvt_pk_bf16_f32 v8, v8, v9
	v_cvt_pk_bf16_f32 v9, v10, v11
	global_store_dwordx2 v[64:65], v[8:9], off offset:288 sc0 sc1
	v_pk_fma_f32 v[10:11], v[22:23], 0.5, v[34:35] op_sel_hi:[1,0,1]
	v_pk_fma_f32 v[8:9], v[20:21], 0.5, v[32:33] op_sel_hi:[1,0,1]
	global_store_dwordx4 v[70:71], v[8:11], off sc0 sc1
	v_pk_fma_f32 v[6:7], v[6:7], 0.5, v[42:43] op_sel_hi:[1,0,1]
	v_pk_fma_f32 v[0:1], v[0:1], 0.5, v[44:45] op_sel_hi:[1,0,1]
	v_cvt_pk_bf16_f32 v8, v8, v9
	v_cvt_pk_bf16_f32 v9, v10, v11
	global_store_dwordx2 v[66:67], v[8:9], off sc0 sc1
	global_store_dwordx4 v[70:71], v[12:15], off offset:64 sc0 sc1
	v_cvt_pk_bf16_f32 v8, v12, v13
	v_cvt_pk_bf16_f32 v9, v14, v15
	global_store_dwordx2 v[66:67], v[8:9], off offset:32 sc0 sc1
	global_store_dwordx4 v[70:71], v[4:7], off offset:512 sc0 sc1
	v_pk_fma_f32 v[2:3], v[2:3], 0.5, v[46:47] op_sel_hi:[1,0,1]
	s_nop 0
	v_cvt_pk_bf16_f32 v4, v4, v5
	v_cvt_pk_bf16_f32 v5, v6, v7
	global_store_dwordx2 v[66:67], v[4:5], off offset:256 sc0 sc1
	global_store_dwordx4 v[70:71], v[0:3], off offset:576 sc0 sc1
	s_nop 1
	v_cvt_pk_bf16_f32 v0, v0, v1
	v_cvt_pk_bf16_f32 v1, v2, v3
	global_store_dwordx2 v[66:67], v[0:1], off offset:288 sc0 sc1
	s_cbranch_vccz .LBB0_231
	s_waitcnt vmcnt(0)
	s_cmpk_gt_u32 s22, 0xff
	s_mov_b32 s61, s78
	s_mov_b32 s63, s79
	s_cbranch_scc1 .LBB0_242
	s_barrier

; #define PG8_STAGE(bufoff, gbase, voff) do { _Pragma("unroll") for (int _i = 0; _i < 2; ++_i) \
;         __builtin_amdgcn_global_load_lds((const unsigned*)((const char*)(gbase) + (voff)[_i]), (LAS unsigned*)(lds + (bufoff) + ldsw + _i * 8192), 16, 0, 0); } while (0)
; #define PG8_LDA(dst, b, h) do { _Pragma("unroll") for (int m = 0; m < 4; ++m) _Pragma("unroll") for (int k = 0; k < 2; ++k) dst[m][k] = *(const LAS bf16x8*)(lds + PG8_SA(b, h) + aoff + m * 2048 + k * 1024); } while (0)
; #define PG8_LDB(dst, b, h) do { _Pragma("unroll") for (int n = 0; n < 2; ++n) _Pragma("unroll") for (int k = 0; k < 2; ++k) dst[n][k] = *(const LAS bf16x8*)(lds + PG8_SB(b, h) + boff + n * 2048 + k * 1024); } while (0)
; #define PG8_MMA(ai, bj, At, Bt) do { __builtin_amdgcn_s_setprio(1); _Pragma("unroll") for (int m = 0; m < 4; ++m) _Pragma("unroll") for (int n = 0; n < 2; ++n) _Pragma("unroll") for (int k = 0; k < 2; ++k) \
;         acc[ai][bj][m][n] = MmaOp<Epi::I8>::run(Bt[n][k], At[m][k], acc[ai][bj][m][n]); __builtin_amdgcn_s_setprio(0); } while (0)
; #define PG8_WAIT_V(n) asm volatile("s_waitcnt vmcnt(" #n ")" ::: "memory")
; #define PG8_WAIT_L(n) asm volatile("s_waitcnt lgkmcnt(" #n ")" ::: "memory")
; #define PG8_BAR __builtin_amdgcn_s_barrier()
; template <class Epi, class Sched>
; __device__ __forceinline__ void gemm_phase(LAS unsigned char* lds, const Gemm g, const Sched& S, const Epi& E) {
;     ...
;             PG8_LDB(B0, 0, 0); PG8_SCHED; PG8_LDA(At, 0, 0); PG8_STAGE(PG8_SA(1, 1), a1 + hstepA, voffA);
;             PG8_WAIT_L(8); PG8_BAR; PG8_WAIT_L(0); PG8_MMA(0, 0, At, B0); PG8_BAR; PG8_SCHED;
;             PG8_LDB(B1, 0, 1); PG8_STAGE(PG8_SB(0, 0), b2, voffB);
;             PG8_BAR; PG8_WAIT_L(0); PG8_MMA(0, 1, At, B1); PG8_BAR;
;             PG8_LDA(At, 0, 1); PG8_STAGE(PG8_SA(0, 0), a2, voffA);
;             PG8_BAR; PG8_WAIT_L(0); PG8_MMA(1, 0, At, B0); PG8_BAR; PG8_SCHED;
;             PG8_STAGE(PG8_SB(0, 1), b2 + hstepB, voffB);
;             PG8_WAIT_V(6); PG8_BAR; PG8_MMA(1, 1, At, B1); PG8_BAR;
;             PG8_LDB(B0, 1, 0); PG8_SCHED; PG8_LDA(At, 1, 0); PG8_STAGE(PG8_SA(0, 1), a2 + hstepA, voffA);
;             PG8_WAIT_L(8); PG8_BAR; PG8_WAIT_L(0); PG8_MMA(0, 0, At, B0); PG8_BAR; PG8_SCHED;
;             PG8_LDB(B1, 1, 1); PG8_STAGE(PG8_SB(1, 0), b3, voffB);
;             PG8_BAR; PG8_WAIT_L(0); PG8_MMA(0, 1, At, B1); PG8_BAR;
.LBB0_386:
	ds_read_b128 v[104:107], v169
	ds_read_b128 v[108:111], v169 offset:1024
	ds_read_b128 v[112:115], v169 offset:2048
	ds_read_b128 v[116:119], v169 offset:3072
	s_add_u32 s24, s22, 0xfff80080
	s_addc_u32 s25, s23, -1
	s_cmp_eq_u32 s48, 12
	s_cselect_b32 s27, s15, s25
	s_cselect_b32 s26, s44, s24
	s_cselect_b32 s25, s13, s47
	s_cselect_b32 s24, s45, s46
	v_lshl_add_u64 v[164:165], s[22:23], 0, v[152:153]
	s_add_i32 m0, s21, 0xc000
	ds_read_b128 v[160:163], v170
	ds_read_b128 v[172:175], v170 offset:1024
	ds_read_b128 v[178:181], v170 offset:2048
	ds_read_b128 v[182:185], v170 offset:3072
	ds_read_b128 v[186:189], v170 offset:4096
	ds_read_b128 v[190:193], v170 offset:5120
	ds_read_b128 v[194:197], v170 offset:6144
	ds_read_b128 v[198:201], v170 offset:7168
	global_load_lds_dwordx4 v[164:165], off
	v_lshl_add_u64 v[164:165], s[22:23], 0, v[154:155]
	s_add_i32 m0, s21, 0xe000
	s_nop 0
	global_load_lds_dwordx4 v[164:165], off
	s_waitcnt lgkmcnt(8)
	s_barrier
	s_waitcnt lgkmcnt(0)
	s_setprio 1
	s_waitcnt lgkmcnt(0)
	v_mfma_i32_16x16x64_i8 v[140:143], v[104:107], v[160:163], v[140:143]
	v_mfma_i32_16x16x64_i8 v[136:139], v[112:115], v[160:163], v[136:139]
	v_mfma_i32_16x16x64_i8 v[124:127], v[104:107], v[178:181], v[124:127]
	v_mfma_i32_16x16x64_i8 v[120:123], v[112:115], v[178:181], v[120:123]
	v_mfma_i32_16x16x64_i8 v[92:95], v[104:107], v[186:189], v[92:95]
	v_mfma_i32_16x16x64_i8 v[88:91], v[112:115], v[186:189], v[88:91]
	v_mfma_i32_16x16x64_i8 v[76:79], v[104:107], v[194:197], v[76:79]
	v_mfma_i32_16x16x64_i8 v[72:75], v[112:115], v[194:197], v[72:75]
	v_mfma_i32_16x16x64_i8 v[140:143], v[108:111], v[172:175], v[140:143]
	v_mfma_i32_16x16x64_i8 v[136:139], v[116:119], v[172:175], v[136:139]
	v_mfma_i32_16x16x64_i8 v[124:127], v[108:111], v[182:185], v[124:127]
	v_mfma_i32_16x16x64_i8 v[120:123], v[116:119], v[182:185], v[120:123]
	v_mfma_i32_16x16x64_i8 v[92:95], v[108:111], v[190:193], v[92:95]
	v_mfma_i32_16x16x64_i8 v[88:91], v[116:119], v[190:193], v[88:91]
	v_mfma_i32_16x16x64_i8 v[76:79], v[108:111], v[198:201], v[76:79]
	v_mfma_i32_16x16x64_i8 v[72:75], v[116:119], v[198:201], v[72:75]
	s_setprio 0
	s_barrier
	s_add_i32 s49, s40, s29
	v_lshl_add_u64 v[164:165], s[24:25], 0, v[148:149]
	s_mov_b32 m0, s49
	ds_read_b128 v[202:205], v171
	ds_read_b128 v[206:209], v171 offset:1024
	ds_read_b128 v[210:213], v171 offset:2048
	ds_read_b128 v[214:217], v171 offset:3072
	global_load_lds_dwordx4 v[164:165], off
	v_lshl_add_u64 v[218:219], s[24:25], 0, v[144:145]
	s_add_i32 m0, s49, 0x2000
	s_nop 0
	global_load_lds_dwordx4 v[218:219], off
	s_barrier
	s_waitcnt lgkmcnt(0)
	s_setprio 1
	s_waitcnt lgkmcnt(0)
	v_mfma_i32_16x16x64_i8 v[132:135], v[202:205], v[160:163], v[132:135]
	v_mfma_i32_16x16x64_i8 v[128:131], v[210:213], v[160:163], v[128:131]
	v_mfma_i32_16x16x64_i8 v[100:103], v[202:205], v[178:181], v[100:103]
	v_mfma_i32_16x16x64_i8 v[96:99], v[210:213], v[178:181], v[96:99]
	v_mfma_i32_16x16x64_i8 v[84:87], v[202:205], v[186:189], v[84:87]
	v_mfma_i32_16x16x64_i8 v[80:83], v[210:213], v[186:189], v[80:83]
	v_mfma_i32_16x16x64_i8 v[68:71], v[202:205], v[194:197], v[68:71]
	v_mfma_i32_16x16x64_i8 v[64:67], v[210:213], v[194:197], v[64:67]
	v_mfma_i32_16x16x64_i8 v[132:135], v[206:209], v[172:175], v[132:135]
	v_mfma_i32_16x16x64_i8 v[128:131], v[214:217], v[172:175], v[128:131]
	v_mfma_i32_16x16x64_i8 v[100:103], v[206:209], v[182:185], v[100:103]
	v_mfma_i32_16x16x64_i8 v[96:99], v[214:217], v[182:185], v[96:99]
	v_mfma_i32_16x16x64_i8 v[84:87], v[206:209], v[190:193], v[84:87]
	v_mfma_i32_16x16x64_i8 v[80:83], v[214:217], v[190:193], v[80:83]
	v_mfma_i32_16x16x64_i8 v[68:71], v[206:209], v[198:201], v[68:71]
	v_mfma_i32_16x16x64_i8 v[64:67], v[214:217], v[198:201], v[64:67]
	s_setprio 0
	s_mov_b32 m0, s21
	v_lshl_add_u64 v[220:221], s[26:27], 0, v[150:151]
	s_barrier
	ds_read_b128 v[160:163], v170 offset:16384
	ds_read_b128 v[172:175], v170 offset:17408
	ds_read_b128 v[178:181], v170 offset:18432
	ds_read_b128 v[182:185], v170 offset:19456
	ds_read_b128 v[186:189], v170 offset:20480
	ds_read_b128 v[190:193], v170 offset:21504
	ds_read_b128 v[194:197], v170 offset:22528
	ds_read_b128 v[198:201], v170 offset:23552
	global_load_lds_dwordx4 v[220:221], off
	v_lshl_add_u64 v[222:223], s[26:27], 0, v[146:147]
	s_mov_b32 m0, s33
	s_nop 0
	global_load_lds_dwordx4 v[222:223], off
	s_barrier
	s_waitcnt lgkmcnt(0)
	s_setprio 1
	s_waitcnt lgkmcnt(0)
	v_mfma_i32_16x16x64_i8 v[60:63], v[104:107], v[160:163], v[60:63]
	v_mfma_i32_16x16x64_i8 v[56:59], v[112:115], v[160:163], v[56:59]
	v_mfma_i32_16x16x64_i8 v[44:47], v[104:107], v[178:181], v[44:47]
	v_mfma_i32_16x16x64_i8 v[40:43], v[112:115], v[178:181], v[40:43]
	v_mfma_i32_16x16x64_i8 v[28:31], v[104:107], v[186:189], v[28:31]
	v_mfma_i32_16x16x64_i8 v[24:27], v[112:115], v[186:189], v[24:27]
	v_mfma_i32_16x16x64_i8 v[12:15], v[104:107], v[194:197], v[12:15]
	v_mfma_i32_16x16x64_i8 v[8:11], v[112:115], v[194:197], v[8:11]
	v_mfma_i32_16x16x64_i8 v[60:63], v[108:111], v[172:175], v[60:63]
	v_mfma_i32_16x16x64_i8 v[56:59], v[116:119], v[172:175], v[56:59]
	v_mfma_i32_16x16x64_i8 v[44:47], v[108:111], v[182:185], v[44:47]
	v_mfma_i32_16x16x64_i8 v[40:43], v[116:119], v[182:185], v[40:43]
	v_mfma_i32_16x16x64_i8 v[28:31], v[108:111], v[190:193], v[28:31]
	v_mfma_i32_16x16x64_i8 v[24:27], v[116:119], v[190:193], v[24:27]
	v_mfma_i32_16x16x64_i8 v[12:15], v[108:111], v[198:201], v[12:15]
	v_mfma_i32_16x16x64_i8 v[8:11], v[116:119], v[198:201], v[8:11]
	s_setprio 0
	s_barrier
; #define PG8_STAGE(bufoff, gbase, voff) do { _Pragma("unroll") for (int _i = 0; _i < 2; ++_i) \
;         __builtin_amdgcn_global_load_lds((const unsigned*)((const char*)(gbase) + (voff)[_i]), (LAS unsigned*)(lds + (bufoff) + ldsw + _i * 8192), 16, 0, 0); } while (0)
; #define PG8_LDA(dst, b, h) do { _Pragma("unroll") for (int m = 0; m < 4; ++m) _Pragma("unroll") for (int k = 0; k < 2; ++k) dst[m][k] = *(const LAS bf16x8*)(lds + PG8_SA(b, h) + aoff + m * 2048 + k * 1024); } while (0)
; #define PG8_LDB(dst, b, h) do { _Pragma("unroll") for (int n = 0; n < 2; ++n) _Pragma("unroll") for (int k = 0; k < 2; ++k) dst[n][k] = *(const LAS bf16x8*)(lds + PG8_SB(b, h) + boff + n * 2048 + k * 1024); } while (0)
; #define PG8_MMA(ai, bj, At, Bt) do { __builtin_amdgcn_s_setprio(1); _Pragma("unroll") for (int m = 0; m < 4; ++m) _Pragma("unroll") for (int n = 0; n < 2; ++n) _Pragma("unroll") for (int k = 0; k < 2; ++k) \
;         acc[ai][bj][m][n] = MmaOp<Epi::I8>::run(Bt[n][k], At[m][k], acc[ai][bj][m][n]); __builtin_amdgcn_s_setprio(0); } while (0)
; #define PG8_WAIT_V(n) asm volatile("s_waitcnt vmcnt(" #n ")" ::: "memory")
; #define PG8_WAIT_L(n) asm volatile("s_waitcnt lgkmcnt(" #n ")" ::: "memory")
; #define PG8_BAR __builtin_amdgcn_s_barrier()
; #define PG8_SCHED __builtin_amdgcn_sched_barrier(0)
; template <class Epi, class Sched>
; __device__ __forceinline__ void gemm_phase(LAS unsigned char* lds, const Gemm g, const Sched& S, const Epi& E) {
;     ...
;             PG8_STAGE(PG8_SB(0, 1), b2 + hstepB, voffB);
;             PG8_WAIT_V(6); PG8_BAR; PG8_MMA(1, 1, At, B1); PG8_BAR;
;             PG8_LDB(B0, 1, 0); PG8_SCHED; PG8_LDA(At, 1, 0); PG8_STAGE(PG8_SA(0, 1), a2 + hstepA, voffA);
;             PG8_WAIT_L(8); PG8_BAR; PG8_WAIT_L(0); PG8_MMA(0, 0, At, B0); PG8_BAR; PG8_SCHED;
;             PG8_LDB(B1, 1, 1); PG8_STAGE(PG8_SB(1, 0), b3, voffB);
;             PG8_BAR; PG8_WAIT_L(0); PG8_MMA(0, 1, At, B1); PG8_BAR;
;             PG8_LDA(At, 1, 1); PG8_STAGE(PG8_SA(1, 0), a3, voffA);
;             PG8_BAR; PG8_WAIT_L(0); PG8_MMA(1, 0, At, B0); PG8_BAR; PG8_SCHED;
	s_add_u32 s50, s24, 0x40000
	s_addc_u32 s51, s25, 0
	s_add_i32 s49, s41, s29
	v_lshl_add_u64 v[104:105], s[50:51], 0, v[148:149]
	s_mov_b32 m0, s49
	s_nop 0
	global_load_lds_dwordx4 v[104:105], off
	v_lshl_add_u64 v[104:105], s[50:51], 0, v[144:145]
	s_add_i32 m0, s49, 0x2000
	s_nop 0
	global_load_lds_dwordx4 v[104:105], off
	s_waitcnt vmcnt(6)
	s_barrier
	s_setprio 1
	v_mfma_i32_16x16x64_i8 v[52:55], v[202:205], v[160:163], v[52:55]
	v_mfma_i32_16x16x64_i8 v[48:51], v[210:213], v[160:163], v[48:51]
	v_mfma_i32_16x16x64_i8 v[36:39], v[202:205], v[178:181], v[36:39]
	v_mfma_i32_16x16x64_i8 v[32:35], v[210:213], v[178:181], v[32:35]
	v_mfma_i32_16x16x64_i8 v[20:23], v[202:205], v[186:189], v[20:23]
	v_mfma_i32_16x16x64_i8 v[16:19], v[210:213], v[186:189], v[16:19]
	v_mfma_i32_16x16x64_i8 v[4:7], v[202:205], v[194:197], v[4:7]
	v_mfma_i32_16x16x64_i8 v[0:3], v[210:213], v[194:197], v[0:3]
	v_mfma_i32_16x16x64_i8 v[52:55], v[206:209], v[172:175], v[52:55]
	v_mfma_i32_16x16x64_i8 v[48:51], v[214:217], v[172:175], v[48:51]
	v_mfma_i32_16x16x64_i8 v[36:39], v[206:209], v[182:185], v[36:39]
	v_mfma_i32_16x16x64_i8 v[32:35], v[214:217], v[182:185], v[32:35]
	v_mfma_i32_16x16x64_i8 v[20:23], v[206:209], v[190:193], v[20:23]
	v_mfma_i32_16x16x64_i8 v[16:19], v[214:217], v[190:193], v[16:19]
	v_mfma_i32_16x16x64_i8 v[4:7], v[206:209], v[198:201], v[4:7]
	v_mfma_i32_16x16x64_i8 v[0:3], v[214:217], v[198:201], v[0:3]
	s_setprio 0
	s_add_i32 s49, 0, 0x18000
	v_add_u32_e32 v116, s49, v167
	s_barrier
	ds_read_b128 v[104:107], v116
	ds_read_b128 v[108:111], v116 offset:1024
	ds_read_b128 v[112:115], v116 offset:2048
	ds_read_b128 v[116:119], v116 offset:3072
	s_add_u32 s26, s26, 0x80000
	s_addc_u32 s27, s27, 0
	s_mov_b32 m0, s34
	v_lshl_add_u64 v[202:203], s[26:27], 0, v[150:151]
	ds_read_b128 v[160:163], v170 offset:32768
	ds_read_b128 v[172:175], v170 offset:33792
	ds_read_b128 v[178:181], v170 offset:34816
	ds_read_b128 v[182:185], v170 offset:35840
	ds_read_b128 v[186:189], v170 offset:36864
	ds_read_b128 v[190:193], v170 offset:37888
	ds_read_b128 v[194:197], v170 offset:38912
	ds_read_b128 v[198:201], v170 offset:39936
	global_load_lds_dwordx4 v[202:203], off
	v_lshl_add_u64 v[202:203], s[26:27], 0, v[146:147]
	s_mov_b32 m0, s35
	s_nop 0
	global_load_lds_dwordx4 v[202:203], off
	s_waitcnt lgkmcnt(8)
	s_barrier
	s_waitcnt lgkmcnt(0)
	s_setprio 1
	s_waitcnt lgkmcnt(0)
	v_mfma_i32_16x16x64_i8 v[140:143], v[104:107], v[160:163], v[140:143]
	v_mfma_i32_16x16x64_i8 v[136:139], v[112:115], v[160:163], v[136:139]
	v_mfma_i32_16x16x64_i8 v[124:127], v[104:107], v[178:181], v[124:127]
	v_mfma_i32_16x16x64_i8 v[120:123], v[112:115], v[178:181], v[120:123]
	v_mfma_i32_16x16x64_i8 v[92:95], v[104:107], v[186:189], v[92:95]
	v_mfma_i32_16x16x64_i8 v[88:91], v[112:115], v[186:189], v[88:91]
	v_mfma_i32_16x16x64_i8 v[76:79], v[104:107], v[194:197], v[76:79]
	v_mfma_i32_16x16x64_i8 v[72:75], v[112:115], v[194:197], v[72:75]
	v_mfma_i32_16x16x64_i8 v[140:143], v[108:111], v[172:175], v[140:143]
	v_mfma_i32_16x16x64_i8 v[136:139], v[116:119], v[172:175], v[136:139]
	v_mfma_i32_16x16x64_i8 v[124:127], v[108:111], v[182:185], v[124:127]
	v_mfma_i32_16x16x64_i8 v[120:123], v[116:119], v[182:185], v[120:123]
	v_mfma_i32_16x16x64_i8 v[92:95], v[108:111], v[190:193], v[92:95]
	v_mfma_i32_16x16x64_i8 v[88:91], v[116:119], v[190:193], v[88:91]
	v_mfma_i32_16x16x64_i8 v[76:79], v[108:111], v[198:201], v[76:79]
	v_mfma_i32_16x16x64_i8 v[72:75], v[116:119], v[198:201], v[72:75]
	s_setprio 0
	s_barrier
	s_add_i32 s26, 0, 0x1c000
	s_add_i32 s27, s49, s29
	v_add_u32_e32 v214, s26, v167
	v_lshl_add_u64 v[164:165], v[164:165], 0, s[6:7]
	s_mov_b32 m0, s27
	ds_read_b128 v[202:205], v214
	ds_read_b128 v[206:209], v214 offset:1024
	ds_read_b128 v[210:213], v214 offset:2048
	ds_read_b128 v[214:217], v214 offset:3072
	global_load_lds_dwordx4 v[164:165], off
	v_lshl_add_u64 v[164:165], v[218:219], 0, s[6:7]
	s_add_i32 m0, s27, 0x2000
	s_nop 0
	global_load_lds_dwordx4 v[164:165], off
	s_barrier
	s_waitcnt lgkmcnt(0)
	s_setprio 1
	s_waitcnt lgkmcnt(0)
	v_mfma_i32_16x16x64_i8 v[132:135], v[202:205], v[160:163], v[132:135]
	v_mfma_i32_16x16x64_i8 v[128:131], v[210:213], v[160:163], v[128:131]
	v_mfma_i32_16x16x64_i8 v[100:103], v[202:205], v[178:181], v[100:103]
	v_mfma_i32_16x16x64_i8 v[96:99], v[210:213], v[178:181], v[96:99]
	v_mfma_i32_16x16x64_i8 v[84:87], v[202:205], v[186:189], v[84:87]
	v_mfma_i32_16x16x64_i8 v[80:83], v[210:213], v[186:189], v[80:83]
	v_mfma_i32_16x16x64_i8 v[68:71], v[202:205], v[194:197], v[68:71]
	v_mfma_i32_16x16x64_i8 v[64:67], v[210:213], v[194:197], v[64:67]
	v_mfma_i32_16x16x64_i8 v[132:135], v[206:209], v[172:175], v[132:135]
	v_mfma_i32_16x16x64_i8 v[128:131], v[214:217], v[172:175], v[128:131]
	v_mfma_i32_16x16x64_i8 v[100:103], v[206:209], v[182:185], v[100:103]
	v_mfma_i32_16x16x64_i8 v[96:99], v[214:217], v[182:185], v[96:99]
	v_mfma_i32_16x16x64_i8 v[84:87], v[206:209], v[190:193], v[84:87]
	v_mfma_i32_16x16x64_i8 v[80:83], v[214:217], v[190:193], v[80:83]
	v_mfma_i32_16x16x64_i8 v[68:71], v[206:209], v[198:201], v[68:71]
	v_mfma_i32_16x16x64_i8 v[64:67], v[214:217], v[198:201], v[64:67]
	s_setprio 0
	s_mov_b32 m0, s37
	v_lshl_add_u64 v[164:165], v[220:221], 0, s[6:7]
	s_barrier
	ds_read_b128 v[160:163], v170 offset:49152
	ds_read_b128 v[172:175], v170 offset:50176
	ds_read_b128 v[178:181], v170 offset:51200
	ds_read_b128 v[182:185], v170 offset:52224
	ds_read_b128 v[186:189], v170 offset:53248
	ds_read_b128 v[190:193], v170 offset:54272
	ds_read_b128 v[194:197], v170 offset:55296
	ds_read_b128 v[198:201], v170 offset:56320
	global_load_lds_dwordx4 v[164:165], off
	v_lshl_add_u64 v[164:165], v[222:223], 0, s[6:7]
	s_mov_b32 m0, s38
	s_nop 0
	global_load_lds_dwordx4 v[164:165], off
	s_barrier
; __device__ __forceinline__ float ld_agent(const float* p) { return __hip_atomic_load(p, __ATOMIC_RELAXED, __HIP_MEMORY_SCOPE_AGENT); }
; #define PG8_STAGE(bufoff, gbase, voff) do { _Pragma("unroll") for (int _i = 0; _i < 2; ++_i) \
;         __builtin_amdgcn_global_load_lds((const unsigned*)((const char*)(gbase) + (voff)[_i]), (LAS unsigned*)(lds + (bufoff) + ldsw + _i * 8192), 16, 0, 0); } while (0)
; #define PG8_MMA(ai, bj, At, Bt) do { __builtin_amdgcn_s_setprio(1); _Pragma("unroll") for (int m = 0; m < 4; ++m) _Pragma("unroll") for (int n = 0; n < 2; ++n) _Pragma("unroll") for (int k = 0; k < 2; ++k) \
;         acc[ai][bj][m][n] = MmaOp<Epi::I8>::run(Bt[n][k], At[m][k], acc[ai][bj][m][n]); __builtin_amdgcn_s_setprio(0); } while (0)
; #define PG8_BAR __builtin_amdgcn_s_barrier()
;     __device__ __forceinline__ void operator()(const i32x4 (&acc)[2][2][4][2], const Unit& u, int wr, int wc, int fr_, int fq) const {
;         const int row0 = u.pm * BM + wr * 64 + fr_, col0 = u.pn * BM + wc * 32 + 8 * fq;
;         f32x4 sw[2][2], bv[2][2];
; #pragma unroll
;         for (int bj = 0; bj < 2; ++bj)
; #pragma unroll
;             for (int n = 0; n < 2; ++n) { sw[bj][n] = *(const f32x4*)(swinv + col0 + bj * HALF + 4 * n);
;                 bv[bj][n] = MODE == 1 ? *(const f32x4*)(bias + col0 + bj * HALF + 4 * n) : (f32x4){0.f, 0.f, 0.f, 0.f}; }
; #pragma unroll
;         for (int ai = 0; ai < 2; ++ai)
; #pragma unroll
;             for (int m = 0; m < 4; ++m) {
;                 asm volatile("" ::: "memory");
;                 const int r = row0 + ai * HALF + m * 16; const float rs = ld_agent(fr + r);
;                 bf16_t* rowp = O + (size_t)r * ldc + col0;
; #pragma unroll
;                 for (int bj = 0; bj < 2; ++bj) {
;                     f32x4 v0, v1;
; #pragma unroll
;                     for (int j = 0; j < 4; ++j) { v0[j] = (float)acc[ai][bj][m][0][j] * rs * sw[bj][0][j] + bv[bj][0][j]; v1[j] = (float)acc[ai][bj][m][1][j] * rs * sw[bj][1][j] + bv[bj][1][j]; }
; template <class Epi, class Sched>
; __device__ __forceinline__ void gemm_phase(LAS unsigned char* lds, const Gemm g, const Sched& S, const Epi& E) {
;     ...
;             PG8_BAR; PG8_WAIT_L(0); PG8_MMA(1, 0, At, B0); PG8_BAR; PG8_SCHED;
;             PG8_STAGE(PG8_SB(1, 1), b3 + hstepB, voffB);
;             PG8_WAIT_V(6); PG8_BAR; PG8_MMA(1, 1, At, B1); PG8_BAR;
;         }
	s_waitcnt lgkmcnt(0)
	s_setprio 1
	s_waitcnt lgkmcnt(0)
	v_mfma_i32_16x16x64_i8 v[60:63], v[104:107], v[160:163], v[60:63]
	v_mfma_i32_16x16x64_i8 v[56:59], v[112:115], v[160:163], v[56:59]
	v_mfma_i32_16x16x64_i8 v[44:47], v[104:107], v[178:181], v[44:47]
	v_mfma_i32_16x16x64_i8 v[40:43], v[112:115], v[178:181], v[40:43]
	v_mfma_i32_16x16x64_i8 v[28:31], v[104:107], v[186:189], v[28:31]
	v_mfma_i32_16x16x64_i8 v[24:27], v[112:115], v[186:189], v[24:27]
	v_mfma_i32_16x16x64_i8 v[12:15], v[104:107], v[194:197], v[12:15]
	v_mfma_i32_16x16x64_i8 v[8:11], v[112:115], v[194:197], v[8:11]
	v_mfma_i32_16x16x64_i8 v[60:63], v[108:111], v[172:175], v[60:63]
	v_mfma_i32_16x16x64_i8 v[56:59], v[116:119], v[172:175], v[56:59]
	v_mfma_i32_16x16x64_i8 v[44:47], v[108:111], v[182:185], v[44:47]
	v_mfma_i32_16x16x64_i8 v[40:43], v[116:119], v[182:185], v[40:43]
	v_mfma_i32_16x16x64_i8 v[28:31], v[108:111], v[190:193], v[28:31]
	v_mfma_i32_16x16x64_i8 v[24:27], v[116:119], v[190:193], v[24:27]
	v_mfma_i32_16x16x64_i8 v[12:15], v[108:111], v[198:201], v[12:15]
	v_mfma_i32_16x16x64_i8 v[8:11], v[116:119], v[198:201], v[8:11]
	s_setprio 0
	s_barrier
	s_add_u32 s24, s24, 0x40080
	s_addc_u32 s25, s25, 0
	s_add_i32 s26, s26, s29
	v_lshl_add_u64 v[104:105], s[24:25], 0, v[148:149]
	s_mov_b32 m0, s26
	s_nop 0
	global_load_lds_dwordx4 v[104:105], off
	v_lshl_add_u64 v[104:105], s[24:25], 0, v[144:145]
	s_add_i32 m0, s26, 0x2000
	s_nop 0
	global_load_lds_dwordx4 v[104:105], off
	s_waitcnt vmcnt(6)
	s_barrier
	s_setprio 1
	v_mfma_i32_16x16x64_i8 v[52:55], v[202:205], v[160:163], v[52:55]
	v_mfma_i32_16x16x64_i8 v[48:51], v[210:213], v[160:163], v[48:51]
	v_mfma_i32_16x16x64_i8 v[36:39], v[202:205], v[178:181], v[36:39]
	v_mfma_i32_16x16x64_i8 v[32:35], v[210:213], v[178:181], v[32:35]
	v_mfma_i32_16x16x64_i8 v[20:23], v[202:205], v[186:189], v[20:23]
	v_mfma_i32_16x16x64_i8 v[16:19], v[210:213], v[186:189], v[16:19]
	v_mfma_i32_16x16x64_i8 v[4:7], v[202:205], v[194:197], v[4:7]
	v_mfma_i32_16x16x64_i8 v[0:3], v[210:213], v[194:197], v[0:3]
	v_mfma_i32_16x16x64_i8 v[52:55], v[206:209], v[172:175], v[52:55]
	v_mfma_i32_16x16x64_i8 v[48:51], v[214:217], v[172:175], v[48:51]
	v_mfma_i32_16x16x64_i8 v[36:39], v[206:209], v[182:185], v[36:39]
	v_mfma_i32_16x16x64_i8 v[32:35], v[214:217], v[182:185], v[32:35]
	v_mfma_i32_16x16x64_i8 v[20:23], v[206:209], v[190:193], v[20:23]
	v_mfma_i32_16x16x64_i8 v[16:19], v[214:217], v[190:193], v[16:19]
	v_mfma_i32_16x16x64_i8 v[4:7], v[206:209], v[198:201], v[4:7]
	v_mfma_i32_16x16x64_i8 v[0:3], v[214:217], v[198:201], v[0:3]
	s_setprio 0
	s_add_i32 s48, s48, 2
	s_add_u32 s22, s22, 0x100
	s_addc_u32 s23, s23, 0
	s_add_u32 s46, s46, 0x100
	s_addc_u32 s47, s47, 0
	s_cmp_gt_u32 s48, 13
	s_barrier
	s_cbranch_scc0 .LBB0_386
	v_lshl_or_b32 v172, s43, 8, v168
	v_ashrrev_i32_e32 v173, 31, v172
	v_lshl_add_u32 v160, s20, 8, v166
	v_lshl_add_u64 v[108:109], v[172:173], 2, s[8:9]
	v_ashrrev_i32_e32 v161, 31, v160
	global_load_dwordx4 v[112:115], v[108:109], off offset:16
	global_load_dwordx4 v[116:119], v[108:109], off
	global_load_dwordx4 v[104:107], v[108:109], off offset:528
	s_nop 0
	global_load_dwordx4 v[108:111], v[108:109], off offset:512
	v_lshl_add_u64 v[164:165], v[160:161], 2, s[2:3]
	global_load_dword v161, v[164:165], off sc1
	global_load_dword v190, v[164:165], off offset:64 sc1
	global_load_dword v191, v[164:165], off offset:128 sc1
	global_load_dword v192, v[164:165], off offset:192 sc1
	global_load_dword v193, v[164:165], off offset:512 sc1
	global_load_dword v194, v[164:165], off offset:576 sc1
	global_load_dword v195, v[164:165], off offset:640 sc1
	global_load_dword v196, v[164:165], off offset:704 sc1
	v_cvt_f32_i32_e32 v140, v140
	v_cvt_f32_i32_e32 v174, v136
	v_cvt_f32_i32_e32 v141, v141
	v_cvt_f32_i32_e32 v175, v137
	v_cvt_f32_i32_e32 v142, v142
	v_cvt_f32_i32_e32 v178, v138
	v_cvt_f32_i32_e32 v143, v143
	v_cvt_f32_i32_e32 v179, v139
	v_cvt_f32_i32_e32 v132, v132
	v_cvt_f32_i32_e32 v180, v128
	v_cvt_f32_i32_e32 v133, v133
	v_mov_b64_e32 v[162:163], s[54:55]
	v_cvt_f32_i32_e32 v181, v129
	v_cvt_f32_i32_e32 v182, v134
	v_cvt_f32_i32_e32 v183, v130
	v_cvt_f32_i32_e32 v184, v135
	v_cvt_f32_i32_e32 v185, v131
	v_or_b32_e32 v134, 16, v160
	v_mad_i64_i32 v[130:131], s[22:23], v160, s42, v[162:163]
	v_lshlrev_b64 v[128:129], 1, v[172:173]
	v_ashrrev_i32_e32 v135, 31, v134
	v_lshl_add_u64 v[136:137], v[130:131], 0, v[128:129]
	v_lshl_add_u64 v[138:139], v[134:135], 2, s[2:3]
	v_cvt_f32_i32_e32 v124, v124
	v_cvt_f32_i32_e32 v125, v125
	v_cvt_f32_i32_e32 v126, v126
	v_cvt_f32_i32_e32 v122, v122
	v_cvt_f32_i32_e32 v127, v127
	v_cvt_f32_i32_e32 v123, v123
	v_cvt_f32_i32_e32 v98, v98
	v_cvt_f32_i32_e32 v99, v99
	v_cvt_f32_i32_e32 v92, v92
	v_cvt_f32_i32_e32 v93, v93
	v_cvt_f32_i32_e32 v94, v94
	v_cvt_f32_i32_e32 v90, v90
	v_cvt_f32_i32_e32 v95, v95
	v_cvt_f32_i32_e32 v91, v91
	v_cvt_f32_i32_e32 v82, v82
	v_cvt_f32_i32_e32 v83, v83
	v_cvt_f32_i32_e32 v76, v76
	v_cvt_f32_i32_e32 v72, v72
	v_cvt_f32_i32_e32 v77, v77
	v_cvt_f32_i32_e32 v73, v73
	v_cvt_f32_i32_e32 v78, v78
	v_cvt_f32_i32_e32 v74, v74
	v_cvt_f32_i32_e32 v79, v79
	v_cvt_f32_i32_e32 v75, v75
	v_cvt_f32_i32_e32 v70, v70
	v_cvt_f32_i32_e32 v66, v66
	v_cvt_f32_i32_e32 v71, v71
	v_cvt_f32_i32_e32 v67, v67
	v_cvt_f32_i32_e32 v60, v60
	v_cvt_f32_i32_e32 v56, v56
	v_cvt_f32_i32_e32 v61, v61
	v_cvt_f32_i32_e32 v57, v57
	v_cvt_f32_i32_e32 v62, v62
	v_cvt_f32_i32_e32 v58, v58
	v_cvt_f32_i32_e32 v63, v63
	v_cvt_f32_i32_e32 v59, v59
	v_cvt_f32_i32_e32 v54, v54
	v_cvt_f32_i32_e32 v50, v50
	v_cvt_f32_i32_e32 v55, v55
	v_cvt_f32_i32_e32 v51, v51
	v_cvt_f32_i32_e32 v44, v44
	v_cvt_f32_i32_e32 v40, v40
	v_cvt_f32_i32_e32 v45, v45
	v_cvt_f32_i32_e32 v41, v41
	v_cvt_f32_i32_e32 v46, v46
	v_cvt_f32_i32_e32 v42, v42
	v_cvt_f32_i32_e32 v47, v47
	v_cvt_f32_i32_e32 v43, v43
	v_cvt_f32_i32_e32 v38, v38
	v_cvt_f32_i32_e32 v34, v34
	v_cvt_f32_i32_e32 v39, v39
	v_cvt_f32_i32_e32 v35, v35
	v_cvt_f32_i32_e32 v28, v28
	v_cvt_f32_i32_e32 v24, v24
	v_cvt_f32_i32_e32 v29, v29
	s_waitcnt vmcnt(0)
; __device__ __forceinline__ unsigned cvt_pk_bf16(float lo, float hi) { unsigned r; asm volatile("v_cvt_pk_bf16_f32 %0, %1, %2" : "=v"(r) : "v"(lo), "v"(hi)); return r; }
; __device__ __forceinline__ float ld_agent(const float* p) { return __hip_atomic_load(p, __ATOMIC_RELAXED, __HIP_MEMORY_SCOPE_AGENT); }
; __device__ __forceinline__ float sigm(float x) { return __builtin_amdgcn_rcpf(1.f + __builtin_amdgcn_exp2f(-LOG2E * x)); }
;     __device__ __forceinline__ void operator()(const i32x4 (&acc)[2][2][4][2], const Unit& u, int wr, int wc, int fr_, int fq) const {
;     ...
;         for (int ai = 0; ai < 2; ++ai)
; #pragma unroll
;             for (int m = 0; m < 4; ++m) {
;                 asm volatile("" ::: "memory");
;                 const int r = row0 + ai * HALF + m * 16; const float rs = ld_agent(fr + r);
;                 bf16_t* rowp = O + (size_t)r * ldc + col0;
; #pragma unroll
;                 for (int bj = 0; bj < 2; ++bj) {
;                     f32x4 v0, v1;
; #pragma unroll
;                     for (int j = 0; j < 4; ++j) { v0[j] = (float)acc[ai][bj][m][0][j] * rs * sw[bj][0][j] + bv[bj][0][j]; v1[j] = (float)acc[ai][bj][m][1][j] * rs * sw[bj][1][j] + bv[bj][1][j]; }
;                     if (MODE == 1) {
; #pragma unroll
;                         for (int j = 0; j < 4; ++j) { v0[j] = sigm(v0[j]); v1[j] = sigm(v1[j]); } }
;                     u32x4 w; w.x = cvt_pk_bf16(v0[0], v0[1]); w.y = cvt_pk_bf16(v0[2], v0[3]); w.z = cvt_pk_bf16(v1[0], v1[1]); w.w = cvt_pk_bf16(v1[2], v1[3]);
;                     *(u32x4*)(rowp + bj * HALF) = w;
;                 }
	v_mul_f32_e32 v130, v140, v161
	v_mul_f32_e32 v131, v174, v161
	v_mul_f32_e32 v135, v141, v161
	v_mul_f32_e32 v140, v175, v161
	v_mul_f32_e32 v141, v142, v161
	v_mul_f32_e32 v142, v178, v161
	v_mul_f32_e32 v143, v143, v161
	v_mul_f32_e32 v172, v179, v161
	v_mul_f32_e32 v132, v132, v161
	v_mul_f32_e32 v173, v180, v161
	v_mul_f32_e32 v133, v133, v161
	v_fma_f32 v130, v116, v130, 0
	v_fma_f32 v180, v112, v131, 0
	v_fma_f32 v131, v117, v135, 0
	v_mul_f32_e32 v174, v181, v161
	v_mul_f32_e32 v175, v182, v161
	v_mul_f32_e32 v178, v183, v161
	v_mul_f32_e32 v179, v184, v161
	v_mul_f32_e32 v161, v185, v161
	v_fma_f32 v135, v113, v140, 0
	v_fma_f32 v140, v118, v141, 0
	v_fma_f32 v141, v114, v142, 0
	v_fma_f32 v142, v119, v143, 0
	v_fma_f32 v143, v115, v172, 0
	v_fma_f32 v172, v108, v132, 0
	v_fma_f32 v181, v109, v133, 0
	v_cvt_pk_bf16_f32 v130, v130, v131
	v_cvt_pk_bf16_f32 v131, v140, v142
	v_cvt_pk_bf16_f32 v132, v180, v135
	v_cvt_pk_bf16_f32 v133, v141, v143
	v_fma_f32 v173, v104, v173, 0
	v_fma_f32 v174, v105, v174, 0
	v_fma_f32 v175, v110, v175, 0
	v_fma_f32 v178, v106, v178, 0
	v_fma_f32 v179, v111, v179, 0
	v_fma_f32 v161, v107, v161, 0
	global_store_dwordx4 v[136:137], v[130:133], off sc0 sc1
	v_cvt_f32_i32_e32 v135, v96
	v_cvt_f32_i32_e32 v25, v25
	v_cvt_pk_bf16_f32 v130, v172, v181
	v_cvt_pk_bf16_f32 v131, v175, v179
	v_cvt_pk_bf16_f32 v132, v173, v174
	v_cvt_pk_bf16_f32 v133, v178, v161
	global_store_dwordx4 v[136:137], v[130:133], off offset:256 sc0 sc1
	s_nop 1
	v_mov_b32_e32 v130, v190
	v_cvt_f32_i32_e32 v136, v101
	v_cvt_f32_i32_e32 v131, v120
	v_cvt_f32_i32_e32 v132, v121
	v_cvt_f32_i32_e32 v133, v100
	v_cvt_f32_i32_e32 v137, v97
	v_cvt_f32_i32_e32 v138, v102
	v_cvt_f32_i32_e32 v139, v103
	v_or_b32_e32 v100, 32, v160
	v_mad_i64_i32 v[96:97], s[22:23], v134, s42, v[162:163]
	v_ashrrev_i32_e32 v101, 31, v100
	v_lshl_add_u64 v[102:103], v[96:97], 0, v[128:129]
	v_lshl_add_u64 v[120:121], v[100:101], 2, s[2:3]
	v_cvt_f32_i32_e32 v30, v30
	v_cvt_f32_i32_e32 v26, v26
	v_cvt_f32_i32_e32 v31, v31
	v_cvt_f32_i32_e32 v27, v27
	v_cvt_f32_i32_e32 v22, v22
	v_cvt_f32_i32_e32 v18, v18
	v_cvt_f32_i32_e32 v23, v23
	v_cvt_f32_i32_e32 v19, v19
	v_cvt_f32_i32_e32 v12, v12
	v_cvt_f32_i32_e32 v8, v8
	v_cvt_f32_i32_e32 v13, v13
	v_cvt_f32_i32_e32 v9, v9
	v_cvt_f32_i32_e32 v14, v14
	v_cvt_f32_i32_e32 v10, v10
	v_cvt_f32_i32_e32 v15, v15
	v_cvt_f32_i32_e32 v11, v11
	v_cvt_f32_i32_e32 v6, v6
	v_cvt_f32_i32_e32 v2, v2
	v_cvt_f32_i32_e32 v7, v7
	v_cvt_f32_i32_e32 v3, v3
	s_and_b64 vcc, exec, s[0:1]
	s_mov_b32 s43, s12
	s_mov_b32 s20, s14
	s_mov_b64 s[24:25], s[18:19]
	v_mul_f32_e32 v96, v124, v130
	v_mul_f32_e32 v97, v131, v130
	v_mul_f32_e32 v101, v125, v130
	v_mul_f32_e32 v124, v132, v130
	v_mul_f32_e32 v125, v126, v130
	v_mul_f32_e32 v122, v122, v130
	v_mul_f32_e32 v126, v127, v130
	v_mul_f32_e32 v123, v123, v130
	v_mul_f32_e32 v127, v133, v130
	v_mul_f32_e32 v131, v135, v130
	v_mul_f32_e32 v132, v136, v130
	v_mul_f32_e32 v133, v137, v130
	v_mul_f32_e32 v134, v138, v130
	v_mul_f32_e32 v98, v98, v130
	v_mul_f32_e32 v135, v139, v130
	v_mul_f32_e32 v99, v99, v130
	v_fma_f32 v96, v116, v96, 0
	v_fma_f32 v130, v112, v97, 0
	v_fma_f32 v97, v117, v101, 0
	v_fma_f32 v101, v113, v124, 0
	v_fma_f32 v124, v118, v125, 0
	v_fma_f32 v122, v114, v122, 0
	v_fma_f32 v125, v119, v126, 0
	v_fma_f32 v123, v115, v123, 0
	v_fma_f32 v126, v108, v127, 0
	v_fma_f32 v127, v104, v131, 0
	v_fma_f32 v131, v109, v132, 0
	v_fma_f32 v132, v105, v133, 0
	v_fma_f32 v133, v110, v134, 0
	v_fma_f32 v134, v106, v98, 0
	v_fma_f32 v136, v107, v99, 0
	v_cvt_pk_bf16_f32 v96, v96, v97
	v_cvt_pk_bf16_f32 v97, v124, v125
	v_cvt_pk_bf16_f32 v98, v130, v101
	v_cvt_pk_bf16_f32 v99, v122, v123
	v_fma_f32 v135, v111, v135, 0
	global_store_dwordx4 v[102:103], v[96:99], off sc0 sc1
	v_cvt_f32_i32_e32 v101, v80
	s_nop 0
	v_cvt_pk_bf16_f32 v96, v126, v131
	v_cvt_pk_bf16_f32 v97, v133, v135
	v_cvt_pk_bf16_f32 v98, v127, v132
	v_cvt_pk_bf16_f32 v99, v134, v136
	global_store_dwordx4 v[102:103], v[96:99], off offset:256 sc0 sc1
	s_nop 1
	v_mov_b32_e32 v96, v191
	v_cvt_f32_i32_e32 v102, v85
	v_cvt_f32_i32_e32 v97, v88
	v_cvt_f32_i32_e32 v98, v89
	v_cvt_f32_i32_e32 v99, v84
	v_cvt_f32_i32_e32 v103, v81
	v_cvt_f32_i32_e32 v120, v86
	v_cvt_f32_i32_e32 v121, v87
	v_or_b32_e32 v84, 48, v160
	v_mad_i64_i32 v[80:81], s[22:23], v100, s42, v[162:163]
	v_ashrrev_i32_e32 v85, 31, v84
	v_lshl_add_u64 v[86:87], v[80:81], 0, v[128:129]
	v_lshl_add_u64 v[88:89], v[84:85], 2, s[2:3]
	v_mul_f32_e32 v80, v92, v96
	v_mul_f32_e32 v81, v97, v96
	v_mul_f32_e32 v85, v93, v96
	v_mul_f32_e32 v92, v98, v96
	v_mul_f32_e32 v93, v94, v96
	v_mul_f32_e32 v90, v90, v96
	v_mul_f32_e32 v94, v95, v96
	v_mul_f32_e32 v91, v91, v96
	v_mul_f32_e32 v95, v99, v96
	v_mul_f32_e32 v97, v101, v96
	v_mul_f32_e32 v98, v102, v96
	v_mul_f32_e32 v99, v103, v96
	v_mul_f32_e32 v100, v120, v96
	v_mul_f32_e32 v82, v82, v96
	v_mul_f32_e32 v101, v121, v96
	v_mul_f32_e32 v83, v83, v96
	v_fma_f32 v80, v116, v80, 0
	v_fma_f32 v96, v112, v81, 0
	v_fma_f32 v81, v117, v85, 0
	v_fma_f32 v85, v113, v92, 0
	v_fma_f32 v92, v118, v93, 0
	v_fma_f32 v90, v114, v90, 0
	v_fma_f32 v93, v119, v94, 0
	v_fma_f32 v91, v115, v91, 0
	v_fma_f32 v94, v108, v95, 0
	v_fma_f32 v95, v104, v97, 0
	v_fma_f32 v97, v109, v98, 0
	v_fma_f32 v98, v105, v99, 0
	v_fma_f32 v99, v110, v100, 0
	v_fma_f32 v100, v106, v82, 0
	v_fma_f32 v102, v107, v83, 0
	v_cvt_pk_bf16_f32 v80, v80, v81
	v_cvt_pk_bf16_f32 v81, v92, v93
	v_cvt_pk_bf16_f32 v82, v96, v85
	v_cvt_pk_bf16_f32 v83, v90, v91
	v_fma_f32 v101, v111, v101, 0
	global_store_dwordx4 v[86:87], v[80:83], off sc0 sc1
	v_cvt_f32_i32_e32 v85, v65
	s_nop 0
; __device__ __forceinline__ unsigned cvt_pk_bf16(float lo, float hi) { unsigned r; asm volatile("v_cvt_pk_bf16_f32 %0, %1, %2" : "=v"(r) : "v"(lo), "v"(hi)); return r; }
; __device__ __forceinline__ float ld_agent(const float* p) { return __hip_atomic_load(p, __ATOMIC_RELAXED, __HIP_MEMORY_SCOPE_AGENT); }
; __device__ __forceinline__ float sigm(float x) { return __builtin_amdgcn_rcpf(1.f + __builtin_amdgcn_exp2f(-LOG2E * x)); }
;     __device__ __forceinline__ void operator()(const i32x4 (&acc)[2][2][4][2], const Unit& u, int wr, int wc, int fr_, int fq) const {
;     ...
;         for (int ai = 0; ai < 2; ++ai)
; #pragma unroll
;             for (int m = 0; m < 4; ++m) {
;                 asm volatile("" ::: "memory");
;                 const int r = row0 + ai * HALF + m * 16; const float rs = ld_agent(fr + r);
;                 bf16_t* rowp = O + (size_t)r * ldc + col0;
; #pragma unroll
;                 for (int bj = 0; bj < 2; ++bj) {
;                     f32x4 v0, v1;
; #pragma unroll
;                     for (int j = 0; j < 4; ++j) { v0[j] = (float)acc[ai][bj][m][0][j] * rs * sw[bj][0][j] + bv[bj][0][j]; v1[j] = (float)acc[ai][bj][m][1][j] * rs * sw[bj][1][j] + bv[bj][1][j]; }
;                     if (MODE == 1) {
; #pragma unroll
;                         for (int j = 0; j < 4; ++j) { v0[j] = sigm(v0[j]); v1[j] = sigm(v1[j]); } }
;                     u32x4 w; w.x = cvt_pk_bf16(v0[0], v0[1]); w.y = cvt_pk_bf16(v0[2], v0[3]); w.z = cvt_pk_bf16(v1[0], v1[1]); w.w = cvt_pk_bf16(v1[2], v1[3]);
;                     *(u32x4*)(rowp + bj * HALF) = w;
;                 }
	v_cvt_pk_bf16_f32 v80, v94, v97
	v_cvt_pk_bf16_f32 v81, v99, v101
	v_cvt_pk_bf16_f32 v82, v95, v98
	v_cvt_pk_bf16_f32 v83, v100, v102
	global_store_dwordx4 v[86:87], v[80:83], off offset:256 sc0 sc1
	s_nop 1
	v_mov_b32_e32 v80, v192
	v_mul_f32_e32 v73, v73, v80
	v_cvt_f32_i32_e32 v81, v68
	v_cvt_f32_i32_e32 v82, v64
	v_cvt_f32_i32_e32 v83, v69
	v_mad_i64_i32 v[64:65], s[22:23], v84, s42, v[162:163]
	v_lshl_add_u64 v[68:69], v[64:65], 0, v[128:129]
	v_mul_f32_e32 v64, v76, v80
	v_mul_f32_e32 v65, v72, v80
	v_mul_f32_e32 v72, v77, v80
	v_mul_f32_e32 v76, v78, v80
	v_mul_f32_e32 v74, v74, v80
	v_mul_f32_e32 v77, v79, v80
	v_mul_f32_e32 v75, v75, v80
	v_mul_f32_e32 v78, v81, v80
	v_mul_f32_e32 v79, v82, v80
	v_mul_f32_e32 v81, v83, v80
	v_mul_f32_e32 v82, v85, v80
	v_mul_f32_e32 v70, v70, v80
	v_mul_f32_e32 v66, v66, v80
	v_mul_f32_e32 v71, v71, v80
	v_mul_f32_e32 v67, v67, v80
	v_fma_f32 v64, v116, v64, 0
	v_fma_f32 v80, v112, v65, 0
	v_fma_f32 v65, v117, v72, 0
	v_fma_f32 v72, v113, v73, 0
	v_fma_f32 v73, v118, v76, 0
	v_fma_f32 v74, v114, v74, 0
	v_fma_f32 v76, v119, v77, 0
	v_fma_f32 v75, v115, v75, 0
	v_fma_f32 v77, v108, v78, 0
	v_fma_f32 v78, v104, v79, 0
	v_fma_f32 v79, v109, v81, 0
	v_fma_f32 v81, v105, v82, 0
	v_fma_f32 v82, v106, v66, 0
	v_fma_f32 v83, v107, v67, 0
	v_cvt_pk_bf16_f32 v64, v64, v65
	v_cvt_pk_bf16_f32 v65, v73, v76
	v_cvt_pk_bf16_f32 v66, v80, v72
	v_cvt_pk_bf16_f32 v67, v74, v75
	v_fma_f32 v70, v110, v70, 0
	v_fma_f32 v71, v111, v71, 0
	global_store_dwordx4 v[68:69], v[64:67], off sc0 sc1
	s_nop 1
	v_cvt_pk_bf16_f32 v64, v77, v79
	v_cvt_pk_bf16_f32 v65, v70, v71
	v_cvt_pk_bf16_f32 v66, v78, v81
	v_cvt_pk_bf16_f32 v67, v82, v83
	global_store_dwordx4 v[68:69], v[64:67], off offset:256 sc0 sc1
	s_nop 1
	v_mov_b32_e32 v64, v193
	v_cvt_f32_i32_e32 v68, v49
	v_cvt_f32_i32_e32 v65, v52
	v_cvt_f32_i32_e32 v66, v48
	v_cvt_f32_i32_e32 v67, v53
	v_add_u32_e32 v48, 0x80, v160
	v_mad_i64_i32 v[48:49], s[22:23], v48, s42, v[162:163]
	v_lshl_add_u64 v[52:53], v[48:49], 0, v[128:129]
	v_mul_f32_e32 v48, v60, v64
	v_mul_f32_e32 v49, v56, v64
	v_mul_f32_e32 v56, v61, v64
	v_mul_f32_e32 v57, v57, v64
	v_mul_f32_e32 v60, v62, v64
	v_mul_f32_e32 v58, v58, v64
	v_mul_f32_e32 v61, v63, v64
	v_mul_f32_e32 v59, v59, v64
	v_mul_f32_e32 v62, v65, v64
	v_mul_f32_e32 v63, v66, v64
	v_mul_f32_e32 v65, v67, v64
	v_mul_f32_e32 v66, v68, v64
	v_mul_f32_e32 v54, v54, v64
	v_mul_f32_e32 v50, v50, v64
	v_mul_f32_e32 v55, v55, v64
	v_mul_f32_e32 v51, v51, v64
	v_fma_f32 v48, v116, v48, 0
	v_fma_f32 v64, v112, v49, 0
	v_fma_f32 v49, v117, v56, 0
	v_fma_f32 v56, v113, v57, 0
	v_fma_f32 v57, v118, v60, 0
	v_fma_f32 v58, v114, v58, 0
	v_fma_f32 v60, v119, v61, 0
	v_fma_f32 v59, v115, v59, 0
	v_fma_f32 v61, v108, v62, 0
	v_fma_f32 v62, v104, v63, 0
	v_fma_f32 v63, v109, v65, 0
	v_fma_f32 v65, v105, v66, 0
	v_fma_f32 v66, v106, v50, 0
	v_fma_f32 v67, v107, v51, 0
	v_cvt_pk_bf16_f32 v48, v48, v49
	v_cvt_pk_bf16_f32 v49, v57, v60
	v_cvt_pk_bf16_f32 v50, v64, v56
	v_cvt_pk_bf16_f32 v51, v58, v59
	v_fma_f32 v54, v110, v54, 0
	v_fma_f32 v55, v111, v55, 0
	global_store_dwordx4 v[52:53], v[48:51], off sc0 sc1
	s_nop 1
	v_cvt_pk_bf16_f32 v48, v61, v63
	v_cvt_pk_bf16_f32 v49, v54, v55
	v_cvt_pk_bf16_f32 v50, v62, v65
	v_cvt_pk_bf16_f32 v51, v66, v67
	global_store_dwordx4 v[52:53], v[48:51], off offset:256 sc0 sc1
	s_nop 1
	v_mov_b32_e32 v48, v194
	v_cvt_f32_i32_e32 v52, v33
	v_cvt_f32_i32_e32 v49, v36
	v_cvt_f32_i32_e32 v50, v32
	v_cvt_f32_i32_e32 v51, v37
	v_add_u32_e32 v32, 0x90, v160
	v_mad_i64_i32 v[32:33], s[22:23], v32, s42, v[162:163]
	v_lshl_add_u64 v[36:37], v[32:33], 0, v[128:129]
	v_mul_f32_e32 v32, v44, v48
	v_mul_f32_e32 v33, v40, v48
	v_mul_f32_e32 v40, v45, v48
	v_mul_f32_e32 v41, v41, v48
	v_mul_f32_e32 v44, v46, v48
	v_mul_f32_e32 v42, v42, v48
	v_mul_f32_e32 v45, v47, v48
	v_mul_f32_e32 v43, v43, v48
	v_mul_f32_e32 v46, v49, v48
	v_mul_f32_e32 v47, v50, v48
	v_mul_f32_e32 v49, v51, v48
	v_mul_f32_e32 v50, v52, v48
	v_mul_f32_e32 v38, v38, v48
	v_mul_f32_e32 v34, v34, v48
	v_mul_f32_e32 v39, v39, v48
	v_mul_f32_e32 v35, v35, v48
	v_fma_f32 v32, v116, v32, 0
; __device__ __forceinline__ unsigned cvt_pk_bf16(float lo, float hi) { unsigned r; asm volatile("v_cvt_pk_bf16_f32 %0, %1, %2" : "=v"(r) : "v"(lo), "v"(hi)); return r; }
; __device__ __forceinline__ float ld_agent(const float* p) { return __hip_atomic_load(p, __ATOMIC_RELAXED, __HIP_MEMORY_SCOPE_AGENT); }
; __device__ __forceinline__ float sigm(float x) { return __builtin_amdgcn_rcpf(1.f + __builtin_amdgcn_exp2f(-LOG2E * x)); }
; #define PG8_WAIT_V(n) asm volatile("s_waitcnt vmcnt(" #n ")" ::: "memory")
; #define PG8_BAR __builtin_amdgcn_s_barrier()
;     __device__ __forceinline__ void operator()(const i32x4 (&acc)[2][2][4][2], const Unit& u, int wr, int wc, int fr_, int fq) const {
;     ...
;         for (int ai = 0; ai < 2; ++ai)
; #pragma unroll
;             for (int m = 0; m < 4; ++m) {
;                 asm volatile("" ::: "memory");
;                 const int r = row0 + ai * HALF + m * 16; const float rs = ld_agent(fr + r);
;                 bf16_t* rowp = O + (size_t)r * ldc + col0;
; #pragma unroll
;                 for (int bj = 0; bj < 2; ++bj) {
;                     f32x4 v0, v1;
; #pragma unroll
;                     for (int j = 0; j < 4; ++j) { v0[j] = (float)acc[ai][bj][m][0][j] * rs * sw[bj][0][j] + bv[bj][0][j]; v1[j] = (float)acc[ai][bj][m][1][j] * rs * sw[bj][1][j] + bv[bj][1][j]; }
;                     if (MODE == 1) {
; #pragma unroll
;                         for (int j = 0; j < 4; ++j) { v0[j] = sigm(v0[j]); v1[j] = sigm(v1[j]); } }
;                     u32x4 w; w.x = cvt_pk_bf16(v0[0], v0[1]); w.y = cvt_pk_bf16(v0[2], v0[3]); w.z = cvt_pk_bf16(v1[0], v1[1]); w.w = cvt_pk_bf16(v1[2], v1[3]);
;                     *(u32x4*)(rowp + bj * HALF) = w;
;                 }
; template <class Epi, class Sched>
; __device__ __forceinline__ void gemm_phase(LAS unsigned char* lds, const Gemm g, const Sched& S, const Epi& E) {
;     ...
;         E(acc, cur, wr, wc, fr, fq);
;         if (!has_next) break;
; #pragma unroll
;         for (int a = 0; a < 2; ++a)
; #pragma unroll
;             for (int b = 0; b < 2; ++b)
; #pragma unroll
;                 for (int m = 0; m < 4; ++m)
; #pragma unroll
;                     for (int n = 0; n < 2; ++n) acc[a][b][m][n] = (acc_t){0, 0, 0, 0};
;         cur = nxt; cA = nA; cB = nB; ++ui;
;     }
;     PG8_WAIT_V(0);
;     if (wr == 0) PG8_BAR;
;     PG8_BAR;
	v_fma_f32 v48, v112, v33, 0
	v_fma_f32 v33, v117, v40, 0
	v_fma_f32 v40, v113, v41, 0
	v_fma_f32 v41, v118, v44, 0
	v_fma_f32 v42, v114, v42, 0
	v_fma_f32 v44, v119, v45, 0
	v_fma_f32 v43, v115, v43, 0
	v_fma_f32 v45, v108, v46, 0
	v_fma_f32 v46, v104, v47, 0
	v_fma_f32 v47, v109, v49, 0
	v_fma_f32 v49, v105, v50, 0
	v_fma_f32 v50, v106, v34, 0
	v_fma_f32 v51, v107, v35, 0
	v_cvt_pk_bf16_f32 v32, v32, v33
	v_cvt_pk_bf16_f32 v33, v41, v44
	v_cvt_pk_bf16_f32 v34, v48, v40
	v_cvt_pk_bf16_f32 v35, v42, v43
	v_fma_f32 v38, v110, v38, 0
	v_fma_f32 v39, v111, v39, 0
	global_store_dwordx4 v[36:37], v[32:35], off sc0 sc1
	s_nop 1
	v_cvt_pk_bf16_f32 v32, v45, v47
	v_cvt_pk_bf16_f32 v33, v38, v39
	v_cvt_pk_bf16_f32 v34, v46, v49
	v_cvt_pk_bf16_f32 v35, v50, v51
	global_store_dwordx4 v[36:37], v[32:35], off offset:256 sc0 sc1
	s_nop 1
	v_mov_b32_e32 v32, v195
	v_cvt_f32_i32_e32 v36, v17
	v_cvt_f32_i32_e32 v33, v20
	v_cvt_f32_i32_e32 v34, v16
	v_cvt_f32_i32_e32 v35, v21
	v_add_u32_e32 v16, 0xa0, v160
	v_mad_i64_i32 v[16:17], s[22:23], v16, s42, v[162:163]
	v_lshl_add_u64 v[20:21], v[16:17], 0, v[128:129]
	s_mov_b64 s[22:23], s[16:17]
	v_mul_f32_e32 v16, v28, v32
	v_mul_f32_e32 v17, v24, v32
	v_mul_f32_e32 v24, v29, v32
	v_mul_f32_e32 v25, v25, v32
	v_mul_f32_e32 v28, v30, v32
	v_mul_f32_e32 v26, v26, v32
	v_mul_f32_e32 v29, v31, v32
	v_mul_f32_e32 v27, v27, v32
	v_mul_f32_e32 v30, v33, v32
	v_mul_f32_e32 v31, v34, v32
	v_mul_f32_e32 v33, v35, v32
	v_mul_f32_e32 v34, v36, v32
	v_mul_f32_e32 v22, v22, v32
	v_mul_f32_e32 v18, v18, v32
	v_mul_f32_e32 v23, v23, v32
	v_mul_f32_e32 v19, v19, v32
	v_fma_f32 v16, v116, v16, 0
	v_fma_f32 v32, v112, v17, 0
	v_fma_f32 v17, v117, v24, 0
	v_fma_f32 v24, v113, v25, 0
	v_fma_f32 v25, v118, v28, 0
	v_fma_f32 v26, v114, v26, 0
	v_fma_f32 v28, v119, v29, 0
	v_fma_f32 v27, v115, v27, 0
	v_fma_f32 v29, v108, v30, 0
	v_fma_f32 v30, v104, v31, 0
	v_fma_f32 v31, v109, v33, 0
	v_fma_f32 v33, v105, v34, 0
	v_fma_f32 v34, v106, v18, 0
	v_fma_f32 v35, v107, v19, 0
	v_cvt_pk_bf16_f32 v16, v16, v17
	v_cvt_pk_bf16_f32 v17, v25, v28
	v_cvt_pk_bf16_f32 v18, v32, v24
	v_cvt_pk_bf16_f32 v19, v26, v27
	v_fma_f32 v22, v110, v22, 0
	v_fma_f32 v23, v111, v23, 0
	global_store_dwordx4 v[20:21], v[16:19], off sc0 sc1
	s_nop 1
	v_cvt_pk_bf16_f32 v16, v29, v31
	v_cvt_pk_bf16_f32 v17, v22, v23
	v_cvt_pk_bf16_f32 v18, v30, v33
	v_cvt_pk_bf16_f32 v19, v34, v35
	global_store_dwordx4 v[20:21], v[16:19], off offset:256 sc0 sc1
	s_nop 1
	v_mov_b32_e32 v16, v196
	v_cvt_f32_i32_e32 v20, v1
	v_cvt_f32_i32_e32 v17, v4
	v_cvt_f32_i32_e32 v18, v0
	v_cvt_f32_i32_e32 v19, v5
	v_add_u32_e32 v0, 0xb0, v160
	v_mad_i64_i32 v[0:1], s[0:1], v0, s42, v[162:163]
	v_lshl_add_u64 v[4:5], v[0:1], 0, v[128:129]
	v_mul_f32_e32 v0, v12, v16
	v_mul_f32_e32 v1, v8, v16
	v_mul_f32_e32 v8, v13, v16
	v_mul_f32_e32 v9, v9, v16
	v_mul_f32_e32 v12, v14, v16
	v_mul_f32_e32 v10, v10, v16
	v_mul_f32_e32 v13, v15, v16
	v_mul_f32_e32 v11, v11, v16
	v_mul_f32_e32 v14, v17, v16
	v_mul_f32_e32 v15, v18, v16
	v_mul_f32_e32 v17, v19, v16
	v_mul_f32_e32 v18, v20, v16
	v_mul_f32_e32 v6, v6, v16
	v_mul_f32_e32 v2, v2, v16
	v_mul_f32_e32 v7, v7, v16
	v_mul_f32_e32 v3, v3, v16
	v_fma_f32 v0, v116, v0, 0
	v_fma_f32 v16, v112, v1, 0
	v_fma_f32 v1, v117, v8, 0
	v_fma_f32 v8, v113, v9, 0
	v_fma_f32 v9, v118, v12, 0
	v_fma_f32 v10, v114, v10, 0
	v_fma_f32 v12, v119, v13, 0
	v_fma_f32 v11, v115, v11, 0
	v_fma_f32 v13, v108, v14, 0
	v_fma_f32 v14, v104, v15, 0
	v_fma_f32 v15, v109, v17, 0
	v_fma_f32 v17, v105, v18, 0
	v_fma_f32 v18, v106, v2, 0
	v_fma_f32 v19, v107, v3, 0
	v_cvt_pk_bf16_f32 v0, v0, v1
	v_cvt_pk_bf16_f32 v1, v9, v12
	v_cvt_pk_bf16_f32 v2, v16, v8
	v_cvt_pk_bf16_f32 v3, v10, v11
	v_fma_f32 v6, v110, v6, 0
	v_fma_f32 v7, v111, v7, 0
	global_store_dwordx4 v[4:5], v[0:3], off sc0 sc1
	s_nop 1
	v_cvt_pk_bf16_f32 v0, v13, v15
	v_cvt_pk_bf16_f32 v1, v6, v7
	v_cvt_pk_bf16_f32 v2, v14, v17
	v_cvt_pk_bf16_f32 v3, v18, v19
	global_store_dwordx4 v[4:5], v[0:3], off offset:256 sc0 sc1
	s_cbranch_vccz .LBB0_383
	s_waitcnt vmcnt(0)
	s_cmpk_gt_u32 s28, 0xff
	s_cbranch_scc1 .LBB0_390
	s_barrier

; #define PG8_STAGE(bufoff, gbase, voff) do { _Pragma("unroll") for (int _i = 0; _i < 2; ++_i) \
;         __builtin_amdgcn_global_load_lds((const unsigned*)((const char*)(gbase) + (voff)[_i]), (LAS unsigned*)(lds + (bufoff) + ldsw + _i * 8192), 16, 0, 0); } while (0)
; #define PG8_LDA(dst, b, h) do { _Pragma("unroll") for (int m = 0; m < 4; ++m) _Pragma("unroll") for (int k = 0; k < 2; ++k) dst[m][k] = *(const LAS bf16x8*)(lds + PG8_SA(b, h) + aoff + m * 2048 + k * 1024); } while (0)
; #define PG8_LDB(dst, b, h) do { _Pragma("unroll") for (int n = 0; n < 2; ++n) _Pragma("unroll") for (int k = 0; k < 2; ++k) dst[n][k] = *(const LAS bf16x8*)(lds + PG8_SB(b, h) + boff + n * 2048 + k * 1024); } while (0)
; #define PG8_MMA(ai, bj, At, Bt) do { __builtin_amdgcn_s_setprio(1); _Pragma("unroll") for (int m = 0; m < 4; ++m) _Pragma("unroll") for (int n = 0; n < 2; ++n) _Pragma("unroll") for (int k = 0; k < 2; ++k) \
;         acc[ai][bj][m][n] = MmaOp<Epi::I8>::run(Bt[n][k], At[m][k], acc[ai][bj][m][n]); __builtin_amdgcn_s_setprio(0); } while (0)
; #define PG8_WAIT_V(n) asm volatile("s_waitcnt vmcnt(" #n ")" ::: "memory")
; #define PG8_WAIT_L(n) asm volatile("s_waitcnt lgkmcnt(" #n ")" ::: "memory")
; #define PG8_BAR __builtin_amdgcn_s_barrier()
; template <class Epi, class Sched>
; __device__ __forceinline__ void gemm_phase(LAS unsigned char* lds, const Gemm g, const Sched& S, const Epi& E) {
;     ...
;             PG8_LDB(B0, 0, 0); PG8_SCHED; PG8_LDA(At, 0, 0); PG8_STAGE(PG8_SA(1, 1), a1 + hstepA, voffA);
;             PG8_WAIT_L(8); PG8_BAR; PG8_WAIT_L(0); PG8_MMA(0, 0, At, B0); PG8_BAR; PG8_SCHED;
;             PG8_LDB(B1, 0, 1); PG8_STAGE(PG8_SB(0, 0), b2, voffB);
;             PG8_BAR; PG8_WAIT_L(0); PG8_MMA(0, 1, At, B1); PG8_BAR;
;             PG8_LDA(At, 0, 1); PG8_STAGE(PG8_SA(0, 0), a2, voffA);
;             PG8_BAR; PG8_WAIT_L(0); PG8_MMA(1, 0, At, B0); PG8_BAR; PG8_SCHED;
;             PG8_STAGE(PG8_SB(0, 1), b2 + hstepB, voffB);
;             PG8_WAIT_V(6); PG8_BAR; PG8_MMA(1, 1, At, B1); PG8_BAR;
;             PG8_LDB(B0, 1, 0); PG8_SCHED; PG8_LDA(At, 1, 0); PG8_STAGE(PG8_SA(0, 1), a2 + hstepA, voffA);
;             PG8_WAIT_L(8); PG8_BAR; PG8_WAIT_L(0); PG8_MMA(0, 0, At, B0); PG8_BAR; PG8_SCHED;
;             PG8_LDB(B1, 1, 1); PG8_STAGE(PG8_SB(1, 0), b3, voffB);
;             PG8_BAR; PG8_WAIT_L(0); PG8_MMA(0, 1, At, B1); PG8_BAR;
.LBB0_635:
	ds_read_b128 v[56:59], v169
	ds_read_b128 v[60:63], v169 offset:1024
	ds_read_b128 v[72:75], v169 offset:2048
	ds_read_b128 v[76:79], v169 offset:3072
	s_add_u32 s30, s28, 0xfff80080
	s_addc_u32 s31, s29, -1
	s_cmp_eq_u32 s59, 12
	s_cselect_b32 s35, s21, s31
	s_cselect_b32 s34, s55, s30
	s_cselect_b32 s31, s19, s58
	s_cselect_b32 s30, s56, s57
	v_lshl_add_u64 v[164:165], s[28:29], 0, v[152:153]
	s_add_i32 m0, s27, 0xc000
	ds_read_b128 v[160:163], v170
	ds_read_b128 v[178:181], v170 offset:1024
	ds_read_b128 v[182:185], v170 offset:2048
	ds_read_b128 v[186:189], v170 offset:3072
	ds_read_b128 v[190:193], v170 offset:4096
	ds_read_b128 v[194:197], v170 offset:5120
	ds_read_b128 v[198:201], v170 offset:6144
	ds_read_b128 v[202:205], v170 offset:7168
	global_load_lds_dwordx4 v[164:165], off
	v_lshl_add_u64 v[164:165], s[28:29], 0, v[154:155]
	s_add_i32 m0, s27, 0xe000
	s_nop 0
	global_load_lds_dwordx4 v[164:165], off
	s_waitcnt lgkmcnt(8)
	s_barrier
	s_waitcnt lgkmcnt(0)
	s_setprio 1
	s_waitcnt lgkmcnt(0)
	v_mfma_i32_16x16x64_i8 v[140:143], v[56:59], v[160:163], v[140:143]
	v_mfma_i32_16x16x64_i8 v[136:139], v[72:75], v[160:163], v[136:139]
	v_mfma_i32_16x16x64_i8 v[124:127], v[56:59], v[182:185], v[124:127]
	v_mfma_i32_16x16x64_i8 v[120:123], v[72:75], v[182:185], v[120:123]
	v_mfma_i32_16x16x64_i8 v[108:111], v[56:59], v[190:193], v[108:111]
	v_mfma_i32_16x16x64_i8 v[104:107], v[72:75], v[190:193], v[104:107]
	v_mfma_i32_16x16x64_i8 v[92:95], v[56:59], v[198:201], v[92:95]
	v_mfma_i32_16x16x64_i8 v[88:91], v[72:75], v[198:201], v[88:91]
	v_mfma_i32_16x16x64_i8 v[140:143], v[60:63], v[178:181], v[140:143]
	v_mfma_i32_16x16x64_i8 v[136:139], v[76:79], v[178:181], v[136:139]
	v_mfma_i32_16x16x64_i8 v[124:127], v[60:63], v[186:189], v[124:127]
	v_mfma_i32_16x16x64_i8 v[120:123], v[76:79], v[186:189], v[120:123]
	v_mfma_i32_16x16x64_i8 v[108:111], v[60:63], v[194:197], v[108:111]
	v_mfma_i32_16x16x64_i8 v[104:107], v[76:79], v[194:197], v[104:107]
	v_mfma_i32_16x16x64_i8 v[92:95], v[60:63], v[202:205], v[92:95]
	v_mfma_i32_16x16x64_i8 v[88:91], v[76:79], v[202:205], v[88:91]
	s_setprio 0
	s_barrier
	s_add_i32 s60, s48, s38
	v_lshl_add_u64 v[164:165], s[30:31], 0, v[148:149]
	s_mov_b32 m0, s60
	ds_read_b128 v[206:209], v171
	ds_read_b128 v[210:213], v171 offset:1024
	ds_read_b128 v[214:217], v171 offset:2048
	ds_read_b128 v[218:221], v171 offset:3072
	global_load_lds_dwordx4 v[164:165], off
	v_lshl_add_u64 v[174:175], s[30:31], 0, v[144:145]
	s_add_i32 m0, s60, 0x2000
	s_nop 0
	global_load_lds_dwordx4 v[174:175], off
	s_barrier
	s_waitcnt lgkmcnt(0)
	s_setprio 1
	s_waitcnt lgkmcnt(0)
	v_mfma_i32_16x16x64_i8 v[132:135], v[206:209], v[160:163], v[132:135]
	v_mfma_i32_16x16x64_i8 v[128:131], v[214:217], v[160:163], v[128:131]
	v_mfma_i32_16x16x64_i8 v[116:119], v[206:209], v[182:185], v[116:119]
	v_mfma_i32_16x16x64_i8 v[112:115], v[214:217], v[182:185], v[112:115]
	v_mfma_i32_16x16x64_i8 v[100:103], v[206:209], v[190:193], v[100:103]
	v_mfma_i32_16x16x64_i8 v[96:99], v[214:217], v[190:193], v[96:99]
	v_mfma_i32_16x16x64_i8 v[84:87], v[206:209], v[198:201], v[84:87]
	v_mfma_i32_16x16x64_i8 v[80:83], v[214:217], v[198:201], v[80:83]
	v_mfma_i32_16x16x64_i8 v[132:135], v[210:213], v[178:181], v[132:135]
	v_mfma_i32_16x16x64_i8 v[128:131], v[218:221], v[178:181], v[128:131]
	v_mfma_i32_16x16x64_i8 v[116:119], v[210:213], v[186:189], v[116:119]
	v_mfma_i32_16x16x64_i8 v[112:115], v[218:221], v[186:189], v[112:115]
	v_mfma_i32_16x16x64_i8 v[100:103], v[210:213], v[194:197], v[100:103]
	v_mfma_i32_16x16x64_i8 v[96:99], v[218:221], v[194:197], v[96:99]
	v_mfma_i32_16x16x64_i8 v[84:87], v[210:213], v[202:205], v[84:87]
	v_mfma_i32_16x16x64_i8 v[80:83], v[218:221], v[202:205], v[80:83]
	s_setprio 0
	s_mov_b32 m0, s27
	v_lshl_add_u64 v[222:223], s[34:35], 0, v[150:151]
	s_barrier
	ds_read_b128 v[160:163], v170 offset:16384
	ds_read_b128 v[178:181], v170 offset:17408
	ds_read_b128 v[182:185], v170 offset:18432
	ds_read_b128 v[186:189], v170 offset:19456
	ds_read_b128 v[190:193], v170 offset:20480
	ds_read_b128 v[194:197], v170 offset:21504
	ds_read_b128 v[198:201], v170 offset:22528
	ds_read_b128 v[202:205], v170 offset:23552
	global_load_lds_dwordx4 v[222:223], off
	v_lshl_add_u64 v[224:225], s[34:35], 0, v[146:147]
	s_mov_b32 m0, s41
	s_nop 0
	global_load_lds_dwordx4 v[224:225], off
	s_barrier
	s_waitcnt lgkmcnt(0)
	s_setprio 1
	s_waitcnt lgkmcnt(0)
	v_mfma_i32_16x16x64_i8 v[68:71], v[56:59], v[160:163], v[68:71]
	v_mfma_i32_16x16x64_i8 v[64:67], v[72:75], v[160:163], v[64:67]
	v_mfma_i32_16x16x64_i8 v[44:47], v[56:59], v[182:185], v[44:47]
	v_mfma_i32_16x16x64_i8 v[40:43], v[72:75], v[182:185], v[40:43]
	v_mfma_i32_16x16x64_i8 v[28:31], v[56:59], v[190:193], v[28:31]
	v_mfma_i32_16x16x64_i8 v[24:27], v[72:75], v[190:193], v[24:27]
	v_mfma_i32_16x16x64_i8 v[12:15], v[56:59], v[198:201], v[12:15]
	v_mfma_i32_16x16x64_i8 v[8:11], v[72:75], v[198:201], v[8:11]
	v_mfma_i32_16x16x64_i8 v[68:71], v[60:63], v[178:181], v[68:71]
	v_mfma_i32_16x16x64_i8 v[64:67], v[76:79], v[178:181], v[64:67]
	v_mfma_i32_16x16x64_i8 v[44:47], v[60:63], v[186:189], v[44:47]
	v_mfma_i32_16x16x64_i8 v[40:43], v[76:79], v[186:189], v[40:43]
	v_mfma_i32_16x16x64_i8 v[28:31], v[60:63], v[194:197], v[28:31]
	v_mfma_i32_16x16x64_i8 v[24:27], v[76:79], v[194:197], v[24:27]
	v_mfma_i32_16x16x64_i8 v[12:15], v[60:63], v[202:205], v[12:15]
	v_mfma_i32_16x16x64_i8 v[8:11], v[76:79], v[202:205], v[8:11]
	s_setprio 0
	s_barrier
; #define PG8_STAGE(bufoff, gbase, voff) do { _Pragma("unroll") for (int _i = 0; _i < 2; ++_i) \
;         __builtin_amdgcn_global_load_lds((const unsigned*)((const char*)(gbase) + (voff)[_i]), (LAS unsigned*)(lds + (bufoff) + ldsw + _i * 8192), 16, 0, 0); } while (0)
; #define PG8_LDA(dst, b, h) do { _Pragma("unroll") for (int m = 0; m < 4; ++m) _Pragma("unroll") for (int k = 0; k < 2; ++k) dst[m][k] = *(const LAS bf16x8*)(lds + PG8_SA(b, h) + aoff + m * 2048 + k * 1024); } while (0)
; #define PG8_LDB(dst, b, h) do { _Pragma("unroll") for (int n = 0; n < 2; ++n) _Pragma("unroll") for (int k = 0; k < 2; ++k) dst[n][k] = *(const LAS bf16x8*)(lds + PG8_SB(b, h) + boff + n * 2048 + k * 1024); } while (0)
; #define PG8_MMA(ai, bj, At, Bt) do { __builtin_amdgcn_s_setprio(1); _Pragma("unroll") for (int m = 0; m < 4; ++m) _Pragma("unroll") for (int n = 0; n < 2; ++n) _Pragma("unroll") for (int k = 0; k < 2; ++k) \
;         acc[ai][bj][m][n] = MmaOp<Epi::I8>::run(Bt[n][k], At[m][k], acc[ai][bj][m][n]); __builtin_amdgcn_s_setprio(0); } while (0)
; #define PG8_WAIT_V(n) asm volatile("s_waitcnt vmcnt(" #n ")" ::: "memory")
; #define PG8_WAIT_L(n) asm volatile("s_waitcnt lgkmcnt(" #n ")" ::: "memory")
; #define PG8_BAR __builtin_amdgcn_s_barrier()
; #define PG8_SCHED __builtin_amdgcn_sched_barrier(0)
; template <class Epi, class Sched>
; __device__ __forceinline__ void gemm_phase(LAS unsigned char* lds, const Gemm g, const Sched& S, const Epi& E) {
;     ...
;             PG8_STAGE(PG8_SB(0, 1), b2 + hstepB, voffB);
;             PG8_WAIT_V(6); PG8_BAR; PG8_MMA(1, 1, At, B1); PG8_BAR;
;             PG8_LDB(B0, 1, 0); PG8_SCHED; PG8_LDA(At, 1, 0); PG8_STAGE(PG8_SA(0, 1), a2 + hstepA, voffA);
;             PG8_WAIT_L(8); PG8_BAR; PG8_WAIT_L(0); PG8_MMA(0, 0, At, B0); PG8_BAR; PG8_SCHED;
;             PG8_LDB(B1, 1, 1); PG8_STAGE(PG8_SB(1, 0), b3, voffB);
;             PG8_BAR; PG8_WAIT_L(0); PG8_MMA(0, 1, At, B1); PG8_BAR;
;             PG8_LDA(At, 1, 1); PG8_STAGE(PG8_SA(1, 0), a3, voffA);
;             PG8_BAR; PG8_WAIT_L(0); PG8_MMA(1, 0, At, B0); PG8_BAR; PG8_SCHED;
	s_add_u32 s60, s30, 0x40000
	s_addc_u32 s61, s31, 0
	s_add_i32 s62, s49, s38
	v_lshl_add_u64 v[56:57], s[60:61], 0, v[148:149]
	s_mov_b32 m0, s62
	s_nop 0
	global_load_lds_dwordx4 v[56:57], off
	v_lshl_add_u64 v[56:57], s[60:61], 0, v[144:145]
	s_add_i32 m0, s62, 0x2000
	s_nop 0
	global_load_lds_dwordx4 v[56:57], off
	s_waitcnt vmcnt(6)
	s_barrier
	s_setprio 1
	v_mfma_i32_16x16x64_i8 v[52:55], v[206:209], v[160:163], v[52:55]
	v_mfma_i32_16x16x64_i8 v[48:51], v[214:217], v[160:163], v[48:51]
	v_mfma_i32_16x16x64_i8 v[36:39], v[206:209], v[182:185], v[36:39]
	v_mfma_i32_16x16x64_i8 v[32:35], v[214:217], v[182:185], v[32:35]
	v_mfma_i32_16x16x64_i8 v[20:23], v[206:209], v[190:193], v[20:23]
	v_mfma_i32_16x16x64_i8 v[16:19], v[214:217], v[190:193], v[16:19]
	v_mfma_i32_16x16x64_i8 v[4:7], v[206:209], v[198:201], v[4:7]
	v_mfma_i32_16x16x64_i8 v[0:3], v[214:217], v[198:201], v[0:3]
	v_mfma_i32_16x16x64_i8 v[52:55], v[210:213], v[178:181], v[52:55]
	v_mfma_i32_16x16x64_i8 v[48:51], v[218:221], v[178:181], v[48:51]
	v_mfma_i32_16x16x64_i8 v[36:39], v[210:213], v[186:189], v[36:39]
	v_mfma_i32_16x16x64_i8 v[32:35], v[218:221], v[186:189], v[32:35]
	v_mfma_i32_16x16x64_i8 v[20:23], v[210:213], v[194:197], v[20:23]
	v_mfma_i32_16x16x64_i8 v[16:19], v[218:221], v[194:197], v[16:19]
	v_mfma_i32_16x16x64_i8 v[4:7], v[210:213], v[202:205], v[4:7]
	v_mfma_i32_16x16x64_i8 v[0:3], v[218:221], v[202:205], v[0:3]
	s_setprio 0
	s_add_i32 s60, 0, 0x18000
	v_add_u32_e32 v76, s60, v167
	s_barrier
	ds_read_b128 v[56:59], v76
	ds_read_b128 v[60:63], v76 offset:1024
	ds_read_b128 v[72:75], v76 offset:2048
	ds_read_b128 v[76:79], v76 offset:3072
	s_add_u32 s34, s34, 0x80000
	s_addc_u32 s35, s35, 0
	s_mov_b32 m0, s42
	v_lshl_add_u64 v[206:207], s[34:35], 0, v[150:151]
	ds_read_b128 v[160:163], v170 offset:32768
	ds_read_b128 v[178:181], v170 offset:33792
	ds_read_b128 v[182:185], v170 offset:34816
	ds_read_b128 v[186:189], v170 offset:35840
	ds_read_b128 v[190:193], v170 offset:36864
	ds_read_b128 v[194:197], v170 offset:37888
	ds_read_b128 v[198:201], v170 offset:38912
	ds_read_b128 v[202:205], v170 offset:39936
	global_load_lds_dwordx4 v[206:207], off
	v_lshl_add_u64 v[206:207], s[34:35], 0, v[146:147]
	s_mov_b32 m0, s43
	s_nop 0
	global_load_lds_dwordx4 v[206:207], off
	s_waitcnt lgkmcnt(8)
	s_barrier
	s_waitcnt lgkmcnt(0)
	s_setprio 1
	s_waitcnt lgkmcnt(0)
	v_mfma_i32_16x16x64_i8 v[140:143], v[56:59], v[160:163], v[140:143]
	v_mfma_i32_16x16x64_i8 v[136:139], v[72:75], v[160:163], v[136:139]
	v_mfma_i32_16x16x64_i8 v[124:127], v[56:59], v[182:185], v[124:127]
	v_mfma_i32_16x16x64_i8 v[120:123], v[72:75], v[182:185], v[120:123]
	v_mfma_i32_16x16x64_i8 v[108:111], v[56:59], v[190:193], v[108:111]
	v_mfma_i32_16x16x64_i8 v[104:107], v[72:75], v[190:193], v[104:107]
	v_mfma_i32_16x16x64_i8 v[92:95], v[56:59], v[198:201], v[92:95]
	v_mfma_i32_16x16x64_i8 v[88:91], v[72:75], v[198:201], v[88:91]
	v_mfma_i32_16x16x64_i8 v[140:143], v[60:63], v[178:181], v[140:143]
	v_mfma_i32_16x16x64_i8 v[136:139], v[76:79], v[178:181], v[136:139]
	v_mfma_i32_16x16x64_i8 v[124:127], v[60:63], v[186:189], v[124:127]
	v_mfma_i32_16x16x64_i8 v[120:123], v[76:79], v[186:189], v[120:123]
	v_mfma_i32_16x16x64_i8 v[108:111], v[60:63], v[194:197], v[108:111]
	v_mfma_i32_16x16x64_i8 v[104:107], v[76:79], v[194:197], v[104:107]
	v_mfma_i32_16x16x64_i8 v[92:95], v[60:63], v[202:205], v[92:95]
	v_mfma_i32_16x16x64_i8 v[88:91], v[76:79], v[202:205], v[88:91]
	s_setprio 0
	s_barrier
	s_add_i32 s34, 0, 0x1c000
	s_add_i32 s35, s60, s38
	v_add_u32_e32 v173, s34, v167
	v_lshl_add_u64 v[164:165], v[164:165], 0, s[8:9]
	s_mov_b32 m0, s35
	ds_read_b128 v[206:209], v173
	ds_read_b128 v[210:213], v173 offset:1024
	ds_read_b128 v[214:217], v173 offset:2048
	ds_read_b128 v[218:221], v173 offset:3072
	global_load_lds_dwordx4 v[164:165], off
	v_lshl_add_u64 v[164:165], v[174:175], 0, s[8:9]
	s_add_i32 m0, s35, 0x2000
	s_nop 0
	global_load_lds_dwordx4 v[164:165], off
	s_barrier
	s_waitcnt lgkmcnt(0)
	s_setprio 1
	s_waitcnt lgkmcnt(0)
	v_mfma_i32_16x16x64_i8 v[132:135], v[206:209], v[160:163], v[132:135]
	v_mfma_i32_16x16x64_i8 v[128:131], v[214:217], v[160:163], v[128:131]
	v_mfma_i32_16x16x64_i8 v[116:119], v[206:209], v[182:185], v[116:119]
	v_mfma_i32_16x16x64_i8 v[112:115], v[214:217], v[182:185], v[112:115]
	v_mfma_i32_16x16x64_i8 v[100:103], v[206:209], v[190:193], v[100:103]
	v_mfma_i32_16x16x64_i8 v[96:99], v[214:217], v[190:193], v[96:99]
	v_mfma_i32_16x16x64_i8 v[84:87], v[206:209], v[198:201], v[84:87]
	v_mfma_i32_16x16x64_i8 v[80:83], v[214:217], v[198:201], v[80:83]
	v_mfma_i32_16x16x64_i8 v[132:135], v[210:213], v[178:181], v[132:135]
	v_mfma_i32_16x16x64_i8 v[128:131], v[218:221], v[178:181], v[128:131]
	v_mfma_i32_16x16x64_i8 v[116:119], v[210:213], v[186:189], v[116:119]
	v_mfma_i32_16x16x64_i8 v[112:115], v[218:221], v[186:189], v[112:115]
	v_mfma_i32_16x16x64_i8 v[100:103], v[210:213], v[194:197], v[100:103]
	v_mfma_i32_16x16x64_i8 v[96:99], v[218:221], v[194:197], v[96:99]
	v_mfma_i32_16x16x64_i8 v[84:87], v[210:213], v[202:205], v[84:87]
	v_mfma_i32_16x16x64_i8 v[80:83], v[218:221], v[202:205], v[80:83]
	s_setprio 0
	s_mov_b32 m0, s45
	v_lshl_add_u64 v[164:165], v[222:223], 0, s[8:9]
	s_barrier
	ds_read_b128 v[160:163], v170 offset:49152
	ds_read_b128 v[178:181], v170 offset:50176
	ds_read_b128 v[182:185], v170 offset:51200
	ds_read_b128 v[186:189], v170 offset:52224
	ds_read_b128 v[190:193], v170 offset:53248
	ds_read_b128 v[194:197], v170 offset:54272
	ds_read_b128 v[198:201], v170 offset:55296
	ds_read_b128 v[202:205], v170 offset:56320
	global_load_lds_dwordx4 v[164:165], off
	v_lshl_add_u64 v[164:165], v[224:225], 0, s[8:9]
	s_mov_b32 m0, s46
	s_nop 0
	global_load_lds_dwordx4 v[164:165], off
	s_barrier
; __device__ __forceinline__ float rs_of(const float* ssq, int r) { return __builtin_amdgcn_rsqf(ld_agent(ssq + r) * (1.f / 2048.f) + EPS); }
; #define PG8_STAGE(bufoff, gbase, voff) do { _Pragma("unroll") for (int _i = 0; _i < 2; ++_i) \
;         __builtin_amdgcn_global_load_lds((const unsigned*)((const char*)(gbase) + (voff)[_i]), (LAS unsigned*)(lds + (bufoff) + ldsw + _i * 8192), 16, 0, 0); } while (0)
; #define PG8_MMA(ai, bj, At, Bt) do { __builtin_amdgcn_s_setprio(1); _Pragma("unroll") for (int m = 0; m < 4; ++m) _Pragma("unroll") for (int n = 0; n < 2; ++n) _Pragma("unroll") for (int k = 0; k < 2; ++k) \
;         acc[ai][bj][m][n] = MmaOp<Epi::I8>::run(Bt[n][k], At[m][k], acc[ai][bj][m][n]); __builtin_amdgcn_s_setprio(0); } while (0)
; #define PG8_WAIT_V(n) asm volatile("s_waitcnt vmcnt(" #n ")" ::: "memory")
; #define PG8_WAIT_L(n) asm volatile("s_waitcnt lgkmcnt(" #n ")" ::: "memory")
; #define PG8_BAR __builtin_amdgcn_s_barrier()
; #define PG8_SCHED __builtin_amdgcn_sched_barrier(0)
;     __device__ __forceinline__ void operator()(const i32x4 (&acc)[2][2][4][2], const Unit& u, int wr, int wc, int fr, int fq) const {
;         const int row0 = u.pm * BM + wr * 64 + fr, col0 = u.pn * BM + wc * 32 + 8 * fq;
;         f32x4 bv[2][2];
; #pragma unroll
;         for (int bj = 0; bj < 2; ++bj)
; #pragma unroll
;             for (int n = 0; n < 2; ++n) bv[bj][n] = *(const f32x4*)(bias + col0 + bj * HALF + 4 * n);
; #pragma unroll
;         for (int ai = 0; ai < 2; ++ai)
; #pragma unroll
;             for (int m = 0; m < 4; ++m) {
;                 const int r = row0 + ai * HALF + m * 16; const float rs = rs_of(ssq, r);
;                 bf16_t* rowp = O + (size_t)r * ldc + col0;
; #pragma unroll
;                 for (int bj = 0; bj < 2; ++bj) {
;                     const f32x4 s0 = *(const f32x4*)(swp + col0 + bj * HALF), s1 = *(const f32x4*)(swp + col0 + bj * HALF + 4);
; template <class Epi, class Sched>
; __device__ __forceinline__ void gemm_phase(LAS unsigned char* lds, const Gemm g, const Sched& S, const Epi& E) {
;     ...
;             PG8_BAR; PG8_WAIT_L(0); PG8_MMA(1, 0, At, B0); PG8_BAR; PG8_SCHED;
;             PG8_STAGE(PG8_SB(1, 1), b3 + hstepB, voffB);
;             PG8_WAIT_V(6); PG8_BAR; PG8_MMA(1, 1, At, B1); PG8_BAR;
;         }
	s_waitcnt lgkmcnt(0)
	s_setprio 1
	s_waitcnt lgkmcnt(0)
	v_mfma_i32_16x16x64_i8 v[68:71], v[56:59], v[160:163], v[68:71]
	v_mfma_i32_16x16x64_i8 v[64:67], v[72:75], v[160:163], v[64:67]
	v_mfma_i32_16x16x64_i8 v[44:47], v[56:59], v[182:185], v[44:47]
	v_mfma_i32_16x16x64_i8 v[40:43], v[72:75], v[182:185], v[40:43]
	v_mfma_i32_16x16x64_i8 v[28:31], v[56:59], v[190:193], v[28:31]
	v_mfma_i32_16x16x64_i8 v[24:27], v[72:75], v[190:193], v[24:27]
	v_mfma_i32_16x16x64_i8 v[12:15], v[56:59], v[198:201], v[12:15]
	v_mfma_i32_16x16x64_i8 v[8:11], v[72:75], v[198:201], v[8:11]
	v_mfma_i32_16x16x64_i8 v[68:71], v[60:63], v[178:181], v[68:71]
	v_mfma_i32_16x16x64_i8 v[64:67], v[76:79], v[178:181], v[64:67]
	v_mfma_i32_16x16x64_i8 v[44:47], v[60:63], v[186:189], v[44:47]
	v_mfma_i32_16x16x64_i8 v[40:43], v[76:79], v[186:189], v[40:43]
	v_mfma_i32_16x16x64_i8 v[28:31], v[60:63], v[194:197], v[28:31]
	v_mfma_i32_16x16x64_i8 v[24:27], v[76:79], v[194:197], v[24:27]
	v_mfma_i32_16x16x64_i8 v[12:15], v[60:63], v[202:205], v[12:15]
	v_mfma_i32_16x16x64_i8 v[8:11], v[76:79], v[202:205], v[8:11]
	s_setprio 0
	s_barrier
	s_add_u32 s30, s30, 0x40080
	s_addc_u32 s31, s31, 0
	s_add_i32 s34, s34, s38
	v_lshl_add_u64 v[56:57], s[30:31], 0, v[148:149]
	s_mov_b32 m0, s34
	s_nop 0
	global_load_lds_dwordx4 v[56:57], off
	v_lshl_add_u64 v[56:57], s[30:31], 0, v[144:145]
	s_add_i32 m0, s34, 0x2000
	s_nop 0
	global_load_lds_dwordx4 v[56:57], off
	s_waitcnt vmcnt(6)
	s_barrier
	s_setprio 1
	v_mfma_i32_16x16x64_i8 v[52:55], v[206:209], v[160:163], v[52:55]
	v_mfma_i32_16x16x64_i8 v[48:51], v[214:217], v[160:163], v[48:51]
	v_mfma_i32_16x16x64_i8 v[36:39], v[206:209], v[182:185], v[36:39]
	v_mfma_i32_16x16x64_i8 v[32:35], v[214:217], v[182:185], v[32:35]
	v_mfma_i32_16x16x64_i8 v[20:23], v[206:209], v[190:193], v[20:23]
	v_mfma_i32_16x16x64_i8 v[16:19], v[214:217], v[190:193], v[16:19]
	v_mfma_i32_16x16x64_i8 v[4:7], v[206:209], v[198:201], v[4:7]
	v_mfma_i32_16x16x64_i8 v[0:3], v[214:217], v[198:201], v[0:3]
	v_mfma_i32_16x16x64_i8 v[52:55], v[210:213], v[178:181], v[52:55]
	v_mfma_i32_16x16x64_i8 v[48:51], v[218:221], v[178:181], v[48:51]
	v_mfma_i32_16x16x64_i8 v[36:39], v[210:213], v[186:189], v[36:39]
	v_mfma_i32_16x16x64_i8 v[32:35], v[218:221], v[186:189], v[32:35]
	v_mfma_i32_16x16x64_i8 v[20:23], v[210:213], v[194:197], v[20:23]
	v_mfma_i32_16x16x64_i8 v[16:19], v[218:221], v[194:197], v[16:19]
	v_mfma_i32_16x16x64_i8 v[4:7], v[210:213], v[202:205], v[4:7]
	v_mfma_i32_16x16x64_i8 v[0:3], v[218:221], v[202:205], v[0:3]
	s_setprio 0
	s_add_i32 s59, s59, 2
	s_add_u32 s28, s28, 0x100
	s_addc_u32 s29, s29, 0
	s_add_u32 s57, s57, 0x100
	s_addc_u32 s58, s58, 0
	s_cmp_gt_u32 s59, 13
	s_barrier
	s_cbranch_scc0 .LBB0_635
	v_lshl_or_b32 v174, s54, 8, v168
	v_ashrrev_i32_e32 v175, 31, v174
	v_readlane_b32 s76, v239, 2
	v_lshl_add_u32 v164, s26, 8, v166
	v_lshlrev_b64 v[160:161], 2, v[174:175]
	v_readlane_b32 s90, v239, 16
	v_readlane_b32 s91, v239, 17
	v_ashrrev_i32_e32 v165, 31, v164
	v_lshl_add_u64 v[162:163], v[164:165], 2, s[4:5]
	v_lshl_add_u64 v[60:61], s[90:91], 0, v[160:161]
	global_load_dwordx4 v[72:75], v[60:61], off offset:16
	global_load_dwordx4 v[76:79], v[60:61], off
	global_load_dwordx4 v[56:59], v[60:61], off offset:528
	s_nop 0
	global_load_dwordx4 v[60:63], v[60:61], off offset:512
	v_lshl_add_u64 v[160:161], s[6:7], 0, v[160:161]
	global_load_dword v173, v[162:163], off sc1
	global_load_dword v206, v[162:163], off offset:64 sc1
	global_load_dword v207, v[162:163], off offset:128 sc1
	global_load_dword v208, v[162:163], off offset:192 sc1
	global_load_dword v209, v[162:163], off offset:512 sc1
	global_load_dword v210, v[162:163], off offset:576 sc1
	global_load_dword v211, v[162:163], off offset:640 sc1
	global_load_dword v212, v[162:163], off offset:704 sc1
	global_load_dwordx4 v[178:181], v[160:161], off
	global_load_dwordx4 v[182:185], v[160:161], off offset:16
	global_load_dwordx4 v[190:193], v[160:161], off
	global_load_dwordx4 v[194:197], v[160:161], off offset:16
	global_load_dwordx4 v[198:201], v[160:161], off offset:512
	global_load_dwordx4 v[202:205], v[160:161], off offset:528
	v_cvt_f32_i32_e32 v141, v141
	v_cvt_f32_i32_e32 v140, v140
	v_cvt_f32_i32_e32 v143, v143
	v_cvt_f32_i32_e32 v142, v142
	v_cvt_f32_i32_e32 v187, v137
	v_cvt_f32_i32_e32 v186, v136
	v_lshlrev_b64 v[136:137], 13, v[164:165]
	v_cvt_f32_i32_e32 v189, v139
	v_cvt_f32_i32_e32 v188, v138
	v_lshlrev_b64 v[138:139], 1, v[174:175]
	v_readlane_b32 s28, v239, 46
	v_readlane_b32 s29, v239, 47
	v_cvt_f32_i32_e32 v133, v133
	v_cvt_f32_i32_e32 v132, v132
	v_lshl_add_u64 v[136:137], s[28:29], 0, v[136:137]
	v_lshl_add_u64 v[136:137], v[136:137], 0, v[138:139]
	v_cvt_f32_i32_e32 v135, v135
	v_cvt_f32_i32_e32 v134, v134
	v_cvt_f32_i32_e32 v129, v129
	v_cvt_f32_i32_e32 v128, v128
	v_cvt_f32_i32_e32 v131, v131
	v_cvt_f32_i32_e32 v130, v130
	v_cvt_f32_i32_e32 v127, v127
	v_cvt_f32_i32_e32 v126, v126
	v_cvt_f32_i32_e32 v125, v125
	v_cvt_f32_i32_e32 v124, v124
	v_cvt_f32_i32_e32 v121, v121
	v_cvt_f32_i32_e32 v120, v120
	v_cvt_f32_i32_e32 v123, v123
	v_cvt_f32_i32_e32 v122, v122
	v_cvt_f32_i32_e32 v117, v117
	v_cvt_f32_i32_e32 v116, v116
	v_cvt_f32_i32_e32 v119, v119
	v_cvt_f32_i32_e32 v118, v118
	v_cvt_f32_i32_e32 v113, v113
	v_cvt_f32_i32_e32 v112, v112
	v_cvt_f32_i32_e32 v115, v115
	v_cvt_f32_i32_e32 v114, v114
	v_cvt_f32_i32_e32 v111, v111
	v_cvt_f32_i32_e32 v110, v110
	v_cvt_f32_i32_e32 v109, v109
	v_cvt_f32_i32_e32 v108, v108
	v_cvt_f32_i32_e32 v105, v105
	v_cvt_f32_i32_e32 v104, v104
	v_cvt_f32_i32_e32 v107, v107
	v_cvt_f32_i32_e32 v106, v106
	v_cvt_f32_i32_e32 v101, v101
	v_cvt_f32_i32_e32 v100, v100
	v_cvt_f32_i32_e32 v103, v103
	v_cvt_f32_i32_e32 v102, v102
	v_cvt_f32_i32_e32 v97, v97
	v_cvt_f32_i32_e32 v96, v96
	v_cvt_f32_i32_e32 v99, v99
	v_cvt_f32_i32_e32 v98, v98
	v_cvt_f32_i32_e32 v95, v95
	v_cvt_f32_i32_e32 v94, v94
	v_cvt_f32_i32_e32 v93, v93
	v_cvt_f32_i32_e32 v92, v92
	v_cvt_f32_i32_e32 v89, v89
	v_cvt_f32_i32_e32 v88, v88
	v_cvt_f32_i32_e32 v91, v91
	v_cvt_f32_i32_e32 v90, v90
	v_cvt_f32_i32_e32 v85, v85
	v_cvt_f32_i32_e32 v84, v84
	v_cvt_f32_i32_e32 v87, v87
	v_cvt_f32_i32_e32 v86, v86
	v_cvt_f32_i32_e32 v81, v81
	v_cvt_f32_i32_e32 v83, v83
	v_cvt_f32_i32_e32 v82, v82
	v_cvt_f32_i32_e32 v80, v80
	v_cvt_f32_i32_e32 v71, v71
	v_cvt_f32_i32_e32 v70, v70
	v_cvt_f32_i32_e32 v69, v69
	v_cvt_f32_i32_e32 v68, v68
	v_cvt_f32_i32_e32 v65, v65
	v_cvt_f32_i32_e32 v64, v64
	v_cvt_f32_i32_e32 v67, v67
	v_cvt_f32_i32_e32 v66, v66
	s_waitcnt vmcnt(0)
; __device__ __forceinline__ unsigned cvt_pk_bf16(float lo, float hi) { unsigned r; asm volatile("v_cvt_pk_bf16_f32 %0, %1, %2" : "=v"(r) : "v"(lo), "v"(hi)); return r; }
; __device__ __forceinline__ float rs_of(const float* ssq, int r) { return __builtin_amdgcn_rsqf(ld_agent(ssq + r) * (1.f / 2048.f) + EPS); }
; __device__ __forceinline__ float sigm(float x) { return __builtin_amdgcn_rcpf(1.f + __builtin_amdgcn_exp2f(-LOG2E * x)); }
;     __device__ __forceinline__ void operator()(const i32x4 (&acc)[2][2][4][2], const Unit& u, int wr, int wc, int fr, int fq) const {
;     ...
; #pragma unroll
;         for (int ai = 0; ai < 2; ++ai)
; #pragma unroll
;             for (int m = 0; m < 4; ++m) {
;                 const int r = row0 + ai * HALF + m * 16; const float rs = rs_of(ssq, r);
;                 bf16_t* rowp = O + (size_t)r * ldc + col0;
; #pragma unroll
;                 for (int bj = 0; bj < 2; ++bj) {
;                     const f32x4 s0 = *(const f32x4*)(swp + col0 + bj * HALF), s1 = *(const f32x4*)(swp + col0 + bj * HALF + 4);
;                     f32x4 v0 = __builtin_convertvector(acc[ai][bj][m][0], f32x4) * s0 * rs + bv[bj][0], v1 = __builtin_convertvector(acc[ai][bj][m][1], f32x4) * s1 * rs + bv[bj][1];
; #pragma unroll
;                     for (int j = 0; j < 4; ++j) { v0[j] = sigm(v0[j]); v1[j] = sigm(v1[j]); }
;                     u32x4 w; w.x = cvt_pk_bf16(v0[0], v0[1]); w.y = cvt_pk_bf16(v0[2], v0[3]); w.z = cvt_pk_bf16(v1[0], v1[1]); w.w = cvt_pk_bf16(v1[2], v1[3]);
;                     *(u32x4*)(rowp + bj * HALF) = w;
	v_fmamk_f32 v165, v173, 0x3a000000, v172
	v_rsq_f32_e32 v174, v165
	v_pk_mul_f32 v[142:143], v[180:181], v[142:143]
	v_pk_mul_f32 v[140:141], v[178:179], v[140:141]
	v_pk_mul_f32 v[178:179], v[184:185], v[188:189]
	v_pk_mul_f32 v[180:181], v[182:183], v[186:187]
	v_pk_fma_f32 v[142:143], v[142:143], v[174:175], v[78:79] op_sel_hi:[1,0,1]
	v_pk_fma_f32 v[140:141], v[140:141], v[174:175], v[76:77] op_sel_hi:[1,0,1]
	v_pk_fma_f32 v[178:179], v[178:179], v[174:175], v[74:75] op_sel_hi:[1,0,1]
	v_pk_fma_f32 v[180:181], v[180:181], v[174:175], v[72:73] op_sel_hi:[1,0,1]
	v_mul_f32_e32 v140, 0xbfb8aa3b, v140
	v_mul_f32_e32 v141, 0xbfb8aa3b, v141
	v_mul_f32_e32 v142, 0xbfb8aa3b, v142
	v_mul_f32_e32 v143, 0xbfb8aa3b, v143
	v_mul_f32_e32 v165, 0xbfb8aa3b, v180
	v_mul_f32_e32 v173, 0xbfb8aa3b, v181
	v_mul_f32_e32 v175, 0xbfb8aa3b, v178
	v_mul_f32_e32 v178, 0xbfb8aa3b, v179
	v_exp_f32_e32 v140, v140
	v_exp_f32_e32 v141, v141
	v_exp_f32_e32 v142, v142
	v_exp_f32_e32 v143, v143
	v_exp_f32_e32 v165, v165
	v_exp_f32_e32 v173, v173
	v_exp_f32_e32 v175, v175
	v_exp_f32_e32 v178, v178
	v_add_f32_e32 v140, 1.0, v140
	v_add_f32_e32 v141, 1.0, v141
	v_add_f32_e32 v142, 1.0, v142
	v_add_f32_e32 v143, 1.0, v143
	v_add_f32_e32 v165, 1.0, v165
	v_add_f32_e32 v173, 1.0, v173
	v_add_f32_e32 v175, 1.0, v175
	v_add_f32_e32 v178, 1.0, v178
	v_rcp_f32_e32 v140, v140
	v_rcp_f32_e32 v141, v141
	v_rcp_f32_e32 v142, v142
	v_rcp_f32_e32 v143, v143
	v_rcp_f32_e32 v165, v165
	v_rcp_f32_e32 v173, v173
	v_rcp_f32_e32 v175, v175
	v_rcp_f32_e32 v178, v178
	v_cvt_pk_bf16_f32 v140, v140, v141
	v_cvt_pk_bf16_f32 v141, v142, v143
	v_cvt_pk_bf16_f32 v142, v165, v173
	v_cvt_pk_bf16_f32 v143, v175, v178
	global_store_dwordx4 v[136:137], v[140:143], off sc0 sc1
	s_nop 1
	v_mov_b64_e32 v[140:141], v[198:199]
	v_mov_b64_e32 v[142:143], v[200:201]
	s_nop 0
	v_mov_b64_e32 v[178:179], v[202:203]
	v_mov_b64_e32 v[180:181], v[204:205]
	v_or_b32_e32 v182, 16, v164
	v_ashrrev_i32_e32 v183, 31, v182
	v_lshl_add_u64 v[184:185], v[182:183], 2, s[4:5]
	v_cvt_f32_i32_e32 v53, v53
	v_cvt_f32_i32_e32 v52, v52
	v_cvt_f32_i32_e32 v55, v55
	v_cvt_f32_i32_e32 v54, v54
	v_cvt_f32_i32_e32 v49, v49
	v_cvt_f32_i32_e32 v48, v48
	v_cvt_f32_i32_e32 v51, v51
	v_cvt_f32_i32_e32 v50, v50
	v_cvt_f32_i32_e32 v47, v47
	v_cvt_f32_i32_e32 v46, v46
	v_cvt_f32_i32_e32 v45, v45
	v_cvt_f32_i32_e32 v44, v44
	v_cvt_f32_i32_e32 v41, v41
	v_cvt_f32_i32_e32 v40, v40
	v_cvt_f32_i32_e32 v43, v43
	v_cvt_f32_i32_e32 v42, v42
	v_cvt_f32_i32_e32 v37, v37
	v_cvt_f32_i32_e32 v36, v36
	v_cvt_f32_i32_e32 v39, v39
	v_cvt_f32_i32_e32 v38, v38
	v_cvt_f32_i32_e32 v33, v33
	v_cvt_f32_i32_e32 v32, v32
	v_cvt_f32_i32_e32 v35, v35
	v_cvt_f32_i32_e32 v34, v34
	v_cvt_f32_i32_e32 v31, v31
	v_cvt_f32_i32_e32 v30, v30
	v_cvt_f32_i32_e32 v29, v29
	v_cvt_f32_i32_e32 v28, v28
	v_cvt_f32_i32_e32 v25, v25
	v_cvt_f32_i32_e32 v24, v24
	v_cvt_f32_i32_e32 v27, v27
	v_cvt_f32_i32_e32 v26, v26
	v_cvt_f32_i32_e32 v21, v21
	v_cvt_f32_i32_e32 v20, v20
	v_cvt_f32_i32_e32 v23, v23
	v_cvt_f32_i32_e32 v22, v22
	v_cvt_f32_i32_e32 v17, v17
	v_cvt_f32_i32_e32 v16, v16
	v_cvt_f32_i32_e32 v19, v19
	v_cvt_f32_i32_e32 v18, v18
	v_cvt_f32_i32_e32 v15, v15
	v_cvt_f32_i32_e32 v14, v14
	v_cvt_f32_i32_e32 v13, v13
	v_cvt_f32_i32_e32 v12, v12
	v_cvt_f32_i32_e32 v9, v9
	v_cvt_f32_i32_e32 v8, v8
	v_cvt_f32_i32_e32 v11, v11
	v_cvt_f32_i32_e32 v10, v10
	v_cvt_f32_i32_e32 v5, v5
	v_cvt_f32_i32_e32 v4, v4
	v_cvt_f32_i32_e32 v7, v7
	v_cvt_f32_i32_e32 v6, v6
	v_cvt_f32_i32_e32 v1, v1
	v_cvt_f32_i32_e32 v0, v0
	v_cvt_f32_i32_e32 v3, v3
	v_cvt_f32_i32_e32 v2, v2
	s_mov_b32 s54, s18
	s_mov_b32 s26, s20
	s_mov_b64 s[30:31], s[24:25]
	v_readlane_b32 s61, v239, 50
	v_readlane_b32 s77, v239, 3
	v_readlane_b32 s78, v239, 4
	v_readlane_b32 s79, v239, 5
	v_readlane_b32 s80, v239, 6
	v_readlane_b32 s81, v239, 7
	v_readlane_b32 s82, v239, 8
	v_readlane_b32 s83, v239, 9
	v_readlane_b32 s84, v239, 10
	v_readlane_b32 s85, v239, 11
	v_readlane_b32 s86, v239, 12
	v_readlane_b32 s87, v239, 13
	v_readlane_b32 s88, v239, 14
	v_readlane_b32 s89, v239, 15
	v_pk_mul_f32 v[134:135], v[142:143], v[134:135]
	v_pk_mul_f32 v[132:133], v[140:141], v[132:133]
	v_pk_mul_f32 v[130:131], v[180:181], v[130:131]
	v_pk_mul_f32 v[128:129], v[178:179], v[128:129]
	v_pk_fma_f32 v[134:135], v[174:175], v[134:135], v[62:63] op_sel_hi:[0,1,1]
	v_pk_fma_f32 v[132:133], v[174:175], v[132:133], v[60:61] op_sel_hi:[0,1,1]
	v_pk_fma_f32 v[130:131], v[174:175], v[130:131], v[58:59] op_sel_hi:[0,1,1]
	v_pk_fma_f32 v[128:129], v[174:175], v[128:129], v[56:57] op_sel_hi:[0,1,1]
	v_mul_f32_e32 v128, 0xbfb8aa3b, v128
	v_mul_f32_e32 v133, 0xbfb8aa3b, v133
	v_mul_f32_e32 v129, 0xbfb8aa3b, v129
	v_mul_f32_e32 v134, 0xbfb8aa3b, v134
	v_mul_f32_e32 v131, 0xbfb8aa3b, v131
	v_mul_f32_e32 v132, 0xbfb8aa3b, v132
	v_mul_f32_e32 v130, 0xbfb8aa3b, v130
	v_mul_f32_e32 v135, 0xbfb8aa3b, v135
	v_exp_f32_e32 v128, v128
	v_exp_f32_e32 v133, v133
	v_exp_f32_e32 v129, v129
	v_exp_f32_e32 v134, v134
	v_exp_f32_e32 v131, v131
	v_exp_f32_e32 v132, v132
	v_exp_f32_e32 v130, v130
	v_exp_f32_e32 v135, v135
	v_add_f32_e32 v128, 1.0, v128
	v_add_f32_e32 v133, 1.0, v133
	v_add_f32_e32 v129, 1.0, v129
	v_add_f32_e32 v134, 1.0, v134
	v_add_f32_e32 v131, 1.0, v131
	v_add_f32_e32 v132, 1.0, v132
	v_add_f32_e32 v130, 1.0, v130
	v_add_f32_e32 v135, 1.0, v135
	v_rcp_f32_e32 v140, v128
	v_rcp_f32_e32 v128, v133
	v_rcp_f32_e32 v133, v129
	v_rcp_f32_e32 v129, v134
	v_rcp_f32_e32 v131, v131
	v_rcp_f32_e32 v132, v132
	v_rcp_f32_e32 v134, v135
	v_rcp_f32_e32 v135, v130
	v_cvt_pk_bf16_f32 v128, v132, v128
	v_cvt_pk_bf16_f32 v129, v129, v134
	v_cvt_pk_bf16_f32 v130, v140, v133
; __device__ __forceinline__ unsigned cvt_pk_bf16(float lo, float hi) { unsigned r; asm volatile("v_cvt_pk_bf16_f32 %0, %1, %2" : "=v"(r) : "v"(lo), "v"(hi)); return r; }
; __device__ __forceinline__ float rs_of(const float* ssq, int r) { return __builtin_amdgcn_rsqf(ld_agent(ssq + r) * (1.f / 2048.f) + EPS); }
; __device__ __forceinline__ float sigm(float x) { return __builtin_amdgcn_rcpf(1.f + __builtin_amdgcn_exp2f(-LOG2E * x)); }
;     __device__ __forceinline__ void operator()(const i32x4 (&acc)[2][2][4][2], const Unit& u, int wr, int wc, int fr, int fq) const {
;     ...
; #pragma unroll
;         for (int ai = 0; ai < 2; ++ai)
; #pragma unroll
;             for (int m = 0; m < 4; ++m) {
;                 const int r = row0 + ai * HALF + m * 16; const float rs = rs_of(ssq, r);
;                 bf16_t* rowp = O + (size_t)r * ldc + col0;
; #pragma unroll
;                 for (int bj = 0; bj < 2; ++bj) {
;                     const f32x4 s0 = *(const f32x4*)(swp + col0 + bj * HALF), s1 = *(const f32x4*)(swp + col0 + bj * HALF + 4);
;                     f32x4 v0 = __builtin_convertvector(acc[ai][bj][m][0], f32x4) * s0 * rs + bv[bj][0], v1 = __builtin_convertvector(acc[ai][bj][m][1], f32x4) * s1 * rs + bv[bj][1];
; #pragma unroll
;                     for (int j = 0; j < 4; ++j) { v0[j] = sigm(v0[j]); v1[j] = sigm(v1[j]); }
;                     u32x4 w; w.x = cvt_pk_bf16(v0[0], v0[1]); w.y = cvt_pk_bf16(v0[2], v0[3]); w.z = cvt_pk_bf16(v1[0], v1[1]); w.w = cvt_pk_bf16(v1[2], v1[3]);
;                     *(u32x4*)(rowp + bj * HALF) = w;
;                 }
;             }
	v_cvt_pk_bf16_f32 v131, v135, v131
	global_store_dwordx4 v[136:137], v[128:131], off offset:256 sc0 sc1
	s_nop 1
	v_mov_b32_e32 v142, v206
	s_nop 0
	v_mov_b64_e32 v[128:129], v[190:191]
	v_mov_b64_e32 v[130:131], v[192:193]
	v_mov_b64_e32 v[132:133], v[194:195]
	v_mov_b64_e32 v[134:135], v[196:197]
	v_lshlrev_b64 v[140:141], 13, v[182:183]
	v_lshl_add_u64 v[140:141], s[28:29], 0, v[140:141]
	v_lshl_add_u64 v[140:141], v[140:141], 0, v[138:139]
	v_fmamk_f32 v142, v142, 0x3a000000, v172
	v_pk_mul_f32 v[126:127], v[130:131], v[126:127]
	v_rsq_f32_e32 v130, v142
	v_pk_mul_f32 v[124:125], v[128:129], v[124:125]
	v_pk_mul_f32 v[122:123], v[134:135], v[122:123]
	v_pk_mul_f32 v[120:121], v[132:133], v[120:121]
	v_pk_fma_f32 v[126:127], v[126:127], v[130:131], v[78:79] op_sel_hi:[1,0,1]
	v_pk_fma_f32 v[124:125], v[124:125], v[130:131], v[76:77] op_sel_hi:[1,0,1]
	v_pk_fma_f32 v[122:123], v[122:123], v[130:131], v[74:75] op_sel_hi:[1,0,1]
	v_pk_fma_f32 v[120:121], v[120:121], v[130:131], v[72:73] op_sel_hi:[1,0,1]
	v_mul_f32_e32 v125, 0xbfb8aa3b, v125
	v_mul_f32_e32 v120, 0xbfb8aa3b, v120
	v_mul_f32_e32 v121, 0xbfb8aa3b, v121
	v_mul_f32_e32 v126, 0xbfb8aa3b, v126
	v_mul_f32_e32 v123, 0xbfb8aa3b, v123
	v_mul_f32_e32 v124, 0xbfb8aa3b, v124
	v_mul_f32_e32 v122, 0xbfb8aa3b, v122
	v_mul_f32_e32 v127, 0xbfb8aa3b, v127
	v_exp_f32_e32 v120, v120
	v_exp_f32_e32 v125, v125
	v_exp_f32_e32 v121, v121
	v_exp_f32_e32 v126, v126
	v_exp_f32_e32 v123, v123
	v_exp_f32_e32 v124, v124
	v_exp_f32_e32 v122, v122
	v_exp_f32_e32 v127, v127
	v_add_f32_e32 v120, 1.0, v120
	v_add_f32_e32 v125, 1.0, v125
	v_add_f32_e32 v121, 1.0, v121
	v_add_f32_e32 v126, 1.0, v126
	v_add_f32_e32 v123, 1.0, v123
	v_add_f32_e32 v124, 1.0, v124
	v_add_f32_e32 v122, 1.0, v122
	v_add_f32_e32 v127, 1.0, v127
	v_rcp_f32_e32 v128, v120
	v_rcp_f32_e32 v120, v125
	v_rcp_f32_e32 v125, v121
	v_rcp_f32_e32 v121, v126
	v_rcp_f32_e32 v123, v123
	v_rcp_f32_e32 v124, v124
	v_rcp_f32_e32 v126, v127
	v_rcp_f32_e32 v127, v122
	v_cvt_pk_bf16_f32 v120, v124, v120
	v_cvt_pk_bf16_f32 v121, v121, v126
	v_cvt_pk_bf16_f32 v122, v128, v125
	v_cvt_pk_bf16_f32 v123, v127, v123
	global_store_dwordx4 v[140:141], v[120:123], off sc0 sc1
	s_nop 1
	v_mov_b64_e32 v[120:121], v[198:199]
	v_mov_b64_e32 v[122:123], v[200:201]
	s_nop 0
	v_mov_b64_e32 v[124:125], v[202:203]
	v_mov_b64_e32 v[126:127], v[204:205]
	v_or_b32_e32 v128, 32, v164
	v_ashrrev_i32_e32 v129, 31, v128
	v_lshl_add_u64 v[132:133], v[128:129], 2, s[4:5]
	v_pk_mul_f32 v[118:119], v[122:123], v[118:119]
	v_pk_mul_f32 v[116:117], v[120:121], v[116:117]
	v_pk_mul_f32 v[114:115], v[126:127], v[114:115]
	v_pk_mul_f32 v[112:113], v[124:125], v[112:113]
	v_pk_fma_f32 v[118:119], v[130:131], v[118:119], v[62:63] op_sel_hi:[0,1,1]
	v_pk_fma_f32 v[116:117], v[130:131], v[116:117], v[60:61] op_sel_hi:[0,1,1]
	v_pk_fma_f32 v[114:115], v[130:131], v[114:115], v[58:59] op_sel_hi:[0,1,1]
	v_pk_fma_f32 v[112:113], v[130:131], v[112:113], v[56:57] op_sel_hi:[0,1,1]
	v_mul_f32_e32 v112, 0xbfb8aa3b, v112
	v_mul_f32_e32 v117, 0xbfb8aa3b, v117
	v_mul_f32_e32 v113, 0xbfb8aa3b, v113
	v_mul_f32_e32 v118, 0xbfb8aa3b, v118
	v_mul_f32_e32 v115, 0xbfb8aa3b, v115
	v_mul_f32_e32 v116, 0xbfb8aa3b, v116
	v_mul_f32_e32 v114, 0xbfb8aa3b, v114
	v_mul_f32_e32 v119, 0xbfb8aa3b, v119
	v_exp_f32_e32 v112, v112
	v_exp_f32_e32 v117, v117
	v_exp_f32_e32 v113, v113
	v_exp_f32_e32 v118, v118
	v_exp_f32_e32 v115, v115
	v_exp_f32_e32 v116, v116
	v_exp_f32_e32 v114, v114
	v_exp_f32_e32 v119, v119
	v_add_f32_e32 v112, 1.0, v112
	v_add_f32_e32 v117, 1.0, v117
	v_add_f32_e32 v113, 1.0, v113
	v_add_f32_e32 v118, 1.0, v118
	v_add_f32_e32 v115, 1.0, v115
	v_add_f32_e32 v116, 1.0, v116
	v_add_f32_e32 v114, 1.0, v114
	v_add_f32_e32 v119, 1.0, v119
	v_rcp_f32_e32 v120, v112
	v_rcp_f32_e32 v112, v117
	v_rcp_f32_e32 v117, v113
	v_rcp_f32_e32 v113, v118
	v_rcp_f32_e32 v115, v115
	v_rcp_f32_e32 v116, v116
	v_rcp_f32_e32 v118, v119
	v_rcp_f32_e32 v119, v114
	v_cvt_pk_bf16_f32 v112, v116, v112
	v_cvt_pk_bf16_f32 v113, v113, v118
	v_cvt_pk_bf16_f32 v114, v120, v117
	v_cvt_pk_bf16_f32 v115, v119, v115
	global_store_dwordx4 v[140:141], v[112:115], off offset:256 sc0 sc1
	s_nop 1
	v_mov_b32_e32 v122, v207
	s_nop 0
	v_mov_b64_e32 v[112:113], v[190:191]
	v_mov_b64_e32 v[114:115], v[192:193]
	v_mov_b64_e32 v[116:117], v[194:195]
	v_mov_b64_e32 v[118:119], v[196:197]
	v_lshlrev_b64 v[120:121], 13, v[128:129]
	v_lshl_add_u64 v[120:121], s[28:29], 0, v[120:121]
	v_lshl_add_u64 v[120:121], v[120:121], 0, v[138:139]
	v_fmamk_f32 v122, v122, 0x3a000000, v172
	v_pk_mul_f32 v[110:111], v[114:115], v[110:111]
	v_rsq_f32_e32 v114, v122
	v_pk_mul_f32 v[108:109], v[112:113], v[108:109]
	v_pk_mul_f32 v[106:107], v[118:119], v[106:107]
	v_pk_mul_f32 v[104:105], v[116:117], v[104:105]
	v_pk_fma_f32 v[110:111], v[110:111], v[114:115], v[78:79] op_sel_hi:[1,0,1]
	v_pk_fma_f32 v[108:109], v[108:109], v[114:115], v[76:77] op_sel_hi:[1,0,1]
	v_pk_fma_f32 v[106:107], v[106:107], v[114:115], v[74:75] op_sel_hi:[1,0,1]
	v_pk_fma_f32 v[104:105], v[104:105], v[114:115], v[72:73] op_sel_hi:[1,0,1]
	v_mul_f32_e32 v109, 0xbfb8aa3b, v109
	v_mul_f32_e32 v104, 0xbfb8aa3b, v104
	v_mul_f32_e32 v105, 0xbfb8aa3b, v105
	v_mul_f32_e32 v110, 0xbfb8aa3b, v110
	v_mul_f32_e32 v107, 0xbfb8aa3b, v107
	v_mul_f32_e32 v108, 0xbfb8aa3b, v108
	v_mul_f32_e32 v106, 0xbfb8aa3b, v106
	v_mul_f32_e32 v111, 0xbfb8aa3b, v111
	v_exp_f32_e32 v104, v104
	v_exp_f32_e32 v109, v109
	v_exp_f32_e32 v105, v105
	v_exp_f32_e32 v110, v110
	v_exp_f32_e32 v107, v107
	v_exp_f32_e32 v108, v108
	v_exp_f32_e32 v106, v106
	v_exp_f32_e32 v111, v111
	v_add_f32_e32 v104, 1.0, v104
	v_add_f32_e32 v109, 1.0, v109
; __device__ __forceinline__ unsigned cvt_pk_bf16(float lo, float hi) { unsigned r; asm volatile("v_cvt_pk_bf16_f32 %0, %1, %2" : "=v"(r) : "v"(lo), "v"(hi)); return r; }
; __device__ __forceinline__ float rs_of(const float* ssq, int r) { return __builtin_amdgcn_rsqf(ld_agent(ssq + r) * (1.f / 2048.f) + EPS); }
; __device__ __forceinline__ float sigm(float x) { return __builtin_amdgcn_rcpf(1.f + __builtin_amdgcn_exp2f(-LOG2E * x)); }
;     __device__ __forceinline__ void operator()(const i32x4 (&acc)[2][2][4][2], const Unit& u, int wr, int wc, int fr, int fq) const {
;     ...
; #pragma unroll
;         for (int ai = 0; ai < 2; ++ai)
; #pragma unroll
;             for (int m = 0; m < 4; ++m) {
;                 const int r = row0 + ai * HALF + m * 16; const float rs = rs_of(ssq, r);
;                 bf16_t* rowp = O + (size_t)r * ldc + col0;
; #pragma unroll
;                 for (int bj = 0; bj < 2; ++bj) {
;                     const f32x4 s0 = *(const f32x4*)(swp + col0 + bj * HALF), s1 = *(const f32x4*)(swp + col0 + bj * HALF + 4);
;                     f32x4 v0 = __builtin_convertvector(acc[ai][bj][m][0], f32x4) * s0 * rs + bv[bj][0], v1 = __builtin_convertvector(acc[ai][bj][m][1], f32x4) * s1 * rs + bv[bj][1];
; #pragma unroll
;                     for (int j = 0; j < 4; ++j) { v0[j] = sigm(v0[j]); v1[j] = sigm(v1[j]); }
;                     u32x4 w; w.x = cvt_pk_bf16(v0[0], v0[1]); w.y = cvt_pk_bf16(v0[2], v0[3]); w.z = cvt_pk_bf16(v1[0], v1[1]); w.w = cvt_pk_bf16(v1[2], v1[3]);
;                     *(u32x4*)(rowp + bj * HALF) = w;
;                 }
;             }
	v_add_f32_e32 v105, 1.0, v105
	v_add_f32_e32 v110, 1.0, v110
	v_add_f32_e32 v107, 1.0, v107
	v_add_f32_e32 v108, 1.0, v108
	v_add_f32_e32 v106, 1.0, v106
	v_add_f32_e32 v111, 1.0, v111
	v_rcp_f32_e32 v112, v104
	v_rcp_f32_e32 v104, v109
	v_rcp_f32_e32 v109, v105
	v_rcp_f32_e32 v105, v110
	v_rcp_f32_e32 v107, v107
	v_rcp_f32_e32 v108, v108
	v_rcp_f32_e32 v110, v111
	v_rcp_f32_e32 v111, v106
	v_cvt_pk_bf16_f32 v104, v108, v104
	v_cvt_pk_bf16_f32 v105, v105, v110
	v_cvt_pk_bf16_f32 v106, v112, v109
	v_cvt_pk_bf16_f32 v107, v111, v107
	global_store_dwordx4 v[120:121], v[104:107], off sc0 sc1
	s_nop 1
	v_mov_b64_e32 v[104:105], v[198:199]
	v_mov_b64_e32 v[106:107], v[200:201]
	s_nop 0
	v_mov_b64_e32 v[108:109], v[202:203]
	v_mov_b64_e32 v[110:111], v[204:205]
	v_or_b32_e32 v112, 48, v164
	v_ashrrev_i32_e32 v113, 31, v112
	v_lshl_add_u64 v[116:117], v[112:113], 2, s[4:5]
	v_pk_mul_f32 v[102:103], v[106:107], v[102:103]
	v_pk_mul_f32 v[100:101], v[104:105], v[100:101]
	v_pk_mul_f32 v[98:99], v[110:111], v[98:99]
	v_pk_mul_f32 v[96:97], v[108:109], v[96:97]
	v_pk_fma_f32 v[102:103], v[114:115], v[102:103], v[62:63] op_sel_hi:[0,1,1]
	v_pk_fma_f32 v[100:101], v[114:115], v[100:101], v[60:61] op_sel_hi:[0,1,1]
	v_pk_fma_f32 v[98:99], v[114:115], v[98:99], v[58:59] op_sel_hi:[0,1,1]
	v_pk_fma_f32 v[96:97], v[114:115], v[96:97], v[56:57] op_sel_hi:[0,1,1]
	v_mul_f32_e32 v96, 0xbfb8aa3b, v96
	v_mul_f32_e32 v101, 0xbfb8aa3b, v101
	v_mul_f32_e32 v97, 0xbfb8aa3b, v97
	v_mul_f32_e32 v102, 0xbfb8aa3b, v102
	v_mul_f32_e32 v99, 0xbfb8aa3b, v99
	v_mul_f32_e32 v100, 0xbfb8aa3b, v100
	v_mul_f32_e32 v98, 0xbfb8aa3b, v98
	v_mul_f32_e32 v103, 0xbfb8aa3b, v103
	v_exp_f32_e32 v96, v96
	v_exp_f32_e32 v101, v101
	v_exp_f32_e32 v97, v97
	v_exp_f32_e32 v102, v102
	v_exp_f32_e32 v99, v99
	v_exp_f32_e32 v100, v100
	v_exp_f32_e32 v98, v98
	v_exp_f32_e32 v103, v103
	v_add_f32_e32 v96, 1.0, v96
	v_add_f32_e32 v101, 1.0, v101
	v_add_f32_e32 v97, 1.0, v97
	v_add_f32_e32 v102, 1.0, v102
	v_add_f32_e32 v99, 1.0, v99
	v_add_f32_e32 v100, 1.0, v100
	v_add_f32_e32 v98, 1.0, v98
	v_add_f32_e32 v103, 1.0, v103
	v_rcp_f32_e32 v104, v96
	v_rcp_f32_e32 v96, v101
	v_rcp_f32_e32 v101, v97
	v_rcp_f32_e32 v97, v102
	v_rcp_f32_e32 v99, v99
	v_rcp_f32_e32 v100, v100
	v_rcp_f32_e32 v102, v103
	v_rcp_f32_e32 v103, v98
	v_cvt_pk_bf16_f32 v96, v100, v96
	v_cvt_pk_bf16_f32 v97, v97, v102
	v_cvt_pk_bf16_f32 v98, v104, v101
	v_cvt_pk_bf16_f32 v99, v103, v99
	global_store_dwordx4 v[120:121], v[96:99], off offset:256 sc0 sc1
	s_nop 1
	v_mov_b32_e32 v106, v208
	s_nop 0
	v_mov_b64_e32 v[96:97], v[190:191]
	v_mov_b64_e32 v[98:99], v[192:193]
	v_mov_b64_e32 v[100:101], v[194:195]
	v_mov_b64_e32 v[102:103], v[196:197]
	v_lshlrev_b64 v[104:105], 13, v[112:113]
	v_lshl_add_u64 v[104:105], s[28:29], 0, v[104:105]
	v_lshl_add_u64 v[104:105], v[104:105], 0, v[138:139]
	s_mov_b64 s[28:29], s[22:23]
	v_fmamk_f32 v106, v106, 0x3a000000, v172
	v_pk_mul_f32 v[94:95], v[98:99], v[94:95]
	v_rsq_f32_e32 v98, v106
	v_pk_mul_f32 v[92:93], v[96:97], v[92:93]
	v_pk_mul_f32 v[90:91], v[102:103], v[90:91]
	v_pk_mul_f32 v[88:89], v[100:101], v[88:89]
	v_pk_fma_f32 v[94:95], v[94:95], v[98:99], v[78:79] op_sel_hi:[1,0,1]
	v_pk_fma_f32 v[92:93], v[92:93], v[98:99], v[76:77] op_sel_hi:[1,0,1]
	v_pk_fma_f32 v[90:91], v[90:91], v[98:99], v[74:75] op_sel_hi:[1,0,1]
	v_pk_fma_f32 v[88:89], v[88:89], v[98:99], v[72:73] op_sel_hi:[1,0,1]
	v_mul_f32_e32 v93, 0xbfb8aa3b, v93
	v_mul_f32_e32 v88, 0xbfb8aa3b, v88
	v_mul_f32_e32 v89, 0xbfb8aa3b, v89
	v_mul_f32_e32 v94, 0xbfb8aa3b, v94
	v_mul_f32_e32 v91, 0xbfb8aa3b, v91
	v_mul_f32_e32 v92, 0xbfb8aa3b, v92
	v_mul_f32_e32 v90, 0xbfb8aa3b, v90
	v_mul_f32_e32 v95, 0xbfb8aa3b, v95
	v_exp_f32_e32 v88, v88
	v_exp_f32_e32 v93, v93
	v_exp_f32_e32 v89, v89
	v_exp_f32_e32 v94, v94
	v_exp_f32_e32 v91, v91
	v_exp_f32_e32 v92, v92
	v_exp_f32_e32 v90, v90
	v_exp_f32_e32 v95, v95
	v_add_f32_e32 v88, 1.0, v88
	v_add_f32_e32 v93, 1.0, v93
	v_add_f32_e32 v89, 1.0, v89
	v_add_f32_e32 v94, 1.0, v94
	v_add_f32_e32 v91, 1.0, v91
	v_add_f32_e32 v92, 1.0, v92
	v_add_f32_e32 v90, 1.0, v90
	v_add_f32_e32 v95, 1.0, v95
	v_rcp_f32_e32 v96, v88
	v_rcp_f32_e32 v88, v93
	v_rcp_f32_e32 v93, v89
	v_rcp_f32_e32 v89, v94
	v_rcp_f32_e32 v91, v91
	v_rcp_f32_e32 v92, v92
	v_rcp_f32_e32 v94, v95
	v_rcp_f32_e32 v95, v90
	v_cvt_pk_bf16_f32 v88, v92, v88
	v_cvt_pk_bf16_f32 v89, v89, v94
	v_cvt_pk_bf16_f32 v90, v96, v93
	v_cvt_pk_bf16_f32 v91, v95, v91
	global_store_dwordx4 v[104:105], v[88:91], off sc0 sc1
	s_nop 1
	v_mov_b64_e32 v[88:89], v[198:199]
	v_mov_b64_e32 v[90:91], v[200:201]
	s_nop 0
	v_mov_b64_e32 v[92:93], v[202:203]
	v_mov_b64_e32 v[94:95], v[204:205]
	v_pk_mul_f32 v[86:87], v[90:91], v[86:87]
	v_pk_mul_f32 v[84:85], v[88:89], v[84:85]
	v_pk_mul_f32 v[82:83], v[94:95], v[82:83]
	v_pk_mul_f32 v[80:81], v[92:93], v[80:81]
	v_pk_fma_f32 v[86:87], v[98:99], v[86:87], v[62:63] op_sel_hi:[0,1,1]
	v_pk_fma_f32 v[84:85], v[98:99], v[84:85], v[60:61] op_sel_hi:[0,1,1]
	v_pk_fma_f32 v[82:83], v[98:99], v[82:83], v[58:59] op_sel_hi:[0,1,1]
	v_pk_fma_f32 v[80:81], v[98:99], v[80:81], v[56:57] op_sel_hi:[0,1,1]
	v_mul_f32_e32 v80, 0xbfb8aa3b, v80
	v_mul_f32_e32 v85, 0xbfb8aa3b, v85
	v_mul_f32_e32 v81, 0xbfb8aa3b, v81
	v_mul_f32_e32 v86, 0xbfb8aa3b, v86
	v_mul_f32_e32 v83, 0xbfb8aa3b, v83
	v_mul_f32_e32 v84, 0xbfb8aa3b, v84
	v_mul_f32_e32 v82, 0xbfb8aa3b, v82
	v_mul_f32_e32 v87, 0xbfb8aa3b, v87
	v_exp_f32_e32 v80, v80
	v_exp_f32_e32 v85, v85
	v_exp_f32_e32 v81, v81
	v_exp_f32_e32 v86, v86
	v_exp_f32_e32 v83, v83
	v_exp_f32_e32 v84, v84
	v_exp_f32_e32 v82, v82
	v_exp_f32_e32 v87, v87
	v_add_f32_e32 v80, 1.0, v80
	v_add_f32_e32 v85, 1.0, v85
; __device__ __forceinline__ unsigned cvt_pk_bf16(float lo, float hi) { unsigned r; asm volatile("v_cvt_pk_bf16_f32 %0, %1, %2" : "=v"(r) : "v"(lo), "v"(hi)); return r; }
; __device__ __forceinline__ float rs_of(const float* ssq, int r) { return __builtin_amdgcn_rsqf(ld_agent(ssq + r) * (1.f / 2048.f) + EPS); }
; __device__ __forceinline__ float sigm(float x) { return __builtin_amdgcn_rcpf(1.f + __builtin_amdgcn_exp2f(-LOG2E * x)); }
;     __device__ __forceinline__ void operator()(const i32x4 (&acc)[2][2][4][2], const Unit& u, int wr, int wc, int fr, int fq) const {
;     ...
; #pragma unroll
;         for (int ai = 0; ai < 2; ++ai)
; #pragma unroll
;             for (int m = 0; m < 4; ++m) {
;                 const int r = row0 + ai * HALF + m * 16; const float rs = rs_of(ssq, r);
;                 bf16_t* rowp = O + (size_t)r * ldc + col0;
; #pragma unroll
;                 for (int bj = 0; bj < 2; ++bj) {
;                     const f32x4 s0 = *(const f32x4*)(swp + col0 + bj * HALF), s1 = *(const f32x4*)(swp + col0 + bj * HALF + 4);
;                     f32x4 v0 = __builtin_convertvector(acc[ai][bj][m][0], f32x4) * s0 * rs + bv[bj][0], v1 = __builtin_convertvector(acc[ai][bj][m][1], f32x4) * s1 * rs + bv[bj][1];
; #pragma unroll
;                     for (int j = 0; j < 4; ++j) { v0[j] = sigm(v0[j]); v1[j] = sigm(v1[j]); }
;                     u32x4 w; w.x = cvt_pk_bf16(v0[0], v0[1]); w.y = cvt_pk_bf16(v0[2], v0[3]); w.z = cvt_pk_bf16(v1[0], v1[1]); w.w = cvt_pk_bf16(v1[2], v1[3]);
;                     *(u32x4*)(rowp + bj * HALF) = w;
;                 }
;             }
	v_add_f32_e32 v81, 1.0, v81
	v_add_f32_e32 v86, 1.0, v86
	v_add_f32_e32 v83, 1.0, v83
	v_add_f32_e32 v84, 1.0, v84
	v_add_f32_e32 v82, 1.0, v82
	v_add_f32_e32 v87, 1.0, v87
	v_rcp_f32_e32 v88, v80
	v_rcp_f32_e32 v80, v85
	v_rcp_f32_e32 v85, v81
	v_rcp_f32_e32 v81, v86
	v_rcp_f32_e32 v83, v83
	v_rcp_f32_e32 v84, v84
	v_rcp_f32_e32 v86, v87
	v_rcp_f32_e32 v87, v82
	v_cvt_pk_bf16_f32 v80, v84, v80
	v_cvt_pk_bf16_f32 v81, v81, v86
	v_cvt_pk_bf16_f32 v82, v88, v85
	v_cvt_pk_bf16_f32 v83, v87, v83
	global_store_dwordx4 v[104:105], v[80:83], off offset:256 sc0 sc1
	s_nop 1
	v_mov_b32_e32 v90, v209
	s_nop 0
	v_mov_b64_e32 v[80:81], v[190:191]
	v_mov_b64_e32 v[82:83], v[192:193]
	v_mov_b64_e32 v[84:85], v[194:195]
	v_mov_b64_e32 v[86:87], v[196:197]
	v_add_co_u32_e32 v88, vcc, s50, v136
	v_fmamk_f32 v90, v90, 0x3a000000, v172
	v_pk_mul_f32 v[70:71], v[82:83], v[70:71]
	v_rsq_f32_e32 v82, v90
	v_pk_mul_f32 v[68:69], v[80:81], v[68:69]
	v_pk_mul_f32 v[66:67], v[86:87], v[66:67]
	v_pk_mul_f32 v[64:65], v[84:85], v[64:65]
	v_pk_fma_f32 v[70:71], v[70:71], v[82:83], v[78:79] op_sel_hi:[1,0,1]
	v_pk_fma_f32 v[68:69], v[68:69], v[82:83], v[76:77] op_sel_hi:[1,0,1]
	v_pk_fma_f32 v[66:67], v[66:67], v[82:83], v[74:75] op_sel_hi:[1,0,1]
	v_pk_fma_f32 v[64:65], v[64:65], v[82:83], v[72:73] op_sel_hi:[1,0,1]
	v_mul_f32_e32 v69, 0xbfb8aa3b, v69
	v_mul_f32_e32 v64, 0xbfb8aa3b, v64
	v_mul_f32_e32 v65, 0xbfb8aa3b, v65
	v_mul_f32_e32 v70, 0xbfb8aa3b, v70
	v_mul_f32_e32 v67, 0xbfb8aa3b, v67
	v_mul_f32_e32 v68, 0xbfb8aa3b, v68
	v_mul_f32_e32 v66, 0xbfb8aa3b, v66
	v_mul_f32_e32 v71, 0xbfb8aa3b, v71
	v_exp_f32_e32 v64, v64
	v_exp_f32_e32 v69, v69
	v_exp_f32_e32 v65, v65
	v_exp_f32_e32 v70, v70
	v_exp_f32_e32 v67, v67
	v_exp_f32_e32 v68, v68
	v_exp_f32_e32 v66, v66
	v_exp_f32_e32 v71, v71
	v_add_f32_e32 v64, 1.0, v64
	v_add_f32_e32 v69, 1.0, v69
	v_add_f32_e32 v65, 1.0, v65
	v_add_f32_e32 v70, 1.0, v70
	v_add_f32_e32 v67, 1.0, v67
	v_addc_co_u32_e32 v89, vcc, 0, v137, vcc
	v_add_f32_e32 v68, 1.0, v68
	v_add_f32_e32 v66, 1.0, v66
	v_add_f32_e32 v71, 1.0, v71
	v_rcp_f32_e32 v80, v64
	v_rcp_f32_e32 v64, v69
	v_rcp_f32_e32 v69, v65
	v_rcp_f32_e32 v65, v70
	v_rcp_f32_e32 v67, v67
	v_rcp_f32_e32 v68, v68
	v_rcp_f32_e32 v70, v71
	v_rcp_f32_e32 v71, v66
	v_cvt_pk_bf16_f32 v64, v68, v64
	v_cvt_pk_bf16_f32 v65, v65, v70
	v_cvt_pk_bf16_f32 v66, v80, v69
	v_cvt_pk_bf16_f32 v67, v71, v67
	global_store_dwordx4 v[88:89], v[64:67], off sc0 sc1
	s_nop 1
	v_mov_b64_e32 v[64:65], v[198:199]
	v_mov_b64_e32 v[66:67], v[200:201]
	s_nop 0
	v_mov_b64_e32 v[68:69], v[202:203]
	v_mov_b64_e32 v[70:71], v[204:205]
	v_lshl_add_u64 v[80:81], v[136:137], 0, s[10:11]
	v_pk_mul_f32 v[54:55], v[66:67], v[54:55]
	v_pk_mul_f32 v[52:53], v[64:65], v[52:53]
	v_pk_mul_f32 v[50:51], v[70:71], v[50:51]
	v_pk_mul_f32 v[48:49], v[68:69], v[48:49]
	v_pk_fma_f32 v[54:55], v[82:83], v[54:55], v[62:63] op_sel_hi:[0,1,1]
	v_pk_fma_f32 v[52:53], v[82:83], v[52:53], v[60:61] op_sel_hi:[0,1,1]
	v_pk_fma_f32 v[50:51], v[82:83], v[50:51], v[58:59] op_sel_hi:[0,1,1]
	v_pk_fma_f32 v[48:49], v[82:83], v[48:49], v[56:57] op_sel_hi:[0,1,1]
	v_mul_f32_e32 v48, 0xbfb8aa3b, v48
	v_mul_f32_e32 v53, 0xbfb8aa3b, v53
	v_mul_f32_e32 v49, 0xbfb8aa3b, v49
	v_mul_f32_e32 v54, 0xbfb8aa3b, v54
	v_mul_f32_e32 v51, 0xbfb8aa3b, v51
	v_mul_f32_e32 v52, 0xbfb8aa3b, v52
	v_mul_f32_e32 v50, 0xbfb8aa3b, v50
	v_mul_f32_e32 v55, 0xbfb8aa3b, v55
	v_exp_f32_e32 v48, v48
	v_exp_f32_e32 v53, v53
	v_exp_f32_e32 v49, v49
	v_exp_f32_e32 v54, v54
	v_exp_f32_e32 v51, v51
	v_exp_f32_e32 v52, v52
	v_exp_f32_e32 v50, v50
	v_exp_f32_e32 v55, v55
	v_add_f32_e32 v48, 1.0, v48
	v_add_f32_e32 v53, 1.0, v53
	v_add_f32_e32 v49, 1.0, v49
	v_add_f32_e32 v54, 1.0, v54
	v_add_f32_e32 v51, 1.0, v51
	v_add_f32_e32 v52, 1.0, v52
	v_add_f32_e32 v50, 1.0, v50
	v_add_f32_e32 v55, 1.0, v55
	v_rcp_f32_e32 v64, v48
	v_rcp_f32_e32 v48, v53
	v_rcp_f32_e32 v53, v49
	v_rcp_f32_e32 v49, v54
	v_rcp_f32_e32 v51, v51
	v_rcp_f32_e32 v52, v52
	v_rcp_f32_e32 v54, v55
	v_rcp_f32_e32 v55, v50
	v_cvt_pk_bf16_f32 v48, v52, v48
	v_cvt_pk_bf16_f32 v49, v49, v54
	v_cvt_pk_bf16_f32 v50, v64, v53
	v_cvt_pk_bf16_f32 v51, v55, v51
	global_store_dwordx4 v[80:81], v[48:51], off offset:256 sc0 sc1
	s_nop 1
	v_mov_b32_e32 v66, v210
	s_nop 0
	v_mov_b64_e32 v[48:49], v[190:191]
	v_mov_b64_e32 v[50:51], v[192:193]
	v_mov_b64_e32 v[52:53], v[194:195]
	v_mov_b64_e32 v[54:55], v[196:197]
	v_add_co_u32_e32 v64, vcc, s51, v136
	v_fmamk_f32 v66, v66, 0x3a000000, v172
	v_pk_mul_f32 v[46:47], v[50:51], v[46:47]
	v_rsq_f32_e32 v50, v66
	v_pk_mul_f32 v[44:45], v[48:49], v[44:45]
	v_pk_mul_f32 v[42:43], v[54:55], v[42:43]
	v_pk_mul_f32 v[40:41], v[52:53], v[40:41]
	v_pk_fma_f32 v[46:47], v[46:47], v[50:51], v[78:79] op_sel_hi:[1,0,1]
	v_pk_fma_f32 v[44:45], v[44:45], v[50:51], v[76:77] op_sel_hi:[1,0,1]
	v_pk_fma_f32 v[42:43], v[42:43], v[50:51], v[74:75] op_sel_hi:[1,0,1]
	v_pk_fma_f32 v[40:41], v[40:41], v[50:51], v[72:73] op_sel_hi:[1,0,1]
	v_mul_f32_e32 v45, 0xbfb8aa3b, v45
	v_mul_f32_e32 v40, 0xbfb8aa3b, v40
	v_mul_f32_e32 v41, 0xbfb8aa3b, v41
	v_mul_f32_e32 v46, 0xbfb8aa3b, v46
	v_mul_f32_e32 v43, 0xbfb8aa3b, v43
	v_mul_f32_e32 v44, 0xbfb8aa3b, v44
	v_mul_f32_e32 v42, 0xbfb8aa3b, v42
	v_mul_f32_e32 v47, 0xbfb8aa3b, v47
	v_exp_f32_e32 v40, v40
	v_exp_f32_e32 v45, v45
	v_exp_f32_e32 v41, v41
	v_exp_f32_e32 v46, v46
	v_exp_f32_e32 v43, v43
	v_exp_f32_e32 v44, v44
	v_exp_f32_e32 v42, v42
	v_exp_f32_e32 v47, v47
	v_add_f32_e32 v40, 1.0, v40
	v_add_f32_e32 v45, 1.0, v45
	v_add_f32_e32 v41, 1.0, v41
	v_add_f32_e32 v46, 1.0, v46
	v_add_f32_e32 v43, 1.0, v43
	v_addc_co_u32_e32 v65, vcc, 0, v137, vcc
	v_add_f32_e32 v44, 1.0, v44
; __device__ __forceinline__ unsigned cvt_pk_bf16(float lo, float hi) { unsigned r; asm volatile("v_cvt_pk_bf16_f32 %0, %1, %2" : "=v"(r) : "v"(lo), "v"(hi)); return r; }
; __device__ __forceinline__ float rs_of(const float* ssq, int r) { return __builtin_amdgcn_rsqf(ld_agent(ssq + r) * (1.f / 2048.f) + EPS); }
; __device__ __forceinline__ float sigm(float x) { return __builtin_amdgcn_rcpf(1.f + __builtin_amdgcn_exp2f(-LOG2E * x)); }
;     __device__ __forceinline__ void operator()(const i32x4 (&acc)[2][2][4][2], const Unit& u, int wr, int wc, int fr, int fq) const {
;     ...
; #pragma unroll
;         for (int ai = 0; ai < 2; ++ai)
; #pragma unroll
;             for (int m = 0; m < 4; ++m) {
;                 const int r = row0 + ai * HALF + m * 16; const float rs = rs_of(ssq, r);
;                 bf16_t* rowp = O + (size_t)r * ldc + col0;
; #pragma unroll
;                 for (int bj = 0; bj < 2; ++bj) {
;                     const f32x4 s0 = *(const f32x4*)(swp + col0 + bj * HALF), s1 = *(const f32x4*)(swp + col0 + bj * HALF + 4);
;                     f32x4 v0 = __builtin_convertvector(acc[ai][bj][m][0], f32x4) * s0 * rs + bv[bj][0], v1 = __builtin_convertvector(acc[ai][bj][m][1], f32x4) * s1 * rs + bv[bj][1];
; #pragma unroll
;                     for (int j = 0; j < 4; ++j) { v0[j] = sigm(v0[j]); v1[j] = sigm(v1[j]); }
;                     u32x4 w; w.x = cvt_pk_bf16(v0[0], v0[1]); w.y = cvt_pk_bf16(v0[2], v0[3]); w.z = cvt_pk_bf16(v1[0], v1[1]); w.w = cvt_pk_bf16(v1[2], v1[3]);
;                     *(u32x4*)(rowp + bj * HALF) = w;
;                 }
;             }
	v_add_f32_e32 v42, 1.0, v42
	v_add_f32_e32 v47, 1.0, v47
	v_rcp_f32_e32 v48, v40
	v_rcp_f32_e32 v40, v45
	v_rcp_f32_e32 v45, v41
	v_rcp_f32_e32 v41, v46
	v_rcp_f32_e32 v43, v43
	v_rcp_f32_e32 v44, v44
	v_rcp_f32_e32 v46, v47
	v_rcp_f32_e32 v47, v42
	v_cvt_pk_bf16_f32 v40, v44, v40
	v_cvt_pk_bf16_f32 v41, v41, v46
	v_cvt_pk_bf16_f32 v42, v48, v45
	v_cvt_pk_bf16_f32 v43, v47, v43
	global_store_dwordx4 v[64:65], v[40:43], off sc0 sc1
	s_nop 1
	v_mov_b64_e32 v[40:41], v[198:199]
	v_mov_b64_e32 v[42:43], v[200:201]
	s_nop 0
	v_mov_b64_e32 v[44:45], v[202:203]
	v_mov_b64_e32 v[46:47], v[204:205]
	v_lshl_add_u64 v[48:49], v[136:137], 0, s[12:13]
	v_pk_mul_f32 v[38:39], v[42:43], v[38:39]
	v_pk_mul_f32 v[36:37], v[40:41], v[36:37]
	v_pk_mul_f32 v[34:35], v[46:47], v[34:35]
	v_pk_mul_f32 v[32:33], v[44:45], v[32:33]
	v_pk_fma_f32 v[38:39], v[50:51], v[38:39], v[62:63] op_sel_hi:[0,1,1]
	v_pk_fma_f32 v[36:37], v[50:51], v[36:37], v[60:61] op_sel_hi:[0,1,1]
	v_pk_fma_f32 v[34:35], v[50:51], v[34:35], v[58:59] op_sel_hi:[0,1,1]
	v_pk_fma_f32 v[32:33], v[50:51], v[32:33], v[56:57] op_sel_hi:[0,1,1]
	v_mul_f32_e32 v32, 0xbfb8aa3b, v32
	v_mul_f32_e32 v37, 0xbfb8aa3b, v37
	v_mul_f32_e32 v33, 0xbfb8aa3b, v33
	v_mul_f32_e32 v38, 0xbfb8aa3b, v38
	v_mul_f32_e32 v35, 0xbfb8aa3b, v35
	v_mul_f32_e32 v36, 0xbfb8aa3b, v36
	v_mul_f32_e32 v34, 0xbfb8aa3b, v34
	v_mul_f32_e32 v39, 0xbfb8aa3b, v39
	v_exp_f32_e32 v32, v32
	v_exp_f32_e32 v37, v37
	v_exp_f32_e32 v33, v33
	v_exp_f32_e32 v38, v38
	v_exp_f32_e32 v35, v35
	v_exp_f32_e32 v36, v36
	v_exp_f32_e32 v34, v34
	v_exp_f32_e32 v39, v39
	v_add_f32_e32 v32, 1.0, v32
	v_add_f32_e32 v37, 1.0, v37
	v_add_f32_e32 v33, 1.0, v33
	v_add_f32_e32 v38, 1.0, v38
	v_add_f32_e32 v35, 1.0, v35
	v_add_f32_e32 v36, 1.0, v36
	v_add_f32_e32 v34, 1.0, v34
	v_add_f32_e32 v39, 1.0, v39
	v_rcp_f32_e32 v40, v32
	v_rcp_f32_e32 v32, v37
	v_rcp_f32_e32 v37, v33
	v_rcp_f32_e32 v33, v38
	v_rcp_f32_e32 v35, v35
	v_rcp_f32_e32 v36, v36
	v_rcp_f32_e32 v38, v39
	v_rcp_f32_e32 v39, v34
	v_cvt_pk_bf16_f32 v32, v36, v32
	v_cvt_pk_bf16_f32 v33, v33, v38
	v_cvt_pk_bf16_f32 v34, v40, v37
	v_cvt_pk_bf16_f32 v35, v39, v35
	global_store_dwordx4 v[48:49], v[32:35], off offset:256 sc0 sc1
	s_nop 1
	v_mov_b32_e32 v42, v211
	s_nop 0
	v_mov_b64_e32 v[32:33], v[190:191]
	v_mov_b64_e32 v[34:35], v[192:193]
	v_mov_b64_e32 v[36:37], v[194:195]
	v_mov_b64_e32 v[38:39], v[196:197]
	v_add_co_u32_e32 v40, vcc, s52, v136
	v_fmamk_f32 v42, v42, 0x3a000000, v172
	v_pk_mul_f32 v[30:31], v[34:35], v[30:31]
	v_rsq_f32_e32 v34, v42
	v_pk_mul_f32 v[28:29], v[32:33], v[28:29]
	v_pk_mul_f32 v[26:27], v[38:39], v[26:27]
	v_pk_mul_f32 v[24:25], v[36:37], v[24:25]
	v_pk_fma_f32 v[30:31], v[30:31], v[34:35], v[78:79] op_sel_hi:[1,0,1]
	v_pk_fma_f32 v[28:29], v[28:29], v[34:35], v[76:77] op_sel_hi:[1,0,1]
	v_pk_fma_f32 v[26:27], v[26:27], v[34:35], v[74:75] op_sel_hi:[1,0,1]
	v_pk_fma_f32 v[24:25], v[24:25], v[34:35], v[72:73] op_sel_hi:[1,0,1]
	v_mul_f32_e32 v29, 0xbfb8aa3b, v29
	v_mul_f32_e32 v24, 0xbfb8aa3b, v24
	v_mul_f32_e32 v25, 0xbfb8aa3b, v25
	v_mul_f32_e32 v30, 0xbfb8aa3b, v30
	v_mul_f32_e32 v27, 0xbfb8aa3b, v27
	v_mul_f32_e32 v28, 0xbfb8aa3b, v28
	v_mul_f32_e32 v26, 0xbfb8aa3b, v26
	v_mul_f32_e32 v31, 0xbfb8aa3b, v31
	v_exp_f32_e32 v24, v24
	v_exp_f32_e32 v29, v29
	v_exp_f32_e32 v25, v25
	v_exp_f32_e32 v30, v30
	v_exp_f32_e32 v27, v27
	v_exp_f32_e32 v28, v28
	v_exp_f32_e32 v26, v26
	v_exp_f32_e32 v31, v31
	v_add_f32_e32 v24, 1.0, v24
	v_add_f32_e32 v29, 1.0, v29
	v_add_f32_e32 v25, 1.0, v25
	v_add_f32_e32 v30, 1.0, v30
	v_add_f32_e32 v27, 1.0, v27
	v_addc_co_u32_e32 v41, vcc, 0, v137, vcc
	v_add_f32_e32 v28, 1.0, v28
	v_add_f32_e32 v26, 1.0, v26
	v_add_f32_e32 v31, 1.0, v31
	v_rcp_f32_e32 v32, v24
	v_rcp_f32_e32 v24, v29
	v_rcp_f32_e32 v29, v25
	v_rcp_f32_e32 v25, v30
	v_rcp_f32_e32 v27, v27
	v_rcp_f32_e32 v28, v28
	v_rcp_f32_e32 v30, v31
	v_rcp_f32_e32 v31, v26
	v_cvt_pk_bf16_f32 v24, v28, v24
	v_cvt_pk_bf16_f32 v25, v25, v30
	v_cvt_pk_bf16_f32 v26, v32, v29
	v_cvt_pk_bf16_f32 v27, v31, v27
	global_store_dwordx4 v[40:41], v[24:27], off sc0 sc1
	s_nop 1
	v_mov_b64_e32 v[24:25], v[198:199]
	v_mov_b64_e32 v[26:27], v[200:201]
	s_nop 0
	v_mov_b64_e32 v[28:29], v[202:203]
	v_mov_b64_e32 v[30:31], v[204:205]
	v_lshl_add_u64 v[32:33], v[136:137], 0, s[14:15]
	v_pk_mul_f32 v[22:23], v[26:27], v[22:23]
	v_pk_mul_f32 v[20:21], v[24:25], v[20:21]
	v_pk_mul_f32 v[18:19], v[30:31], v[18:19]
	v_pk_mul_f32 v[16:17], v[28:29], v[16:17]
	v_pk_fma_f32 v[22:23], v[34:35], v[22:23], v[62:63] op_sel_hi:[0,1,1]
	v_pk_fma_f32 v[20:21], v[34:35], v[20:21], v[60:61] op_sel_hi:[0,1,1]
	v_pk_fma_f32 v[18:19], v[34:35], v[18:19], v[58:59] op_sel_hi:[0,1,1]
	v_pk_fma_f32 v[16:17], v[34:35], v[16:17], v[56:57] op_sel_hi:[0,1,1]
; __device__ __forceinline__ unsigned cvt_pk_bf16(float lo, float hi) { unsigned r; asm volatile("v_cvt_pk_bf16_f32 %0, %1, %2" : "=v"(r) : "v"(lo), "v"(hi)); return r; }
; __device__ __forceinline__ float rs_of(const float* ssq, int r) { return __builtin_amdgcn_rsqf(ld_agent(ssq + r) * (1.f / 2048.f) + EPS); }
; __device__ __forceinline__ float sigm(float x) { return __builtin_amdgcn_rcpf(1.f + __builtin_amdgcn_exp2f(-LOG2E * x)); }
; #define PG8_WAIT_V(n) asm volatile("s_waitcnt vmcnt(" #n ")" ::: "memory")
; #define PG8_BAR __builtin_amdgcn_s_barrier()
;     __device__ __forceinline__ void operator()(const i32x4 (&acc)[2][2][4][2], const Unit& u, int wr, int wc, int fr, int fq) const {
;     ...
; #pragma unroll
;         for (int ai = 0; ai < 2; ++ai)
; #pragma unroll
;             for (int m = 0; m < 4; ++m) {
;                 const int r = row0 + ai * HALF + m * 16; const float rs = rs_of(ssq, r);
;                 bf16_t* rowp = O + (size_t)r * ldc + col0;
; #pragma unroll
;                 for (int bj = 0; bj < 2; ++bj) {
;                     const f32x4 s0 = *(const f32x4*)(swp + col0 + bj * HALF), s1 = *(const f32x4*)(swp + col0 + bj * HALF + 4);
;                     f32x4 v0 = __builtin_convertvector(acc[ai][bj][m][0], f32x4) * s0 * rs + bv[bj][0], v1 = __builtin_convertvector(acc[ai][bj][m][1], f32x4) * s1 * rs + bv[bj][1];
; #pragma unroll
;                     for (int j = 0; j < 4; ++j) { v0[j] = sigm(v0[j]); v1[j] = sigm(v1[j]); }
;                     u32x4 w; w.x = cvt_pk_bf16(v0[0], v0[1]); w.y = cvt_pk_bf16(v0[2], v0[3]); w.z = cvt_pk_bf16(v1[0], v1[1]); w.w = cvt_pk_bf16(v1[2], v1[3]);
;                     *(u32x4*)(rowp + bj * HALF) = w;
;                 }
;             }
; template <class Epi, class Sched>
; __device__ __forceinline__ void gemm_phase(LAS unsigned char* lds, const Gemm g, const Sched& S, const Epi& E) {
;     ...
;         E(acc, cur, wr, wc, fr, fq);
;         if (!has_next) break;
; #pragma unroll
;         for (int a = 0; a < 2; ++a)
; #pragma unroll
;             for (int b = 0; b < 2; ++b)
; #pragma unroll
;                 for (int m = 0; m < 4; ++m)
; #pragma unroll
;                     for (int n = 0; n < 2; ++n) acc[a][b][m][n] = (acc_t){0, 0, 0, 0};
;         cur = nxt; cA = nA; cB = nB; ++ui;
;     }
;     PG8_WAIT_V(0);
;     if (wr == 0) PG8_BAR;
;     PG8_BAR;
	v_mul_f32_e32 v16, 0xbfb8aa3b, v16
	v_mul_f32_e32 v21, 0xbfb8aa3b, v21
	v_mul_f32_e32 v17, 0xbfb8aa3b, v17
	v_mul_f32_e32 v22, 0xbfb8aa3b, v22
	v_mul_f32_e32 v19, 0xbfb8aa3b, v19
	v_mul_f32_e32 v20, 0xbfb8aa3b, v20
	v_mul_f32_e32 v18, 0xbfb8aa3b, v18
	v_mul_f32_e32 v23, 0xbfb8aa3b, v23
	v_exp_f32_e32 v16, v16
	v_exp_f32_e32 v21, v21
	v_exp_f32_e32 v17, v17
	v_exp_f32_e32 v22, v22
	v_exp_f32_e32 v19, v19
	v_exp_f32_e32 v20, v20
	v_exp_f32_e32 v18, v18
	v_exp_f32_e32 v23, v23
	v_add_f32_e32 v16, 1.0, v16
	v_add_f32_e32 v21, 1.0, v21
	v_add_f32_e32 v17, 1.0, v17
	v_add_f32_e32 v22, 1.0, v22
	v_add_f32_e32 v19, 1.0, v19
	v_add_f32_e32 v20, 1.0, v20
	v_add_f32_e32 v18, 1.0, v18
	v_add_f32_e32 v23, 1.0, v23
	v_rcp_f32_e32 v24, v16
	v_rcp_f32_e32 v16, v21
	v_rcp_f32_e32 v21, v17
	v_rcp_f32_e32 v17, v22
	v_rcp_f32_e32 v19, v19
	v_rcp_f32_e32 v20, v20
	v_rcp_f32_e32 v22, v23
	v_rcp_f32_e32 v23, v18
	v_cvt_pk_bf16_f32 v16, v20, v16
	v_cvt_pk_bf16_f32 v17, v17, v22
	v_cvt_pk_bf16_f32 v18, v24, v21
	v_cvt_pk_bf16_f32 v19, v23, v19
	global_store_dwordx4 v[32:33], v[16:19], off offset:256 sc0 sc1
	s_nop 1
	v_mov_b32_e32 v26, v212
	s_nop 0
	v_mov_b64_e32 v[16:17], v[190:191]
	v_mov_b64_e32 v[18:19], v[192:193]
	v_mov_b64_e32 v[20:21], v[194:195]
	v_mov_b64_e32 v[22:23], v[196:197]
	v_add_co_u32_e32 v24, vcc, s53, v136
	v_fmamk_f32 v26, v26, 0x3a000000, v172
	v_pk_mul_f32 v[14:15], v[18:19], v[14:15]
	v_rsq_f32_e32 v18, v26
	v_pk_mul_f32 v[12:13], v[16:17], v[12:13]
	v_pk_mul_f32 v[10:11], v[22:23], v[10:11]
	v_pk_mul_f32 v[8:9], v[20:21], v[8:9]
	v_pk_fma_f32 v[14:15], v[14:15], v[18:19], v[78:79] op_sel_hi:[1,0,1]
	v_pk_fma_f32 v[12:13], v[12:13], v[18:19], v[76:77] op_sel_hi:[1,0,1]
	v_pk_fma_f32 v[10:11], v[10:11], v[18:19], v[74:75] op_sel_hi:[1,0,1]
	v_pk_fma_f32 v[8:9], v[8:9], v[18:19], v[72:73] op_sel_hi:[1,0,1]
	v_mul_f32_e32 v13, 0xbfb8aa3b, v13
	v_mul_f32_e32 v8, 0xbfb8aa3b, v8
	v_mul_f32_e32 v9, 0xbfb8aa3b, v9
	v_mul_f32_e32 v14, 0xbfb8aa3b, v14
	v_mul_f32_e32 v11, 0xbfb8aa3b, v11
	v_mul_f32_e32 v12, 0xbfb8aa3b, v12
	v_mul_f32_e32 v10, 0xbfb8aa3b, v10
	v_mul_f32_e32 v15, 0xbfb8aa3b, v15
	v_exp_f32_e32 v8, v8
	v_exp_f32_e32 v13, v13
	v_exp_f32_e32 v9, v9
	v_exp_f32_e32 v14, v14
	v_exp_f32_e32 v11, v11
	v_exp_f32_e32 v12, v12
	v_exp_f32_e32 v10, v10
	v_exp_f32_e32 v15, v15
	v_add_f32_e32 v8, 1.0, v8
	v_add_f32_e32 v13, 1.0, v13
	v_add_f32_e32 v9, 1.0, v9
	v_add_f32_e32 v14, 1.0, v14
	v_add_f32_e32 v11, 1.0, v11
	v_addc_co_u32_e32 v25, vcc, 0, v137, vcc
	v_add_f32_e32 v12, 1.0, v12
	v_add_f32_e32 v10, 1.0, v10
	v_add_f32_e32 v15, 1.0, v15
	v_rcp_f32_e32 v16, v8
	v_rcp_f32_e32 v8, v13
	v_rcp_f32_e32 v13, v9
	v_rcp_f32_e32 v9, v14
	v_rcp_f32_e32 v11, v11
	v_rcp_f32_e32 v12, v12
	v_rcp_f32_e32 v14, v15
	v_rcp_f32_e32 v15, v10
	v_cvt_pk_bf16_f32 v8, v12, v8
	v_cvt_pk_bf16_f32 v9, v9, v14
	v_cvt_pk_bf16_f32 v10, v16, v13
	v_cvt_pk_bf16_f32 v11, v15, v11
	global_store_dwordx4 v[24:25], v[8:11], off sc0 sc1
	s_nop 1
	v_mov_b64_e32 v[8:9], v[198:199]
	v_mov_b64_e32 v[10:11], v[200:201]
	s_nop 0
	v_mov_b64_e32 v[12:13], v[202:203]
	v_mov_b64_e32 v[14:15], v[204:205]
	s_and_b64 vcc, exec, s[0:1]
	v_lshl_add_u64 v[16:17], v[136:137], 0, s[16:17]
	v_pk_mul_f32 v[6:7], v[10:11], v[6:7]
	v_pk_mul_f32 v[4:5], v[8:9], v[4:5]
	v_pk_mul_f32 v[2:3], v[14:15], v[2:3]
	v_pk_mul_f32 v[0:1], v[12:13], v[0:1]
	v_pk_fma_f32 v[6:7], v[18:19], v[6:7], v[62:63] op_sel_hi:[0,1,1]
	v_pk_fma_f32 v[4:5], v[18:19], v[4:5], v[60:61] op_sel_hi:[0,1,1]
	v_pk_fma_f32 v[2:3], v[18:19], v[2:3], v[58:59] op_sel_hi:[0,1,1]
	v_pk_fma_f32 v[0:1], v[18:19], v[0:1], v[56:57] op_sel_hi:[0,1,1]
	v_mul_f32_e32 v0, 0xbfb8aa3b, v0
	v_mul_f32_e32 v5, 0xbfb8aa3b, v5
	v_mul_f32_e32 v1, 0xbfb8aa3b, v1
	v_mul_f32_e32 v6, 0xbfb8aa3b, v6
	v_mul_f32_e32 v3, 0xbfb8aa3b, v3
	v_mul_f32_e32 v4, 0xbfb8aa3b, v4
	v_mul_f32_e32 v2, 0xbfb8aa3b, v2
	v_mul_f32_e32 v7, 0xbfb8aa3b, v7
	v_exp_f32_e32 v0, v0
	v_exp_f32_e32 v5, v5
	v_exp_f32_e32 v1, v1
	v_exp_f32_e32 v6, v6
	v_exp_f32_e32 v3, v3
	v_exp_f32_e32 v4, v4
	v_exp_f32_e32 v2, v2
	v_exp_f32_e32 v7, v7
	v_add_f32_e32 v0, 1.0, v0
	v_add_f32_e32 v5, 1.0, v5
	v_add_f32_e32 v1, 1.0, v1
	v_add_f32_e32 v6, 1.0, v6
	v_add_f32_e32 v3, 1.0, v3
	v_add_f32_e32 v4, 1.0, v4
	v_add_f32_e32 v2, 1.0, v2
	v_add_f32_e32 v7, 1.0, v7
	v_rcp_f32_e32 v8, v0
	v_rcp_f32_e32 v0, v5
	v_rcp_f32_e32 v5, v1
	v_rcp_f32_e32 v1, v6
	v_rcp_f32_e32 v3, v3
	v_rcp_f32_e32 v4, v4
	v_rcp_f32_e32 v6, v7
	v_rcp_f32_e32 v7, v2
	v_cvt_pk_bf16_f32 v0, v4, v0
	v_cvt_pk_bf16_f32 v1, v1, v6
	v_cvt_pk_bf16_f32 v2, v8, v5
	v_cvt_pk_bf16_f32 v3, v7, v3
	global_store_dwordx4 v[16:17], v[0:3], off offset:256 sc0 sc1
	s_nop 1
	s_cbranch_vccz .LBB0_632
	s_waitcnt vmcnt(0)
	s_cmpk_gt_u32 s33, 0xff
	s_cbranch_scc1 .LBB0_639
	s_barrier

; #define PG8_STAGE(bufoff, gbase, voff) do { _Pragma("unroll") for (int _i = 0; _i < 2; ++_i) \
;         __builtin_amdgcn_global_load_lds((const unsigned*)((const char*)(gbase) + (voff)[_i]), (LAS unsigned*)(lds + (bufoff) + ldsw + _i * 8192), 16, 0, 0); } while (0)
; #define PG8_LDA(dst, b, h) do { _Pragma("unroll") for (int m = 0; m < 4; ++m) _Pragma("unroll") for (int k = 0; k < 2; ++k) dst[m][k] = *(const LAS bf16x8*)(lds + PG8_SA(b, h) + aoff + m * 2048 + k * 1024); } while (0)
; #define PG8_WAIT_V(n) asm volatile("s_waitcnt vmcnt(" #n ")" ::: "memory")
; #define PG8_BAR __builtin_amdgcn_s_barrier()
; template <class Epi, class Sched>
; __device__ __forceinline__ void gemm_phase(LAS unsigned char* lds, const Gemm g, const Sched& S, const Epi& E) {
;     ...
;         for (int t = 0; t < nt; t += 2) {
;             const bool last = (t == nt - 2);
;             const char* a1 = cA + (size_t)(t + 1) * kstep;
;             const char* a2 = last ? nA : cA + (size_t)(t + 2) * kstep; const char* b2 = last ? nB : cB + (size_t)(t + 2) * kstep;
;             const char* a3 = a2 + kstep; const char* b3 = b2 + kstep;
;             PG8_LDB(B0, 0, 0); PG8_SCHED; PG8_LDA(At, 0, 0); PG8_STAGE(PG8_SA(1, 1), a1 + hstepA, voffA);
;             PG8_WAIT_L(8); PG8_BAR; PG8_WAIT_L(0); PG8_MMA(0, 0, At, B0); PG8_BAR; PG8_SCHED;
;             PG8_LDB(B1, 0, 1); PG8_STAGE(PG8_SB(0, 0), b2, voffB);
;             PG8_BAR; PG8_WAIT_L(0); PG8_MMA(0, 1, At, B1); PG8_BAR;
;             PG8_LDA(At, 0, 1); PG8_STAGE(PG8_SA(0, 0), a2, voffA);
;             PG8_BAR; PG8_WAIT_L(0); PG8_MMA(1, 0, At, B0); PG8_BAR; PG8_SCHED;
;             PG8_STAGE(PG8_SB(0, 1), b2 + hstepB, voffB);
;             PG8_WAIT_V(6); PG8_BAR; PG8_MMA(1, 1, At, B1); PG8_BAR;
;             PG8_LDB(B0, 1, 0); PG8_SCHED; PG8_LDA(At, 1, 0); PG8_STAGE(PG8_SA(0, 1), a2 + hstepA, voffA);
;             PG8_WAIT_L(8); PG8_BAR; PG8_WAIT_L(0); PG8_MMA(0, 0, At, B0); PG8_BAR; PG8_SCHED;
;             PG8_LDB(B1, 1, 1); PG8_STAGE(PG8_SB(1, 0), b3, voffB);
;             PG8_BAR; PG8_WAIT_L(0); PG8_MMA(0, 1, At, B1); PG8_BAR;
;             PG8_LDA(At, 1, 1); PG8_STAGE(PG8_SA(1, 0), a3, voffA);
;             PG8_BAR; PG8_WAIT_L(0); PG8_MMA(1, 0, At, B0); PG8_BAR; PG8_SCHED;
;             PG8_STAGE(PG8_SB(1, 1), b3 + hstepB, voffB);
;             PG8_WAIT_V(6); PG8_BAR; PG8_MMA(1, 1, At, B1); PG8_BAR;
;         }
.LBB0_715:
	ds_read_b128 v[152:155], v149
	ds_read_b128 v[156:159], v149 offset:1024
	ds_read_b128 v[160:163], v149 offset:2048
	ds_read_b128 v[164:167], v149 offset:3072
	s_add_u32 s18, s16, 0xfff80080
	s_addc_u32 s19, s17, -1
	s_cmp_eq_u32 s57, 12
	s_cselect_b32 s21, s9, s19
	s_cselect_b32 s20, s53, s18
	s_cselect_b32 s19, s7, s56
	s_cselect_b32 s18, s54, s55
	v_lshl_add_u64 v[144:145], s[16:17], 0, v[136:137]
	s_add_i32 m0, s15, 0xc000
	ds_read_b128 v[168:171], v150
	ds_read_b128 v[172:175], v150 offset:1024
	ds_read_b128 v[178:181], v150 offset:2048
	ds_read_b128 v[182:185], v150 offset:3072
	ds_read_b128 v[186:189], v150 offset:4096
	ds_read_b128 v[190:193], v150 offset:5120
	ds_read_b128 v[194:197], v150 offset:6144
	ds_read_b128 v[198:201], v150 offset:7168
	global_load_lds_dwordx4 v[144:145], off
	v_lshl_add_u64 v[144:145], s[16:17], 0, v[138:139]
	s_add_i32 m0, s15, 0xe000
	s_nop 0
	global_load_lds_dwordx4 v[144:145], off
	s_waitcnt lgkmcnt(8)
	s_barrier
	s_waitcnt lgkmcnt(0)
	s_setprio 1
	s_waitcnt lgkmcnt(0)
	v_mfma_f32_16x16x32_bf16 v[124:127], v[152:155], v[168:171], v[124:127]
	v_mfma_f32_16x16x32_bf16 v[120:123], v[160:163], v[168:171], v[120:123]
	v_mfma_f32_16x16x32_bf16 v[108:111], v[152:155], v[178:181], v[108:111]
	v_mfma_f32_16x16x32_bf16 v[104:107], v[160:163], v[178:181], v[104:107]
	v_mfma_f32_16x16x32_bf16 v[92:95], v[152:155], v[186:189], v[92:95]
	v_mfma_f32_16x16x32_bf16 v[88:91], v[160:163], v[186:189], v[88:91]
	v_mfma_f32_16x16x32_bf16 v[76:79], v[152:155], v[194:197], v[76:79]
	v_mfma_f32_16x16x32_bf16 v[72:75], v[160:163], v[194:197], v[72:75]
	v_mfma_f32_16x16x32_bf16 v[124:127], v[156:159], v[172:175], v[124:127]
	v_mfma_f32_16x16x32_bf16 v[120:123], v[164:167], v[172:175], v[120:123]
	v_mfma_f32_16x16x32_bf16 v[108:111], v[156:159], v[182:185], v[108:111]
	v_mfma_f32_16x16x32_bf16 v[104:107], v[164:167], v[182:185], v[104:107]
	v_mfma_f32_16x16x32_bf16 v[92:95], v[156:159], v[190:193], v[92:95]
	v_mfma_f32_16x16x32_bf16 v[88:91], v[164:167], v[190:193], v[88:91]
	v_mfma_f32_16x16x32_bf16 v[76:79], v[156:159], v[198:201], v[76:79]
	v_mfma_f32_16x16x32_bf16 v[72:75], v[164:167], v[198:201], v[72:75]
	s_setprio 0
	s_barrier
	s_add_i32 s58, s36, s25
	v_lshl_add_u64 v[144:145], s[18:19], 0, v[132:133]
	s_mov_b32 m0, s58
	ds_read_b128 v[202:205], v151
	ds_read_b128 v[206:209], v151 offset:1024
	ds_read_b128 v[210:213], v151 offset:2048
	ds_read_b128 v[214:217], v151 offset:3072
	global_load_lds_dwordx4 v[144:145], off
	v_lshl_add_u64 v[218:219], s[18:19], 0, v[128:129]
	s_add_i32 m0, s58, 0x2000
	s_nop 0
	global_load_lds_dwordx4 v[218:219], off
	s_barrier
	s_waitcnt lgkmcnt(0)
	s_setprio 1
	s_waitcnt lgkmcnt(0)
	v_mfma_f32_16x16x32_bf16 v[116:119], v[202:205], v[168:171], v[116:119]
	v_mfma_f32_16x16x32_bf16 v[112:115], v[210:213], v[168:171], v[112:115]
	v_mfma_f32_16x16x32_bf16 v[100:103], v[202:205], v[178:181], v[100:103]
	v_mfma_f32_16x16x32_bf16 v[96:99], v[210:213], v[178:181], v[96:99]
	v_mfma_f32_16x16x32_bf16 v[84:87], v[202:205], v[186:189], v[84:87]
	v_mfma_f32_16x16x32_bf16 v[80:83], v[210:213], v[186:189], v[80:83]
	v_mfma_f32_16x16x32_bf16 v[68:71], v[202:205], v[194:197], v[68:71]
	v_mfma_f32_16x16x32_bf16 v[64:67], v[210:213], v[194:197], v[64:67]
	v_mfma_f32_16x16x32_bf16 v[116:119], v[206:209], v[172:175], v[116:119]
	v_mfma_f32_16x16x32_bf16 v[112:115], v[214:217], v[172:175], v[112:115]
	v_mfma_f32_16x16x32_bf16 v[100:103], v[206:209], v[182:185], v[100:103]
	v_mfma_f32_16x16x32_bf16 v[96:99], v[214:217], v[182:185], v[96:99]
	v_mfma_f32_16x16x32_bf16 v[84:87], v[206:209], v[190:193], v[84:87]
	v_mfma_f32_16x16x32_bf16 v[80:83], v[214:217], v[190:193], v[80:83]
	v_mfma_f32_16x16x32_bf16 v[68:71], v[206:209], v[198:201], v[68:71]
	v_mfma_f32_16x16x32_bf16 v[64:67], v[214:217], v[198:201], v[64:67]
	s_setprio 0
	s_mov_b32 m0, s15
	v_lshl_add_u64 v[220:221], s[20:21], 0, v[134:135]
	s_barrier
	ds_read_b128 v[168:171], v150 offset:16384
	ds_read_b128 v[172:175], v150 offset:17408
	ds_read_b128 v[178:181], v150 offset:18432
	ds_read_b128 v[182:185], v150 offset:19456
	ds_read_b128 v[186:189], v150 offset:20480
	ds_read_b128 v[190:193], v150 offset:21504
	ds_read_b128 v[194:197], v150 offset:22528
	ds_read_b128 v[198:201], v150 offset:23552
	global_load_lds_dwordx4 v[220:221], off
	v_lshl_add_u64 v[222:223], s[20:21], 0, v[130:131]
	s_mov_b32 m0, s28
	s_nop 0
	global_load_lds_dwordx4 v[222:223], off
	s_barrier
	s_waitcnt lgkmcnt(0)
	s_setprio 1
	s_waitcnt lgkmcnt(0)
	v_mfma_f32_16x16x32_bf16 v[60:63], v[152:155], v[168:171], v[60:63]
	v_mfma_f32_16x16x32_bf16 v[56:59], v[160:163], v[168:171], v[56:59]
	v_mfma_f32_16x16x32_bf16 v[44:47], v[152:155], v[178:181], v[44:47]
	v_mfma_f32_16x16x32_bf16 v[40:43], v[160:163], v[178:181], v[40:43]
	v_mfma_f32_16x16x32_bf16 v[28:31], v[152:155], v[186:189], v[28:31]
	v_mfma_f32_16x16x32_bf16 v[24:27], v[160:163], v[186:189], v[24:27]
	v_mfma_f32_16x16x32_bf16 v[16:19], v[152:155], v[194:197], v[16:19]
	v_mfma_f32_16x16x32_bf16 v[8:11], v[160:163], v[194:197], v[8:11]
	v_mfma_f32_16x16x32_bf16 v[60:63], v[156:159], v[172:175], v[60:63]
	v_mfma_f32_16x16x32_bf16 v[56:59], v[164:167], v[172:175], v[56:59]
	v_mfma_f32_16x16x32_bf16 v[44:47], v[156:159], v[182:185], v[44:47]
	v_mfma_f32_16x16x32_bf16 v[40:43], v[164:167], v[182:185], v[40:43]
	v_mfma_f32_16x16x32_bf16 v[28:31], v[156:159], v[190:193], v[28:31]
	v_mfma_f32_16x16x32_bf16 v[24:27], v[164:167], v[190:193], v[24:27]
	v_mfma_f32_16x16x32_bf16 v[16:19], v[156:159], v[198:201], v[16:19]
	v_mfma_f32_16x16x32_bf16 v[8:11], v[164:167], v[198:201], v[8:11]
	s_setprio 0
	s_barrier
; #define PG8_STAGE(bufoff, gbase, voff) do { _Pragma("unroll") for (int _i = 0; _i < 2; ++_i) \
;         __builtin_amdgcn_global_load_lds((const unsigned*)((const char*)(gbase) + (voff)[_i]), (LAS unsigned*)(lds + (bufoff) + ldsw + _i * 8192), 16, 0, 0); } while (0)
; #define PG8_LDA(dst, b, h) do { _Pragma("unroll") for (int m = 0; m < 4; ++m) _Pragma("unroll") for (int k = 0; k < 2; ++k) dst[m][k] = *(const LAS bf16x8*)(lds + PG8_SA(b, h) + aoff + m * 2048 + k * 1024); } while (0)
; #define PG8_WAIT_V(n) asm volatile("s_waitcnt vmcnt(" #n ")" ::: "memory")
; #define PG8_BAR __builtin_amdgcn_s_barrier()
; template <class Epi, class Sched>
; __device__ __forceinline__ void gemm_phase(LAS unsigned char* lds, const Gemm g, const Sched& S, const Epi& E) {
;     ...
;         for (int t = 0; t < nt; t += 2) {
;             const bool last = (t == nt - 2);
;             const char* a1 = cA + (size_t)(t + 1) * kstep;
;             const char* a2 = last ? nA : cA + (size_t)(t + 2) * kstep; const char* b2 = last ? nB : cB + (size_t)(t + 2) * kstep;
;             const char* a3 = a2 + kstep; const char* b3 = b2 + kstep;
;             PG8_LDB(B0, 0, 0); PG8_SCHED; PG8_LDA(At, 0, 0); PG8_STAGE(PG8_SA(1, 1), a1 + hstepA, voffA);
;             PG8_WAIT_L(8); PG8_BAR; PG8_WAIT_L(0); PG8_MMA(0, 0, At, B0); PG8_BAR; PG8_SCHED;
;             PG8_LDB(B1, 0, 1); PG8_STAGE(PG8_SB(0, 0), b2, voffB);
;             PG8_BAR; PG8_WAIT_L(0); PG8_MMA(0, 1, At, B1); PG8_BAR;
;             PG8_LDA(At, 0, 1); PG8_STAGE(PG8_SA(0, 0), a2, voffA);
;             PG8_BAR; PG8_WAIT_L(0); PG8_MMA(1, 0, At, B0); PG8_BAR; PG8_SCHED;
;             PG8_STAGE(PG8_SB(0, 1), b2 + hstepB, voffB);
;             PG8_WAIT_V(6); PG8_BAR; PG8_MMA(1, 1, At, B1); PG8_BAR;
;             PG8_LDB(B0, 1, 0); PG8_SCHED; PG8_LDA(At, 1, 0); PG8_STAGE(PG8_SA(0, 1), a2 + hstepA, voffA);
;             PG8_WAIT_L(8); PG8_BAR; PG8_WAIT_L(0); PG8_MMA(0, 0, At, B0); PG8_BAR; PG8_SCHED;
;             PG8_LDB(B1, 1, 1); PG8_STAGE(PG8_SB(1, 0), b3, voffB);
;             PG8_BAR; PG8_WAIT_L(0); PG8_MMA(0, 1, At, B1); PG8_BAR;
;             PG8_LDA(At, 1, 1); PG8_STAGE(PG8_SA(1, 0), a3, voffA);
;             PG8_BAR; PG8_WAIT_L(0); PG8_MMA(1, 0, At, B0); PG8_BAR; PG8_SCHED;
;             PG8_STAGE(PG8_SB(1, 1), b3 + hstepB, voffB);
;             PG8_WAIT_V(6); PG8_BAR; PG8_MMA(1, 1, At, B1); PG8_BAR;
;         }
	s_add_u32 s58, s18, 0x40000
	s_addc_u32 s59, s19, 0
	s_add_i32 s60, s37, s25
	v_lshl_add_u64 v[152:153], s[58:59], 0, v[132:133]
	s_mov_b32 m0, s60
	s_nop 0
	global_load_lds_dwordx4 v[152:153], off
	v_lshl_add_u64 v[152:153], s[58:59], 0, v[128:129]
	s_add_i32 m0, s60, 0x2000
	s_nop 0
	global_load_lds_dwordx4 v[152:153], off
	s_waitcnt vmcnt(6)
	s_barrier
	s_setprio 1
	v_mfma_f32_16x16x32_bf16 v[52:55], v[202:205], v[168:171], v[52:55]
	v_mfma_f32_16x16x32_bf16 v[48:51], v[210:213], v[168:171], v[48:51]
	v_mfma_f32_16x16x32_bf16 v[36:39], v[202:205], v[178:181], v[36:39]
	v_mfma_f32_16x16x32_bf16 v[32:35], v[210:213], v[178:181], v[32:35]
	v_mfma_f32_16x16x32_bf16 v[20:23], v[202:205], v[186:189], v[20:23]
	v_mfma_f32_16x16x32_bf16 v[12:15], v[210:213], v[186:189], v[12:15]
	v_mfma_f32_16x16x32_bf16 v[4:7], v[202:205], v[194:197], v[4:7]
	v_mfma_f32_16x16x32_bf16 v[0:3], v[210:213], v[194:197], v[0:3]
	v_mfma_f32_16x16x32_bf16 v[52:55], v[206:209], v[172:175], v[52:55]
	v_mfma_f32_16x16x32_bf16 v[48:51], v[214:217], v[172:175], v[48:51]
	v_mfma_f32_16x16x32_bf16 v[36:39], v[206:209], v[182:185], v[36:39]
	v_mfma_f32_16x16x32_bf16 v[32:35], v[214:217], v[182:185], v[32:35]
	v_mfma_f32_16x16x32_bf16 v[20:23], v[206:209], v[190:193], v[20:23]
	v_mfma_f32_16x16x32_bf16 v[12:15], v[214:217], v[190:193], v[12:15]
	v_mfma_f32_16x16x32_bf16 v[4:7], v[206:209], v[198:201], v[4:7]
	v_mfma_f32_16x16x32_bf16 v[0:3], v[214:217], v[198:201], v[0:3]
	s_setprio 0
	s_add_i32 s58, 0, 0x18000
	v_add_u32_e32 v164, s58, v147
	s_barrier
	ds_read_b128 v[152:155], v164
	ds_read_b128 v[156:159], v164 offset:1024
	ds_read_b128 v[160:163], v164 offset:2048
	ds_read_b128 v[164:167], v164 offset:3072
	s_add_u32 s20, s20, 0x80000
	s_addc_u32 s21, s21, 0
	s_mov_b32 m0, s29
	v_lshl_add_u64 v[202:203], s[20:21], 0, v[134:135]
	ds_read_b128 v[168:171], v150 offset:32768
	ds_read_b128 v[172:175], v150 offset:33792
	ds_read_b128 v[178:181], v150 offset:34816
	ds_read_b128 v[182:185], v150 offset:35840
	ds_read_b128 v[186:189], v150 offset:36864
	ds_read_b128 v[190:193], v150 offset:37888
	ds_read_b128 v[194:197], v150 offset:38912
	ds_read_b128 v[198:201], v150 offset:39936
	global_load_lds_dwordx4 v[202:203], off
	v_lshl_add_u64 v[202:203], s[20:21], 0, v[130:131]
	s_mov_b32 m0, s30
	s_nop 0
	global_load_lds_dwordx4 v[202:203], off
	s_waitcnt lgkmcnt(8)
	s_barrier
	s_waitcnt lgkmcnt(0)
	s_setprio 1
	s_waitcnt lgkmcnt(0)
	v_mfma_f32_16x16x32_bf16 v[124:127], v[152:155], v[168:171], v[124:127]
	v_mfma_f32_16x16x32_bf16 v[120:123], v[160:163], v[168:171], v[120:123]
	v_mfma_f32_16x16x32_bf16 v[108:111], v[152:155], v[178:181], v[108:111]
	v_mfma_f32_16x16x32_bf16 v[104:107], v[160:163], v[178:181], v[104:107]
	v_mfma_f32_16x16x32_bf16 v[92:95], v[152:155], v[186:189], v[92:95]
	v_mfma_f32_16x16x32_bf16 v[88:91], v[160:163], v[186:189], v[88:91]
	v_mfma_f32_16x16x32_bf16 v[76:79], v[152:155], v[194:197], v[76:79]
	v_mfma_f32_16x16x32_bf16 v[72:75], v[160:163], v[194:197], v[72:75]
	v_mfma_f32_16x16x32_bf16 v[124:127], v[156:159], v[172:175], v[124:127]
	v_mfma_f32_16x16x32_bf16 v[120:123], v[164:167], v[172:175], v[120:123]
	v_mfma_f32_16x16x32_bf16 v[108:111], v[156:159], v[182:185], v[108:111]
	v_mfma_f32_16x16x32_bf16 v[104:107], v[164:167], v[182:185], v[104:107]
	v_mfma_f32_16x16x32_bf16 v[92:95], v[156:159], v[190:193], v[92:95]
	v_mfma_f32_16x16x32_bf16 v[88:91], v[164:167], v[190:193], v[88:91]
	v_mfma_f32_16x16x32_bf16 v[76:79], v[156:159], v[198:201], v[76:79]
	v_mfma_f32_16x16x32_bf16 v[72:75], v[164:167], v[198:201], v[72:75]
	s_setprio 0
	s_barrier
	s_add_i32 s20, 0, 0x1c000
	s_add_i32 s21, s58, s25
	v_add_u32_e32 v214, s20, v147
	v_lshl_add_u64 v[144:145], v[144:145], 0, s[4:5]
	s_mov_b32 m0, s21
	ds_read_b128 v[202:205], v214
	ds_read_b128 v[206:209], v214 offset:1024
	ds_read_b128 v[210:213], v214 offset:2048
	ds_read_b128 v[214:217], v214 offset:3072
	global_load_lds_dwordx4 v[144:145], off
	v_lshl_add_u64 v[144:145], v[218:219], 0, s[4:5]
	s_add_i32 m0, s21, 0x2000
	s_nop 0
	global_load_lds_dwordx4 v[144:145], off
	s_barrier
	s_waitcnt lgkmcnt(0)
	s_setprio 1
	s_waitcnt lgkmcnt(0)
	v_mfma_f32_16x16x32_bf16 v[116:119], v[202:205], v[168:171], v[116:119]
	v_mfma_f32_16x16x32_bf16 v[112:115], v[210:213], v[168:171], v[112:115]
	v_mfma_f32_16x16x32_bf16 v[100:103], v[202:205], v[178:181], v[100:103]
	v_mfma_f32_16x16x32_bf16 v[96:99], v[210:213], v[178:181], v[96:99]
	v_mfma_f32_16x16x32_bf16 v[84:87], v[202:205], v[186:189], v[84:87]
	v_mfma_f32_16x16x32_bf16 v[80:83], v[210:213], v[186:189], v[80:83]
	v_mfma_f32_16x16x32_bf16 v[68:71], v[202:205], v[194:197], v[68:71]
	v_mfma_f32_16x16x32_bf16 v[64:67], v[210:213], v[194:197], v[64:67]
	v_mfma_f32_16x16x32_bf16 v[116:119], v[206:209], v[172:175], v[116:119]
	v_mfma_f32_16x16x32_bf16 v[112:115], v[214:217], v[172:175], v[112:115]
	v_mfma_f32_16x16x32_bf16 v[100:103], v[206:209], v[182:185], v[100:103]
	v_mfma_f32_16x16x32_bf16 v[96:99], v[214:217], v[182:185], v[96:99]
	v_mfma_f32_16x16x32_bf16 v[84:87], v[206:209], v[190:193], v[84:87]
	v_mfma_f32_16x16x32_bf16 v[80:83], v[214:217], v[190:193], v[80:83]
	v_mfma_f32_16x16x32_bf16 v[68:71], v[206:209], v[198:201], v[68:71]
	v_mfma_f32_16x16x32_bf16 v[64:67], v[214:217], v[198:201], v[64:67]
	s_setprio 0
	s_mov_b32 m0, s33
	v_lshl_add_u64 v[144:145], v[220:221], 0, s[4:5]
	s_barrier
	ds_read_b128 v[168:171], v150 offset:49152
	ds_read_b128 v[172:175], v150 offset:50176
	ds_read_b128 v[178:181], v150 offset:51200
	ds_read_b128 v[182:185], v150 offset:52224
	ds_read_b128 v[186:189], v150 offset:53248
	ds_read_b128 v[190:193], v150 offset:54272
	ds_read_b128 v[194:197], v150 offset:55296
	ds_read_b128 v[198:201], v150 offset:56320
	global_load_lds_dwordx4 v[144:145], off
	v_lshl_add_u64 v[144:145], v[222:223], 0, s[4:5]
	s_mov_b32 m0, s34
	s_nop 0
	global_load_lds_dwordx4 v[144:145], off
	s_barrier
;     __device__ __forceinline__ void operator()(const f32x4 (&acc)[2][2][4][2], const Unit& u, int wr, int wc, int fr, int fq) const {
;         const int row0 = u.pm * BM + wr * 64 + fr, col0 = u.pn * BM + wc * 32 + 8 * fq;
;         bf16_t* base = G + (size_t)row0 * NGATE + col0;
;         u32x4 ga[2], gb[2], na[2], nb[2];
; #pragma unroll
;         for (int bj = 0; bj < 2; ++bj) { ga[bj] = *(const u32x4*)(base + bj * HALF); if (STEP == 1) gb[bj] = *(const u32x4*)(base + bj * HALF + DM); }
; #pragma unroll
;         for (int g = 0; g < 8; ++g) {
;             const int ai = g >> 2, m = g & 3;
; template <class Epi, class Sched>
; __device__ __forceinline__ void gemm_phase(LAS unsigned char* lds, const Gemm g, const Sched& S, const Epi& E) {
;     ...
;         for (int t = 0; t < nt; t += 2) {
;             const bool last = (t == nt - 2);
;             const char* a1 = cA + (size_t)(t + 1) * kstep;
;             const char* a2 = last ? nA : cA + (size_t)(t + 2) * kstep; const char* b2 = last ? nB : cB + (size_t)(t + 2) * kstep;
;             const char* a3 = a2 + kstep; const char* b3 = b2 + kstep;
;             PG8_LDB(B0, 0, 0); PG8_SCHED; PG8_LDA(At, 0, 0); PG8_STAGE(PG8_SA(1, 1), a1 + hstepA, voffA);
;             PG8_WAIT_L(8); PG8_BAR; PG8_WAIT_L(0); PG8_MMA(0, 0, At, B0); PG8_BAR; PG8_SCHED;
;             PG8_LDB(B1, 0, 1); PG8_STAGE(PG8_SB(0, 0), b2, voffB);
;             PG8_BAR; PG8_WAIT_L(0); PG8_MMA(0, 1, At, B1); PG8_BAR;
;             PG8_LDA(At, 0, 1); PG8_STAGE(PG8_SA(0, 0), a2, voffA);
;             PG8_BAR; PG8_WAIT_L(0); PG8_MMA(1, 0, At, B0); PG8_BAR; PG8_SCHED;
;             PG8_STAGE(PG8_SB(0, 1), b2 + hstepB, voffB);
;             PG8_WAIT_V(6); PG8_BAR; PG8_MMA(1, 1, At, B1); PG8_BAR;
;             PG8_LDB(B0, 1, 0); PG8_SCHED; PG8_LDA(At, 1, 0); PG8_STAGE(PG8_SA(0, 1), a2 + hstepA, voffA);
;             PG8_WAIT_L(8); PG8_BAR; PG8_WAIT_L(0); PG8_MMA(0, 0, At, B0); PG8_BAR; PG8_SCHED;
;             PG8_LDB(B1, 1, 1); PG8_STAGE(PG8_SB(1, 0), b3, voffB);
;             PG8_BAR; PG8_WAIT_L(0); PG8_MMA(0, 1, At, B1); PG8_BAR;
;             PG8_LDA(At, 1, 1); PG8_STAGE(PG8_SA(1, 0), a3, voffA);
;             PG8_BAR; PG8_WAIT_L(0); PG8_MMA(1, 0, At, B0); PG8_BAR; PG8_SCHED;
;             PG8_STAGE(PG8_SB(1, 1), b3 + hstepB, voffB);
;             PG8_WAIT_V(6); PG8_BAR; PG8_MMA(1, 1, At, B1); PG8_BAR;
;         }
	s_waitcnt lgkmcnt(0)
	s_setprio 1
	s_waitcnt lgkmcnt(0)
	v_mfma_f32_16x16x32_bf16 v[60:63], v[152:155], v[168:171], v[60:63]
	v_mfma_f32_16x16x32_bf16 v[56:59], v[160:163], v[168:171], v[56:59]
	v_mfma_f32_16x16x32_bf16 v[44:47], v[152:155], v[178:181], v[44:47]
	v_mfma_f32_16x16x32_bf16 v[40:43], v[160:163], v[178:181], v[40:43]
	v_mfma_f32_16x16x32_bf16 v[28:31], v[152:155], v[186:189], v[28:31]
	v_mfma_f32_16x16x32_bf16 v[24:27], v[160:163], v[186:189], v[24:27]
	v_mfma_f32_16x16x32_bf16 v[16:19], v[152:155], v[194:197], v[16:19]
	v_mfma_f32_16x16x32_bf16 v[8:11], v[160:163], v[194:197], v[8:11]
	v_mfma_f32_16x16x32_bf16 v[60:63], v[156:159], v[172:175], v[60:63]
	v_mfma_f32_16x16x32_bf16 v[56:59], v[164:167], v[172:175], v[56:59]
	v_mfma_f32_16x16x32_bf16 v[44:47], v[156:159], v[182:185], v[44:47]
	v_mfma_f32_16x16x32_bf16 v[40:43], v[164:167], v[182:185], v[40:43]
	v_mfma_f32_16x16x32_bf16 v[28:31], v[156:159], v[190:193], v[28:31]
	v_mfma_f32_16x16x32_bf16 v[24:27], v[164:167], v[190:193], v[24:27]
	v_mfma_f32_16x16x32_bf16 v[16:19], v[156:159], v[198:201], v[16:19]
	v_mfma_f32_16x16x32_bf16 v[8:11], v[164:167], v[198:201], v[8:11]
	s_setprio 0
	s_barrier
	s_add_u32 s18, s18, 0x40080
	s_addc_u32 s19, s19, 0
	s_add_i32 s20, s20, s25
	v_lshl_add_u64 v[144:145], s[18:19], 0, v[132:133]
	s_mov_b32 m0, s20
	s_nop 0
	global_load_lds_dwordx4 v[144:145], off
	v_lshl_add_u64 v[144:145], s[18:19], 0, v[128:129]
	s_add_i32 m0, s20, 0x2000
	s_nop 0
	global_load_lds_dwordx4 v[144:145], off
	s_waitcnt vmcnt(6)
	s_barrier
	s_setprio 1
	v_mfma_f32_16x16x32_bf16 v[52:55], v[202:205], v[168:171], v[52:55]
	v_mfma_f32_16x16x32_bf16 v[48:51], v[210:213], v[168:171], v[48:51]
	v_mfma_f32_16x16x32_bf16 v[36:39], v[202:205], v[178:181], v[36:39]
	v_mfma_f32_16x16x32_bf16 v[32:35], v[210:213], v[178:181], v[32:35]
	v_mfma_f32_16x16x32_bf16 v[20:23], v[202:205], v[186:189], v[20:23]
	v_mfma_f32_16x16x32_bf16 v[12:15], v[210:213], v[186:189], v[12:15]
	v_mfma_f32_16x16x32_bf16 v[4:7], v[202:205], v[194:197], v[4:7]
	v_mfma_f32_16x16x32_bf16 v[0:3], v[210:213], v[194:197], v[0:3]
	v_mfma_f32_16x16x32_bf16 v[52:55], v[206:209], v[172:175], v[52:55]
	v_mfma_f32_16x16x32_bf16 v[48:51], v[214:217], v[172:175], v[48:51]
	v_mfma_f32_16x16x32_bf16 v[36:39], v[206:209], v[182:185], v[36:39]
	v_mfma_f32_16x16x32_bf16 v[32:35], v[214:217], v[182:185], v[32:35]
	v_mfma_f32_16x16x32_bf16 v[20:23], v[206:209], v[190:193], v[20:23]
	v_mfma_f32_16x16x32_bf16 v[12:15], v[214:217], v[190:193], v[12:15]
	v_mfma_f32_16x16x32_bf16 v[4:7], v[206:209], v[198:201], v[4:7]
	v_mfma_f32_16x16x32_bf16 v[0:3], v[214:217], v[198:201], v[0:3]
	s_setprio 0
	s_add_i32 s57, s57, 2
	s_add_u32 s16, s16, 0x100
	s_addc_u32 s17, s17, 0
	s_add_u32 s55, s55, 0x100
	s_addc_u32 s56, s56, 0
	s_cmp_gt_u32 s57, 13
	s_barrier
	s_cbranch_scc0 .LBB0_715
	v_lshl_add_u32 v144, s14, 8, v146
	v_ashrrev_i32_e32 v145, 31, v144
	v_readlane_b32 s54, v239, 46
	v_lshl_or_b32 v152, s52, 8, v148
	v_lshlrev_b64 v[144:145], 13, v[144:145]
	v_readlane_b32 s55, v239, 47
	v_ashrrev_i32_e32 v153, 31, v152
	s_mov_b32 s52, s6
	v_lshl_add_u64 v[144:145], s[54:55], 0, v[144:145]
	v_lshl_add_u64 v[144:145], v[152:153], 1, v[144:145]
	v_add_co_u32_e32 v164, vcc, 0x1000, v144
	global_load_dwordx4 v[152:155], v[144:145], off
	global_load_dwordx4 v[156:159], v[144:145], off offset:256
	v_addc_co_u32_e32 v165, vcc, 0, v145, vcc
	global_load_dwordx4 v[160:163], v[164:165], off
	s_nop 0
	global_load_dwordx4 v[164:167], v[164:165], off offset:256
	v_add_co_u32_e32 v178, vcc, s38, v144
	s_mov_b32 s14, s8
	s_nop 0
	v_addc_co_u32_e32 v179, vcc, 0, v145, vcc
	v_add_co_u32_e32 v186, vcc, s39, v144
	s_mov_b64 s[18:19], s[12:13]
	s_nop 0
	v_addc_co_u32_e32 v187, vcc, 0, v145, vcc
	global_load_dwordx4 v[168:171], v[186:187], off
	global_load_dwordx4 v[172:175], v[178:179], off
	s_nop 0
	global_load_dwordx4 v[178:181], v[178:179], off offset:256
	s_nop 0
	global_load_dwordx4 v[182:185], v[186:187], off offset:256
	v_add_co_u32_e32 v188, vcc, s40, v144
	s_mov_b64 s[16:17], s[10:11]
	s_nop 0
	v_addc_co_u32_e32 v189, vcc, 0, v145, vcc
	s_waitcnt vmcnt(0)
	v_lshlrev_b32_e32 v190, 16, v152
	v_and_b32_e32 v152, 0xffff0000, v152
	v_lshlrev_b32_e32 v191, 16, v153
	v_and_b32_e32 v153, 0xffff0000, v153
	v_lshlrev_b32_e32 v192, 16, v154
	v_and_b32_e32 v154, 0xffff0000, v154
	v_lshlrev_b32_e32 v193, 16, v155
	v_and_b32_e32 v155, 0xffff0000, v155
	v_lshlrev_b32_e32 v196, 16, v158
	v_and_b32_e32 v158, 0xffff0000, v158
	v_lshlrev_b32_e32 v197, 16, v159
	v_and_b32_e32 v159, 0xffff0000, v159
	v_lshlrev_b32_e32 v198, 16, v160
	v_and_b32_e32 v160, 0xffff0000, v160
	v_lshlrev_b32_e32 v199, 16, v161
	v_and_b32_e32 v161, 0xffff0000, v161
	v_lshlrev_b32_e32 v200, 16, v162
	v_and_b32_e32 v162, 0xffff0000, v162
	v_lshlrev_b32_e32 v201, 16, v163
	v_and_b32_e32 v163, 0xffff0000, v163
	v_lshlrev_b32_e32 v204, 16, v166
	v_and_b32_e32 v166, 0xffff0000, v166
	v_lshlrev_b32_e32 v205, 16, v167
	v_and_b32_e32 v167, 0xffff0000, v167
	v_lshlrev_b32_e32 v194, 16, v156
	v_and_b32_e32 v156, 0xffff0000, v156
	v_lshlrev_b32_e32 v195, 16, v157
	v_and_b32_e32 v157, 0xffff0000, v157
	v_lshlrev_b32_e32 v202, 16, v164
	v_and_b32_e32 v164, 0xffff0000, v164
	v_lshlrev_b32_e32 v203, 16, v165
	v_and_b32_e32 v165, 0xffff0000, v165
	v_fmac_f32_e32 v190, v124, v198
	v_fmac_f32_e32 v152, v125, v160
	v_fmac_f32_e32 v191, v126, v199
	v_fmac_f32_e32 v153, v127, v161
	v_fmac_f32_e32 v192, v120, v200
	v_fmac_f32_e32 v154, v121, v162
	v_fmac_f32_e32 v193, v122, v201
	v_fmac_f32_e32 v155, v123, v163
	v_fmac_f32_e32 v196, v112, v204
	v_fmac_f32_e32 v158, v113, v166
	v_fmac_f32_e32 v197, v114, v205
;     __device__ __forceinline__ void operator()(const f32x4 (&acc)[2][2][4][2], const Unit& u, int wr, int wc, int fr, int fq) const {
;         const int row0 = u.pm * BM + wr * 64 + fr, col0 = u.pn * BM + wc * 32 + 8 * fq;
;         bf16_t* base = G + (size_t)row0 * NGATE + col0;
;         u32x4 ga[2], gb[2], na[2], nb[2];
; #pragma unroll
;         for (int bj = 0; bj < 2; ++bj) { ga[bj] = *(const u32x4*)(base + bj * HALF); if (STEP == 1) gb[bj] = *(const u32x4*)(base + bj * HALF + DM); }
; #pragma unroll
;         for (int g = 0; g < 8; ++g) {
;             const int ai = g >> 2, m = g & 3;
;             bf16_t* rowp = base + (size_t)(ai * HALF + m * 16) * NGATE;
;             if (g < 7) { const bf16_t* nrow = base + (size_t)(((g + 1) >> 2) * HALF + ((g + 1) & 3) * 16) * NGATE;
; #pragma unroll
;                 for (int bj = 0; bj < 2; ++bj) { na[bj] = *(const u32x4*)(nrow + bj * HALF); if (STEP == 1) nb[bj] = *(const u32x4*)(nrow + bj * HALF + DM); } }
; #pragma unroll
;             for (int bj = 0; bj < 2; ++bj) {
;                 const f32x4 a0 = acc[ai][bj][m][0], a1 = acc[ai][bj][m][1];
;                 float v[8];
;                 if (STEP == 0) {
;                     v[0] = bf_lo(ga[bj].x) * a0[0]; v[1] = bf_hi(ga[bj].x) * a0[1]; v[2] = bf_lo(ga[bj].y) * a0[2]; v[3] = bf_hi(ga[bj].y) * a0[3];
;                     v[4] = bf_lo(ga[bj].z) * a1[0]; v[5] = bf_hi(ga[bj].z) * a1[1]; v[6] = bf_lo(ga[bj].w) * a1[2]; v[7] = bf_hi(ga[bj].w) * a1[3];
;                 } else {
;                     v[0] = bf_lo(ga[bj].x) + bf_lo(gb[bj].x) * a0[0]; v[1] = bf_hi(ga[bj].x) + bf_hi(gb[bj].x) * a0[1]; v[2] = bf_lo(ga[bj].y) + bf_lo(gb[bj].y) * a0[2]; v[3] = bf_hi(ga[bj].y) + bf_hi(gb[bj].y) * a0[3];
;                     v[4] = bf_lo(ga[bj].z) + bf_lo(gb[bj].z) * a1[0]; v[5] = bf_hi(ga[bj].z) + bf_hi(gb[bj].z) * a1[1]; v[6] = bf_lo(ga[bj].w) + bf_lo(gb[bj].w) * a1[2]; v[7] = bf_hi(ga[bj].w) + bf_hi(gb[bj].w) * a1[3];
;                 }
;                 u32x4 w; w.x = cvt_pk_bf16(v[0], v[1]); w.y = cvt_pk_bf16(v[2], v[3]); w.z = cvt_pk_bf16(v[4], v[5]); w.w = cvt_pk_bf16(v[6], v[7]);
;                 *(u32x4*)(rowp + bj * HALF) = w;
;             }
;             asm volatile("" ::: "memory");
; #pragma unroll
;             for (int bj = 0; bj < 2; ++bj) { ga[bj] = na[bj]; if (STEP == 1) gb[bj] = nb[bj]; }
;         }
	v_fmac_f32_e32 v159, v115, v167
	v_cvt_pk_bf16_f32 v112, v190, v152
	v_cvt_pk_bf16_f32 v113, v191, v153
	v_cvt_pk_bf16_f32 v114, v192, v154
	v_cvt_pk_bf16_f32 v115, v193, v155
	v_fmac_f32_e32 v194, v116, v202
	v_fmac_f32_e32 v156, v117, v164
	v_fmac_f32_e32 v195, v118, v203
	v_fmac_f32_e32 v157, v119, v165
	global_store_dwordx4 v[144:145], v[112:115], off sc0 sc1
	v_add_co_u32_e32 v152, vcc, s41, v144
	s_nop 0
	v_cvt_pk_bf16_f32 v112, v194, v156
	v_cvt_pk_bf16_f32 v113, v195, v157
	v_cvt_pk_bf16_f32 v114, v196, v158
	v_cvt_pk_bf16_f32 v115, v197, v159
	global_store_dwordx4 v[144:145], v[112:115], off offset:256 sc0 sc1
	v_lshlrev_b32_e32 v154, 16, v168
	v_lshlrev_b32_e32 v155, 16, v172
	v_addc_co_u32_e32 v153, vcc, 0, v145, vcc
	v_fmac_f32_e32 v154, v108, v155
	v_and_b32_e32 v108, 0xffff0000, v168
	v_and_b32_e32 v155, 0xffff0000, v172
	global_load_dwordx4 v[112:115], v[152:153], off
	global_load_dwordx4 v[116:119], v[188:189], off
	global_load_dwordx4 v[120:123], v[188:189], off offset:256
	global_load_dwordx4 v[124:127], v[152:153], off offset:256
	v_fmac_f32_e32 v108, v109, v155
	v_lshlrev_b32_e32 v109, 16, v169
	v_lshlrev_b32_e32 v155, 16, v173
	v_fmac_f32_e32 v109, v110, v155
	v_and_b32_e32 v110, 0xffff0000, v169
	v_and_b32_e32 v155, 0xffff0000, v173
	v_fmac_f32_e32 v110, v111, v155
	v_lshlrev_b32_e32 v111, 16, v170
	v_lshlrev_b32_e32 v155, 16, v174
	v_fmac_f32_e32 v111, v104, v155
	v_and_b32_e32 v155, 0xffff0000, v170
	v_and_b32_e32 v104, 0xffff0000, v174
	v_fmac_f32_e32 v155, v105, v104
	v_lshlrev_b32_e32 v156, 16, v171
	v_lshlrev_b32_e32 v104, 16, v175
	v_fmac_f32_e32 v156, v106, v104
	v_and_b32_e32 v157, 0xffff0000, v171
	v_and_b32_e32 v104, 0xffff0000, v175
	v_fmac_f32_e32 v157, v107, v104
	v_cvt_pk_bf16_f32 v104, v154, v108
	v_cvt_pk_bf16_f32 v105, v109, v110
	v_cvt_pk_bf16_f32 v106, v111, v155
	v_cvt_pk_bf16_f32 v107, v156, v157
	global_store_dwordx4 v[186:187], v[104:107], off sc0 sc1
	s_waitcnt vmcnt(0)
	v_lshlrev_b32_e32 v156, 16, v112
	v_lshlrev_b32_e32 v104, 16, v182
	v_lshlrev_b32_e32 v105, 16, v178
	v_fmac_f32_e32 v104, v100, v105
	v_and_b32_e32 v100, 0xffff0000, v182
	v_and_b32_e32 v105, 0xffff0000, v178
	v_fmac_f32_e32 v100, v101, v105
	v_lshlrev_b32_e32 v101, 16, v183
	v_lshlrev_b32_e32 v105, 16, v179
	v_fmac_f32_e32 v101, v102, v105
	v_and_b32_e32 v102, 0xffff0000, v183
	v_and_b32_e32 v105, 0xffff0000, v179
	v_fmac_f32_e32 v102, v103, v105
	v_lshlrev_b32_e32 v103, 16, v184
	v_lshlrev_b32_e32 v105, 16, v180
	v_fmac_f32_e32 v103, v96, v105
	v_and_b32_e32 v105, 0xffff0000, v184
	v_and_b32_e32 v96, 0xffff0000, v180
	v_fmac_f32_e32 v105, v97, v96
	v_lshlrev_b32_e32 v106, 16, v185
	v_lshlrev_b32_e32 v96, 16, v181
	v_fmac_f32_e32 v106, v98, v96
	v_and_b32_e32 v107, 0xffff0000, v185
	v_and_b32_e32 v96, 0xffff0000, v181
	v_fmac_f32_e32 v107, v99, v96
	v_cvt_pk_bf16_f32 v96, v104, v100
	v_add_co_u32_e32 v104, vcc, s42, v144
	v_cvt_pk_bf16_f32 v97, v101, v102
	v_cvt_pk_bf16_f32 v98, v103, v105
	v_cvt_pk_bf16_f32 v99, v106, v107
	global_store_dwordx4 v[186:187], v[96:99], off offset:256 sc0 sc1
	s_nop 0
	v_addc_co_u32_e32 v105, vcc, 0, v145, vcc
	v_add_co_u32_e32 v154, vcc, s43, v144
	v_lshlrev_b32_e32 v157, 16, v116
	s_nop 0
	v_addc_co_u32_e32 v155, vcc, 0, v145, vcc
	global_load_dwordx4 v[96:99], v[154:155], off
	global_load_dwordx4 v[100:103], v[104:105], off
	s_nop 0
	global_load_dwordx4 v[104:107], v[104:105], off offset:256
	s_nop 0
	global_load_dwordx4 v[108:111], v[154:155], off offset:256
	v_fmac_f32_e32 v156, v92, v157
	v_and_b32_e32 v92, 0xffff0000, v112
	v_and_b32_e32 v112, 0xffff0000, v116
	v_fmac_f32_e32 v92, v93, v112
	v_lshlrev_b32_e32 v93, 16, v113
	v_lshlrev_b32_e32 v112, 16, v117
	v_fmac_f32_e32 v93, v94, v112
	v_and_b32_e32 v94, 0xffff0000, v113
	v_and_b32_e32 v112, 0xffff0000, v117
	v_fmac_f32_e32 v94, v95, v112
	v_lshlrev_b32_e32 v95, 16, v114
	v_lshlrev_b32_e32 v112, 16, v118
	v_fmac_f32_e32 v95, v88, v112
	v_and_b32_e32 v112, 0xffff0000, v114
	v_and_b32_e32 v88, 0xffff0000, v118
	v_fmac_f32_e32 v112, v89, v88
	v_lshlrev_b32_e32 v113, 16, v115
	v_lshlrev_b32_e32 v88, 16, v119
	v_fmac_f32_e32 v113, v90, v88
	v_and_b32_e32 v114, 0xffff0000, v115
	v_and_b32_e32 v88, 0xffff0000, v119
	v_fmac_f32_e32 v114, v91, v88
	v_cvt_pk_bf16_f32 v88, v156, v92
	v_cvt_pk_bf16_f32 v89, v93, v94
	v_cvt_pk_bf16_f32 v90, v95, v112
	v_cvt_pk_bf16_f32 v91, v113, v114
	global_store_dwordx4 v[152:153], v[88:91], off sc0 sc1
	s_waitcnt vmcnt(0)
	v_lshlrev_b32_e32 v114, 16, v96
	v_lshlrev_b32_e32 v88, 16, v124
	v_lshlrev_b32_e32 v89, 16, v120
	v_fmac_f32_e32 v88, v84, v89
	v_and_b32_e32 v84, 0xffff0000, v124
	v_and_b32_e32 v89, 0xffff0000, v120
	v_fmac_f32_e32 v84, v85, v89
	v_lshlrev_b32_e32 v85, 16, v125
	v_lshlrev_b32_e32 v89, 16, v121
	v_fmac_f32_e32 v85, v86, v89
	v_and_b32_e32 v86, 0xffff0000, v125
	v_and_b32_e32 v89, 0xffff0000, v121
	v_fmac_f32_e32 v86, v87, v89
	v_lshlrev_b32_e32 v87, 16, v126
	v_lshlrev_b32_e32 v89, 16, v122
	v_fmac_f32_e32 v87, v80, v89
	v_and_b32_e32 v89, 0xffff0000, v126
	v_and_b32_e32 v80, 0xffff0000, v122
	v_fmac_f32_e32 v89, v81, v80
	v_lshlrev_b32_e32 v90, 16, v127
	v_lshlrev_b32_e32 v80, 16, v123
	v_fmac_f32_e32 v90, v82, v80
	v_and_b32_e32 v91, 0xffff0000, v127
	v_and_b32_e32 v80, 0xffff0000, v123
	v_fmac_f32_e32 v91, v83, v80
	v_cvt_pk_bf16_f32 v80, v88, v84
	v_add_co_u32_e32 v88, vcc, s44, v144
	v_cvt_pk_bf16_f32 v81, v85, v86
	v_cvt_pk_bf16_f32 v82, v87, v89
	v_cvt_pk_bf16_f32 v83, v90, v91
	global_store_dwordx4 v[152:153], v[80:83], off offset:256 sc0 sc1
	s_nop 0
	v_addc_co_u32_e32 v89, vcc, 0, v145, vcc
	v_add_co_u32_e32 v112, vcc, s45, v144
	v_lshlrev_b32_e32 v115, 16, v100
	s_nop 0
	v_addc_co_u32_e32 v113, vcc, 0, v145, vcc
	v_fmac_f32_e32 v114, v76, v115
	v_and_b32_e32 v76, 0xffff0000, v96
	v_and_b32_e32 v96, 0xffff0000, v100
	global_load_dwordx4 v[80:83], v[112:113], off
	global_load_dwordx4 v[84:87], v[88:89], off
	s_nop 0
	global_load_dwordx4 v[88:91], v[88:89], off offset:256
	s_nop 0
	global_load_dwordx4 v[92:95], v[112:113], off offset:256
	v_fmac_f32_e32 v76, v77, v96
	v_lshlrev_b32_e32 v77, 16, v97
	v_lshlrev_b32_e32 v96, 16, v101
	v_fmac_f32_e32 v77, v78, v96
	v_and_b32_e32 v78, 0xffff0000, v97
	v_and_b32_e32 v96, 0xffff0000, v101
	v_fmac_f32_e32 v78, v79, v96
	v_lshlrev_b32_e32 v79, 16, v98
	v_lshlrev_b32_e32 v96, 16, v102
	v_fmac_f32_e32 v79, v72, v96
	v_and_b32_e32 v96, 0xffff0000, v98
	v_and_b32_e32 v72, 0xffff0000, v102
	v_fmac_f32_e32 v96, v73, v72
	v_lshlrev_b32_e32 v97, 16, v99
	v_lshlrev_b32_e32 v72, 16, v103
	v_fmac_f32_e32 v97, v74, v72
	v_and_b32_e32 v98, 0xffff0000, v99
	v_and_b32_e32 v72, 0xffff0000, v103
	v_fmac_f32_e32 v98, v75, v72
	v_cvt_pk_bf16_f32 v72, v114, v76
	v_cvt_pk_bf16_f32 v73, v77, v78
	v_cvt_pk_bf16_f32 v74, v79, v96
	v_cvt_pk_bf16_f32 v75, v97, v98
	global_store_dwordx4 v[154:155], v[72:75], off sc0 sc1
	s_waitcnt vmcnt(0)
;     __device__ __forceinline__ void operator()(const f32x4 (&acc)[2][2][4][2], const Unit& u, int wr, int wc, int fr, int fq) const {
;         const int row0 = u.pm * BM + wr * 64 + fr, col0 = u.pn * BM + wc * 32 + 8 * fq;
;         bf16_t* base = G + (size_t)row0 * NGATE + col0;
;         u32x4 ga[2], gb[2], na[2], nb[2];
; #pragma unroll
;         for (int bj = 0; bj < 2; ++bj) { ga[bj] = *(const u32x4*)(base + bj * HALF); if (STEP == 1) gb[bj] = *(const u32x4*)(base + bj * HALF + DM); }
; #pragma unroll
;         for (int g = 0; g < 8; ++g) {
;             const int ai = g >> 2, m = g & 3;
;             bf16_t* rowp = base + (size_t)(ai * HALF + m * 16) * NGATE;
;             if (g < 7) { const bf16_t* nrow = base + (size_t)(((g + 1) >> 2) * HALF + ((g + 1) & 3) * 16) * NGATE;
; #pragma unroll
;                 for (int bj = 0; bj < 2; ++bj) { na[bj] = *(const u32x4*)(nrow + bj * HALF); if (STEP == 1) nb[bj] = *(const u32x4*)(nrow + bj * HALF + DM); } }
; #pragma unroll
;             for (int bj = 0; bj < 2; ++bj) {
;                 const f32x4 a0 = acc[ai][bj][m][0], a1 = acc[ai][bj][m][1];
;                 float v[8];
;                 if (STEP == 0) {
;                     v[0] = bf_lo(ga[bj].x) * a0[0]; v[1] = bf_hi(ga[bj].x) * a0[1]; v[2] = bf_lo(ga[bj].y) * a0[2]; v[3] = bf_hi(ga[bj].y) * a0[3];
;                     v[4] = bf_lo(ga[bj].z) * a1[0]; v[5] = bf_hi(ga[bj].z) * a1[1]; v[6] = bf_lo(ga[bj].w) * a1[2]; v[7] = bf_hi(ga[bj].w) * a1[3];
;                 } else {
;                     v[0] = bf_lo(ga[bj].x) + bf_lo(gb[bj].x) * a0[0]; v[1] = bf_hi(ga[bj].x) + bf_hi(gb[bj].x) * a0[1]; v[2] = bf_lo(ga[bj].y) + bf_lo(gb[bj].y) * a0[2]; v[3] = bf_hi(ga[bj].y) + bf_hi(gb[bj].y) * a0[3];
;                     v[4] = bf_lo(ga[bj].z) + bf_lo(gb[bj].z) * a1[0]; v[5] = bf_hi(ga[bj].z) + bf_hi(gb[bj].z) * a1[1]; v[6] = bf_lo(ga[bj].w) + bf_lo(gb[bj].w) * a1[2]; v[7] = bf_hi(ga[bj].w) + bf_hi(gb[bj].w) * a1[3];
;                 }
;                 u32x4 w; w.x = cvt_pk_bf16(v[0], v[1]); w.y = cvt_pk_bf16(v[2], v[3]); w.z = cvt_pk_bf16(v[4], v[5]); w.w = cvt_pk_bf16(v[6], v[7]);
;                 *(u32x4*)(rowp + bj * HALF) = w;
;             }
;             asm volatile("" ::: "memory");
; #pragma unroll
;             for (int bj = 0; bj < 2; ++bj) { ga[bj] = na[bj]; if (STEP == 1) gb[bj] = nb[bj]; }
;         }
	v_lshlrev_b32_e32 v98, 16, v80
	v_lshlrev_b32_e32 v72, 16, v108
	v_lshlrev_b32_e32 v73, 16, v104
	v_fmac_f32_e32 v72, v68, v73
	v_and_b32_e32 v68, 0xffff0000, v108
	v_and_b32_e32 v73, 0xffff0000, v104
	v_fmac_f32_e32 v68, v69, v73
	v_lshlrev_b32_e32 v69, 16, v109
	v_lshlrev_b32_e32 v73, 16, v105
	v_fmac_f32_e32 v69, v70, v73
	v_and_b32_e32 v70, 0xffff0000, v109
	v_and_b32_e32 v73, 0xffff0000, v105
	v_fmac_f32_e32 v70, v71, v73
	v_lshlrev_b32_e32 v71, 16, v110
	v_lshlrev_b32_e32 v73, 16, v106
	v_fmac_f32_e32 v71, v64, v73
	v_and_b32_e32 v73, 0xffff0000, v110
	v_and_b32_e32 v64, 0xffff0000, v106
	v_fmac_f32_e32 v73, v65, v64
	v_lshlrev_b32_e32 v74, 16, v111
	v_lshlrev_b32_e32 v64, 16, v107
	v_fmac_f32_e32 v74, v66, v64
	v_and_b32_e32 v75, 0xffff0000, v111
	v_and_b32_e32 v64, 0xffff0000, v107
	v_fmac_f32_e32 v75, v67, v64
	v_cvt_pk_bf16_f32 v64, v72, v68
	v_add_co_u32_e32 v72, vcc, s46, v144
	v_cvt_pk_bf16_f32 v65, v69, v70
	v_cvt_pk_bf16_f32 v66, v71, v73
	v_cvt_pk_bf16_f32 v67, v74, v75
	global_store_dwordx4 v[154:155], v[64:67], off offset:256 sc0 sc1
	s_nop 0
	v_addc_co_u32_e32 v73, vcc, 0, v145, vcc
	v_add_co_u32_e32 v96, vcc, s47, v144
	v_lshlrev_b32_e32 v99, 16, v84
	s_nop 0
	v_addc_co_u32_e32 v97, vcc, 0, v145, vcc
	global_load_dwordx4 v[64:67], v[96:97], off
	global_load_dwordx4 v[68:71], v[72:73], off
	s_nop 0
	global_load_dwordx4 v[72:75], v[72:73], off offset:256
	s_nop 0
	global_load_dwordx4 v[76:79], v[96:97], off offset:256
	v_fmac_f32_e32 v98, v60, v99
	v_and_b32_e32 v60, 0xffff0000, v80
	v_and_b32_e32 v80, 0xffff0000, v84
	v_fmac_f32_e32 v60, v61, v80
	v_lshlrev_b32_e32 v61, 16, v81
	v_lshlrev_b32_e32 v80, 16, v85
	v_fmac_f32_e32 v61, v62, v80
	v_and_b32_e32 v62, 0xffff0000, v81
	v_and_b32_e32 v80, 0xffff0000, v85
	v_fmac_f32_e32 v62, v63, v80
	v_lshlrev_b32_e32 v63, 16, v82
	v_lshlrev_b32_e32 v80, 16, v86
	v_fmac_f32_e32 v63, v56, v80
	v_and_b32_e32 v80, 0xffff0000, v82
	v_and_b32_e32 v56, 0xffff0000, v86
	v_fmac_f32_e32 v80, v57, v56
	v_lshlrev_b32_e32 v81, 16, v83
	v_lshlrev_b32_e32 v56, 16, v87
	v_fmac_f32_e32 v81, v58, v56
	v_and_b32_e32 v82, 0xffff0000, v83
	v_and_b32_e32 v56, 0xffff0000, v87
	v_fmac_f32_e32 v82, v59, v56
	v_cvt_pk_bf16_f32 v56, v98, v60
	v_cvt_pk_bf16_f32 v57, v61, v62
	v_cvt_pk_bf16_f32 v58, v63, v80
	v_cvt_pk_bf16_f32 v59, v81, v82
	global_store_dwordx4 v[112:113], v[56:59], off sc0 sc1
	s_waitcnt vmcnt(0)
	v_lshlrev_b32_e32 v82, 16, v64
	v_lshlrev_b32_e32 v56, 16, v92
	v_lshlrev_b32_e32 v57, 16, v88
	v_fmac_f32_e32 v56, v52, v57
	v_and_b32_e32 v52, 0xffff0000, v92
	v_and_b32_e32 v57, 0xffff0000, v88
	v_fmac_f32_e32 v52, v53, v57
	v_lshlrev_b32_e32 v53, 16, v93
	v_lshlrev_b32_e32 v57, 16, v89
	v_fmac_f32_e32 v53, v54, v57
	v_and_b32_e32 v54, 0xffff0000, v93
	v_and_b32_e32 v57, 0xffff0000, v89
	v_fmac_f32_e32 v54, v55, v57
	v_lshlrev_b32_e32 v55, 16, v94
	v_lshlrev_b32_e32 v57, 16, v90
	v_fmac_f32_e32 v55, v48, v57
	v_and_b32_e32 v57, 0xffff0000, v94
	v_and_b32_e32 v48, 0xffff0000, v90
	v_fmac_f32_e32 v57, v49, v48
	v_lshlrev_b32_e32 v58, 16, v95
	v_lshlrev_b32_e32 v48, 16, v91
	v_fmac_f32_e32 v58, v50, v48
	v_and_b32_e32 v59, 0xffff0000, v95
	v_and_b32_e32 v48, 0xffff0000, v91
	v_fmac_f32_e32 v59, v51, v48
	v_cvt_pk_bf16_f32 v48, v56, v52
	v_add_co_u32_e32 v52, vcc, s48, v144
	v_cvt_pk_bf16_f32 v49, v53, v54
	v_cvt_pk_bf16_f32 v50, v55, v57
	v_cvt_pk_bf16_f32 v51, v58, v59
	global_store_dwordx4 v[112:113], v[48:51], off offset:256 sc0 sc1
	s_nop 0
	v_addc_co_u32_e32 v53, vcc, 0, v145, vcc
	v_add_co_u32_e32 v80, vcc, s49, v144
	v_lshlrev_b32_e32 v83, 16, v68
	s_nop 0
	v_addc_co_u32_e32 v81, vcc, 0, v145, vcc
	global_load_dwordx4 v[48:51], v[52:53], off offset:256
	s_nop 0
	global_load_dwordx4 v[52:55], v[52:53], off
	s_nop 0
	global_load_dwordx4 v[56:59], v[80:81], off offset:256
	global_load_dwordx4 v[60:63], v[80:81], off
	v_fmac_f32_e32 v82, v44, v83
	v_and_b32_e32 v44, 0xffff0000, v64
	v_and_b32_e32 v64, 0xffff0000, v68
	v_fmac_f32_e32 v44, v45, v64
	v_lshlrev_b32_e32 v45, 16, v65
	v_lshlrev_b32_e32 v64, 16, v69
	v_fmac_f32_e32 v45, v46, v64
	v_and_b32_e32 v46, 0xffff0000, v65
	v_and_b32_e32 v64, 0xffff0000, v69
	v_fmac_f32_e32 v46, v47, v64
	v_lshlrev_b32_e32 v47, 16, v66
	v_lshlrev_b32_e32 v64, 16, v70
	v_fmac_f32_e32 v47, v40, v64
	v_and_b32_e32 v64, 0xffff0000, v66
	v_and_b32_e32 v40, 0xffff0000, v70
	v_fmac_f32_e32 v64, v41, v40
	v_lshlrev_b32_e32 v65, 16, v67
	v_lshlrev_b32_e32 v40, 16, v71
	v_fmac_f32_e32 v65, v42, v40
	v_and_b32_e32 v66, 0xffff0000, v67
	v_and_b32_e32 v40, 0xffff0000, v71
	v_fmac_f32_e32 v66, v43, v40
	v_cvt_pk_bf16_f32 v40, v82, v44
	v_cvt_pk_bf16_f32 v41, v45, v46
	v_cvt_pk_bf16_f32 v42, v47, v64
	v_cvt_pk_bf16_f32 v43, v65, v66
	global_store_dwordx4 v[96:97], v[40:43], off sc0 sc1
	s_waitcnt vmcnt(0)
;     __device__ __forceinline__ void operator()(const f32x4 (&acc)[2][2][4][2], const Unit& u, int wr, int wc, int fr, int fq) const {
;         const int row0 = u.pm * BM + wr * 64 + fr, col0 = u.pn * BM + wc * 32 + 8 * fq;
;         bf16_t* base = G + (size_t)row0 * NGATE + col0;
;         u32x4 ga[2], gb[2], na[2], nb[2];
; #pragma unroll
;         for (int bj = 0; bj < 2; ++bj) { ga[bj] = *(const u32x4*)(base + bj * HALF); if (STEP == 1) gb[bj] = *(const u32x4*)(base + bj * HALF + DM); }
; #pragma unroll
;         for (int g = 0; g < 8; ++g) {
;             const int ai = g >> 2, m = g & 3;
;             bf16_t* rowp = base + (size_t)(ai * HALF + m * 16) * NGATE;
;             if (g < 7) { const bf16_t* nrow = base + (size_t)(((g + 1) >> 2) * HALF + ((g + 1) & 3) * 16) * NGATE;
; #pragma unroll
;                 for (int bj = 0; bj < 2; ++bj) { na[bj] = *(const u32x4*)(nrow + bj * HALF); if (STEP == 1) nb[bj] = *(const u32x4*)(nrow + bj * HALF + DM); } }
; #pragma unroll
;             for (int bj = 0; bj < 2; ++bj) {
;                 const f32x4 a0 = acc[ai][bj][m][0], a1 = acc[ai][bj][m][1];
;                 float v[8];
;                 if (STEP == 0) {
;                     v[0] = bf_lo(ga[bj].x) * a0[0]; v[1] = bf_hi(ga[bj].x) * a0[1]; v[2] = bf_lo(ga[bj].y) * a0[2]; v[3] = bf_hi(ga[bj].y) * a0[3];
;                     v[4] = bf_lo(ga[bj].z) * a1[0]; v[5] = bf_hi(ga[bj].z) * a1[1]; v[6] = bf_lo(ga[bj].w) * a1[2]; v[7] = bf_hi(ga[bj].w) * a1[3];
;                 } else {
;                     v[0] = bf_lo(ga[bj].x) + bf_lo(gb[bj].x) * a0[0]; v[1] = bf_hi(ga[bj].x) + bf_hi(gb[bj].x) * a0[1]; v[2] = bf_lo(ga[bj].y) + bf_lo(gb[bj].y) * a0[2]; v[3] = bf_hi(ga[bj].y) + bf_hi(gb[bj].y) * a0[3];
;                     v[4] = bf_lo(ga[bj].z) + bf_lo(gb[bj].z) * a1[0]; v[5] = bf_hi(ga[bj].z) + bf_hi(gb[bj].z) * a1[1]; v[6] = bf_lo(ga[bj].w) + bf_lo(gb[bj].w) * a1[2]; v[7] = bf_hi(ga[bj].w) + bf_hi(gb[bj].w) * a1[3];
;                 }
;                 u32x4 w; w.x = cvt_pk_bf16(v[0], v[1]); w.y = cvt_pk_bf16(v[2], v[3]); w.z = cvt_pk_bf16(v[4], v[5]); w.w = cvt_pk_bf16(v[6], v[7]);
;                 *(u32x4*)(rowp + bj * HALF) = w;
;             }
;             asm volatile("" ::: "memory");
; #pragma unroll
;             for (int bj = 0; bj < 2; ++bj) { ga[bj] = na[bj]; if (STEP == 1) gb[bj] = nb[bj]; }
;         }
	v_lshlrev_b32_e32 v67, 16, v52
	v_lshlrev_b32_e32 v40, 16, v76
	v_lshlrev_b32_e32 v41, 16, v72
	v_fmac_f32_e32 v40, v36, v41
	v_and_b32_e32 v36, 0xffff0000, v76
	v_and_b32_e32 v41, 0xffff0000, v72
	v_fmac_f32_e32 v36, v37, v41
	v_lshlrev_b32_e32 v37, 16, v77
	v_lshlrev_b32_e32 v41, 16, v73
	v_fmac_f32_e32 v37, v38, v41
	v_and_b32_e32 v38, 0xffff0000, v77
	v_and_b32_e32 v41, 0xffff0000, v73
	v_fmac_f32_e32 v38, v39, v41
	v_lshlrev_b32_e32 v39, 16, v78
	v_lshlrev_b32_e32 v41, 16, v74
	v_fmac_f32_e32 v39, v32, v41
	v_and_b32_e32 v41, 0xffff0000, v78
	v_and_b32_e32 v32, 0xffff0000, v74
	v_fmac_f32_e32 v41, v33, v32
	v_lshlrev_b32_e32 v42, 16, v79
	v_lshlrev_b32_e32 v32, 16, v75
	v_fmac_f32_e32 v42, v34, v32
	v_and_b32_e32 v43, 0xffff0000, v79
	v_and_b32_e32 v32, 0xffff0000, v75
	v_fmac_f32_e32 v43, v35, v32
	v_cvt_pk_bf16_f32 v32, v40, v36
	v_add_co_u32_e32 v40, vcc, s50, v144
	v_cvt_pk_bf16_f32 v33, v37, v38
	v_cvt_pk_bf16_f32 v34, v39, v41
	v_cvt_pk_bf16_f32 v35, v42, v43
	global_store_dwordx4 v[96:97], v[32:35], off offset:256 sc0 sc1
	s_nop 0
	v_addc_co_u32_e32 v41, vcc, 0, v145, vcc
	v_add_co_u32_e32 v64, vcc, s51, v144
	v_lshlrev_b32_e32 v66, 16, v60
	s_nop 0
	v_addc_co_u32_e32 v65, vcc, 0, v145, vcc
	global_load_dwordx4 v[32:35], v[64:65], off
	global_load_dwordx4 v[36:39], v[40:41], off
	s_nop 0
	global_load_dwordx4 v[40:43], v[40:41], off offset:256
	s_nop 0
	global_load_dwordx4 v[44:47], v[64:65], off offset:256
	v_fmac_f32_e32 v66, v28, v67
	v_and_b32_e32 v28, 0xffff0000, v60
	v_and_b32_e32 v52, 0xffff0000, v52
	v_fmac_f32_e32 v28, v29, v52
	v_lshlrev_b32_e32 v29, 16, v61
	v_lshlrev_b32_e32 v52, 16, v53
	v_fmac_f32_e32 v29, v30, v52
	v_and_b32_e32 v30, 0xffff0000, v61
	v_and_b32_e32 v52, 0xffff0000, v53
	v_fmac_f32_e32 v30, v31, v52
	v_lshlrev_b32_e32 v31, 16, v62
	v_lshlrev_b32_e32 v52, 16, v54
	v_fmac_f32_e32 v31, v24, v52
	v_and_b32_e32 v52, 0xffff0000, v62
	v_and_b32_e32 v24, 0xffff0000, v54
	v_fmac_f32_e32 v52, v25, v24
	v_lshlrev_b32_e32 v53, 16, v63
	v_lshlrev_b32_e32 v24, 16, v55
	v_fmac_f32_e32 v53, v26, v24
	v_and_b32_e32 v54, 0xffff0000, v63
	v_and_b32_e32 v24, 0xffff0000, v55
	v_fmac_f32_e32 v54, v27, v24
	v_cvt_pk_bf16_f32 v24, v66, v28
	v_cvt_pk_bf16_f32 v25, v29, v30
	v_cvt_pk_bf16_f32 v26, v31, v52
	v_cvt_pk_bf16_f32 v27, v53, v54
	global_store_dwordx4 v[80:81], v[24:27], off sc0 sc1
	s_and_b64 vcc, exec, s[0:1]
	s_nop 0
	v_lshlrev_b32_e32 v24, 16, v56
	v_lshlrev_b32_e32 v25, 16, v48
	v_fmac_f32_e32 v24, v20, v25
	v_and_b32_e32 v20, 0xffff0000, v56
	v_and_b32_e32 v25, 0xffff0000, v48
	v_fmac_f32_e32 v20, v21, v25
	v_lshlrev_b32_e32 v21, 16, v57
	v_lshlrev_b32_e32 v25, 16, v49
	v_fmac_f32_e32 v21, v22, v25
	v_and_b32_e32 v22, 0xffff0000, v57
	v_and_b32_e32 v25, 0xffff0000, v49
	v_fmac_f32_e32 v22, v23, v25
	v_lshlrev_b32_e32 v23, 16, v58
	v_lshlrev_b32_e32 v25, 16, v50
	v_fmac_f32_e32 v23, v12, v25
	v_and_b32_e32 v25, 0xffff0000, v58
	v_and_b32_e32 v12, 0xffff0000, v50
	v_fmac_f32_e32 v25, v13, v12
	v_lshlrev_b32_e32 v26, 16, v59
	v_lshlrev_b32_e32 v12, 16, v51
	v_fmac_f32_e32 v26, v14, v12
	v_and_b32_e32 v27, 0xffff0000, v59
	v_and_b32_e32 v12, 0xffff0000, v51
	v_fmac_f32_e32 v27, v15, v12
	v_cvt_pk_bf16_f32 v12, v24, v20
	v_cvt_pk_bf16_f32 v13, v21, v22
	v_cvt_pk_bf16_f32 v14, v23, v25
	v_cvt_pk_bf16_f32 v15, v26, v27
	global_store_dwordx4 v[80:81], v[12:15], off offset:256 sc0 sc1
	s_waitcnt vmcnt(0)
	s_nop 0
	v_lshlrev_b32_e32 v12, 16, v32
	v_lshlrev_b32_e32 v13, 16, v36
	v_fmac_f32_e32 v12, v16, v13
	v_and_b32_e32 v13, 0xffff0000, v32
	v_and_b32_e32 v14, 0xffff0000, v36
	v_fmac_f32_e32 v13, v17, v14
	v_lshlrev_b32_e32 v14, 16, v33
	v_lshlrev_b32_e32 v15, 16, v37
	v_fmac_f32_e32 v14, v18, v15
	v_and_b32_e32 v15, 0xffff0000, v33
	v_and_b32_e32 v16, 0xffff0000, v37
	v_fmac_f32_e32 v15, v19, v16
	v_lshlrev_b32_e32 v16, 16, v34
	v_lshlrev_b32_e32 v17, 16, v38
	v_fmac_f32_e32 v16, v8, v17
	v_and_b32_e32 v17, 0xffff0000, v34
	v_and_b32_e32 v8, 0xffff0000, v38
	v_fmac_f32_e32 v17, v9, v8
	v_lshlrev_b32_e32 v18, 16, v35
	v_lshlrev_b32_e32 v8, 16, v39
	v_fmac_f32_e32 v18, v10, v8
	v_and_b32_e32 v19, 0xffff0000, v35
	v_and_b32_e32 v8, 0xffff0000, v39
	v_fmac_f32_e32 v19, v11, v8
	v_cvt_pk_bf16_f32 v8, v12, v13
	v_cvt_pk_bf16_f32 v9, v14, v15
	v_cvt_pk_bf16_f32 v10, v16, v17
	v_cvt_pk_bf16_f32 v11, v18, v19
	global_store_dwordx4 v[64:65], v[8:11], off sc0 sc1
	s_nop 1
	v_lshlrev_b32_e32 v8, 16, v44
	v_lshlrev_b32_e32 v9, 16, v40
	v_fmac_f32_e32 v8, v4, v9
	v_and_b32_e32 v4, 0xffff0000, v44
	v_and_b32_e32 v9, 0xffff0000, v40
	v_fmac_f32_e32 v4, v5, v9
	v_lshlrev_b32_e32 v5, 16, v45
	v_lshlrev_b32_e32 v9, 16, v41
	v_fmac_f32_e32 v5, v6, v9
	v_and_b32_e32 v6, 0xffff0000, v45
	v_and_b32_e32 v9, 0xffff0000, v41
	v_fmac_f32_e32 v6, v7, v9
	v_lshlrev_b32_e32 v7, 16, v46
	v_lshlrev_b32_e32 v9, 16, v42
	v_fmac_f32_e32 v7, v0, v9
	v_and_b32_e32 v9, 0xffff0000, v46
	v_and_b32_e32 v0, 0xffff0000, v42
	v_fmac_f32_e32 v9, v1, v0
	v_lshlrev_b32_e32 v10, 16, v47
	v_lshlrev_b32_e32 v0, 16, v43
	v_fmac_f32_e32 v10, v2, v0
	v_and_b32_e32 v11, 0xffff0000, v47
	v_and_b32_e32 v0, 0xffff0000, v43
	v_fmac_f32_e32 v11, v3, v0
	v_cvt_pk_bf16_f32 v0, v8, v4
	v_cvt_pk_bf16_f32 v1, v5, v6
	v_cvt_pk_bf16_f32 v2, v7, v9
	v_cvt_pk_bf16_f32 v3, v10, v11
	global_store_dwordx4 v[64:65], v[0:3], off offset:256 sc0 sc1
	s_cbranch_vccz .LBB0_712
	s_waitcnt vmcnt(0)
	s_cmpk_gt_u32 s22, 0xff
	s_cbranch_scc1 .LBB0_719
	s_barrier

; #define PG8_STAGE(bufoff, gbase, voff) do { _Pragma("unroll") for (int _i = 0; _i < 2; ++_i) \
;         __builtin_amdgcn_global_load_lds((const unsigned*)((const char*)(gbase) + (voff)[_i]), (LAS unsigned*)(lds + (bufoff) + ldsw + _i * 8192), 16, 0, 0); } while (0)
; #define PG8_LDA(dst, b, h) do { _Pragma("unroll") for (int m = 0; m < 4; ++m) _Pragma("unroll") for (int k = 0; k < 2; ++k) dst[m][k] = *(const LAS bf16x8*)(lds + PG8_SA(b, h) + aoff + m * 2048 + k * 1024); } while (0)
; #define PG8_WAIT_V(n) asm volatile("s_waitcnt vmcnt(" #n ")" ::: "memory")
; #define PG8_BAR __builtin_amdgcn_s_barrier()
; template <class Epi, class Sched>
; __device__ __forceinline__ void gemm_phase(LAS unsigned char* lds, const Gemm g, const Sched& S, const Epi& E) {
;     ...
;         for (int t = 0; t < nt; t += 2) {
;             const bool last = (t == nt - 2);
;             const char* a1 = cA + (size_t)(t + 1) * kstep;
;             const char* a2 = last ? nA : cA + (size_t)(t + 2) * kstep; const char* b2 = last ? nB : cB + (size_t)(t + 2) * kstep;
;             const char* a3 = a2 + kstep; const char* b3 = b2 + kstep;
;             PG8_LDB(B0, 0, 0); PG8_SCHED; PG8_LDA(At, 0, 0); PG8_STAGE(PG8_SA(1, 1), a1 + hstepA, voffA);
;             PG8_WAIT_L(8); PG8_BAR; PG8_WAIT_L(0); PG8_MMA(0, 0, At, B0); PG8_BAR; PG8_SCHED;
;             PG8_LDB(B1, 0, 1); PG8_STAGE(PG8_SB(0, 0), b2, voffB);
;             PG8_BAR; PG8_WAIT_L(0); PG8_MMA(0, 1, At, B1); PG8_BAR;
;             PG8_LDA(At, 0, 1); PG8_STAGE(PG8_SA(0, 0), a2, voffA);
;             PG8_BAR; PG8_WAIT_L(0); PG8_MMA(1, 0, At, B0); PG8_BAR; PG8_SCHED;
;             PG8_STAGE(PG8_SB(0, 1), b2 + hstepB, voffB);
;             PG8_WAIT_V(6); PG8_BAR; PG8_MMA(1, 1, At, B1); PG8_BAR;
;             PG8_LDB(B0, 1, 0); PG8_SCHED; PG8_LDA(At, 1, 0); PG8_STAGE(PG8_SA(0, 1), a2 + hstepA, voffA);
;             PG8_WAIT_L(8); PG8_BAR; PG8_WAIT_L(0); PG8_MMA(0, 0, At, B0); PG8_BAR; PG8_SCHED;
;             PG8_LDB(B1, 1, 1); PG8_STAGE(PG8_SB(1, 0), b3, voffB);
;             PG8_BAR; PG8_WAIT_L(0); PG8_MMA(0, 1, At, B1); PG8_BAR;
;             PG8_LDA(At, 1, 1); PG8_STAGE(PG8_SA(1, 0), a3, voffA);
;             PG8_BAR; PG8_WAIT_L(0); PG8_MMA(1, 0, At, B0); PG8_BAR; PG8_SCHED;
;             PG8_STAGE(PG8_SB(1, 1), b3 + hstepB, voffB);
;             PG8_WAIT_V(6); PG8_BAR; PG8_MMA(1, 1, At, B1); PG8_BAR;
;         }
.LBB0_783:
	ds_read_b128 v[128:131], v171
	ds_read_b128 v[132:135], v171 offset:1024
	ds_read_b128 v[136:139], v171 offset:2048
	ds_read_b128 v[140:143], v171 offset:3072
	s_add_u32 s22, s20, 0xfff00080
	s_addc_u32 s23, s21, -1
	s_cmp_eq_u32 s46, 28
	s_cselect_b32 s25, s13, s23
	s_cselect_b32 s24, s42, s22
	s_cselect_b32 s23, s11, s45
	s_cselect_b32 s22, s43, s44
	v_lshl_add_u64 v[202:203], s[20:21], 0, v[152:153]
	s_add_i32 m0, s30, 0xc000
	ds_read_b128 v[160:163], v172
	ds_read_b128 v[164:167], v172 offset:1024
	ds_read_b128 v[178:181], v172 offset:2048
	ds_read_b128 v[182:185], v172 offset:3072
	ds_read_b128 v[186:189], v172 offset:4096
	ds_read_b128 v[190:193], v172 offset:5120
	ds_read_b128 v[194:197], v172 offset:6144
	ds_read_b128 v[198:201], v172 offset:7168
	global_load_lds_dwordx4 v[202:203], off
	v_lshl_add_u64 v[202:203], s[20:21], 0, v[154:155]
	s_add_i32 m0, s30, 0xe000
	s_nop 0
	global_load_lds_dwordx4 v[202:203], off
	s_waitcnt lgkmcnt(8)
	s_barrier
	s_waitcnt lgkmcnt(0)
	s_setprio 1
	s_waitcnt lgkmcnt(0)
	v_mfma_f32_16x16x32_bf16 v[124:127], v[128:131], v[160:163], v[124:127]
	v_mfma_f32_16x16x32_bf16 v[120:123], v[136:139], v[160:163], v[120:123]
	v_mfma_f32_16x16x32_bf16 v[108:111], v[128:131], v[178:181], v[108:111]
	v_mfma_f32_16x16x32_bf16 v[104:107], v[136:139], v[178:181], v[104:107]
	v_mfma_f32_16x16x32_bf16 v[92:95], v[128:131], v[186:189], v[92:95]
	v_mfma_f32_16x16x32_bf16 v[88:91], v[136:139], v[186:189], v[88:91]
	v_mfma_f32_16x16x32_bf16 v[76:79], v[128:131], v[194:197], v[76:79]
	v_mfma_f32_16x16x32_bf16 v[72:75], v[136:139], v[194:197], v[72:75]
	v_mfma_f32_16x16x32_bf16 v[124:127], v[132:135], v[164:167], v[124:127]
	v_mfma_f32_16x16x32_bf16 v[120:123], v[140:143], v[164:167], v[120:123]
	v_mfma_f32_16x16x32_bf16 v[108:111], v[132:135], v[182:185], v[108:111]
	v_mfma_f32_16x16x32_bf16 v[104:107], v[140:143], v[182:185], v[104:107]
	v_mfma_f32_16x16x32_bf16 v[92:95], v[132:135], v[190:193], v[92:95]
	v_mfma_f32_16x16x32_bf16 v[88:91], v[140:143], v[190:193], v[88:91]
	v_mfma_f32_16x16x32_bf16 v[76:79], v[132:135], v[198:201], v[76:79]
	v_mfma_f32_16x16x32_bf16 v[72:75], v[140:143], v[198:201], v[72:75]
	s_setprio 0
	s_barrier
	s_add_i32 s47, s39, s27
	v_lshl_add_u64 v[218:219], s[22:23], 0, v[148:149]
	s_mov_b32 m0, s47
	ds_read_b128 v[202:205], v173
	ds_read_b128 v[206:209], v173 offset:1024
	ds_read_b128 v[210:213], v173 offset:2048
	ds_read_b128 v[214:217], v173 offset:3072
	global_load_lds_dwordx4 v[218:219], off
	v_lshl_add_u64 v[220:221], s[22:23], 0, v[144:145]
	s_add_i32 m0, s47, 0x2000
	s_nop 0
	global_load_lds_dwordx4 v[220:221], off
	s_barrier
	s_waitcnt lgkmcnt(0)
	s_setprio 1
	s_waitcnt lgkmcnt(0)
	v_mfma_f32_16x16x32_bf16 v[116:119], v[202:205], v[160:163], v[116:119]
	v_mfma_f32_16x16x32_bf16 v[112:115], v[210:213], v[160:163], v[112:115]
	v_mfma_f32_16x16x32_bf16 v[100:103], v[202:205], v[178:181], v[100:103]
	v_mfma_f32_16x16x32_bf16 v[96:99], v[210:213], v[178:181], v[96:99]
	v_mfma_f32_16x16x32_bf16 v[84:87], v[202:205], v[186:189], v[84:87]
	v_mfma_f32_16x16x32_bf16 v[80:83], v[210:213], v[186:189], v[80:83]
	v_mfma_f32_16x16x32_bf16 v[68:71], v[202:205], v[194:197], v[68:71]
	v_mfma_f32_16x16x32_bf16 v[64:67], v[210:213], v[194:197], v[64:67]
	v_mfma_f32_16x16x32_bf16 v[116:119], v[206:209], v[164:167], v[116:119]
	v_mfma_f32_16x16x32_bf16 v[112:115], v[214:217], v[164:167], v[112:115]
	v_mfma_f32_16x16x32_bf16 v[100:103], v[206:209], v[182:185], v[100:103]
	v_mfma_f32_16x16x32_bf16 v[96:99], v[214:217], v[182:185], v[96:99]
	v_mfma_f32_16x16x32_bf16 v[84:87], v[206:209], v[190:193], v[84:87]
	v_mfma_f32_16x16x32_bf16 v[80:83], v[214:217], v[190:193], v[80:83]
	v_mfma_f32_16x16x32_bf16 v[68:71], v[206:209], v[198:201], v[68:71]
	v_mfma_f32_16x16x32_bf16 v[64:67], v[214:217], v[198:201], v[64:67]
	s_setprio 0
	s_mov_b32 m0, s30
	v_lshl_add_u64 v[222:223], s[24:25], 0, v[150:151]
	s_barrier
	ds_read_b128 v[160:163], v172 offset:16384
	ds_read_b128 v[164:167], v172 offset:17408
	ds_read_b128 v[178:181], v172 offset:18432
	ds_read_b128 v[182:185], v172 offset:19456
	ds_read_b128 v[186:189], v172 offset:20480
	ds_read_b128 v[190:193], v172 offset:21504
	ds_read_b128 v[194:197], v172 offset:22528
	ds_read_b128 v[198:201], v172 offset:23552
	global_load_lds_dwordx4 v[222:223], off
	v_lshl_add_u64 v[224:225], s[24:25], 0, v[146:147]
	s_mov_b32 m0, s31
	s_nop 0
	global_load_lds_dwordx4 v[224:225], off
	s_barrier
	s_waitcnt lgkmcnt(0)
	s_setprio 1
	s_waitcnt lgkmcnt(0)
	v_mfma_f32_16x16x32_bf16 v[60:63], v[128:131], v[160:163], v[60:63]
	v_mfma_f32_16x16x32_bf16 v[56:59], v[136:139], v[160:163], v[56:59]
	v_mfma_f32_16x16x32_bf16 v[44:47], v[128:131], v[178:181], v[44:47]
	v_mfma_f32_16x16x32_bf16 v[40:43], v[136:139], v[178:181], v[40:43]
	v_mfma_f32_16x16x32_bf16 v[28:31], v[128:131], v[186:189], v[28:31]
	v_mfma_f32_16x16x32_bf16 v[24:27], v[136:139], v[186:189], v[24:27]
	v_mfma_f32_16x16x32_bf16 v[12:15], v[128:131], v[194:197], v[12:15]
	v_mfma_f32_16x16x32_bf16 v[8:11], v[136:139], v[194:197], v[8:11]
	v_mfma_f32_16x16x32_bf16 v[60:63], v[132:135], v[164:167], v[60:63]
	v_mfma_f32_16x16x32_bf16 v[56:59], v[140:143], v[164:167], v[56:59]
	v_mfma_f32_16x16x32_bf16 v[44:47], v[132:135], v[182:185], v[44:47]
	v_mfma_f32_16x16x32_bf16 v[40:43], v[140:143], v[182:185], v[40:43]
	v_mfma_f32_16x16x32_bf16 v[28:31], v[132:135], v[190:193], v[28:31]
	v_mfma_f32_16x16x32_bf16 v[24:27], v[140:143], v[190:193], v[24:27]
	v_mfma_f32_16x16x32_bf16 v[12:15], v[132:135], v[198:201], v[12:15]
	v_mfma_f32_16x16x32_bf16 v[8:11], v[140:143], v[198:201], v[8:11]
	s_setprio 0
	s_barrier
; #define PG8_STAGE(bufoff, gbase, voff) do { _Pragma("unroll") for (int _i = 0; _i < 2; ++_i) \
;         __builtin_amdgcn_global_load_lds((const unsigned*)((const char*)(gbase) + (voff)[_i]), (LAS unsigned*)(lds + (bufoff) + ldsw + _i * 8192), 16, 0, 0); } while (0)
; #define PG8_LDA(dst, b, h) do { _Pragma("unroll") for (int m = 0; m < 4; ++m) _Pragma("unroll") for (int k = 0; k < 2; ++k) dst[m][k] = *(const LAS bf16x8*)(lds + PG8_SA(b, h) + aoff + m * 2048 + k * 1024); } while (0)
; #define PG8_WAIT_V(n) asm volatile("s_waitcnt vmcnt(" #n ")" ::: "memory")
; #define PG8_BAR __builtin_amdgcn_s_barrier()
; template <class Epi, class Sched>
; __device__ __forceinline__ void gemm_phase(LAS unsigned char* lds, const Gemm g, const Sched& S, const Epi& E) {
;     ...
;         for (int t = 0; t < nt; t += 2) {
;             const bool last = (t == nt - 2);
;             const char* a1 = cA + (size_t)(t + 1) * kstep;
;             const char* a2 = last ? nA : cA + (size_t)(t + 2) * kstep; const char* b2 = last ? nB : cB + (size_t)(t + 2) * kstep;
;             const char* a3 = a2 + kstep; const char* b3 = b2 + kstep;
;             PG8_LDB(B0, 0, 0); PG8_SCHED; PG8_LDA(At, 0, 0); PG8_STAGE(PG8_SA(1, 1), a1 + hstepA, voffA);
;             PG8_WAIT_L(8); PG8_BAR; PG8_WAIT_L(0); PG8_MMA(0, 0, At, B0); PG8_BAR; PG8_SCHED;
;             PG8_LDB(B1, 0, 1); PG8_STAGE(PG8_SB(0, 0), b2, voffB);
;             PG8_BAR; PG8_WAIT_L(0); PG8_MMA(0, 1, At, B1); PG8_BAR;
;             PG8_LDA(At, 0, 1); PG8_STAGE(PG8_SA(0, 0), a2, voffA);
;             PG8_BAR; PG8_WAIT_L(0); PG8_MMA(1, 0, At, B0); PG8_BAR; PG8_SCHED;
;             PG8_STAGE(PG8_SB(0, 1), b2 + hstepB, voffB);
;             PG8_WAIT_V(6); PG8_BAR; PG8_MMA(1, 1, At, B1); PG8_BAR;
;             PG8_LDB(B0, 1, 0); PG8_SCHED; PG8_LDA(At, 1, 0); PG8_STAGE(PG8_SA(0, 1), a2 + hstepA, voffA);
;             PG8_WAIT_L(8); PG8_BAR; PG8_WAIT_L(0); PG8_MMA(0, 0, At, B0); PG8_BAR; PG8_SCHED;
;             PG8_LDB(B1, 1, 1); PG8_STAGE(PG8_SB(1, 0), b3, voffB);
;             PG8_BAR; PG8_WAIT_L(0); PG8_MMA(0, 1, At, B1); PG8_BAR;
;             PG8_LDA(At, 1, 1); PG8_STAGE(PG8_SA(1, 0), a3, voffA);
;             PG8_BAR; PG8_WAIT_L(0); PG8_MMA(1, 0, At, B0); PG8_BAR; PG8_SCHED;
;             PG8_STAGE(PG8_SB(1, 1), b3 + hstepB, voffB);
;             PG8_WAIT_V(6); PG8_BAR; PG8_MMA(1, 1, At, B1); PG8_BAR;
;         }
	s_add_u32 s48, s22, 0x80000
	s_addc_u32 s49, s23, 0
	s_add_i32 s47, s40, s27
	v_lshl_add_u64 v[128:129], s[48:49], 0, v[148:149]
	s_mov_b32 m0, s47
	s_nop 0
	global_load_lds_dwordx4 v[128:129], off
	v_lshl_add_u64 v[128:129], s[48:49], 0, v[144:145]
	s_add_i32 m0, s47, 0x2000
	s_nop 0
	global_load_lds_dwordx4 v[128:129], off
	s_waitcnt vmcnt(6)
	s_barrier
	s_setprio 1
	v_mfma_f32_16x16x32_bf16 v[52:55], v[202:205], v[160:163], v[52:55]
	v_mfma_f32_16x16x32_bf16 v[48:51], v[210:213], v[160:163], v[48:51]
	v_mfma_f32_16x16x32_bf16 v[36:39], v[202:205], v[178:181], v[36:39]
	v_mfma_f32_16x16x32_bf16 v[32:35], v[210:213], v[178:181], v[32:35]
	v_mfma_f32_16x16x32_bf16 v[20:23], v[202:205], v[186:189], v[20:23]
	v_mfma_f32_16x16x32_bf16 v[16:19], v[210:213], v[186:189], v[16:19]
	v_mfma_f32_16x16x32_bf16 v[4:7], v[202:205], v[194:197], v[4:7]
	v_mfma_f32_16x16x32_bf16 v[0:3], v[210:213], v[194:197], v[0:3]
	v_mfma_f32_16x16x32_bf16 v[52:55], v[206:209], v[164:167], v[52:55]
	v_mfma_f32_16x16x32_bf16 v[48:51], v[214:217], v[164:167], v[48:51]
	v_mfma_f32_16x16x32_bf16 v[36:39], v[206:209], v[182:185], v[36:39]
	v_mfma_f32_16x16x32_bf16 v[32:35], v[214:217], v[182:185], v[32:35]
	v_mfma_f32_16x16x32_bf16 v[20:23], v[206:209], v[190:193], v[20:23]
	v_mfma_f32_16x16x32_bf16 v[16:19], v[214:217], v[190:193], v[16:19]
	v_mfma_f32_16x16x32_bf16 v[4:7], v[206:209], v[198:201], v[4:7]
	v_mfma_f32_16x16x32_bf16 v[0:3], v[214:217], v[198:201], v[0:3]
	s_setprio 0
	s_add_i32 s47, 0, 0x18000
	v_add_u32_e32 v140, s47, v169
	s_barrier
	ds_read_b128 v[128:131], v140
	ds_read_b128 v[132:135], v140 offset:1024
	ds_read_b128 v[136:139], v140 offset:2048
	ds_read_b128 v[140:143], v140 offset:3072
	s_add_u32 s24, s24, 0x100000
	s_addc_u32 s25, s25, 0
	s_mov_b32 m0, s33
	v_lshl_add_u64 v[202:203], s[24:25], 0, v[150:151]
	ds_read_b128 v[160:163], v172 offset:32768
	ds_read_b128 v[164:167], v172 offset:33792
	ds_read_b128 v[178:181], v172 offset:34816
	ds_read_b128 v[182:185], v172 offset:35840
	ds_read_b128 v[186:189], v172 offset:36864
	ds_read_b128 v[190:193], v172 offset:37888
	ds_read_b128 v[194:197], v172 offset:38912
	ds_read_b128 v[198:201], v172 offset:39936
	global_load_lds_dwordx4 v[202:203], off
	v_lshl_add_u64 v[202:203], s[24:25], 0, v[146:147]
	s_mov_b32 m0, s34
	s_nop 0
	global_load_lds_dwordx4 v[202:203], off
	s_waitcnt lgkmcnt(8)
	s_barrier
	s_waitcnt lgkmcnt(0)
	s_setprio 1
	s_waitcnt lgkmcnt(0)
	v_mfma_f32_16x16x32_bf16 v[124:127], v[128:131], v[160:163], v[124:127]
	v_mfma_f32_16x16x32_bf16 v[120:123], v[136:139], v[160:163], v[120:123]
	v_mfma_f32_16x16x32_bf16 v[108:111], v[128:131], v[178:181], v[108:111]
	v_mfma_f32_16x16x32_bf16 v[104:107], v[136:139], v[178:181], v[104:107]
	v_mfma_f32_16x16x32_bf16 v[92:95], v[128:131], v[186:189], v[92:95]
	v_mfma_f32_16x16x32_bf16 v[88:91], v[136:139], v[186:189], v[88:91]
	v_mfma_f32_16x16x32_bf16 v[76:79], v[128:131], v[194:197], v[76:79]
	v_mfma_f32_16x16x32_bf16 v[72:75], v[136:139], v[194:197], v[72:75]
	v_mfma_f32_16x16x32_bf16 v[124:127], v[132:135], v[164:167], v[124:127]
	v_mfma_f32_16x16x32_bf16 v[120:123], v[140:143], v[164:167], v[120:123]
	v_mfma_f32_16x16x32_bf16 v[108:111], v[132:135], v[182:185], v[108:111]
	v_mfma_f32_16x16x32_bf16 v[104:107], v[140:143], v[182:185], v[104:107]
	v_mfma_f32_16x16x32_bf16 v[92:95], v[132:135], v[190:193], v[92:95]
	v_mfma_f32_16x16x32_bf16 v[88:91], v[140:143], v[190:193], v[88:91]
	v_mfma_f32_16x16x32_bf16 v[76:79], v[132:135], v[198:201], v[76:79]
	v_mfma_f32_16x16x32_bf16 v[72:75], v[140:143], v[198:201], v[72:75]
	s_setprio 0
	s_barrier
	s_add_i32 s24, 0, 0x1c000
	s_add_i32 s25, s47, s27
	v_add_u32_e32 v175, s24, v169
	v_lshl_add_u64 v[218:219], v[218:219], 0, s[8:9]
	s_mov_b32 m0, s25
	ds_read_b128 v[202:205], v175
	ds_read_b128 v[206:209], v175 offset:1024
	ds_read_b128 v[210:213], v175 offset:2048
	ds_read_b128 v[214:217], v175 offset:3072
	global_load_lds_dwordx4 v[218:219], off
	v_lshl_add_u64 v[218:219], v[220:221], 0, s[8:9]
	s_add_i32 m0, s25, 0x2000
	s_nop 0
	global_load_lds_dwordx4 v[218:219], off
	s_barrier
	s_waitcnt lgkmcnt(0)
	s_setprio 1
	s_waitcnt lgkmcnt(0)
	v_mfma_f32_16x16x32_bf16 v[116:119], v[202:205], v[160:163], v[116:119]
	v_mfma_f32_16x16x32_bf16 v[112:115], v[210:213], v[160:163], v[112:115]
	v_mfma_f32_16x16x32_bf16 v[100:103], v[202:205], v[178:181], v[100:103]
	v_mfma_f32_16x16x32_bf16 v[96:99], v[210:213], v[178:181], v[96:99]
	v_mfma_f32_16x16x32_bf16 v[84:87], v[202:205], v[186:189], v[84:87]
	v_mfma_f32_16x16x32_bf16 v[80:83], v[210:213], v[186:189], v[80:83]
	v_mfma_f32_16x16x32_bf16 v[68:71], v[202:205], v[194:197], v[68:71]
	v_mfma_f32_16x16x32_bf16 v[64:67], v[210:213], v[194:197], v[64:67]
	v_mfma_f32_16x16x32_bf16 v[116:119], v[206:209], v[164:167], v[116:119]
	v_mfma_f32_16x16x32_bf16 v[112:115], v[214:217], v[164:167], v[112:115]
	v_mfma_f32_16x16x32_bf16 v[100:103], v[206:209], v[182:185], v[100:103]
	v_mfma_f32_16x16x32_bf16 v[96:99], v[214:217], v[182:185], v[96:99]
	v_mfma_f32_16x16x32_bf16 v[84:87], v[206:209], v[190:193], v[84:87]
	v_mfma_f32_16x16x32_bf16 v[80:83], v[214:217], v[190:193], v[80:83]
	v_mfma_f32_16x16x32_bf16 v[68:71], v[206:209], v[198:201], v[68:71]
	v_mfma_f32_16x16x32_bf16 v[64:67], v[214:217], v[198:201], v[64:67]
	s_setprio 0
	s_mov_b32 m0, s36
	v_lshl_add_u64 v[218:219], v[222:223], 0, s[8:9]
	s_barrier
	ds_read_b128 v[160:163], v172 offset:49152
	ds_read_b128 v[164:167], v172 offset:50176
	ds_read_b128 v[178:181], v172 offset:51200
	ds_read_b128 v[182:185], v172 offset:52224
	ds_read_b128 v[186:189], v172 offset:53248
	ds_read_b128 v[190:193], v172 offset:54272
	ds_read_b128 v[194:197], v172 offset:55296
	ds_read_b128 v[198:201], v172 offset:56320
	global_load_lds_dwordx4 v[218:219], off
	v_lshl_add_u64 v[218:219], v[224:225], 0, s[8:9]
	s_mov_b32 m0, s37
	s_nop 0
	global_load_lds_dwordx4 v[218:219], off
	s_barrier
;     __device__ __forceinline__ void operator()(const f32x4 (&acc)[2][2][4][2], const Unit& u, int wr, int wc, int fr, int fq) const {
;         const int row0 = u.pm * BM + wr * 64 + fr, col0 = u.pn * BM + wc * 32 + 4 * fq;
;         const float* base = ((u.pm < MP / BM) ? base_lo : base_hi - (size_t)MP * DM) + (size_t)row0 * DM + col0;
;         f32x4 b[2][2], nb[2][2];
; #pragma unroll
;         for (int bj = 0; bj < 2; ++bj)
; #pragma unroll
;             for (int n = 0; n < 2; ++n) b[bj][n] = *(const f32x4*)(base + bj * HALF + n * 16);
; #pragma unroll
;         for (int g = 0; g < 8; ++g) {
; template <class Epi, class Sched>
; __device__ __forceinline__ void gemm_phase(LAS unsigned char* lds, const Gemm g, const Sched& S, const Epi& E) {
;     ...
;         for (int t = 0; t < nt; t += 2) {
;             const bool last = (t == nt - 2);
;             const char* a1 = cA + (size_t)(t + 1) * kstep;
;             const char* a2 = last ? nA : cA + (size_t)(t + 2) * kstep; const char* b2 = last ? nB : cB + (size_t)(t + 2) * kstep;
;             const char* a3 = a2 + kstep; const char* b3 = b2 + kstep;
;             PG8_LDB(B0, 0, 0); PG8_SCHED; PG8_LDA(At, 0, 0); PG8_STAGE(PG8_SA(1, 1), a1 + hstepA, voffA);
;             PG8_WAIT_L(8); PG8_BAR; PG8_WAIT_L(0); PG8_MMA(0, 0, At, B0); PG8_BAR; PG8_SCHED;
;             PG8_LDB(B1, 0, 1); PG8_STAGE(PG8_SB(0, 0), b2, voffB);
;             PG8_BAR; PG8_WAIT_L(0); PG8_MMA(0, 1, At, B1); PG8_BAR;
;             PG8_LDA(At, 0, 1); PG8_STAGE(PG8_SA(0, 0), a2, voffA);
;             PG8_BAR; PG8_WAIT_L(0); PG8_MMA(1, 0, At, B0); PG8_BAR; PG8_SCHED;
;             PG8_STAGE(PG8_SB(0, 1), b2 + hstepB, voffB);
;             PG8_WAIT_V(6); PG8_BAR; PG8_MMA(1, 1, At, B1); PG8_BAR;
;             PG8_LDB(B0, 1, 0); PG8_SCHED; PG8_LDA(At, 1, 0); PG8_STAGE(PG8_SA(0, 1), a2 + hstepA, voffA);
;             PG8_WAIT_L(8); PG8_BAR; PG8_WAIT_L(0); PG8_MMA(0, 0, At, B0); PG8_BAR; PG8_SCHED;
;             PG8_LDB(B1, 1, 1); PG8_STAGE(PG8_SB(1, 0), b3, voffB);
;             PG8_BAR; PG8_WAIT_L(0); PG8_MMA(0, 1, At, B1); PG8_BAR;
;             PG8_LDA(At, 1, 1); PG8_STAGE(PG8_SA(1, 0), a3, voffA);
;             PG8_BAR; PG8_WAIT_L(0); PG8_MMA(1, 0, At, B0); PG8_BAR; PG8_SCHED;
;             PG8_STAGE(PG8_SB(1, 1), b3 + hstepB, voffB);
;             PG8_WAIT_V(6); PG8_BAR; PG8_MMA(1, 1, At, B1); PG8_BAR;
	s_waitcnt lgkmcnt(0)
	s_setprio 1
	s_waitcnt lgkmcnt(0)
	v_mfma_f32_16x16x32_bf16 v[60:63], v[128:131], v[160:163], v[60:63]
	v_mfma_f32_16x16x32_bf16 v[56:59], v[136:139], v[160:163], v[56:59]
	v_mfma_f32_16x16x32_bf16 v[44:47], v[128:131], v[178:181], v[44:47]
	v_mfma_f32_16x16x32_bf16 v[40:43], v[136:139], v[178:181], v[40:43]
	v_mfma_f32_16x16x32_bf16 v[28:31], v[128:131], v[186:189], v[28:31]
	v_mfma_f32_16x16x32_bf16 v[24:27], v[136:139], v[186:189], v[24:27]
	v_mfma_f32_16x16x32_bf16 v[12:15], v[128:131], v[194:197], v[12:15]
	v_mfma_f32_16x16x32_bf16 v[8:11], v[136:139], v[194:197], v[8:11]
	v_mfma_f32_16x16x32_bf16 v[60:63], v[132:135], v[164:167], v[60:63]
	v_mfma_f32_16x16x32_bf16 v[56:59], v[140:143], v[164:167], v[56:59]
	v_mfma_f32_16x16x32_bf16 v[44:47], v[132:135], v[182:185], v[44:47]
	v_mfma_f32_16x16x32_bf16 v[40:43], v[140:143], v[182:185], v[40:43]
	v_mfma_f32_16x16x32_bf16 v[28:31], v[132:135], v[190:193], v[28:31]
	v_mfma_f32_16x16x32_bf16 v[24:27], v[140:143], v[190:193], v[24:27]
	v_mfma_f32_16x16x32_bf16 v[12:15], v[132:135], v[198:201], v[12:15]
	v_mfma_f32_16x16x32_bf16 v[8:11], v[140:143], v[198:201], v[8:11]
	s_setprio 0
	s_barrier
	s_add_u32 s22, s22, 0x80080
	s_addc_u32 s23, s23, 0
	s_add_i32 s24, s24, s27
	v_lshl_add_u64 v[128:129], s[22:23], 0, v[148:149]
	s_mov_b32 m0, s24
	s_nop 0
	global_load_lds_dwordx4 v[128:129], off
	v_lshl_add_u64 v[128:129], s[22:23], 0, v[144:145]
	s_add_i32 m0, s24, 0x2000
	s_nop 0
	global_load_lds_dwordx4 v[128:129], off
	s_waitcnt vmcnt(6)
	s_barrier
	s_setprio 1
	v_mfma_f32_16x16x32_bf16 v[52:55], v[202:205], v[160:163], v[52:55]
	v_mfma_f32_16x16x32_bf16 v[48:51], v[210:213], v[160:163], v[48:51]
	v_mfma_f32_16x16x32_bf16 v[36:39], v[202:205], v[178:181], v[36:39]
	v_mfma_f32_16x16x32_bf16 v[32:35], v[210:213], v[178:181], v[32:35]
	v_mfma_f32_16x16x32_bf16 v[20:23], v[202:205], v[186:189], v[20:23]
	v_mfma_f32_16x16x32_bf16 v[16:19], v[210:213], v[186:189], v[16:19]
	v_mfma_f32_16x16x32_bf16 v[4:7], v[202:205], v[194:197], v[4:7]
	v_mfma_f32_16x16x32_bf16 v[0:3], v[210:213], v[194:197], v[0:3]
	v_mfma_f32_16x16x32_bf16 v[52:55], v[206:209], v[164:167], v[52:55]
	v_mfma_f32_16x16x32_bf16 v[48:51], v[214:217], v[164:167], v[48:51]
	v_mfma_f32_16x16x32_bf16 v[36:39], v[206:209], v[182:185], v[36:39]
	v_mfma_f32_16x16x32_bf16 v[32:35], v[214:217], v[182:185], v[32:35]
	v_mfma_f32_16x16x32_bf16 v[20:23], v[206:209], v[190:193], v[20:23]
	v_mfma_f32_16x16x32_bf16 v[16:19], v[214:217], v[190:193], v[16:19]
	v_mfma_f32_16x16x32_bf16 v[4:7], v[206:209], v[198:201], v[4:7]
	v_mfma_f32_16x16x32_bf16 v[0:3], v[214:217], v[198:201], v[0:3]
	s_setprio 0
	s_add_i32 s46, s46, 2
	s_add_u32 s20, s20, 0x100
	s_addc_u32 s21, s21, 0
	s_add_u32 s44, s44, 0x100
	s_addc_u32 s45, s45, 0
	s_cmp_gt_u32 s46, 29
	s_barrier
	s_cbranch_scc0 .LBB0_783
	v_lshl_add_u32 v164, s18, 8, v168
	v_ashrrev_i32_e32 v165, 31, v164
	v_lshl_or_b32 v160, s19, 8, v170
	v_lshlrev_b64 v[128:129], 13, v[164:165]
	v_lshl_add_u64 v[128:129], s[68:69], 0, v[128:129]
	v_ashrrev_i32_e32 v161, 31, v160
	v_lshl_add_u64 v[162:163], v[160:161], 2, v[128:129]
	global_load_dwordx4 v[178:181], v[162:163], off
	global_load_dwordx4 v[182:185], v[162:163], off offset:64
	global_load_dwordx4 v[186:189], v[162:163], off offset:512
	global_load_dwordx4 v[190:193], v[162:163], off offset:576
	v_add_co_u32_e32 v128, vcc, s41, v162
	v_and_b32_e32 v166, 64, v174
	s_nop 0
	v_addc_co_u32_e32 v129, vcc, 0, v163, vcc
	global_load_dwordx4 v[140:143], v[128:129], off
	global_load_dwordx4 v[136:139], v[128:129], off offset:64
	global_load_dwordx4 v[132:135], v[128:129], off offset:512
	s_nop 0
	global_load_dwordx4 v[128:131], v[128:129], off offset:576
	v_add_u32_e32 v195, 64, v166
	v_lshlrev_b64 v[166:167], 11, v[164:165]
	v_readlane_b32 s18, v239, 25
	v_lshl_add_u64 v[166:167], v[166:167], 0, v[160:161]
	v_readlane_b32 s19, v239, 26
	v_xor_b32_e32 v175, 16, v174
	v_cmp_lt_i32_e32 vcc, v175, v195
	v_lshl_add_u64 v[166:167], v[166:167], 1, s[18:19]
	v_xor_b32_e32 v194, 32, v174
	v_cndmask_b32_e32 v175, v174, v175, vcc
	v_lshlrev_b32_e32 v175, 2, v175
	v_cmp_lt_i32_e32 vcc, v194, v195
	s_waitcnt vmcnt(0)
	v_pk_add_f32 v[126:127], v[126:127], v[180:181]
	v_pk_add_f32 v[124:125], v[124:125], v[178:179]
	v_pk_add_f32 v[122:123], v[122:123], v[184:185]
	v_pk_add_f32 v[120:121], v[120:121], v[182:183]
	v_pk_add_f32 v[118:119], v[118:119], v[188:189]
	v_pk_add_f32 v[116:117], v[116:117], v[186:187]
	v_pk_add_f32 v[182:183], v[114:115], v[192:193]
	v_pk_add_f32 v[180:181], v[112:113], v[190:191]
	global_store_dwordx4 v[162:163], v[124:127], off sc0 sc1
	v_mul_f32_e32 v114, v125, v125
	v_mul_f32_e32 v115, v127, v127
	v_cvt_pk_bf16_f32 v112, v124, v125
	v_cvt_pk_bf16_f32 v113, v126, v127
	v_mul_f32_e32 v125, v121, v121
	v_mul_f32_e32 v127, v123, v123
	v_mul_f32_e32 v178, v117, v117
	v_mul_f32_e32 v179, v119, v119
	v_fmac_f32_e32 v114, v124, v124
	v_fmac_f32_e32 v115, v126, v126
	v_fmac_f32_e32 v125, v120, v120
	v_fmac_f32_e32 v127, v122, v122
	v_mul_f32_e32 v184, v181, v181
	v_mul_f32_e32 v185, v183, v183
	global_store_dwordx2 v[166:167], v[112:113], off sc0 sc1
	global_store_dwordx4 v[162:163], v[120:123], off offset:64 sc0 sc1
	v_cvt_pk_bf16_f32 v112, v120, v121
	v_fmac_f32_e32 v178, v116, v116
	v_fmac_f32_e32 v179, v118, v118
	v_add_f32_e32 v114, v114, v115
	v_add_f32_e32 v115, v125, v127
	v_cvt_pk_bf16_f32 v113, v122, v123
	v_fmac_f32_e32 v184, v180, v180
	v_fmac_f32_e32 v185, v182, v182
	global_store_dwordx2 v[166:167], v[112:113], off offset:32 sc0 sc1
	v_add_f32_e32 v112, v178, v179
	v_add_f32_e32 v114, v114, v115
	v_add_f32_e32 v113, v184, v185
	v_add_f32_e32 v112, v114, v112
	v_add_f32_e32 v114, v112, v113
	ds_bpermute_b32 v115, v175, v114
	v_cndmask_b32_e32 v194, v174, v194, vcc
	global_store_dwordx4 v[162:163], v[116:119], off offset:512 sc0 sc1
	v_cvt_pk_bf16_f32 v112, v116, v117
	v_cvt_pk_bf16_f32 v113, v118, v119
	global_store_dwordx2 v[166:167], v[112:113], off offset:256 sc0 sc1
	s_waitcnt lgkmcnt(0)
	v_add_f32_e32 v112, v114, v115
	v_lshlrev_b32_e32 v178, 2, v194
	ds_bpermute_b32 v113, v178, v112
	global_store_dwordx4 v[162:163], v[180:183], off offset:576 sc0 sc1
	v_cvt_pk_bf16_f32 v114, v180, v181
	v_cvt_pk_bf16_f32 v115, v182, v183
	global_store_dwordx2 v[166:167], v[114:115], off offset:288 sc0 sc1
	s_and_saveexec_b64 s[18:19], s[0:1]
	s_cbranch_execz .LBB0_786
	v_lshl_add_u64 v[114:115], v[164:165], 2, s[2:3]
	s_waitcnt lgkmcnt(0)
	v_add_f32_e32 v112, v112, v113
	global_atomic_add_f32 v[114:115], v112, off
; __device__ __forceinline__ unsigned cvt_pk_bf16(float lo, float hi) { unsigned r; asm volatile("v_cvt_pk_bf16_f32 %0, %1, %2" : "=v"(r) : "v"(lo), "v"(hi)); return r; }
;     __device__ __forceinline__ void operator()(const f32x4 (&acc)[2][2][4][2], const Unit& u, int wr, int wc, int fr, int fq) const {
;     ...
;         for (int g = 0; g < 8; ++g) {
;             const int ai = g >> 2, m = g & 3;
;             const int r = row0 + ai * HALF + m * 16; const size_t off = (size_t)r * DM + col0; float s = 0.f;
;             if (g < 7) { const float* nrow = base + (size_t)(((g + 1) >> 2) * HALF + ((g + 1) & 3) * 16) * DM;
; #pragma unroll
;                 for (int bj = 0; bj < 2; ++bj)
; #pragma unroll
;                     for (int n = 0; n < 2; ++n) nb[bj][n] = *(const f32x4*)(nrow + bj * HALF + n * 16); }
; #pragma unroll
;             for (int bj = 0; bj < 2; ++bj)
; #pragma unroll
;                 for (int n = 0; n < 2; ++n) {
;                     const f32x4 o = b[bj][n] + acc[ai][bj][m][n] * alpha;
;                     *(f32x4*)(out + off + bj * HALF + n * 16) = o;
;                     if (WITH_SSQ) s += (o[0] * o[0] + o[1] * o[1]) + (o[2] * o[2] + o[3] * o[3]);
;                     if (WITH_HB) { u32x2 w; w.x = cvt_pk_bf16(o[0], o[1]); w.y = cvt_pk_bf16(o[2], o[3]); *(u32x2*)(hb + off + bj * HALF + n * 16) = w; }
;                 }
;             if (WITH_SSQ) { s += __shfl_xor(s, 16); s += __shfl_xor(s, 32); if (fq == 0) atomicAdd(ssq + r, s); }
.LBB0_786:
	s_or_b64 exec, exec, s[18:19]
	v_add_co_u32_e32 v112, vcc, 0x40000, v162
	v_or_b32_e32 v166, 16, v164
	s_waitcnt lgkmcnt(0)
	v_addc_co_u32_e32 v113, vcc, 0, v163, vcc
	global_load_dwordx4 v[124:127], v[112:113], off
	global_load_dwordx4 v[120:123], v[112:113], off offset:64
	global_load_dwordx4 v[116:119], v[112:113], off offset:512
	s_nop 0
	global_load_dwordx4 v[112:115], v[112:113], off offset:576
	v_ashrrev_i32_e32 v167, 31, v166
	v_lshlrev_b64 v[180:181], 11, v[166:167]
	v_lshl_add_u64 v[180:181], v[180:181], 0, v[160:161]
	v_pk_add_f32 v[110:111], v[110:111], v[142:143]
	v_pk_add_f32 v[108:109], v[108:109], v[140:141]
	v_readlane_b32 s18, v239, 25
	v_lshl_add_u64 v[140:141], v[180:181], 2, s[68:69]
	v_mul_f32_e32 v142, v109, v109
	v_mul_f32_e32 v143, v111, v111
	v_readlane_b32 s19, v239, 26
	global_store_dwordx4 v[140:141], v[108:111], off sc0 sc1
	v_fmac_f32_e32 v142, v108, v108
	v_fmac_f32_e32 v143, v110, v110
	v_cvt_pk_bf16_f32 v108, v108, v109
	v_cvt_pk_bf16_f32 v109, v110, v111
	v_lshl_add_u64 v[110:111], v[180:181], 1, s[18:19]
	v_pk_add_f32 v[104:105], v[104:105], v[136:137]
	global_store_dwordx2 v[110:111], v[108:109], off sc0 sc1
	v_pk_add_f32 v[106:107], v[106:107], v[138:139]
	v_mul_f32_e32 v108, v105, v105
	global_store_dwordx4 v[140:141], v[104:107], off offset:64 sc0 sc1
	v_fmac_f32_e32 v108, v104, v104
	v_mul_f32_e32 v109, v107, v107
	v_cvt_pk_bf16_f32 v104, v104, v105
	v_cvt_pk_bf16_f32 v105, v106, v107
	v_pk_add_f32 v[102:103], v[102:103], v[134:135]
	v_pk_add_f32 v[100:101], v[100:101], v[132:133]
	v_fmac_f32_e32 v109, v106, v106
	global_store_dwordx2 v[110:111], v[104:105], off offset:32 sc0 sc1
	v_mul_f32_e32 v104, v101, v101
	v_mul_f32_e32 v105, v103, v103
	v_add_f32_e32 v142, v142, v143
	v_add_f32_e32 v108, v108, v109
	v_fmac_f32_e32 v104, v100, v100
	v_fmac_f32_e32 v105, v102, v102
	v_add_f32_e32 v108, v142, v108
	v_add_f32_e32 v104, v104, v105
	v_add_f32_e32 v108, v108, v104
	v_pk_add_f32 v[106:107], v[98:99], v[130:131]
	v_pk_add_f32 v[104:105], v[96:97], v[128:129]
	v_mul_f32_e32 v97, v107, v107
	v_mul_f32_e32 v96, v105, v105
	v_fmac_f32_e32 v96, v104, v104
	v_fmac_f32_e32 v97, v106, v106
	v_add_f32_e32 v96, v96, v97
	v_add_f32_e32 v98, v108, v96
	ds_bpermute_b32 v99, v175, v98
	global_store_dwordx4 v[140:141], v[100:103], off offset:512 sc0 sc1
	v_cvt_pk_bf16_f32 v96, v100, v101
	v_cvt_pk_bf16_f32 v97, v102, v103
	global_store_dwordx2 v[110:111], v[96:97], off offset:256 sc0 sc1
	s_waitcnt lgkmcnt(0)
	v_add_f32_e32 v96, v98, v99
	ds_bpermute_b32 v97, v178, v96
	global_store_dwordx4 v[140:141], v[104:107], off offset:576 sc0 sc1
	v_cvt_pk_bf16_f32 v98, v104, v105
	v_cvt_pk_bf16_f32 v99, v106, v107
	global_store_dwordx2 v[110:111], v[98:99], off offset:288 sc0 sc1
	s_and_saveexec_b64 s[18:19], s[0:1]
	s_cbranch_execz .LBB0_788
	v_lshl_add_u64 v[98:99], v[166:167], 2, s[2:3]
	s_waitcnt lgkmcnt(0)
	v_add_f32_e32 v96, v96, v97
	global_atomic_add_f32 v[98:99], v96, off
.LBB0_788:
	s_or_b64 exec, exec, s[18:19]
	v_add_co_u32_e32 v96, vcc, 0x60000, v162
	v_or_b32_e32 v128, 32, v164
	s_waitcnt lgkmcnt(0)
	v_addc_co_u32_e32 v97, vcc, 0, v163, vcc
	global_load_dwordx4 v[108:111], v[96:97], off
	global_load_dwordx4 v[104:107], v[96:97], off offset:64
	global_load_dwordx4 v[100:103], v[96:97], off offset:512
	s_nop 0
	global_load_dwordx4 v[96:99], v[96:97], off offset:576
	v_ashrrev_i32_e32 v129, 31, v128
	v_lshlrev_b64 v[130:131], 11, v[128:129]
	v_lshl_add_u64 v[130:131], v[130:131], 0, v[160:161]
	s_waitcnt vmcnt(15)
	v_pk_add_f32 v[94:95], v[94:95], v[126:127]
	v_pk_add_f32 v[92:93], v[92:93], v[124:125]
	v_readlane_b32 s18, v239, 25
	v_lshl_add_u64 v[124:125], v[130:131], 2, s[68:69]
	v_mul_f32_e32 v126, v93, v93
	v_mul_f32_e32 v127, v95, v95
	v_readlane_b32 s19, v239, 26
	global_store_dwordx4 v[124:125], v[92:95], off sc0 sc1
	v_fmac_f32_e32 v126, v92, v92
	v_fmac_f32_e32 v127, v94, v94
	v_cvt_pk_bf16_f32 v92, v92, v93
	v_cvt_pk_bf16_f32 v93, v94, v95
	v_lshl_add_u64 v[94:95], v[130:131], 1, s[18:19]
	s_waitcnt vmcnt(15)
	v_pk_add_f32 v[88:89], v[88:89], v[120:121]
	global_store_dwordx2 v[94:95], v[92:93], off sc0 sc1
	v_pk_add_f32 v[90:91], v[90:91], v[122:123]
	v_mul_f32_e32 v92, v89, v89
	global_store_dwordx4 v[124:125], v[88:91], off offset:64 sc0 sc1
	v_fmac_f32_e32 v92, v88, v88
	v_mul_f32_e32 v93, v91, v91
	v_cvt_pk_bf16_f32 v88, v88, v89
	v_cvt_pk_bf16_f32 v89, v90, v91
	s_waitcnt vmcnt(16)
	v_pk_add_f32 v[86:87], v[86:87], v[118:119]
	v_pk_add_f32 v[84:85], v[84:85], v[116:117]
	v_fmac_f32_e32 v93, v90, v90
	global_store_dwordx2 v[94:95], v[88:89], off offset:32 sc0 sc1
	v_mul_f32_e32 v88, v85, v85
	v_mul_f32_e32 v89, v87, v87
	v_add_f32_e32 v126, v126, v127
	v_add_f32_e32 v92, v92, v93
	v_fmac_f32_e32 v88, v84, v84
	v_fmac_f32_e32 v89, v86, v86
	v_add_f32_e32 v92, v126, v92
	v_add_f32_e32 v88, v88, v89
	v_add_f32_e32 v92, v92, v88
	s_waitcnt vmcnt(16)
	v_pk_add_f32 v[90:91], v[82:83], v[114:115]
	v_pk_add_f32 v[88:89], v[80:81], v[112:113]
	v_mul_f32_e32 v81, v91, v91
	v_mul_f32_e32 v80, v89, v89
	v_fmac_f32_e32 v80, v88, v88
	v_fmac_f32_e32 v81, v90, v90
	v_add_f32_e32 v80, v80, v81
	v_add_f32_e32 v82, v92, v80
	ds_bpermute_b32 v83, v175, v82
	global_store_dwordx4 v[124:125], v[84:87], off offset:512 sc0 sc1
	v_cvt_pk_bf16_f32 v80, v84, v85
	v_cvt_pk_bf16_f32 v81, v86, v87
	global_store_dwordx2 v[94:95], v[80:81], off offset:256 sc0 sc1
	s_waitcnt lgkmcnt(0)
	v_add_f32_e32 v80, v82, v83
	ds_bpermute_b32 v81, v178, v80
	global_store_dwordx4 v[124:125], v[88:91], off offset:576 sc0 sc1
	v_cvt_pk_bf16_f32 v82, v88, v89
	v_cvt_pk_bf16_f32 v83, v90, v91
	global_store_dwordx2 v[94:95], v[82:83], off offset:288 sc0 sc1
	s_and_saveexec_b64 s[18:19], s[0:1]
	s_cbranch_execz .LBB0_790
	v_lshl_add_u64 v[82:83], v[128:129], 2, s[2:3]
	s_waitcnt lgkmcnt(0)
	v_add_f32_e32 v80, v80, v81
	global_atomic_add_f32 v[82:83], v80, off
; __device__ __forceinline__ unsigned cvt_pk_bf16(float lo, float hi) { unsigned r; asm volatile("v_cvt_pk_bf16_f32 %0, %1, %2" : "=v"(r) : "v"(lo), "v"(hi)); return r; }
;     __device__ __forceinline__ void operator()(const f32x4 (&acc)[2][2][4][2], const Unit& u, int wr, int wc, int fr, int fq) const {
;     ...
;         for (int g = 0; g < 8; ++g) {
;             const int ai = g >> 2, m = g & 3;
;             const int r = row0 + ai * HALF + m * 16; const size_t off = (size_t)r * DM + col0; float s = 0.f;
;             if (g < 7) { const float* nrow = base + (size_t)(((g + 1) >> 2) * HALF + ((g + 1) & 3) * 16) * DM;
; #pragma unroll
;                 for (int bj = 0; bj < 2; ++bj)
; #pragma unroll
;                     for (int n = 0; n < 2; ++n) nb[bj][n] = *(const f32x4*)(nrow + bj * HALF + n * 16); }
; #pragma unroll
;             for (int bj = 0; bj < 2; ++bj)
; #pragma unroll
;                 for (int n = 0; n < 2; ++n) {
;                     const f32x4 o = b[bj][n] + acc[ai][bj][m][n] * alpha;
;                     *(f32x4*)(out + off + bj * HALF + n * 16) = o;
;                     if (WITH_SSQ) s += (o[0] * o[0] + o[1] * o[1]) + (o[2] * o[2] + o[3] * o[3]);
;                     if (WITH_HB) { u32x2 w; w.x = cvt_pk_bf16(o[0], o[1]); w.y = cvt_pk_bf16(o[2], o[3]); *(u32x2*)(hb + off + bj * HALF + n * 16) = w; }
;                 }
;             if (WITH_SSQ) { s += __shfl_xor(s, 16); s += __shfl_xor(s, 32); if (fq == 0) atomicAdd(ssq + r, s); }
.LBB0_790:
	s_or_b64 exec, exec, s[18:19]
	v_add_co_u32_e32 v80, vcc, 0x100000, v162
	v_or_b32_e32 v112, 48, v164
	s_waitcnt lgkmcnt(0)
	v_addc_co_u32_e32 v81, vcc, 0, v163, vcc
	global_load_dwordx4 v[92:95], v[80:81], off
	global_load_dwordx4 v[88:91], v[80:81], off offset:64
	global_load_dwordx4 v[84:87], v[80:81], off offset:512
	s_nop 0
	global_load_dwordx4 v[80:83], v[80:81], off offset:576
	v_ashrrev_i32_e32 v113, 31, v112
	v_lshlrev_b64 v[114:115], 11, v[112:113]
	v_lshl_add_u64 v[114:115], v[114:115], 0, v[160:161]
	s_waitcnt vmcnt(15)
	v_pk_add_f32 v[78:79], v[78:79], v[110:111]
	v_pk_add_f32 v[76:77], v[76:77], v[108:109]
	v_readlane_b32 s18, v239, 25
	v_lshl_add_u64 v[108:109], v[114:115], 2, s[68:69]
	v_mul_f32_e32 v110, v77, v77
	v_mul_f32_e32 v111, v79, v79
	v_readlane_b32 s19, v239, 26
	global_store_dwordx4 v[108:109], v[76:79], off sc0 sc1
	v_fmac_f32_e32 v110, v76, v76
	v_fmac_f32_e32 v111, v78, v78
	v_cvt_pk_bf16_f32 v76, v76, v77
	v_cvt_pk_bf16_f32 v77, v78, v79
	v_lshl_add_u64 v[78:79], v[114:115], 1, s[18:19]
	s_waitcnt vmcnt(15)
	v_pk_add_f32 v[72:73], v[72:73], v[104:105]
	global_store_dwordx2 v[78:79], v[76:77], off sc0 sc1
	v_pk_add_f32 v[74:75], v[74:75], v[106:107]
	v_mul_f32_e32 v76, v73, v73
	global_store_dwordx4 v[108:109], v[72:75], off offset:64 sc0 sc1
	v_fmac_f32_e32 v76, v72, v72
	v_mul_f32_e32 v77, v75, v75
	v_cvt_pk_bf16_f32 v72, v72, v73
	v_cvt_pk_bf16_f32 v73, v74, v75
	s_waitcnt vmcnt(16)
	v_pk_add_f32 v[70:71], v[70:71], v[102:103]
	v_pk_add_f32 v[68:69], v[68:69], v[100:101]
	v_fmac_f32_e32 v77, v74, v74
	global_store_dwordx2 v[78:79], v[72:73], off offset:32 sc0 sc1
	v_mul_f32_e32 v72, v69, v69
	v_mul_f32_e32 v73, v71, v71
	v_add_f32_e32 v110, v110, v111
	v_add_f32_e32 v76, v76, v77
	v_fmac_f32_e32 v72, v68, v68
	v_fmac_f32_e32 v73, v70, v70
	v_add_f32_e32 v76, v110, v76
	v_add_f32_e32 v72, v72, v73
	v_add_f32_e32 v76, v76, v72
	s_waitcnt vmcnt(16)
	v_pk_add_f32 v[74:75], v[66:67], v[98:99]
	v_pk_add_f32 v[72:73], v[64:65], v[96:97]
	v_mul_f32_e32 v65, v75, v75
	v_mul_f32_e32 v64, v73, v73
	v_fmac_f32_e32 v64, v72, v72
	v_fmac_f32_e32 v65, v74, v74
	v_add_f32_e32 v64, v64, v65
	v_add_f32_e32 v66, v76, v64
	ds_bpermute_b32 v67, v175, v66
	global_store_dwordx4 v[108:109], v[68:71], off offset:512 sc0 sc1
	v_cvt_pk_bf16_f32 v64, v68, v69
	v_cvt_pk_bf16_f32 v65, v70, v71
	global_store_dwordx2 v[78:79], v[64:65], off offset:256 sc0 sc1
	s_waitcnt lgkmcnt(0)
	v_add_f32_e32 v64, v66, v67
	ds_bpermute_b32 v65, v178, v64
	global_store_dwordx4 v[108:109], v[72:75], off offset:576 sc0 sc1
	v_cvt_pk_bf16_f32 v66, v72, v73
	v_cvt_pk_bf16_f32 v67, v74, v75
	global_store_dwordx2 v[78:79], v[66:67], off offset:288 sc0 sc1
	s_and_saveexec_b64 s[18:19], s[0:1]
	s_cbranch_execz .LBB0_792
	v_lshl_add_u64 v[66:67], v[112:113], 2, s[2:3]
	s_waitcnt lgkmcnt(0)
	v_add_f32_e32 v64, v64, v65
	global_atomic_add_f32 v[66:67], v64, off
.LBB0_792:
	s_or_b64 exec, exec, s[18:19]
	v_add_co_u32_e32 v64, vcc, 0x120000, v162
	v_add_u32_e32 v96, 0x80, v164
	s_waitcnt lgkmcnt(0)
	v_addc_co_u32_e32 v65, vcc, 0, v163, vcc
	global_load_dwordx4 v[76:79], v[64:65], off
	global_load_dwordx4 v[72:75], v[64:65], off offset:64
	global_load_dwordx4 v[68:71], v[64:65], off offset:512
	s_nop 0
	global_load_dwordx4 v[64:67], v[64:65], off offset:576
	v_ashrrev_i32_e32 v97, 31, v96
	v_lshlrev_b64 v[98:99], 11, v[96:97]
	v_lshl_add_u64 v[98:99], v[98:99], 0, v[160:161]
	s_waitcnt vmcnt(15)
	v_pk_add_f32 v[62:63], v[62:63], v[94:95]
	v_pk_add_f32 v[60:61], v[60:61], v[92:93]
	v_readlane_b32 s18, v239, 25
	v_lshl_add_u64 v[92:93], v[98:99], 2, s[68:69]
	v_mul_f32_e32 v94, v61, v61
	v_mul_f32_e32 v95, v63, v63
	v_readlane_b32 s19, v239, 26
	global_store_dwordx4 v[92:93], v[60:63], off sc0 sc1
	v_fmac_f32_e32 v94, v60, v60
	v_fmac_f32_e32 v95, v62, v62
	v_cvt_pk_bf16_f32 v60, v60, v61
	v_cvt_pk_bf16_f32 v61, v62, v63
	v_lshl_add_u64 v[62:63], v[98:99], 1, s[18:19]
	s_waitcnt vmcnt(15)
	v_pk_add_f32 v[56:57], v[56:57], v[88:89]
	global_store_dwordx2 v[62:63], v[60:61], off sc0 sc1
	v_pk_add_f32 v[58:59], v[58:59], v[90:91]
	v_mul_f32_e32 v60, v57, v57
	global_store_dwordx4 v[92:93], v[56:59], off offset:64 sc0 sc1
	v_fmac_f32_e32 v60, v56, v56
	v_mul_f32_e32 v61, v59, v59
	v_cvt_pk_bf16_f32 v56, v56, v57
	v_cvt_pk_bf16_f32 v57, v58, v59
	s_waitcnt vmcnt(16)
	v_pk_add_f32 v[54:55], v[54:55], v[86:87]
	v_pk_add_f32 v[52:53], v[52:53], v[84:85]
	v_fmac_f32_e32 v61, v58, v58
	global_store_dwordx2 v[62:63], v[56:57], off offset:32 sc0 sc1
	v_mul_f32_e32 v56, v53, v53
	v_mul_f32_e32 v57, v55, v55
	v_add_f32_e32 v94, v94, v95
	v_add_f32_e32 v60, v60, v61
	v_fmac_f32_e32 v56, v52, v52
	v_fmac_f32_e32 v57, v54, v54
	v_add_f32_e32 v60, v94, v60
	v_add_f32_e32 v56, v56, v57
	v_add_f32_e32 v60, v60, v56
	s_waitcnt vmcnt(16)
	v_pk_add_f32 v[58:59], v[50:51], v[82:83]
	v_pk_add_f32 v[56:57], v[48:49], v[80:81]
	v_mul_f32_e32 v49, v59, v59
	v_mul_f32_e32 v48, v57, v57
	v_fmac_f32_e32 v48, v56, v56
	v_fmac_f32_e32 v49, v58, v58
	v_add_f32_e32 v48, v48, v49
	v_add_f32_e32 v50, v60, v48
	ds_bpermute_b32 v51, v175, v50
	global_store_dwordx4 v[92:93], v[52:55], off offset:512 sc0 sc1
	v_cvt_pk_bf16_f32 v48, v52, v53
	v_cvt_pk_bf16_f32 v49, v54, v55
	global_store_dwordx2 v[62:63], v[48:49], off offset:256 sc0 sc1
	s_waitcnt lgkmcnt(0)
	v_add_f32_e32 v48, v50, v51
	ds_bpermute_b32 v49, v178, v48
	global_store_dwordx4 v[92:93], v[56:59], off offset:576 sc0 sc1
	v_cvt_pk_bf16_f32 v50, v56, v57
	v_cvt_pk_bf16_f32 v51, v58, v59
	global_store_dwordx2 v[62:63], v[50:51], off offset:288 sc0 sc1
	s_and_saveexec_b64 s[18:19], s[0:1]
	s_cbranch_execz .LBB0_794
	v_lshl_add_u64 v[50:51], v[96:97], 2, s[2:3]
	s_waitcnt lgkmcnt(0)
	v_add_f32_e32 v48, v48, v49
	global_atomic_add_f32 v[50:51], v48, off
; __device__ __forceinline__ unsigned cvt_pk_bf16(float lo, float hi) { unsigned r; asm volatile("v_cvt_pk_bf16_f32 %0, %1, %2" : "=v"(r) : "v"(lo), "v"(hi)); return r; }
;     __device__ __forceinline__ void operator()(const f32x4 (&acc)[2][2][4][2], const Unit& u, int wr, int wc, int fr, int fq) const {
;     ...
;         for (int g = 0; g < 8; ++g) {
;             const int ai = g >> 2, m = g & 3;
;             const int r = row0 + ai * HALF + m * 16; const size_t off = (size_t)r * DM + col0; float s = 0.f;
;             if (g < 7) { const float* nrow = base + (size_t)(((g + 1) >> 2) * HALF + ((g + 1) & 3) * 16) * DM;
; #pragma unroll
;                 for (int bj = 0; bj < 2; ++bj)
; #pragma unroll
;                     for (int n = 0; n < 2; ++n) nb[bj][n] = *(const f32x4*)(nrow + bj * HALF + n * 16); }
; #pragma unroll
;             for (int bj = 0; bj < 2; ++bj)
; #pragma unroll
;                 for (int n = 0; n < 2; ++n) {
;                     const f32x4 o = b[bj][n] + acc[ai][bj][m][n] * alpha;
;                     *(f32x4*)(out + off + bj * HALF + n * 16) = o;
;                     if (WITH_SSQ) s += (o[0] * o[0] + o[1] * o[1]) + (o[2] * o[2] + o[3] * o[3]);
;                     if (WITH_HB) { u32x2 w; w.x = cvt_pk_bf16(o[0], o[1]); w.y = cvt_pk_bf16(o[2], o[3]); *(u32x2*)(hb + off + bj * HALF + n * 16) = w; }
;                 }
;             if (WITH_SSQ) { s += __shfl_xor(s, 16); s += __shfl_xor(s, 32); if (fq == 0) atomicAdd(ssq + r, s); }
.LBB0_794:
	s_or_b64 exec, exec, s[18:19]
	v_add_co_u32_e32 v48, vcc, 0x140000, v162
	v_or_b32_e32 v80, 16, v96
	s_waitcnt lgkmcnt(0)
	v_addc_co_u32_e32 v49, vcc, 0, v163, vcc
	global_load_dwordx4 v[60:63], v[48:49], off
	global_load_dwordx4 v[56:59], v[48:49], off offset:64
	global_load_dwordx4 v[52:55], v[48:49], off offset:512
	s_nop 0
	global_load_dwordx4 v[48:51], v[48:49], off offset:576
	v_ashrrev_i32_e32 v81, 31, v80
	v_lshlrev_b64 v[82:83], 11, v[80:81]
	v_lshl_add_u64 v[82:83], v[82:83], 0, v[160:161]
	s_waitcnt vmcnt(15)
	v_pk_add_f32 v[46:47], v[46:47], v[78:79]
	v_pk_add_f32 v[44:45], v[44:45], v[76:77]
	v_readlane_b32 s18, v239, 25
	v_lshl_add_u64 v[76:77], v[82:83], 2, s[68:69]
	v_mul_f32_e32 v78, v45, v45
	v_mul_f32_e32 v79, v47, v47
	v_readlane_b32 s19, v239, 26
	global_store_dwordx4 v[76:77], v[44:47], off sc0 sc1
	v_fmac_f32_e32 v78, v44, v44
	v_fmac_f32_e32 v79, v46, v46
	v_cvt_pk_bf16_f32 v44, v44, v45
	v_cvt_pk_bf16_f32 v45, v46, v47
	v_lshl_add_u64 v[46:47], v[82:83], 1, s[18:19]
	s_waitcnt vmcnt(15)
	v_pk_add_f32 v[40:41], v[40:41], v[72:73]
	global_store_dwordx2 v[46:47], v[44:45], off sc0 sc1
	v_pk_add_f32 v[42:43], v[42:43], v[74:75]
	v_mul_f32_e32 v44, v41, v41
	global_store_dwordx4 v[76:77], v[40:43], off offset:64 sc0 sc1
	v_fmac_f32_e32 v44, v40, v40
	v_mul_f32_e32 v45, v43, v43
	v_cvt_pk_bf16_f32 v40, v40, v41
	v_cvt_pk_bf16_f32 v41, v42, v43
	s_waitcnt vmcnt(16)
	v_pk_add_f32 v[38:39], v[38:39], v[70:71]
	v_pk_add_f32 v[36:37], v[36:37], v[68:69]
	v_fmac_f32_e32 v45, v42, v42
	global_store_dwordx2 v[46:47], v[40:41], off offset:32 sc0 sc1
	v_mul_f32_e32 v40, v37, v37
	v_mul_f32_e32 v41, v39, v39
	v_add_f32_e32 v78, v78, v79
	v_add_f32_e32 v44, v44, v45
	v_fmac_f32_e32 v40, v36, v36
	v_fmac_f32_e32 v41, v38, v38
	v_add_f32_e32 v44, v78, v44
	v_add_f32_e32 v40, v40, v41
	v_add_f32_e32 v44, v44, v40
	s_waitcnt vmcnt(16)
	v_pk_add_f32 v[42:43], v[34:35], v[66:67]
	v_pk_add_f32 v[40:41], v[32:33], v[64:65]
	v_mul_f32_e32 v33, v43, v43
	v_mul_f32_e32 v32, v41, v41
	v_fmac_f32_e32 v32, v40, v40
	v_fmac_f32_e32 v33, v42, v42
	v_add_f32_e32 v32, v32, v33
	v_add_f32_e32 v34, v44, v32
	ds_bpermute_b32 v35, v175, v34
	global_store_dwordx4 v[76:77], v[36:39], off offset:512 sc0 sc1
	v_cvt_pk_bf16_f32 v32, v36, v37
	v_cvt_pk_bf16_f32 v33, v38, v39
	global_store_dwordx2 v[46:47], v[32:33], off offset:256 sc0 sc1
	s_waitcnt lgkmcnt(0)
	v_add_f32_e32 v32, v34, v35
	ds_bpermute_b32 v33, v178, v32
	global_store_dwordx4 v[76:77], v[40:43], off offset:576 sc0 sc1
	v_cvt_pk_bf16_f32 v34, v40, v41
	v_cvt_pk_bf16_f32 v35, v42, v43
	global_store_dwordx2 v[46:47], v[34:35], off offset:288 sc0 sc1
	s_and_saveexec_b64 s[18:19], s[0:1]
	s_cbranch_execz .LBB0_796
	v_lshl_add_u64 v[34:35], v[80:81], 2, s[2:3]
	s_waitcnt lgkmcnt(0)
	v_add_f32_e32 v32, v32, v33
	global_atomic_add_f32 v[34:35], v32, off
; __device__ __forceinline__ unsigned cvt_pk_bf16(float lo, float hi) { unsigned r; asm volatile("v_cvt_pk_bf16_f32 %0, %1, %2" : "=v"(r) : "v"(lo), "v"(hi)); return r; }
;     __device__ __forceinline__ void operator()(const f32x4 (&acc)[2][2][4][2], const Unit& u, int wr, int wc, int fr, int fq) const {
;     ...
;         for (int g = 0; g < 8; ++g) {
;             const int ai = g >> 2, m = g & 3;
;             const int r = row0 + ai * HALF + m * 16; const size_t off = (size_t)r * DM + col0; float s = 0.f;
;             if (g < 7) { const float* nrow = base + (size_t)(((g + 1) >> 2) * HALF + ((g + 1) & 3) * 16) * DM;
; #pragma unroll
;                 for (int bj = 0; bj < 2; ++bj)
; #pragma unroll
;                     for (int n = 0; n < 2; ++n) nb[bj][n] = *(const f32x4*)(nrow + bj * HALF + n * 16); }
; #pragma unroll
;             for (int bj = 0; bj < 2; ++bj)
; #pragma unroll
;                 for (int n = 0; n < 2; ++n) {
;                     const f32x4 o = b[bj][n] + acc[ai][bj][m][n] * alpha;
;                     *(f32x4*)(out + off + bj * HALF + n * 16) = o;
;                     if (WITH_SSQ) s += (o[0] * o[0] + o[1] * o[1]) + (o[2] * o[2] + o[3] * o[3]);
;                     if (WITH_HB) { u32x2 w; w.x = cvt_pk_bf16(o[0], o[1]); w.y = cvt_pk_bf16(o[2], o[3]); *(u32x2*)(hb + off + bj * HALF + n * 16) = w; }
;                 }
;             if (WITH_SSQ) { s += __shfl_xor(s, 16); s += __shfl_xor(s, 32); if (fq == 0) atomicAdd(ssq + r, s); }
.LBB0_796:
	s_or_b64 exec, exec, s[18:19]
	v_add_co_u32_e32 v32, vcc, 0x160000, v162
	v_or_b32_e32 v64, 32, v96
	s_waitcnt lgkmcnt(0)
	v_addc_co_u32_e32 v33, vcc, 0, v163, vcc
	global_load_dwordx4 v[44:47], v[32:33], off
	global_load_dwordx4 v[40:43], v[32:33], off offset:64
	global_load_dwordx4 v[36:39], v[32:33], off offset:512
	s_nop 0
	global_load_dwordx4 v[32:35], v[32:33], off offset:576
	v_ashrrev_i32_e32 v65, 31, v64
	v_lshlrev_b64 v[66:67], 11, v[64:65]
	v_lshl_add_u64 v[66:67], v[66:67], 0, v[160:161]
	s_waitcnt vmcnt(15)
	v_pk_add_f32 v[30:31], v[30:31], v[62:63]
	v_pk_add_f32 v[28:29], v[28:29], v[60:61]
	v_readlane_b32 s18, v239, 25
	v_lshl_add_u64 v[60:61], v[66:67], 2, s[68:69]
	v_mul_f32_e32 v62, v29, v29
	v_mul_f32_e32 v63, v31, v31
	v_readlane_b32 s19, v239, 26
	global_store_dwordx4 v[60:61], v[28:31], off sc0 sc1
	v_fmac_f32_e32 v62, v28, v28
	v_fmac_f32_e32 v63, v30, v30
	v_cvt_pk_bf16_f32 v28, v28, v29
	v_cvt_pk_bf16_f32 v29, v30, v31
	v_lshl_add_u64 v[30:31], v[66:67], 1, s[18:19]
	s_waitcnt vmcnt(15)
	v_pk_add_f32 v[24:25], v[24:25], v[56:57]
	global_store_dwordx2 v[30:31], v[28:29], off sc0 sc1
	v_pk_add_f32 v[26:27], v[26:27], v[58:59]
	v_mul_f32_e32 v28, v25, v25
	global_store_dwordx4 v[60:61], v[24:27], off offset:64 sc0 sc1
	v_fmac_f32_e32 v28, v24, v24
	v_mul_f32_e32 v29, v27, v27
	v_cvt_pk_bf16_f32 v24, v24, v25
	v_cvt_pk_bf16_f32 v25, v26, v27
	s_waitcnt vmcnt(16)
	v_pk_add_f32 v[22:23], v[22:23], v[54:55]
	v_pk_add_f32 v[20:21], v[20:21], v[52:53]
	v_fmac_f32_e32 v29, v26, v26
	global_store_dwordx2 v[30:31], v[24:25], off offset:32 sc0 sc1
	v_mul_f32_e32 v24, v21, v21
	v_mul_f32_e32 v25, v23, v23
	v_add_f32_e32 v62, v62, v63
	v_add_f32_e32 v28, v28, v29
	v_fmac_f32_e32 v24, v20, v20
	v_fmac_f32_e32 v25, v22, v22
	v_add_f32_e32 v28, v62, v28
	v_add_f32_e32 v24, v24, v25
	v_add_f32_e32 v28, v28, v24
	s_waitcnt vmcnt(16)
	v_pk_add_f32 v[26:27], v[18:19], v[50:51]
	v_pk_add_f32 v[24:25], v[16:17], v[48:49]
	v_mul_f32_e32 v17, v27, v27
	v_mul_f32_e32 v16, v25, v25
	v_fmac_f32_e32 v16, v24, v24
	v_fmac_f32_e32 v17, v26, v26
	v_add_f32_e32 v16, v16, v17
	v_add_f32_e32 v18, v28, v16
	ds_bpermute_b32 v19, v175, v18
	global_store_dwordx4 v[60:61], v[20:23], off offset:512 sc0 sc1
	v_cvt_pk_bf16_f32 v16, v20, v21
	v_cvt_pk_bf16_f32 v17, v22, v23
	global_store_dwordx2 v[30:31], v[16:17], off offset:256 sc0 sc1
	s_waitcnt lgkmcnt(0)
	v_add_f32_e32 v16, v18, v19
	ds_bpermute_b32 v17, v178, v16
	global_store_dwordx4 v[60:61], v[24:27], off offset:576 sc0 sc1
	v_cvt_pk_bf16_f32 v18, v24, v25
	v_cvt_pk_bf16_f32 v19, v26, v27
	global_store_dwordx2 v[30:31], v[18:19], off offset:288 sc0 sc1
	s_and_saveexec_b64 s[18:19], s[0:1]
	s_cbranch_execz .LBB0_798
	v_lshl_add_u64 v[18:19], v[64:65], 2, s[2:3]
	s_waitcnt lgkmcnt(0)
	v_add_f32_e32 v16, v16, v17
	global_atomic_add_f32 v[18:19], v16, off
.LBB0_798:
	s_or_b64 exec, exec, s[18:19]
	v_or_b32_e32 v16, 48, v96
	s_waitcnt lgkmcnt(0)
	v_ashrrev_i32_e32 v17, 31, v16
	v_lshlrev_b64 v[18:19], 11, v[16:17]
	v_lshl_add_u64 v[18:19], v[18:19], 0, v[160:161]
	s_waitcnt vmcnt(11)
	v_pk_add_f32 v[14:15], v[14:15], v[46:47]
	v_pk_add_f32 v[12:13], v[12:13], v[44:45]
	v_readlane_b32 s18, v239, 25
	v_lshl_add_u64 v[20:21], v[18:19], 2, s[68:69]
	v_mul_f32_e32 v22, v13, v13
	v_mul_f32_e32 v23, v15, v15
	v_readlane_b32 s19, v239, 26
	global_store_dwordx4 v[20:21], v[12:15], off sc0 sc1
	v_fmac_f32_e32 v22, v12, v12
	v_fmac_f32_e32 v23, v14, v14
	v_cvt_pk_bf16_f32 v12, v12, v13
	v_cvt_pk_bf16_f32 v13, v14, v15
	v_lshl_add_u64 v[14:15], v[18:19], 1, s[18:19]
	s_waitcnt vmcnt(11)
	v_pk_add_f32 v[8:9], v[8:9], v[40:41]
	global_store_dwordx2 v[14:15], v[12:13], off sc0 sc1
	v_pk_add_f32 v[10:11], v[10:11], v[42:43]
	v_mul_f32_e32 v12, v9, v9
	global_store_dwordx4 v[20:21], v[8:11], off offset:64 sc0 sc1
	v_fmac_f32_e32 v12, v8, v8
	v_mul_f32_e32 v13, v11, v11
	v_cvt_pk_bf16_f32 v8, v8, v9
	v_cvt_pk_bf16_f32 v9, v10, v11
	s_waitcnt vmcnt(12)
	v_pk_add_f32 v[6:7], v[6:7], v[38:39]
	v_pk_add_f32 v[4:5], v[4:5], v[36:37]
	v_fmac_f32_e32 v13, v10, v10
	global_store_dwordx2 v[14:15], v[8:9], off offset:32 sc0 sc1
	v_mul_f32_e32 v8, v5, v5
	v_mul_f32_e32 v9, v7, v7
	v_add_f32_e32 v22, v22, v23
	v_add_f32_e32 v12, v12, v13
	v_fmac_f32_e32 v8, v4, v4
	v_fmac_f32_e32 v9, v6, v6
	v_add_f32_e32 v12, v22, v12
	v_add_f32_e32 v8, v8, v9
	v_add_f32_e32 v12, v12, v8
	s_waitcnt vmcnt(12)
	v_pk_add_f32 v[10:11], v[2:3], v[34:35]
	v_pk_add_f32 v[8:9], v[0:1], v[32:33]
	v_mul_f32_e32 v1, v11, v11
	v_mul_f32_e32 v0, v9, v9
	v_fmac_f32_e32 v0, v8, v8
	v_fmac_f32_e32 v1, v10, v10
	v_add_f32_e32 v0, v0, v1
	v_add_f32_e32 v2, v12, v0
	ds_bpermute_b32 v3, v175, v2
	global_store_dwordx4 v[20:21], v[4:7], off offset:512 sc0 sc1
	v_cvt_pk_bf16_f32 v0, v4, v5
	v_cvt_pk_bf16_f32 v1, v6, v7
	global_store_dwordx2 v[14:15], v[0:1], off offset:256 sc0 sc1
	s_waitcnt lgkmcnt(0)
	v_add_f32_e32 v0, v2, v3
	ds_bpermute_b32 v1, v178, v0
	global_store_dwordx4 v[20:21], v[8:11], off offset:576 sc0 sc1
	v_cvt_pk_bf16_f32 v2, v8, v9
	v_cvt_pk_bf16_f32 v3, v10, v11
	global_store_dwordx2 v[14:15], v[2:3], off offset:288 sc0 sc1
	s_and_saveexec_b64 s[18:19], s[0:1]
	s_cbranch_execz .LBB0_779
	v_lshl_add_u64 v[2:3], v[16:17], 2, s[2:3]
	s_waitcnt lgkmcnt(0)
	v_add_f32_e32 v0, v0, v1
	global_atomic_add_f32 v[2:3], v0, off
	s_branch .LBB0_779

; #define PG8_STAGE(bufoff, gbase, voff) do { _Pragma("unroll") for (int _i = 0; _i < 2; ++_i) \
;         __builtin_amdgcn_global_load_lds((const unsigned*)((const char*)(gbase) + (voff)[_i]), (LAS unsigned*)(lds + (bufoff) + ldsw + _i * 8192), 16, 0, 0); } while (0)
; #define PG8_LDA(dst, b, h) do { _Pragma("unroll") for (int m = 0; m < 4; ++m) _Pragma("unroll") for (int k = 0; k < 2; ++k) dst[m][k] = *(const LAS bf16x8*)(lds + PG8_SA(b, h) + aoff + m * 2048 + k * 1024); } while (0)
; #define PG8_WAIT_V(n) asm volatile("s_waitcnt vmcnt(" #n ")" ::: "memory")
; #define PG8_BAR __builtin_amdgcn_s_barrier()
; template <class Epi, class Sched>
; __device__ __forceinline__ void gemm_phase(LAS unsigned char* lds, const Gemm g, const Sched& S, const Epi& E) {
;     ...
;         for (int t = 0; t < nt; t += 2) {
;             const bool last = (t == nt - 2);
;             const char* a1 = cA + (size_t)(t + 1) * kstep;
;             const char* a2 = last ? nA : cA + (size_t)(t + 2) * kstep; const char* b2 = last ? nB : cB + (size_t)(t + 2) * kstep;
;             const char* a3 = a2 + kstep; const char* b3 = b2 + kstep;
;             PG8_LDB(B0, 0, 0); PG8_SCHED; PG8_LDA(At, 0, 0); PG8_STAGE(PG8_SA(1, 1), a1 + hstepA, voffA);
;             PG8_WAIT_L(8); PG8_BAR; PG8_WAIT_L(0); PG8_MMA(0, 0, At, B0); PG8_BAR; PG8_SCHED;
;             PG8_LDB(B1, 0, 1); PG8_STAGE(PG8_SB(0, 0), b2, voffB);
;             PG8_BAR; PG8_WAIT_L(0); PG8_MMA(0, 1, At, B1); PG8_BAR;
;             PG8_LDA(At, 0, 1); PG8_STAGE(PG8_SA(0, 0), a2, voffA);
;             PG8_BAR; PG8_WAIT_L(0); PG8_MMA(1, 0, At, B0); PG8_BAR; PG8_SCHED;
;             PG8_STAGE(PG8_SB(0, 1), b2 + hstepB, voffB);
;             PG8_WAIT_V(6); PG8_BAR; PG8_MMA(1, 1, At, B1); PG8_BAR;
;             PG8_LDB(B0, 1, 0); PG8_SCHED; PG8_LDA(At, 1, 0); PG8_STAGE(PG8_SA(0, 1), a2 + hstepA, voffA);
;             PG8_WAIT_L(8); PG8_BAR; PG8_WAIT_L(0); PG8_MMA(0, 0, At, B0); PG8_BAR; PG8_SCHED;
;             PG8_LDB(B1, 1, 1); PG8_STAGE(PG8_SB(1, 0), b3, voffB);
;             PG8_BAR; PG8_WAIT_L(0); PG8_MMA(0, 1, At, B1); PG8_BAR;
;             PG8_LDA(At, 1, 1); PG8_STAGE(PG8_SA(1, 0), a3, voffA);
;             PG8_BAR; PG8_WAIT_L(0); PG8_MMA(1, 0, At, B0); PG8_BAR; PG8_SCHED;
;             PG8_STAGE(PG8_SB(1, 1), b3 + hstepB, voffB);
;             PG8_WAIT_V(6); PG8_BAR; PG8_MMA(1, 1, At, B1); PG8_BAR;
;         }
.LBB0_865:
	ds_read_b128 v[154:157], v149
	ds_read_b128 v[158:161], v149 offset:1024
	ds_read_b128 v[162:165], v149 offset:2048
	ds_read_b128 v[166:169], v149 offset:3072
	s_add_u32 s20, s18, 0xfff80080
	s_addc_u32 s21, s19, -1
	s_cmp_eq_u32 s44, 28
	s_cselect_b32 s23, s11, s21
	s_cselect_b32 s22, s40, s20
	s_cselect_b32 s21, s9, s43
	s_cselect_b32 s20, s41, s42
	v_lshl_add_u64 v[144:145], s[18:19], 0, v[136:137]
	s_add_i32 m0, s17, 0xc000
	ds_read_b128 v[170:173], v150
	ds_read_b128 v[178:181], v150 offset:1024
	ds_read_b128 v[182:185], v150 offset:2048
	ds_read_b128 v[186:189], v150 offset:3072
	ds_read_b128 v[190:193], v150 offset:4096
	ds_read_b128 v[194:197], v150 offset:5120
	ds_read_b128 v[198:201], v150 offset:6144
	ds_read_b128 v[202:205], v150 offset:7168
	global_load_lds_dwordx4 v[144:145], off
	v_lshl_add_u64 v[144:145], s[18:19], 0, v[138:139]
	s_add_i32 m0, s17, 0xe000
	s_nop 0
	global_load_lds_dwordx4 v[144:145], off
	s_waitcnt lgkmcnt(8)
	s_barrier
	s_waitcnt lgkmcnt(0)
	s_setprio 1
	s_waitcnt lgkmcnt(0)
	v_mfma_f32_16x16x32_bf16 v[116:119], v[154:157], v[170:173], v[116:119]
	v_mfma_f32_16x16x32_bf16 v[112:115], v[162:165], v[170:173], v[112:115]
	v_mfma_f32_16x16x32_bf16 v[108:111], v[154:157], v[182:185], v[108:111]
	v_mfma_f32_16x16x32_bf16 v[100:103], v[162:165], v[182:185], v[100:103]
	v_mfma_f32_16x16x32_bf16 v[92:95], v[154:157], v[190:193], v[92:95]
	v_mfma_f32_16x16x32_bf16 v[84:87], v[162:165], v[190:193], v[84:87]
	v_mfma_f32_16x16x32_bf16 v[76:79], v[154:157], v[198:201], v[76:79]
	v_mfma_f32_16x16x32_bf16 v[68:71], v[162:165], v[198:201], v[68:71]
	v_mfma_f32_16x16x32_bf16 v[116:119], v[158:161], v[178:181], v[116:119]
	v_mfma_f32_16x16x32_bf16 v[112:115], v[166:169], v[178:181], v[112:115]
	v_mfma_f32_16x16x32_bf16 v[108:111], v[158:161], v[186:189], v[108:111]
	v_mfma_f32_16x16x32_bf16 v[100:103], v[166:169], v[186:189], v[100:103]
	v_mfma_f32_16x16x32_bf16 v[92:95], v[158:161], v[194:197], v[92:95]
	v_mfma_f32_16x16x32_bf16 v[84:87], v[166:169], v[194:197], v[84:87]
	v_mfma_f32_16x16x32_bf16 v[76:79], v[158:161], v[202:205], v[76:79]
	v_mfma_f32_16x16x32_bf16 v[68:71], v[166:169], v[202:205], v[68:71]
	s_setprio 0
	s_barrier
	s_add_i32 s45, s36, s25
	v_lshl_add_u64 v[144:145], s[20:21], 0, v[132:133]
	s_mov_b32 m0, s45
	ds_read_b128 v[206:209], v151
	ds_read_b128 v[210:213], v151 offset:1024
	ds_read_b128 v[214:217], v151 offset:2048
	ds_read_b128 v[218:221], v151 offset:3072
	global_load_lds_dwordx4 v[144:145], off
	v_lshl_add_u64 v[174:175], s[20:21], 0, v[128:129]
	s_add_i32 m0, s45, 0x2000
	s_nop 0
	global_load_lds_dwordx4 v[174:175], off
	s_barrier
	s_waitcnt lgkmcnt(0)
	s_setprio 1
	s_waitcnt lgkmcnt(0)
	v_mfma_f32_16x16x32_bf16 v[124:127], v[206:209], v[170:173], v[124:127]
	v_mfma_f32_16x16x32_bf16 v[120:123], v[214:217], v[170:173], v[120:123]
	v_mfma_f32_16x16x32_bf16 v[104:107], v[206:209], v[182:185], v[104:107]
	v_mfma_f32_16x16x32_bf16 v[96:99], v[214:217], v[182:185], v[96:99]
	v_mfma_f32_16x16x32_bf16 v[88:91], v[206:209], v[190:193], v[88:91]
	v_mfma_f32_16x16x32_bf16 v[80:83], v[214:217], v[190:193], v[80:83]
	v_mfma_f32_16x16x32_bf16 v[72:75], v[206:209], v[198:201], v[72:75]
	v_mfma_f32_16x16x32_bf16 v[64:67], v[214:217], v[198:201], v[64:67]
	v_mfma_f32_16x16x32_bf16 v[124:127], v[210:213], v[178:181], v[124:127]
	v_mfma_f32_16x16x32_bf16 v[120:123], v[218:221], v[178:181], v[120:123]
	v_mfma_f32_16x16x32_bf16 v[104:107], v[210:213], v[186:189], v[104:107]
	v_mfma_f32_16x16x32_bf16 v[96:99], v[218:221], v[186:189], v[96:99]
	v_mfma_f32_16x16x32_bf16 v[88:91], v[210:213], v[194:197], v[88:91]
	v_mfma_f32_16x16x32_bf16 v[80:83], v[218:221], v[194:197], v[80:83]
	v_mfma_f32_16x16x32_bf16 v[72:75], v[210:213], v[202:205], v[72:75]
	v_mfma_f32_16x16x32_bf16 v[64:67], v[218:221], v[202:205], v[64:67]
	s_setprio 0
	s_mov_b32 m0, s17
	v_lshl_add_u64 v[222:223], s[22:23], 0, v[134:135]
	s_barrier
	ds_read_b128 v[170:173], v150 offset:16384
	ds_read_b128 v[178:181], v150 offset:17408
	ds_read_b128 v[182:185], v150 offset:18432
	ds_read_b128 v[186:189], v150 offset:19456
	ds_read_b128 v[190:193], v150 offset:20480
	ds_read_b128 v[194:197], v150 offset:21504
	ds_read_b128 v[198:201], v150 offset:22528
	ds_read_b128 v[202:205], v150 offset:23552
	global_load_lds_dwordx4 v[222:223], off
	v_lshl_add_u64 v[224:225], s[22:23], 0, v[130:131]
	s_mov_b32 m0, s28
	s_nop 0
	global_load_lds_dwordx4 v[224:225], off
	s_barrier
	s_waitcnt lgkmcnt(0)
	s_setprio 1
	s_waitcnt lgkmcnt(0)
	v_mfma_f32_16x16x32_bf16 v[60:63], v[154:157], v[170:173], v[60:63]
	v_mfma_f32_16x16x32_bf16 v[52:55], v[162:165], v[170:173], v[52:55]
	v_mfma_f32_16x16x32_bf16 v[44:47], v[154:157], v[182:185], v[44:47]
	v_mfma_f32_16x16x32_bf16 v[36:39], v[162:165], v[182:185], v[36:39]
	v_mfma_f32_16x16x32_bf16 v[28:31], v[154:157], v[190:193], v[28:31]
	v_mfma_f32_16x16x32_bf16 v[20:23], v[162:165], v[190:193], v[20:23]
	v_mfma_f32_16x16x32_bf16 v[12:15], v[154:157], v[198:201], v[12:15]
	v_mfma_f32_16x16x32_bf16 v[4:7], v[162:165], v[198:201], v[4:7]
	v_mfma_f32_16x16x32_bf16 v[60:63], v[158:161], v[178:181], v[60:63]
	v_mfma_f32_16x16x32_bf16 v[52:55], v[166:169], v[178:181], v[52:55]
	v_mfma_f32_16x16x32_bf16 v[44:47], v[158:161], v[186:189], v[44:47]
	v_mfma_f32_16x16x32_bf16 v[36:39], v[166:169], v[186:189], v[36:39]
	v_mfma_f32_16x16x32_bf16 v[28:31], v[158:161], v[194:197], v[28:31]
	v_mfma_f32_16x16x32_bf16 v[20:23], v[166:169], v[194:197], v[20:23]
	v_mfma_f32_16x16x32_bf16 v[12:15], v[158:161], v[202:205], v[12:15]
	v_mfma_f32_16x16x32_bf16 v[4:7], v[166:169], v[202:205], v[4:7]
	s_setprio 0
	s_barrier
; #define PG8_STAGE(bufoff, gbase, voff) do { _Pragma("unroll") for (int _i = 0; _i < 2; ++_i) \
;         __builtin_amdgcn_global_load_lds((const unsigned*)((const char*)(gbase) + (voff)[_i]), (LAS unsigned*)(lds + (bufoff) + ldsw + _i * 8192), 16, 0, 0); } while (0)
; #define PG8_LDA(dst, b, h) do { _Pragma("unroll") for (int m = 0; m < 4; ++m) _Pragma("unroll") for (int k = 0; k < 2; ++k) dst[m][k] = *(const LAS bf16x8*)(lds + PG8_SA(b, h) + aoff + m * 2048 + k * 1024); } while (0)
; #define PG8_WAIT_V(n) asm volatile("s_waitcnt vmcnt(" #n ")" ::: "memory")
; #define PG8_BAR __builtin_amdgcn_s_barrier()
; template <class Epi, class Sched>
; __device__ __forceinline__ void gemm_phase(LAS unsigned char* lds, const Gemm g, const Sched& S, const Epi& E) {
;     ...
;         for (int t = 0; t < nt; t += 2) {
;             const bool last = (t == nt - 2);
;             const char* a1 = cA + (size_t)(t + 1) * kstep;
;             const char* a2 = last ? nA : cA + (size_t)(t + 2) * kstep; const char* b2 = last ? nB : cB + (size_t)(t + 2) * kstep;
;             const char* a3 = a2 + kstep; const char* b3 = b2 + kstep;
;             PG8_LDB(B0, 0, 0); PG8_SCHED; PG8_LDA(At, 0, 0); PG8_STAGE(PG8_SA(1, 1), a1 + hstepA, voffA);
;             PG8_WAIT_L(8); PG8_BAR; PG8_WAIT_L(0); PG8_MMA(0, 0, At, B0); PG8_BAR; PG8_SCHED;
;             PG8_LDB(B1, 0, 1); PG8_STAGE(PG8_SB(0, 0), b2, voffB);
;             PG8_BAR; PG8_WAIT_L(0); PG8_MMA(0, 1, At, B1); PG8_BAR;
;             PG8_LDA(At, 0, 1); PG8_STAGE(PG8_SA(0, 0), a2, voffA);
;             PG8_BAR; PG8_WAIT_L(0); PG8_MMA(1, 0, At, B0); PG8_BAR; PG8_SCHED;
;             PG8_STAGE(PG8_SB(0, 1), b2 + hstepB, voffB);
;             PG8_WAIT_V(6); PG8_BAR; PG8_MMA(1, 1, At, B1); PG8_BAR;
;             PG8_LDB(B0, 1, 0); PG8_SCHED; PG8_LDA(At, 1, 0); PG8_STAGE(PG8_SA(0, 1), a2 + hstepA, voffA);
;             PG8_WAIT_L(8); PG8_BAR; PG8_WAIT_L(0); PG8_MMA(0, 0, At, B0); PG8_BAR; PG8_SCHED;
;             PG8_LDB(B1, 1, 1); PG8_STAGE(PG8_SB(1, 0), b3, voffB);
;             PG8_BAR; PG8_WAIT_L(0); PG8_MMA(0, 1, At, B1); PG8_BAR;
;             PG8_LDA(At, 1, 1); PG8_STAGE(PG8_SA(1, 0), a3, voffA);
;             PG8_BAR; PG8_WAIT_L(0); PG8_MMA(1, 0, At, B0); PG8_BAR; PG8_SCHED;
;             PG8_STAGE(PG8_SB(1, 1), b3 + hstepB, voffB);
;             PG8_WAIT_V(6); PG8_BAR; PG8_MMA(1, 1, At, B1); PG8_BAR;
;         }
	s_add_u32 s46, s20, 0x80000
	s_addc_u32 s47, s21, 0
	s_add_i32 s45, s37, s25
	v_lshl_add_u64 v[154:155], s[46:47], 0, v[132:133]
	s_mov_b32 m0, s45
	s_nop 0
	global_load_lds_dwordx4 v[154:155], off
	v_lshl_add_u64 v[154:155], s[46:47], 0, v[128:129]
	s_add_i32 m0, s45, 0x2000
	s_nop 0
	global_load_lds_dwordx4 v[154:155], off
	s_waitcnt vmcnt(6)
	s_barrier
	s_setprio 1
	v_mfma_f32_16x16x32_bf16 v[56:59], v[206:209], v[170:173], v[56:59]
	v_mfma_f32_16x16x32_bf16 v[48:51], v[214:217], v[170:173], v[48:51]
	v_mfma_f32_16x16x32_bf16 v[40:43], v[206:209], v[182:185], v[40:43]
	v_mfma_f32_16x16x32_bf16 v[32:35], v[214:217], v[182:185], v[32:35]
	v_mfma_f32_16x16x32_bf16 v[24:27], v[206:209], v[190:193], v[24:27]
	v_mfma_f32_16x16x32_bf16 v[16:19], v[214:217], v[190:193], v[16:19]
	v_mfma_f32_16x16x32_bf16 v[8:11], v[206:209], v[198:201], v[8:11]
	v_mfma_f32_16x16x32_bf16 v[0:3], v[214:217], v[198:201], v[0:3]
	v_mfma_f32_16x16x32_bf16 v[56:59], v[210:213], v[178:181], v[56:59]
	v_mfma_f32_16x16x32_bf16 v[48:51], v[218:221], v[178:181], v[48:51]
	v_mfma_f32_16x16x32_bf16 v[40:43], v[210:213], v[186:189], v[40:43]
	v_mfma_f32_16x16x32_bf16 v[32:35], v[218:221], v[186:189], v[32:35]
	v_mfma_f32_16x16x32_bf16 v[24:27], v[210:213], v[194:197], v[24:27]
	v_mfma_f32_16x16x32_bf16 v[16:19], v[218:221], v[194:197], v[16:19]
	v_mfma_f32_16x16x32_bf16 v[8:11], v[210:213], v[202:205], v[8:11]
	v_mfma_f32_16x16x32_bf16 v[0:3], v[218:221], v[202:205], v[0:3]
	s_setprio 0
	s_add_i32 s45, 0, 0x18000
	v_add_u32_e32 v153, s45, v147
	s_barrier
	ds_read_b128 v[154:157], v153
	ds_read_b128 v[158:161], v153 offset:1024
	ds_read_b128 v[162:165], v153 offset:2048
	ds_read_b128 v[166:169], v153 offset:3072
	s_add_u32 s22, s22, 0x80000
	s_addc_u32 s23, s23, 0
	s_mov_b32 m0, s29
	v_lshl_add_u64 v[206:207], s[22:23], 0, v[134:135]
	ds_read_b128 v[170:173], v150 offset:32768
	ds_read_b128 v[178:181], v150 offset:33792
	ds_read_b128 v[182:185], v150 offset:34816
	ds_read_b128 v[186:189], v150 offset:35840
	ds_read_b128 v[190:193], v150 offset:36864
	ds_read_b128 v[194:197], v150 offset:37888
	ds_read_b128 v[198:201], v150 offset:38912
	ds_read_b128 v[202:205], v150 offset:39936
	global_load_lds_dwordx4 v[206:207], off
	v_lshl_add_u64 v[206:207], s[22:23], 0, v[130:131]
	s_mov_b32 m0, s30
	s_nop 0
	global_load_lds_dwordx4 v[206:207], off
	s_waitcnt lgkmcnt(8)
	s_barrier
	s_waitcnt lgkmcnt(0)
	s_setprio 1
	s_waitcnt lgkmcnt(0)
	v_mfma_f32_16x16x32_bf16 v[116:119], v[154:157], v[170:173], v[116:119]
	v_mfma_f32_16x16x32_bf16 v[112:115], v[162:165], v[170:173], v[112:115]
	v_mfma_f32_16x16x32_bf16 v[108:111], v[154:157], v[182:185], v[108:111]
	v_mfma_f32_16x16x32_bf16 v[100:103], v[162:165], v[182:185], v[100:103]
	v_mfma_f32_16x16x32_bf16 v[92:95], v[154:157], v[190:193], v[92:95]
	v_mfma_f32_16x16x32_bf16 v[84:87], v[162:165], v[190:193], v[84:87]
	v_mfma_f32_16x16x32_bf16 v[76:79], v[154:157], v[198:201], v[76:79]
	v_mfma_f32_16x16x32_bf16 v[68:71], v[162:165], v[198:201], v[68:71]
	v_mfma_f32_16x16x32_bf16 v[116:119], v[158:161], v[178:181], v[116:119]
	v_mfma_f32_16x16x32_bf16 v[112:115], v[166:169], v[178:181], v[112:115]
	v_mfma_f32_16x16x32_bf16 v[108:111], v[158:161], v[186:189], v[108:111]
	v_mfma_f32_16x16x32_bf16 v[100:103], v[166:169], v[186:189], v[100:103]
	v_mfma_f32_16x16x32_bf16 v[92:95], v[158:161], v[194:197], v[92:95]
	v_mfma_f32_16x16x32_bf16 v[84:87], v[166:169], v[194:197], v[84:87]
	v_mfma_f32_16x16x32_bf16 v[76:79], v[158:161], v[202:205], v[76:79]
	v_mfma_f32_16x16x32_bf16 v[68:71], v[166:169], v[202:205], v[68:71]
	s_setprio 0
	s_barrier
	s_add_i32 s22, 0, 0x1c000
	s_add_i32 s23, s45, s25
	v_add_u32_e32 v153, s22, v147
	v_lshl_add_u64 v[144:145], v[144:145], 0, s[6:7]
	s_mov_b32 m0, s23
	ds_read_b128 v[206:209], v153
	ds_read_b128 v[210:213], v153 offset:1024
	ds_read_b128 v[214:217], v153 offset:2048
	ds_read_b128 v[218:221], v153 offset:3072
	global_load_lds_dwordx4 v[144:145], off
	v_lshl_add_u64 v[144:145], v[174:175], 0, s[6:7]
	s_add_i32 m0, s23, 0x2000
	s_nop 0
	global_load_lds_dwordx4 v[144:145], off
	s_barrier
	s_waitcnt lgkmcnt(0)
	s_setprio 1
	s_waitcnt lgkmcnt(0)
	v_mfma_f32_16x16x32_bf16 v[124:127], v[206:209], v[170:173], v[124:127]
	v_mfma_f32_16x16x32_bf16 v[120:123], v[214:217], v[170:173], v[120:123]
	v_mfma_f32_16x16x32_bf16 v[104:107], v[206:209], v[182:185], v[104:107]
	v_mfma_f32_16x16x32_bf16 v[96:99], v[214:217], v[182:185], v[96:99]
	v_mfma_f32_16x16x32_bf16 v[88:91], v[206:209], v[190:193], v[88:91]
	v_mfma_f32_16x16x32_bf16 v[80:83], v[214:217], v[190:193], v[80:83]
	v_mfma_f32_16x16x32_bf16 v[72:75], v[206:209], v[198:201], v[72:75]
	v_mfma_f32_16x16x32_bf16 v[64:67], v[214:217], v[198:201], v[64:67]
	v_mfma_f32_16x16x32_bf16 v[124:127], v[210:213], v[178:181], v[124:127]
	v_mfma_f32_16x16x32_bf16 v[120:123], v[218:221], v[178:181], v[120:123]
	v_mfma_f32_16x16x32_bf16 v[104:107], v[210:213], v[186:189], v[104:107]
	v_mfma_f32_16x16x32_bf16 v[96:99], v[218:221], v[186:189], v[96:99]
	v_mfma_f32_16x16x32_bf16 v[88:91], v[210:213], v[194:197], v[88:91]
	v_mfma_f32_16x16x32_bf16 v[80:83], v[218:221], v[194:197], v[80:83]
	v_mfma_f32_16x16x32_bf16 v[72:75], v[210:213], v[202:205], v[72:75]
	v_mfma_f32_16x16x32_bf16 v[64:67], v[218:221], v[202:205], v[64:67]
	s_setprio 0
	s_mov_b32 m0, s33
	v_lshl_add_u64 v[144:145], v[222:223], 0, s[6:7]
	s_barrier
	ds_read_b128 v[170:173], v150 offset:49152
	ds_read_b128 v[178:181], v150 offset:50176
	ds_read_b128 v[182:185], v150 offset:51200
	ds_read_b128 v[186:189], v150 offset:52224
	ds_read_b128 v[190:193], v150 offset:53248
	ds_read_b128 v[194:197], v150 offset:54272
	ds_read_b128 v[198:201], v150 offset:55296
	ds_read_b128 v[202:205], v150 offset:56320
	global_load_lds_dwordx4 v[144:145], off
	v_lshl_add_u64 v[144:145], v[224:225], 0, s[6:7]
	s_mov_b32 m0, s34
	s_nop 0
	global_load_lds_dwordx4 v[144:145], off
	s_barrier
; __device__ __forceinline__ float ld_agent(const float* p) { return __hip_atomic_load(p, __ATOMIC_RELAXED, __HIP_MEMORY_SCOPE_AGENT); }
; __device__ __forceinline__ float sigm(float x) { return __builtin_amdgcn_rcpf(1.f + __builtin_amdgcn_exp2f(-LOG2E * x)); }
; #define PG8_STAGE(bufoff, gbase, voff) do { _Pragma("unroll") for (int _i = 0; _i < 2; ++_i) \
;         __builtin_amdgcn_global_load_lds((const unsigned*)((const char*)(gbase) + (voff)[_i]), (LAS unsigned*)(lds + (bufoff) + ldsw + _i * 8192), 16, 0, 0); } while (0)
; #define PG8_WAIT_V(n) asm volatile("s_waitcnt vmcnt(" #n ")" ::: "memory")
;     __device__ __forceinline__ void operator()(const f32x4 (&acc)[2][2][4][2], const Unit& u, int wr, int wc, int fr, int fq) const {
;         const int row0 = u.pm * BM + wr * 64 + fr, col0 = u.pn * HALF + wc * 32 + 8 * fq;
;         float sq[8];
; #pragma unroll
;         for (int g = 0; g < 8; ++g) sq[g] = ld_agent(ssq + row0 + (g >> 2) * HALF + (g & 3) * 16);
; #pragma unroll
;         for (int ai = 0; ai < 2; ++ai)
; #pragma unroll
;             for (int m = 0; m < 4; ++m) {
;                 const int r = row0 + ai * HALF + m * 16; const float rs = __builtin_amdgcn_rsqf(sq[ai * 4 + m] * (1.f / 2048.f) + EPS);
;                 float v[8];
; #pragma unroll
;                 for (int n = 0; n < 2; ++n)
; #pragma unroll
;                     for (int j = 0; j < 4; ++j) { const float g = acc[ai][0][m][n][j] * rs, up = acc[ai][1][m][n][j] * rs; v[n * 4 + j] = g * sigm(g) * up; }
; template <class Epi, class Sched>
; __device__ __forceinline__ void gemm_phase(LAS unsigned char* lds, const Gemm g, const Sched& S, const Epi& E) {
;     ...
;             PG8_WAIT_V(6); PG8_BAR; PG8_MMA(1, 1, At, B1); PG8_BAR;
;             PG8_LDB(B0, 1, 0); PG8_SCHED; PG8_LDA(At, 1, 0); PG8_STAGE(PG8_SA(0, 1), a2 + hstepA, voffA);
;             PG8_WAIT_L(8); PG8_BAR; PG8_WAIT_L(0); PG8_MMA(0, 0, At, B0); PG8_BAR; PG8_SCHED;
;             PG8_LDB(B1, 1, 1); PG8_STAGE(PG8_SB(1, 0), b3, voffB);
;             PG8_BAR; PG8_WAIT_L(0); PG8_MMA(0, 1, At, B1); PG8_BAR;
;             PG8_LDA(At, 1, 1); PG8_STAGE(PG8_SA(1, 0), a3, voffA);
;             PG8_BAR; PG8_WAIT_L(0); PG8_MMA(1, 0, At, B0); PG8_BAR; PG8_SCHED;
;             PG8_STAGE(PG8_SB(1, 1), b3 + hstepB, voffB);
;             PG8_WAIT_V(6); PG8_BAR; PG8_MMA(1, 1, At, B1); PG8_BAR;
;         }
	s_waitcnt lgkmcnt(0)
	s_setprio 1
	s_waitcnt lgkmcnt(0)
	v_mfma_f32_16x16x32_bf16 v[60:63], v[154:157], v[170:173], v[60:63]
	v_mfma_f32_16x16x32_bf16 v[52:55], v[162:165], v[170:173], v[52:55]
	v_mfma_f32_16x16x32_bf16 v[44:47], v[154:157], v[182:185], v[44:47]
	v_mfma_f32_16x16x32_bf16 v[36:39], v[162:165], v[182:185], v[36:39]
	v_mfma_f32_16x16x32_bf16 v[28:31], v[154:157], v[190:193], v[28:31]
	v_mfma_f32_16x16x32_bf16 v[20:23], v[162:165], v[190:193], v[20:23]
	v_mfma_f32_16x16x32_bf16 v[12:15], v[154:157], v[198:201], v[12:15]
	v_mfma_f32_16x16x32_bf16 v[4:7], v[162:165], v[198:201], v[4:7]
	v_mfma_f32_16x16x32_bf16 v[60:63], v[158:161], v[178:181], v[60:63]
	v_mfma_f32_16x16x32_bf16 v[52:55], v[166:169], v[178:181], v[52:55]
	v_mfma_f32_16x16x32_bf16 v[44:47], v[158:161], v[186:189], v[44:47]
	v_mfma_f32_16x16x32_bf16 v[36:39], v[166:169], v[186:189], v[36:39]
	v_mfma_f32_16x16x32_bf16 v[28:31], v[158:161], v[194:197], v[28:31]
	v_mfma_f32_16x16x32_bf16 v[20:23], v[166:169], v[194:197], v[20:23]
	v_mfma_f32_16x16x32_bf16 v[12:15], v[158:161], v[202:205], v[12:15]
	v_mfma_f32_16x16x32_bf16 v[4:7], v[166:169], v[202:205], v[4:7]
	s_setprio 0
	s_barrier
	s_add_u32 s20, s20, 0x80080
	s_addc_u32 s21, s21, 0
	s_add_i32 s22, s22, s25
	v_lshl_add_u64 v[144:145], s[20:21], 0, v[132:133]
	s_mov_b32 m0, s22
	s_nop 0
	global_load_lds_dwordx4 v[144:145], off
	v_lshl_add_u64 v[144:145], s[20:21], 0, v[128:129]
	s_add_i32 m0, s22, 0x2000
	s_nop 0
	global_load_lds_dwordx4 v[144:145], off
	s_waitcnt vmcnt(6)
	s_barrier
	s_setprio 1
	v_mfma_f32_16x16x32_bf16 v[56:59], v[206:209], v[170:173], v[56:59]
	v_mfma_f32_16x16x32_bf16 v[48:51], v[214:217], v[170:173], v[48:51]
	v_mfma_f32_16x16x32_bf16 v[40:43], v[206:209], v[182:185], v[40:43]
	v_mfma_f32_16x16x32_bf16 v[32:35], v[214:217], v[182:185], v[32:35]
	v_mfma_f32_16x16x32_bf16 v[24:27], v[206:209], v[190:193], v[24:27]
	v_mfma_f32_16x16x32_bf16 v[16:19], v[214:217], v[190:193], v[16:19]
	v_mfma_f32_16x16x32_bf16 v[8:11], v[206:209], v[198:201], v[8:11]
	v_mfma_f32_16x16x32_bf16 v[0:3], v[214:217], v[198:201], v[0:3]
	v_mfma_f32_16x16x32_bf16 v[56:59], v[210:213], v[178:181], v[56:59]
	v_mfma_f32_16x16x32_bf16 v[48:51], v[218:221], v[178:181], v[48:51]
	v_mfma_f32_16x16x32_bf16 v[40:43], v[210:213], v[186:189], v[40:43]
	v_mfma_f32_16x16x32_bf16 v[32:35], v[218:221], v[186:189], v[32:35]
	v_mfma_f32_16x16x32_bf16 v[24:27], v[210:213], v[194:197], v[24:27]
	v_mfma_f32_16x16x32_bf16 v[16:19], v[218:221], v[194:197], v[16:19]
	v_mfma_f32_16x16x32_bf16 v[8:11], v[210:213], v[202:205], v[8:11]
	v_mfma_f32_16x16x32_bf16 v[0:3], v[218:221], v[202:205], v[0:3]
	s_setprio 0
	s_add_i32 s44, s44, 2
	s_add_u32 s18, s18, 0x100
	s_addc_u32 s19, s19, 0
	s_add_u32 s42, s42, 0x100
	s_addc_u32 s43, s43, 0
	s_cmp_gt_u32 s44, 29
	s_barrier
	s_cbranch_scc0 .LBB0_865
	v_lshl_add_u32 v144, s16, 8, v146
	v_ashrrev_i32_e32 v145, 31, v144
	v_lshl_add_u64 v[154:155], v[144:145], 2, s[2:3]
	global_load_dword v145, v[154:155], off sc1
	global_load_dword v153, v[154:155], off offset:64 sc1
	v_mov_b32_e32 v158, v124
	v_mov_b32_e32 v159, v116
	v_mov_b32_e32 v116, v125
	v_mov_b32_e32 v163, v114
	v_mov_b32_e32 v114, v123
	global_load_dword v125, v[154:155], off offset:128 sc1
	global_load_dword v168, v[154:155], off offset:192 sc1
	global_load_dword v169, v[154:155], off offset:512 sc1
	global_load_dword v124, v[154:155], off offset:576 sc1
	global_load_dword v123, v[154:155], off offset:640 sc1
	global_load_dword v190, v[154:155], off offset:704 sc1
	v_lshl_or_b32 v156, s39, 7, v148
	v_mov_b32_e32 v162, v122
	v_ashrrev_i32_e32 v157, 31, v156
	v_mov_b32_e32 v164, v104
	v_mov_b32_e32 v165, v108
	v_mov_b32_e32 v108, v105
	v_lshlrev_b64 v[104:105], 1, v[156:157]
	v_mov_b32_e32 v161, v118
	v_mov_b32_e32 v118, v127
	v_mov_b32_e32 v160, v126
	v_mov_b32_e32 v126, v120
	v_mov_b32_e32 v127, v112
	v_mov_b32_e32 v112, v121
	v_mov_b64_e32 v[120:121], s[54:55]
	v_mad_i64_i32 v[166:167], s[18:19], v144, s38, v[120:121]
	s_and_b64 vcc, exec, s[0:1]
	s_mov_b32 s39, s8
	s_mov_b32 s16, s10
	s_mov_b64 s[20:21], s[14:15]
	s_waitcnt vmcnt(0)
	v_fmamk_f32 v122, v145, 0x3a000000, v152
	v_rsq_f32_e32 v156, v122
	v_fmamk_f32 v145, v153, 0x3a000000, v152
	v_rsq_f32_e32 v154, v145
	v_pk_mul_f32 v[118:119], v[118:119], v[156:157] op_sel_hi:[1,0]
	v_pk_mul_f32 v[158:159], v[158:159], v[156:157] op_sel_hi:[1,0]
	v_pk_mul_f32 v[116:117], v[116:117], v[156:157] op_sel_hi:[1,0]
	v_pk_mul_f32 v[160:161], v[160:161], v[156:157] op_sel_hi:[1,0]
	v_pk_mul_f32 v[126:127], v[126:127], v[156:157] op_sel_hi:[1,0]
	v_pk_mul_f32 v[112:113], v[112:113], v[156:157] op_sel_hi:[1,0]
	v_pk_mul_f32 v[162:163], v[162:163], v[156:157] op_sel_hi:[1,0]
	v_pk_mul_f32 v[114:115], v[114:115], v[156:157] op_sel_hi:[1,0]
	v_pk_mul_f32 v[156:157], v[164:165], v[154:155] op_sel_hi:[1,0]
	v_mul_f32_e32 v164, 0xbfb8aa3b, v119
	v_pk_mul_f32 v[108:109], v[108:109], v[154:155] op_sel_hi:[1,0]
	v_mul_f32_e32 v145, 0xbfb8aa3b, v159
	v_mul_f32_e32 v153, 0xbfb8aa3b, v117
	v_mul_f32_e32 v155, 0xbfb8aa3b, v161
	v_mul_f32_e32 v165, 0xbfb8aa3b, v127
	v_mul_f32_e32 v170, 0xbfb8aa3b, v113
	v_exp_f32_e32 v164, v164
	v_exp_f32_e32 v145, v145
	v_exp_f32_e32 v153, v153
	v_exp_f32_e32 v155, v155
	v_exp_f32_e32 v165, v165
	v_exp_f32_e32 v170, v170
	v_mul_f32_e32 v172, 0xbfb8aa3b, v115
	v_add_f32_e32 v164, 1.0, v164
	v_mul_f32_e32 v171, 0xbfb8aa3b, v163
	v_exp_f32_e32 v172, v172
	v_add_f32_e32 v145, 1.0, v145
	v_add_f32_e32 v153, 1.0, v153
	v_add_f32_e32 v155, 1.0, v155
	v_add_f32_e32 v165, 1.0, v165
	v_add_f32_e32 v170, 1.0, v170
	v_rcp_f32_e32 v164, v164
	v_mul_f32_e32 v173, 0xbfb8aa3b, v157
; __device__ __forceinline__ unsigned cvt_pk_bf16(float lo, float hi) { unsigned r; asm volatile("v_cvt_pk_bf16_f32 %0, %1, %2" : "=v"(r) : "v"(lo), "v"(hi)); return r; }
; __device__ __forceinline__ float ld_agent(const float* p) { return __hip_atomic_load(p, __ATOMIC_RELAXED, __HIP_MEMORY_SCOPE_AGENT); }
; __device__ __forceinline__ float sigm(float x) { return __builtin_amdgcn_rcpf(1.f + __builtin_amdgcn_exp2f(-LOG2E * x)); }
;     __device__ __forceinline__ void operator()(const f32x4 (&acc)[2][2][4][2], const Unit& u, int wr, int wc, int fr, int fq) const {
;     ...
;         for (int g = 0; g < 8; ++g) sq[g] = ld_agent(ssq + row0 + (g >> 2) * HALF + (g & 3) * 16);
; #pragma unroll
;         for (int ai = 0; ai < 2; ++ai)
; #pragma unroll
;             for (int m = 0; m < 4; ++m) {
;                 const int r = row0 + ai * HALF + m * 16; const float rs = __builtin_amdgcn_rsqf(sq[ai * 4 + m] * (1.f / 2048.f) + EPS);
;                 float v[8];
; #pragma unroll
;                 for (int n = 0; n < 2; ++n)
; #pragma unroll
;                     for (int j = 0; j < 4; ++j) { const float g = acc[ai][0][m][n][j] * rs, up = acc[ai][1][m][n][j] * rs; v[n * 4 + j] = g * sigm(g) * up; }
;                 u32x4 w; w.x = cvt_pk_bf16(v[0], v[1]); w.y = cvt_pk_bf16(v[2], v[3]); w.z = cvt_pk_bf16(v[4], v[5]); w.w = cvt_pk_bf16(v[6], v[7]);
;                 *(u32x4*)(O + (size_t)r * FF + col0) = w;
	v_exp_f32_e32 v171, v171
	v_rcp_f32_e32 v145, v145
	v_rcp_f32_e32 v153, v153
	v_rcp_f32_e32 v155, v155
	v_rcp_f32_e32 v165, v165
	v_rcp_f32_e32 v170, v170
	v_exp_f32_e32 v173, v173
	v_add_f32_e32 v172, 1.0, v172
	v_mul_f32_e32 v119, v119, v164
	v_add_f32_e32 v171, 1.0, v171
	v_rcp_f32_e32 v172, v172
	v_mul_f32_e32 v145, v159, v145
	v_mul_f32_e32 v117, v117, v153
	v_mul_f32_e32 v153, v161, v155
	v_mul_f32_e32 v127, v127, v165
	v_mul_f32_e32 v113, v113, v170
	v_mul_f32_e32 v118, v118, v119
	v_rcp_f32_e32 v171, v171
	v_mul_f32_e32 v145, v158, v145
	v_mul_f32_e32 v116, v116, v117
	v_mul_f32_e32 v117, v160, v153
	v_mul_f32_e32 v119, v126, v127
	v_mul_f32_e32 v126, v112, v113
	v_cvt_pk_bf16_f32 v112, v145, v116
	v_cvt_pk_bf16_f32 v113, v117, v118
	v_add_f32_e32 v118, 1.0, v173
	v_rcp_f32_e32 v118, v118
	v_mul_f32_e32 v174, 0xbfb8aa3b, v109
	v_mul_f32_e32 v115, v115, v172
	v_exp_f32_e32 v174, v174
	v_mul_f32_e32 v155, v163, v171
	v_mul_f32_e32 v115, v114, v115
	v_lshl_add_u64 v[116:117], v[166:167], 0, v[104:105]
	v_mul_f32_e32 v127, v162, v155
	v_cvt_pk_bf16_f32 v114, v119, v126
	v_cvt_pk_bf16_f32 v115, v127, v115
	global_store_dwordx4 v[116:117], v[112:115], off sc0 sc1
	v_add_f32_e32 v119, 1.0, v174
	v_rcp_f32_e32 v119, v119
	v_mul_f32_e32 v112, v157, v118
	v_mul_f32_e32 v114, v156, v112
	v_mov_b32_e32 v112, v106
	v_mov_b32_e32 v113, v110
	v_pk_mul_f32 v[112:113], v[112:113], v[154:155] op_sel_hi:[1,0]
	v_mov_b32_e32 v110, v107
	v_mul_f32_e32 v106, 0xbfb8aa3b, v113
	v_exp_f32_e32 v115, v106
	v_pk_mul_f32 v[106:107], v[110:111], v[154:155] op_sel_hi:[1,0]
	v_mul_f32_e32 v109, v109, v119
	v_mul_f32_e32 v110, 0xbfb8aa3b, v107
	v_exp_f32_e32 v110, v110
	v_mul_f32_e32 v111, v108, v109
	v_add_f32_e32 v108, 1.0, v115
	v_rcp_f32_e32 v115, v108
	v_add_f32_e32 v108, 1.0, v110
	v_rcp_f32_e32 v110, v108
	v_mov_b32_e32 v108, v96
	v_mov_b32_e32 v109, v100
	v_pk_mul_f32 v[108:109], v[108:109], v[154:155] op_sel_hi:[1,0]
	v_mul_f32_e32 v100, v113, v115
	v_mul_f32_e32 v96, 0xbfb8aa3b, v109
	v_exp_f32_e32 v96, v96
	v_mul_f32_e32 v112, v112, v100
	v_mov_b32_e32 v100, v97
	v_mul_f32_e32 v107, v107, v110
	v_add_f32_e32 v96, 1.0, v96
	v_rcp_f32_e32 v110, v96
	v_pk_mul_f32 v[96:97], v[100:101], v[154:155] op_sel_hi:[1,0]
	v_mul_f32_e32 v106, v106, v107
	v_mul_f32_e32 v100, 0xbfb8aa3b, v97
	v_exp_f32_e32 v100, v100
	v_mul_f32_e32 v101, v109, v110
	v_mul_f32_e32 v107, v108, v101
	v_mov_b32_e32 v101, v102
	v_add_f32_e32 v100, 1.0, v100
	v_rcp_f32_e32 v108, v100
	v_mov_b32_e32 v100, v98
	v_pk_mul_f32 v[100:101], v[100:101], v[154:155] op_sel_hi:[1,0]
	v_mov_b32_e32 v102, v99
	v_mul_f32_e32 v98, 0xbfb8aa3b, v101
	v_exp_f32_e32 v109, v98
	v_pk_mul_f32 v[98:99], v[102:103], v[154:155] op_sel_hi:[1,0]
	v_mul_f32_e32 v97, v97, v108
	v_mul_f32_e32 v102, 0xbfb8aa3b, v99
	v_exp_f32_e32 v102, v102
	v_add_f32_e32 v103, 1.0, v109
	v_rcp_f32_e32 v103, v103
	v_mul_f32_e32 v108, v96, v97
	v_add_f32_e32 v102, 1.0, v102
	v_rcp_f32_e32 v102, v102
	v_mul_f32_e32 v96, v101, v103
	v_mul_f32_e32 v100, v100, v96
	v_or_b32_e32 v101, 16, v144
	v_mul_f32_e32 v96, v99, v102
	v_mul_f32_e32 v99, v98, v96
	v_cvt_pk_bf16_f32 v96, v114, v111
	v_cvt_pk_bf16_f32 v97, v112, v106
	v_cvt_pk_bf16_f32 v98, v107, v108
	v_cvt_pk_bf16_f32 v99, v100, v99
	v_fmamk_f32 v100, v125, 0x3a000000, v152
	v_rsq_f32_e32 v100, v100
	v_mov_b32_e32 v106, v88
	v_mov_b32_e32 v107, v92
	v_mad_i64_i32 v[102:103], s[18:19], v101, s38, v[120:121]
	v_pk_mul_f32 v[106:107], v[106:107], v[100:101] op_sel_hi:[1,0]
	v_mov_b32_e32 v92, v89
	v_mul_f32_e32 v88, 0xbfb8aa3b, v107
	v_exp_f32_e32 v101, v88
	s_nop 0
	v_pk_mul_f32 v[88:89], v[92:93], v[100:101] op_sel_hi:[1,0]
	v_add_f32_e32 v101, 1.0, v101
	v_rcp_f32_e32 v101, v101
	v_mul_f32_e32 v92, 0xbfb8aa3b, v89
	v_exp_f32_e32 v108, v92
	v_lshl_add_u64 v[92:93], v[102:103], 0, v[104:105]
	global_store_dwordx4 v[92:93], v[96:99], off sc0 sc1
	v_mul_f32_e32 v92, v107, v101
	v_mov_b32_e32 v93, v94
	v_mul_f32_e32 v96, v106, v92
	v_mov_b32_e32 v92, v90
	v_pk_mul_f32 v[92:93], v[92:93], v[100:101] op_sel_hi:[1,0]
	v_add_f32_e32 v102, 1.0, v108
	v_mul_f32_e32 v90, 0xbfb8aa3b, v93
	v_mov_b32_e32 v94, v91
	v_rcp_f32_e32 v102, v102
	v_exp_f32_e32 v97, v90
	v_pk_mul_f32 v[90:91], v[94:95], v[100:101] op_sel_hi:[1,0]
	v_mul_f32_e32 v89, v89, v102
	v_mul_f32_e32 v94, 0xbfb8aa3b, v91
	v_exp_f32_e32 v94, v94
	v_mul_f32_e32 v95, v88, v89
	v_add_f32_e32 v88, 1.0, v97
	v_rcp_f32_e32 v97, v88
	v_add_f32_e32 v88, 1.0, v94
	v_rcp_f32_e32 v94, v88
	v_mov_b32_e32 v88, v80
	v_mov_b32_e32 v89, v84
	v_pk_mul_f32 v[88:89], v[88:89], v[100:101] op_sel_hi:[1,0]
	v_mul_f32_e32 v84, v93, v97
	v_mul_f32_e32 v80, 0xbfb8aa3b, v89
	v_exp_f32_e32 v80, v80
	v_mul_f32_e32 v92, v92, v84
	v_mov_b32_e32 v84, v81
	v_mul_f32_e32 v91, v91, v94
	v_add_f32_e32 v80, 1.0, v80
	v_rcp_f32_e32 v93, v80
	v_pk_mul_f32 v[80:81], v[84:85], v[100:101] op_sel_hi:[1,0]
	v_mul_f32_e32 v90, v90, v91
	v_mul_f32_e32 v84, 0xbfb8aa3b, v81
	v_exp_f32_e32 v84, v84
	v_mul_f32_e32 v85, v89, v93
	v_mul_f32_e32 v88, v88, v85
	v_mov_b32_e32 v85, v86
	v_add_f32_e32 v84, 1.0, v84
	v_rcp_f32_e32 v89, v84
	v_mov_b32_e32 v84, v82
	v_pk_mul_f32 v[84:85], v[84:85], v[100:101] op_sel_hi:[1,0]
	v_mov_b32_e32 v86, v83
	v_mul_f32_e32 v82, 0xbfb8aa3b, v85
	v_exp_f32_e32 v91, v82
	v_pk_mul_f32 v[82:83], v[86:87], v[100:101] op_sel_hi:[1,0]
	v_mul_f32_e32 v81, v81, v89
	v_mul_f32_e32 v86, 0xbfb8aa3b, v83
	v_exp_f32_e32 v86, v86
	v_add_f32_e32 v87, 1.0, v91
	v_rcp_f32_e32 v87, v87
	v_mul_f32_e32 v89, v80, v81
	v_add_f32_e32 v86, 1.0, v86
	v_rcp_f32_e32 v86, v86
	v_mul_f32_e32 v80, v85, v87
	v_mul_f32_e32 v84, v84, v80
	v_or_b32_e32 v85, 32, v144
	v_mul_f32_e32 v80, v83, v86
; __device__ __forceinline__ unsigned cvt_pk_bf16(float lo, float hi) { unsigned r; asm volatile("v_cvt_pk_bf16_f32 %0, %1, %2" : "=v"(r) : "v"(lo), "v"(hi)); return r; }
; __device__ __forceinline__ float ld_agent(const float* p) { return __hip_atomic_load(p, __ATOMIC_RELAXED, __HIP_MEMORY_SCOPE_AGENT); }
; __device__ __forceinline__ float sigm(float x) { return __builtin_amdgcn_rcpf(1.f + __builtin_amdgcn_exp2f(-LOG2E * x)); }
;     __device__ __forceinline__ void operator()(const f32x4 (&acc)[2][2][4][2], const Unit& u, int wr, int wc, int fr, int fq) const {
;     ...
;         for (int g = 0; g < 8; ++g) sq[g] = ld_agent(ssq + row0 + (g >> 2) * HALF + (g & 3) * 16);
; #pragma unroll
;         for (int ai = 0; ai < 2; ++ai)
; #pragma unroll
;             for (int m = 0; m < 4; ++m) {
;                 const int r = row0 + ai * HALF + m * 16; const float rs = __builtin_amdgcn_rsqf(sq[ai * 4 + m] * (1.f / 2048.f) + EPS);
;                 float v[8];
; #pragma unroll
;                 for (int n = 0; n < 2; ++n)
; #pragma unroll
;                     for (int j = 0; j < 4; ++j) { const float g = acc[ai][0][m][n][j] * rs, up = acc[ai][1][m][n][j] * rs; v[n * 4 + j] = g * sigm(g) * up; }
;                 u32x4 w; w.x = cvt_pk_bf16(v[0], v[1]); w.y = cvt_pk_bf16(v[2], v[3]); w.z = cvt_pk_bf16(v[4], v[5]); w.w = cvt_pk_bf16(v[6], v[7]);
;                 *(u32x4*)(O + (size_t)r * FF + col0) = w;
	v_mul_f32_e32 v83, v82, v80
	v_cvt_pk_bf16_f32 v80, v96, v95
	v_cvt_pk_bf16_f32 v81, v92, v90
	v_cvt_pk_bf16_f32 v82, v88, v89
	v_cvt_pk_bf16_f32 v83, v84, v83
	v_fmamk_f32 v84, v168, 0x3a000000, v152
	v_rsq_f32_e32 v84, v84
	v_mov_b32_e32 v88, v72
	v_mov_b32_e32 v89, v76
	v_mad_i64_i32 v[86:87], s[18:19], v85, s38, v[120:121]
	v_pk_mul_f32 v[88:89], v[88:89], v[84:85] op_sel_hi:[1,0]
	v_mov_b32_e32 v76, v73
	v_mul_f32_e32 v72, 0xbfb8aa3b, v89
	v_exp_f32_e32 v85, v72
	s_nop 0
	v_pk_mul_f32 v[72:73], v[76:77], v[84:85] op_sel_hi:[1,0]
	v_add_f32_e32 v85, 1.0, v85
	v_rcp_f32_e32 v85, v85
	v_mul_f32_e32 v76, 0xbfb8aa3b, v73
	v_exp_f32_e32 v90, v76
	v_lshl_add_u64 v[76:77], v[86:87], 0, v[104:105]
	global_store_dwordx4 v[76:77], v[80:83], off sc0 sc1
	v_mul_f32_e32 v76, v89, v85
	v_mov_b32_e32 v77, v78
	v_mul_f32_e32 v80, v88, v76
	v_mov_b32_e32 v76, v74
	v_pk_mul_f32 v[76:77], v[76:77], v[84:85] op_sel_hi:[1,0]
	v_add_f32_e32 v86, 1.0, v90
	v_mul_f32_e32 v74, 0xbfb8aa3b, v77
	v_mov_b32_e32 v78, v75
	v_rcp_f32_e32 v86, v86
	v_exp_f32_e32 v81, v74
	v_pk_mul_f32 v[74:75], v[78:79], v[84:85] op_sel_hi:[1,0]
	v_mul_f32_e32 v73, v73, v86
	v_mul_f32_e32 v78, 0xbfb8aa3b, v75
	v_exp_f32_e32 v78, v78
	v_mul_f32_e32 v79, v72, v73
	v_add_f32_e32 v72, 1.0, v81
	v_rcp_f32_e32 v81, v72
	v_add_f32_e32 v72, 1.0, v78
	v_rcp_f32_e32 v78, v72
	v_mov_b32_e32 v72, v64
	v_mov_b32_e32 v73, v68
	v_pk_mul_f32 v[72:73], v[72:73], v[84:85] op_sel_hi:[1,0]
	v_mul_f32_e32 v68, v77, v81
	v_mul_f32_e32 v64, 0xbfb8aa3b, v73
	v_exp_f32_e32 v64, v64
	v_mul_f32_e32 v76, v76, v68
	v_mov_b32_e32 v68, v65
	v_mul_f32_e32 v75, v75, v78
	v_add_f32_e32 v64, 1.0, v64
	v_rcp_f32_e32 v77, v64
	v_pk_mul_f32 v[64:65], v[68:69], v[84:85] op_sel_hi:[1,0]
	v_mul_f32_e32 v74, v74, v75
	v_mul_f32_e32 v68, 0xbfb8aa3b, v65
	v_exp_f32_e32 v68, v68
	v_mul_f32_e32 v69, v73, v77
	v_mul_f32_e32 v72, v72, v69
	v_mov_b32_e32 v69, v70
	v_add_f32_e32 v68, 1.0, v68
	v_rcp_f32_e32 v73, v68
	v_mov_b32_e32 v68, v66
	v_pk_mul_f32 v[68:69], v[68:69], v[84:85] op_sel_hi:[1,0]
	v_mov_b32_e32 v70, v67
	v_mul_f32_e32 v66, 0xbfb8aa3b, v69
	v_exp_f32_e32 v75, v66
	v_pk_mul_f32 v[66:67], v[70:71], v[84:85] op_sel_hi:[1,0]
	v_mul_f32_e32 v65, v65, v73
	v_mul_f32_e32 v70, 0xbfb8aa3b, v67
	v_exp_f32_e32 v70, v70
	v_add_f32_e32 v71, 1.0, v75
	v_rcp_f32_e32 v71, v71
	v_mul_f32_e32 v73, v64, v65
	v_add_f32_e32 v70, 1.0, v70
	v_rcp_f32_e32 v70, v70
	v_mul_f32_e32 v64, v69, v71
	v_mul_f32_e32 v68, v68, v64
	v_or_b32_e32 v69, 48, v144
	v_mul_f32_e32 v64, v67, v70
	v_fmamk_f32 v70, v169, 0x3a000000, v152
	v_rsq_f32_e32 v70, v70
	v_mul_f32_e32 v67, v66, v64
	v_cvt_pk_bf16_f32 v64, v80, v79
	v_cvt_pk_bf16_f32 v65, v76, v74
	v_cvt_pk_bf16_f32 v66, v72, v73
	v_mov_b32_e32 v72, v56
	v_mov_b32_e32 v73, v60
	v_pk_mul_f32 v[72:73], v[72:73], v[70:71] op_sel_hi:[1,0]
	v_mov_b32_e32 v60, v57
	v_mul_f32_e32 v56, 0xbfb8aa3b, v73
	v_exp_f32_e32 v71, v56
	v_cvt_pk_bf16_f32 v67, v68, v67
	v_mad_i64_i32 v[68:69], s[18:19], v69, s38, v[120:121]
	v_pk_mul_f32 v[56:57], v[60:61], v[70:71] op_sel_hi:[1,0]
	v_add_f32_e32 v61, 1.0, v71
	v_mul_f32_e32 v60, 0xbfb8aa3b, v57
	v_exp_f32_e32 v60, v60
	v_rcp_f32_e32 v61, v61
	v_lshl_add_u64 v[68:69], v[68:69], 0, v[104:105]
	global_store_dwordx4 v[68:69], v[64:67], off sc0 sc1
	v_add_f32_e32 v60, 1.0, v60
	v_rcp_f32_e32 v60, v60
	v_mul_f32_e32 v61, v73, v61
	v_mul_f32_e32 v65, v72, v61
	v_mov_b32_e32 v61, v62
	v_mul_f32_e32 v57, v57, v60
	v_mov_b32_e32 v60, v58
	v_pk_mul_f32 v[60:61], v[60:61], v[70:71] op_sel_hi:[1,0]
	v_mov_b32_e32 v62, v59
	v_mul_f32_e32 v58, 0xbfb8aa3b, v61
	v_exp_f32_e32 v66, v58
	v_pk_mul_f32 v[58:59], v[62:63], v[70:71] op_sel_hi:[1,0]
	v_mul_f32_e32 v63, v56, v57
	v_mul_f32_e32 v62, 0xbfb8aa3b, v59
	v_exp_f32_e32 v62, v62
	v_add_f32_e32 v56, 1.0, v66
	v_rcp_f32_e32 v66, v56
	v_mov_b32_e32 v57, v52
	v_add_f32_e32 v56, 1.0, v62
	v_rcp_f32_e32 v62, v56
	v_mov_b32_e32 v56, v48
	v_pk_mul_f32 v[56:57], v[56:57], v[70:71] op_sel_hi:[1,0]
	v_mul_f32_e32 v52, v61, v66
	v_mul_f32_e32 v48, 0xbfb8aa3b, v57
	v_exp_f32_e32 v48, v48
	v_mul_f32_e32 v60, v60, v52
	v_mov_b32_e32 v52, v49
	v_mul_f32_e32 v59, v59, v62
	v_add_f32_e32 v48, 1.0, v48
	v_rcp_f32_e32 v61, v48
	v_pk_mul_f32 v[48:49], v[52:53], v[70:71] op_sel_hi:[1,0]
	v_mul_f32_e32 v58, v58, v59
	v_mul_f32_e32 v52, 0xbfb8aa3b, v49
	v_exp_f32_e32 v52, v52
	v_mul_f32_e32 v53, v57, v61
	v_mul_f32_e32 v56, v56, v53
	v_mov_b32_e32 v53, v54
	v_add_f32_e32 v52, 1.0, v52
	v_rcp_f32_e32 v57, v52
	v_mov_b32_e32 v52, v50
	v_pk_mul_f32 v[52:53], v[52:53], v[70:71] op_sel_hi:[1,0]
	v_mov_b32_e32 v54, v51
	v_mul_f32_e32 v50, 0xbfb8aa3b, v53
	v_exp_f32_e32 v59, v50
	v_pk_mul_f32 v[50:51], v[54:55], v[70:71] op_sel_hi:[1,0]
	v_mul_f32_e32 v49, v49, v57
	v_mul_f32_e32 v54, 0xbfb8aa3b, v51
	v_exp_f32_e32 v54, v54
	v_add_f32_e32 v55, 1.0, v59
	v_rcp_f32_e32 v55, v55
	v_mul_f32_e32 v57, v48, v49
	v_add_f32_e32 v54, 1.0, v54
	v_rcp_f32_e32 v54, v54
	v_mul_f32_e32 v48, v53, v55
	v_mul_f32_e32 v52, v52, v48
	v_add_u32_e32 v64, 0x80, v144
	v_mul_f32_e32 v48, v51, v54
	v_mul_f32_e32 v51, v50, v48
	v_cvt_pk_bf16_f32 v48, v65, v63
	v_cvt_pk_bf16_f32 v49, v60, v58
	v_cvt_pk_bf16_f32 v50, v56, v57
	v_cvt_pk_bf16_f32 v51, v52, v51
	v_fmamk_f32 v52, v124, 0x3a000000, v152
	v_rsq_f32_e32 v52, v52
	v_mov_b32_e32 v56, v40
	v_mov_b32_e32 v57, v44
	v_mov_b32_e32 v44, v41
	v_pk_mul_f32 v[56:57], v[56:57], v[52:53] op_sel_hi:[1,0]
	v_mad_i64_i32 v[54:55], s[18:19], v64, s38, v[120:121]
	v_mul_f32_e32 v40, 0xbfb8aa3b, v57
	v_exp_f32_e32 v53, v40
	s_nop 0
	v_pk_mul_f32 v[40:41], v[44:45], v[52:53] op_sel_hi:[1,0]
	v_add_f32_e32 v53, 1.0, v53
	v_rcp_f32_e32 v53, v53
; __device__ __forceinline__ unsigned cvt_pk_bf16(float lo, float hi) { unsigned r; asm volatile("v_cvt_pk_bf16_f32 %0, %1, %2" : "=v"(r) : "v"(lo), "v"(hi)); return r; }
; __device__ __forceinline__ float ld_agent(const float* p) { return __hip_atomic_load(p, __ATOMIC_RELAXED, __HIP_MEMORY_SCOPE_AGENT); }
; __device__ __forceinline__ float sigm(float x) { return __builtin_amdgcn_rcpf(1.f + __builtin_amdgcn_exp2f(-LOG2E * x)); }
;     __device__ __forceinline__ void operator()(const f32x4 (&acc)[2][2][4][2], const Unit& u, int wr, int wc, int fr, int fq) const {
;     ...
;         for (int g = 0; g < 8; ++g) sq[g] = ld_agent(ssq + row0 + (g >> 2) * HALF + (g & 3) * 16);
; #pragma unroll
;         for (int ai = 0; ai < 2; ++ai)
; #pragma unroll
;             for (int m = 0; m < 4; ++m) {
;                 const int r = row0 + ai * HALF + m * 16; const float rs = __builtin_amdgcn_rsqf(sq[ai * 4 + m] * (1.f / 2048.f) + EPS);
;                 float v[8];
; #pragma unroll
;                 for (int n = 0; n < 2; ++n)
; #pragma unroll
;                     for (int j = 0; j < 4; ++j) { const float g = acc[ai][0][m][n][j] * rs, up = acc[ai][1][m][n][j] * rs; v[n * 4 + j] = g * sigm(g) * up; }
;                 u32x4 w; w.x = cvt_pk_bf16(v[0], v[1]); w.y = cvt_pk_bf16(v[2], v[3]); w.z = cvt_pk_bf16(v[4], v[5]); w.w = cvt_pk_bf16(v[6], v[7]);
;                 *(u32x4*)(O + (size_t)r * FF + col0) = w;
	v_mul_f32_e32 v44, 0xbfb8aa3b, v41
	v_exp_f32_e32 v58, v44
	v_lshl_add_u64 v[44:45], v[54:55], 0, v[104:105]
	global_store_dwordx4 v[44:45], v[48:51], off sc0 sc1
	v_mul_f32_e32 v44, v57, v53
	v_mov_b32_e32 v45, v46
	v_mul_f32_e32 v48, v56, v44
	v_mov_b32_e32 v44, v42
	v_pk_mul_f32 v[44:45], v[44:45], v[52:53] op_sel_hi:[1,0]
	v_add_f32_e32 v54, 1.0, v58
	v_mul_f32_e32 v42, 0xbfb8aa3b, v45
	v_mov_b32_e32 v46, v43
	v_rcp_f32_e32 v54, v54
	v_exp_f32_e32 v49, v42
	v_pk_mul_f32 v[42:43], v[46:47], v[52:53] op_sel_hi:[1,0]
	v_mul_f32_e32 v41, v41, v54
	v_mul_f32_e32 v46, 0xbfb8aa3b, v43
	v_exp_f32_e32 v46, v46
	v_mul_f32_e32 v47, v40, v41
	v_add_f32_e32 v40, 1.0, v49
	v_rcp_f32_e32 v49, v40
	v_add_f32_e32 v40, 1.0, v46
	v_rcp_f32_e32 v46, v40
	v_mov_b32_e32 v40, v32
	v_mov_b32_e32 v41, v36
	v_pk_mul_f32 v[40:41], v[40:41], v[52:53] op_sel_hi:[1,0]
	v_mul_f32_e32 v36, v45, v49
	v_mul_f32_e32 v32, 0xbfb8aa3b, v41
	v_exp_f32_e32 v32, v32
	v_mul_f32_e32 v44, v44, v36
	v_mov_b32_e32 v36, v33
	v_mul_f32_e32 v43, v43, v46
	v_add_f32_e32 v32, 1.0, v32
	v_rcp_f32_e32 v45, v32
	v_pk_mul_f32 v[32:33], v[36:37], v[52:53] op_sel_hi:[1,0]
	v_mul_f32_e32 v42, v42, v43
	v_mul_f32_e32 v36, 0xbfb8aa3b, v33
	v_exp_f32_e32 v36, v36
	v_mul_f32_e32 v37, v41, v45
	v_mul_f32_e32 v40, v40, v37
	v_mov_b32_e32 v37, v38
	v_add_f32_e32 v36, 1.0, v36
	v_rcp_f32_e32 v41, v36
	v_mov_b32_e32 v36, v34
	v_pk_mul_f32 v[36:37], v[36:37], v[52:53] op_sel_hi:[1,0]
	v_mov_b32_e32 v38, v35
	v_mul_f32_e32 v34, 0xbfb8aa3b, v37
	v_exp_f32_e32 v43, v34
	v_pk_mul_f32 v[34:35], v[38:39], v[52:53] op_sel_hi:[1,0]
	v_mul_f32_e32 v33, v33, v41
	v_mul_f32_e32 v38, 0xbfb8aa3b, v35
	v_exp_f32_e32 v38, v38
	v_add_f32_e32 v39, 1.0, v43
	v_rcp_f32_e32 v39, v39
	v_mul_f32_e32 v41, v32, v33
	v_add_f32_e32 v38, 1.0, v38
	v_rcp_f32_e32 v38, v38
	v_mul_f32_e32 v32, v37, v39
	v_mul_f32_e32 v36, v36, v32
	v_add_u32_e32 v37, 0x90, v144
	v_mul_f32_e32 v32, v35, v38
	v_mul_f32_e32 v35, v34, v32
	v_cvt_pk_bf16_f32 v32, v48, v47
	v_cvt_pk_bf16_f32 v33, v44, v42
	v_cvt_pk_bf16_f32 v34, v40, v41
	v_cvt_pk_bf16_f32 v35, v36, v35
	v_fmamk_f32 v36, v123, 0x3a000000, v152
	v_rsq_f32_e32 v36, v36
	v_mov_b32_e32 v40, v24
	v_mov_b32_e32 v41, v28
	v_mad_i64_i32 v[38:39], s[18:19], v37, s38, v[120:121]
	v_pk_mul_f32 v[40:41], v[40:41], v[36:37] op_sel_hi:[1,0]
	v_mov_b32_e32 v28, v25
	v_mul_f32_e32 v24, 0xbfb8aa3b, v41
	v_exp_f32_e32 v37, v24
	s_nop 0
	v_pk_mul_f32 v[24:25], v[28:29], v[36:37] op_sel_hi:[1,0]
	v_add_f32_e32 v37, 1.0, v37
	v_rcp_f32_e32 v37, v37
	v_mul_f32_e32 v28, 0xbfb8aa3b, v25
	v_exp_f32_e32 v42, v28
	v_lshl_add_u64 v[28:29], v[38:39], 0, v[104:105]
	global_store_dwordx4 v[28:29], v[32:35], off sc0 sc1
	v_mul_f32_e32 v28, v41, v37
	v_mov_b32_e32 v29, v30
	v_mul_f32_e32 v32, v40, v28
	v_mov_b32_e32 v28, v26
	v_pk_mul_f32 v[28:29], v[28:29], v[36:37] op_sel_hi:[1,0]
	v_add_f32_e32 v38, 1.0, v42
	v_mul_f32_e32 v26, 0xbfb8aa3b, v29
	v_mov_b32_e32 v30, v27
	v_rcp_f32_e32 v38, v38
	v_exp_f32_e32 v33, v26
	v_pk_mul_f32 v[26:27], v[30:31], v[36:37] op_sel_hi:[1,0]
	v_mul_f32_e32 v25, v25, v38
	v_mul_f32_e32 v30, 0xbfb8aa3b, v27
	v_exp_f32_e32 v30, v30
	v_mul_f32_e32 v31, v24, v25
	v_add_f32_e32 v24, 1.0, v33
	v_rcp_f32_e32 v33, v24
	v_add_f32_e32 v24, 1.0, v30
	v_rcp_f32_e32 v30, v24
	v_mov_b32_e32 v24, v16
	v_mov_b32_e32 v25, v20
	v_pk_mul_f32 v[24:25], v[24:25], v[36:37] op_sel_hi:[1,0]
	v_mul_f32_e32 v20, v29, v33
	v_mul_f32_e32 v16, 0xbfb8aa3b, v25
	v_exp_f32_e32 v16, v16
	v_mul_f32_e32 v28, v28, v20
	v_mov_b32_e32 v20, v17
	v_mul_f32_e32 v27, v27, v30
	v_add_f32_e32 v16, 1.0, v16
	v_rcp_f32_e32 v29, v16
	v_pk_mul_f32 v[16:17], v[20:21], v[36:37] op_sel_hi:[1,0]
; __device__ __forceinline__ unsigned cvt_pk_bf16(float lo, float hi) { unsigned r; asm volatile("v_cvt_pk_bf16_f32 %0, %1, %2" : "=v"(r) : "v"(lo), "v"(hi)); return r; }
; __device__ __forceinline__ float ld_agent(const float* p) { return __hip_atomic_load(p, __ATOMIC_RELAXED, __HIP_MEMORY_SCOPE_AGENT); }
; __device__ __forceinline__ float sigm(float x) { return __builtin_amdgcn_rcpf(1.f + __builtin_amdgcn_exp2f(-LOG2E * x)); }
; #define PG8_WAIT_V(n) asm volatile("s_waitcnt vmcnt(" #n ")" ::: "memory")
; #define PG8_BAR __builtin_amdgcn_s_barrier()
;     __device__ __forceinline__ void operator()(const f32x4 (&acc)[2][2][4][2], const Unit& u, int wr, int wc, int fr, int fq) const {
;     ...
;         for (int g = 0; g < 8; ++g) sq[g] = ld_agent(ssq + row0 + (g >> 2) * HALF + (g & 3) * 16);
; #pragma unroll
;         for (int ai = 0; ai < 2; ++ai)
; #pragma unroll
;             for (int m = 0; m < 4; ++m) {
;                 const int r = row0 + ai * HALF + m * 16; const float rs = __builtin_amdgcn_rsqf(sq[ai * 4 + m] * (1.f / 2048.f) + EPS);
;                 float v[8];
; #pragma unroll
;                 for (int n = 0; n < 2; ++n)
; #pragma unroll
;                     for (int j = 0; j < 4; ++j) { const float g = acc[ai][0][m][n][j] * rs, up = acc[ai][1][m][n][j] * rs; v[n * 4 + j] = g * sigm(g) * up; }
;                 u32x4 w; w.x = cvt_pk_bf16(v[0], v[1]); w.y = cvt_pk_bf16(v[2], v[3]); w.z = cvt_pk_bf16(v[4], v[5]); w.w = cvt_pk_bf16(v[6], v[7]);
;                 *(u32x4*)(O + (size_t)r * FF + col0) = w;
; template <class Epi, class Sched>
; __device__ __forceinline__ void gemm_phase(LAS unsigned char* lds, const Gemm g, const Sched& S, const Epi& E) {
;     ...
;     PG8_WAIT_V(0);
;     if (wr == 0) PG8_BAR;
;     PG8_BAR;
	v_mul_f32_e32 v26, v26, v27
	v_mul_f32_e32 v20, 0xbfb8aa3b, v17
	v_exp_f32_e32 v20, v20
	v_mul_f32_e32 v21, v25, v29
	v_mul_f32_e32 v24, v24, v21
	v_mov_b32_e32 v21, v22
	v_add_f32_e32 v20, 1.0, v20
	v_rcp_f32_e32 v25, v20
	v_mov_b32_e32 v20, v18
	v_pk_mul_f32 v[20:21], v[20:21], v[36:37] op_sel_hi:[1,0]
	v_mov_b32_e32 v22, v19
	v_mul_f32_e32 v18, 0xbfb8aa3b, v21
	v_exp_f32_e32 v27, v18
	v_pk_mul_f32 v[18:19], v[22:23], v[36:37] op_sel_hi:[1,0]
	v_mul_f32_e32 v17, v17, v25
	v_mul_f32_e32 v22, 0xbfb8aa3b, v19
	v_exp_f32_e32 v22, v22
	v_add_f32_e32 v23, 1.0, v27
	v_rcp_f32_e32 v23, v23
	v_mul_f32_e32 v25, v16, v17
	v_add_f32_e32 v22, 1.0, v22
	v_rcp_f32_e32 v22, v22
	v_mul_f32_e32 v16, v21, v23
	v_mul_f32_e32 v20, v20, v16
	v_add_u32_e32 v21, 0xa0, v144
	v_mul_f32_e32 v16, v19, v22
	v_mul_f32_e32 v19, v18, v16
	v_cvt_pk_bf16_f32 v16, v32, v31
	v_cvt_pk_bf16_f32 v17, v28, v26
	v_cvt_pk_bf16_f32 v18, v24, v25
	v_cvt_pk_bf16_f32 v19, v20, v19
	v_fmamk_f32 v20, v190, 0x3a000000, v152
	v_rsq_f32_e32 v20, v20
	v_mov_b32_e32 v24, v8
	v_mov_b32_e32 v25, v12
	v_mad_i64_i32 v[22:23], s[18:19], v21, s38, v[120:121]
	v_pk_mul_f32 v[24:25], v[24:25], v[20:21] op_sel_hi:[1,0]
	v_mov_b32_e32 v12, v9
	v_mul_f32_e32 v8, 0xbfb8aa3b, v25
	v_exp_f32_e32 v21, v8
	s_nop 0
	v_pk_mul_f32 v[8:9], v[12:13], v[20:21] op_sel_hi:[1,0]
	v_add_f32_e32 v21, 1.0, v21
	v_rcp_f32_e32 v21, v21
	v_mul_f32_e32 v12, 0xbfb8aa3b, v9
	v_exp_f32_e32 v26, v12
	v_lshl_add_u64 v[12:13], v[22:23], 0, v[104:105]
	global_store_dwordx4 v[12:13], v[16:19], off sc0 sc1
	v_mul_f32_e32 v12, v25, v21
	v_mov_b32_e32 v13, v14
	v_mul_f32_e32 v16, v24, v12
	v_mov_b32_e32 v12, v10
	v_pk_mul_f32 v[12:13], v[12:13], v[20:21] op_sel_hi:[1,0]
	v_add_f32_e32 v22, 1.0, v26
	v_mul_f32_e32 v10, 0xbfb8aa3b, v13
	v_mov_b32_e32 v14, v11
	v_rcp_f32_e32 v22, v22
	v_exp_f32_e32 v17, v10
	v_pk_mul_f32 v[10:11], v[14:15], v[20:21] op_sel_hi:[1,0]
	v_mul_f32_e32 v9, v9, v22
	v_mul_f32_e32 v14, 0xbfb8aa3b, v11
	v_exp_f32_e32 v14, v14
	v_mul_f32_e32 v15, v8, v9
	v_add_f32_e32 v8, 1.0, v17
	v_rcp_f32_e32 v17, v8
	v_add_f32_e32 v8, 1.0, v14
	v_rcp_f32_e32 v14, v8
	v_mov_b32_e32 v8, v0
	v_mov_b32_e32 v9, v4
	v_pk_mul_f32 v[8:9], v[8:9], v[20:21] op_sel_hi:[1,0]
	v_mul_f32_e32 v4, v13, v17
	v_mul_f32_e32 v0, 0xbfb8aa3b, v9
	v_exp_f32_e32 v0, v0
	v_mul_f32_e32 v12, v12, v4
	v_mov_b32_e32 v4, v1
	v_mul_f32_e32 v11, v11, v14
	v_add_f32_e32 v0, 1.0, v0
	v_rcp_f32_e32 v13, v0
	v_pk_mul_f32 v[0:1], v[4:5], v[20:21] op_sel_hi:[1,0]
	v_mul_f32_e32 v10, v10, v11
	v_mul_f32_e32 v4, 0xbfb8aa3b, v1
	v_exp_f32_e32 v4, v4
	v_mul_f32_e32 v5, v9, v13
	v_mul_f32_e32 v8, v8, v5
	v_mov_b32_e32 v5, v6
	v_add_f32_e32 v4, 1.0, v4
	v_rcp_f32_e32 v9, v4
	v_mov_b32_e32 v4, v2
	v_pk_mul_f32 v[4:5], v[4:5], v[20:21] op_sel_hi:[1,0]
	v_mov_b32_e32 v6, v3
	v_mul_f32_e32 v2, 0xbfb8aa3b, v5
	v_exp_f32_e32 v11, v2
	v_pk_mul_f32 v[2:3], v[6:7], v[20:21] op_sel_hi:[1,0]
	v_mul_f32_e32 v1, v1, v9
	v_mul_f32_e32 v6, 0xbfb8aa3b, v3
	v_exp_f32_e32 v6, v6
	v_add_f32_e32 v7, 1.0, v11
	v_rcp_f32_e32 v7, v7
	v_mul_f32_e32 v9, v0, v1
	v_add_f32_e32 v6, 1.0, v6
	v_rcp_f32_e32 v6, v6
	v_mul_f32_e32 v0, v5, v7
	v_mul_f32_e32 v4, v4, v0
	v_add_u32_e32 v5, 0xb0, v144
	v_mul_f32_e32 v0, v3, v6
	v_mul_f32_e32 v3, v2, v0
	v_cvt_pk_bf16_f32 v0, v16, v15
	v_cvt_pk_bf16_f32 v1, v12, v10
	v_cvt_pk_bf16_f32 v2, v8, v9
	v_cvt_pk_bf16_f32 v3, v4, v3
	v_mad_i64_i32 v[4:5], s[18:19], v5, s38, v[120:121]
	v_lshl_add_u64 v[4:5], v[4:5], 0, v[104:105]
	s_mov_b64 s[18:19], s[12:13]
	global_store_dwordx4 v[4:5], v[0:3], off sc0 sc1
	s_cbranch_vccz .LBB0_862
	s_waitcnt vmcnt(0)
	s_cmpk_gt_u32 s24, 0xff
	s_cbranch_scc1 .LBB0_869
	s_barrier

; #define PG8_STAGE(bufoff, gbase, voff) do { _Pragma("unroll") for (int _i = 0; _i < 2; ++_i) \
;         __builtin_amdgcn_global_load_lds((const unsigned*)((const char*)(gbase) + (voff)[_i]), (LAS unsigned*)(lds + (bufoff) + ldsw + _i * 8192), 16, 0, 0); } while (0)
; #define PG8_LDA(dst, b, h) do { _Pragma("unroll") for (int m = 0; m < 4; ++m) _Pragma("unroll") for (int k = 0; k < 2; ++k) dst[m][k] = *(const LAS bf16x8*)(lds + PG8_SA(b, h) + aoff + m * 2048 + k * 1024); } while (0)
; #define PG8_LDB(dst, b, h) do { _Pragma("unroll") for (int n = 0; n < 2; ++n) _Pragma("unroll") for (int k = 0; k < 2; ++k) dst[n][k] = *(const LAS bf16x8*)(lds + PG8_SB(b, h) + boff + n * 2048 + k * 1024); } while (0)
; #define PG8_MMA(ai, bj, At, Bt) do { __builtin_amdgcn_s_setprio(1); _Pragma("unroll") for (int m = 0; m < 4; ++m) _Pragma("unroll") for (int n = 0; n < 2; ++n) _Pragma("unroll") for (int k = 0; k < 2; ++k) \
;         acc[ai][bj][m][n] = MmaOp<Epi::I8>::run(Bt[n][k], At[m][k], acc[ai][bj][m][n]); __builtin_amdgcn_s_setprio(0); } while (0)
; #define PG8_WAIT_V(n) asm volatile("s_waitcnt vmcnt(" #n ")" ::: "memory")
; #define PG8_WAIT_L(n) asm volatile("s_waitcnt lgkmcnt(" #n ")" ::: "memory")
; #define PG8_BAR __builtin_amdgcn_s_barrier()
; #define PG8_SCHED __builtin_amdgcn_sched_barrier(0)
; template <class Epi, class Sched>
; __device__ __forceinline__ void gemm_phase(LAS unsigned char* lds, const Gemm g, const Sched& S, const Epi& E) {
;     ...
;             PG8_LDB(B0, 0, 0); PG8_SCHED; PG8_LDA(At, 0, 0); PG8_STAGE(PG8_SA(1, 1), a1 + hstepA, voffA);
;             PG8_WAIT_L(8); PG8_BAR; PG8_WAIT_L(0); PG8_MMA(0, 0, At, B0); PG8_BAR; PG8_SCHED;
;             PG8_LDB(B1, 0, 1); PG8_STAGE(PG8_SB(0, 0), b2, voffB);
;             PG8_BAR; PG8_WAIT_L(0); PG8_MMA(0, 1, At, B1); PG8_BAR;
;             PG8_LDA(At, 0, 1); PG8_STAGE(PG8_SA(0, 0), a2, voffA);
;             PG8_BAR; PG8_WAIT_L(0); PG8_MMA(1, 0, At, B0); PG8_BAR; PG8_SCHED;
;             PG8_STAGE(PG8_SB(0, 1), b2 + hstepB, voffB);
;             PG8_WAIT_V(6); PG8_BAR; PG8_MMA(1, 1, At, B1); PG8_BAR;
.LBB0_936:
	ds_read_b128 v[140:143], v149
	ds_read_b128 v[152:155], v149 offset:1024
	ds_read_b128 v[156:159], v149 offset:2048
	ds_read_b128 v[160:163], v149 offset:3072
	s_add_u32 s14, s12, 0xffea8080
	s_addc_u32 s15, s13, -1
	s_cmpk_eq_i32 s45, 0x52
	s_cselect_b32 s17, s5, s15
	s_cselect_b32 s16, s4, s14
	s_cselect_b32 s15, s7, s44
	s_cselect_b32 s14, s6, s43
	v_lshl_add_u64 v[144:145], s[12:13], 0, v[132:133]
	s_add_i32 m0, s22, 0xc000
	ds_read_b128 v[164:167], v150
	ds_read_b128 v[168:171], v150 offset:1024
	ds_read_b128 v[172:175], v150 offset:2048
	ds_read_b128 v[178:181], v150 offset:3072
	ds_read_b128 v[182:185], v150 offset:4096
	ds_read_b128 v[186:189], v150 offset:5120
	ds_read_b128 v[190:193], v150 offset:6144
	ds_read_b128 v[194:197], v150 offset:7168
	global_load_lds_dwordx4 v[144:145], off
	v_lshl_add_u64 v[144:145], s[12:13], 0, v[134:135]
	s_add_i32 m0, s22, 0xe000
	s_nop 0
	global_load_lds_dwordx4 v[144:145], off
	s_waitcnt lgkmcnt(8)
	s_barrier
	s_waitcnt lgkmcnt(0)
	s_setprio 1
	s_waitcnt lgkmcnt(0)
	v_mfma_f32_16x16x32_bf16 v[124:127], v[140:143], v[164:167], v[124:127]
	v_mfma_f32_16x16x32_bf16 v[120:123], v[156:159], v[164:167], v[120:123]
	v_mfma_f32_16x16x32_bf16 v[116:119], v[140:143], v[172:175], v[116:119]
	v_mfma_f32_16x16x32_bf16 v[112:115], v[156:159], v[172:175], v[112:115]
	v_mfma_f32_16x16x32_bf16 v[92:95], v[140:143], v[182:185], v[92:95]
	v_mfma_f32_16x16x32_bf16 v[88:91], v[156:159], v[182:185], v[88:91]
	v_mfma_f32_16x16x32_bf16 v[84:87], v[140:143], v[190:193], v[84:87]
	v_mfma_f32_16x16x32_bf16 v[80:83], v[156:159], v[190:193], v[80:83]
	v_mfma_f32_16x16x32_bf16 v[124:127], v[152:155], v[168:171], v[124:127]
	v_mfma_f32_16x16x32_bf16 v[120:123], v[160:163], v[168:171], v[120:123]
	v_mfma_f32_16x16x32_bf16 v[116:119], v[152:155], v[178:181], v[116:119]
	v_mfma_f32_16x16x32_bf16 v[112:115], v[160:163], v[178:181], v[112:115]
	v_mfma_f32_16x16x32_bf16 v[92:95], v[152:155], v[186:189], v[92:95]
	v_mfma_f32_16x16x32_bf16 v[88:91], v[160:163], v[186:189], v[88:91]
	v_mfma_f32_16x16x32_bf16 v[84:87], v[152:155], v[194:197], v[84:87]
	v_mfma_f32_16x16x32_bf16 v[80:83], v[160:163], v[194:197], v[80:83]
	s_setprio 0
	s_barrier
	s_add_i32 s46, s30, s19
	v_lshl_add_u64 v[144:145], s[14:15], 0, v[130:131]
	s_mov_b32 m0, s46
	ds_read_b128 v[198:201], v151
	ds_read_b128 v[202:205], v151 offset:1024
	ds_read_b128 v[206:209], v151 offset:2048
	ds_read_b128 v[210:213], v151 offset:3072
	global_load_lds_dwordx4 v[144:145], off
	v_lshl_add_u64 v[214:215], s[14:15], 0, v[128:129]
	s_add_i32 m0, s46, 0x2000
	s_nop 0
	global_load_lds_dwordx4 v[214:215], off
	s_barrier
	s_waitcnt lgkmcnt(0)
	s_setprio 1
	s_waitcnt lgkmcnt(0)
	v_mfma_f32_16x16x32_bf16 v[108:111], v[198:201], v[164:167], v[108:111]
	v_mfma_f32_16x16x32_bf16 v[104:107], v[206:209], v[164:167], v[104:107]
	v_mfma_f32_16x16x32_bf16 v[100:103], v[198:201], v[172:175], v[100:103]
	v_mfma_f32_16x16x32_bf16 v[96:99], v[206:209], v[172:175], v[96:99]
	v_mfma_f32_16x16x32_bf16 v[76:79], v[198:201], v[182:185], v[76:79]
	v_mfma_f32_16x16x32_bf16 v[72:75], v[206:209], v[182:185], v[72:75]
	v_mfma_f32_16x16x32_bf16 v[68:71], v[198:201], v[190:193], v[68:71]
	v_mfma_f32_16x16x32_bf16 v[64:67], v[206:209], v[190:193], v[64:67]
	v_mfma_f32_16x16x32_bf16 v[108:111], v[202:205], v[168:171], v[108:111]
	v_mfma_f32_16x16x32_bf16 v[104:107], v[210:213], v[168:171], v[104:107]
	v_mfma_f32_16x16x32_bf16 v[100:103], v[202:205], v[178:181], v[100:103]
	v_mfma_f32_16x16x32_bf16 v[96:99], v[210:213], v[178:181], v[96:99]
	v_mfma_f32_16x16x32_bf16 v[76:79], v[202:205], v[186:189], v[76:79]
	v_mfma_f32_16x16x32_bf16 v[72:75], v[210:213], v[186:189], v[72:75]
	v_mfma_f32_16x16x32_bf16 v[68:71], v[202:205], v[194:197], v[68:71]
	v_mfma_f32_16x16x32_bf16 v[64:67], v[210:213], v[194:197], v[64:67]
	s_setprio 0
	s_mov_b32 m0, s22
	v_lshl_add_u64 v[216:217], s[16:17], 0, v[130:131]
	s_barrier
	ds_read_b128 v[164:167], v150 offset:16384
	ds_read_b128 v[168:171], v150 offset:17408
	ds_read_b128 v[172:175], v150 offset:18432
	ds_read_b128 v[178:181], v150 offset:19456
	ds_read_b128 v[182:185], v150 offset:20480
	ds_read_b128 v[186:189], v150 offset:21504
	ds_read_b128 v[190:193], v150 offset:22528
	ds_read_b128 v[194:197], v150 offset:23552
	global_load_lds_dwordx4 v[216:217], off
	v_lshl_add_u64 v[218:219], s[16:17], 0, v[128:129]
	s_mov_b32 m0, s23
	s_nop 0
	global_load_lds_dwordx4 v[218:219], off
	s_barrier
	s_waitcnt lgkmcnt(0)
	s_setprio 1
	s_waitcnt lgkmcnt(0)
	v_mfma_f32_16x16x32_bf16 v[60:63], v[140:143], v[164:167], v[60:63]
	v_mfma_f32_16x16x32_bf16 v[56:59], v[156:159], v[164:167], v[56:59]
	v_mfma_f32_16x16x32_bf16 v[52:55], v[140:143], v[172:175], v[52:55]
	v_mfma_f32_16x16x32_bf16 v[48:51], v[156:159], v[172:175], v[48:51]
	v_mfma_f32_16x16x32_bf16 v[28:31], v[140:143], v[182:185], v[28:31]
	v_mfma_f32_16x16x32_bf16 v[24:27], v[156:159], v[182:185], v[24:27]
	v_mfma_f32_16x16x32_bf16 v[20:23], v[140:143], v[190:193], v[20:23]
	v_mfma_f32_16x16x32_bf16 v[16:19], v[156:159], v[190:193], v[16:19]
	v_mfma_f32_16x16x32_bf16 v[60:63], v[152:155], v[168:171], v[60:63]
	v_mfma_f32_16x16x32_bf16 v[56:59], v[160:163], v[168:171], v[56:59]
	v_mfma_f32_16x16x32_bf16 v[52:55], v[152:155], v[178:181], v[52:55]
	v_mfma_f32_16x16x32_bf16 v[48:51], v[160:163], v[178:181], v[48:51]
	v_mfma_f32_16x16x32_bf16 v[28:31], v[152:155], v[186:189], v[28:31]
	v_mfma_f32_16x16x32_bf16 v[24:27], v[160:163], v[186:189], v[24:27]
	v_mfma_f32_16x16x32_bf16 v[20:23], v[152:155], v[194:197], v[20:23]
	v_mfma_f32_16x16x32_bf16 v[16:19], v[160:163], v[194:197], v[16:19]
	s_setprio 0
	s_barrier
; #define PG8_STAGE(bufoff, gbase, voff) do { _Pragma("unroll") for (int _i = 0; _i < 2; ++_i) \
;         __builtin_amdgcn_global_load_lds((const unsigned*)((const char*)(gbase) + (voff)[_i]), (LAS unsigned*)(lds + (bufoff) + ldsw + _i * 8192), 16, 0, 0); } while (0)
; #define PG8_LDA(dst, b, h) do { _Pragma("unroll") for (int m = 0; m < 4; ++m) _Pragma("unroll") for (int k = 0; k < 2; ++k) dst[m][k] = *(const LAS bf16x8*)(lds + PG8_SA(b, h) + aoff + m * 2048 + k * 1024); } while (0)
; #define PG8_LDB(dst, b, h) do { _Pragma("unroll") for (int n = 0; n < 2; ++n) _Pragma("unroll") for (int k = 0; k < 2; ++k) dst[n][k] = *(const LAS bf16x8*)(lds + PG8_SB(b, h) + boff + n * 2048 + k * 1024); } while (0)
; #define PG8_MMA(ai, bj, At, Bt) do { __builtin_amdgcn_s_setprio(1); _Pragma("unroll") for (int m = 0; m < 4; ++m) _Pragma("unroll") for (int n = 0; n < 2; ++n) _Pragma("unroll") for (int k = 0; k < 2; ++k) \
;         acc[ai][bj][m][n] = MmaOp<Epi::I8>::run(Bt[n][k], At[m][k], acc[ai][bj][m][n]); __builtin_amdgcn_s_setprio(0); } while (0)
; #define PG8_WAIT_V(n) asm volatile("s_waitcnt vmcnt(" #n ")" ::: "memory")
; #define PG8_WAIT_L(n) asm volatile("s_waitcnt lgkmcnt(" #n ")" ::: "memory")
; #define PG8_BAR __builtin_amdgcn_s_barrier()
; #define PG8_SCHED __builtin_amdgcn_sched_barrier(0)
; template <class Epi, class Sched>
; __device__ __forceinline__ void gemm_phase(LAS unsigned char* lds, const Gemm g, const Sched& S, const Epi& E) {
;     ...
;             PG8_STAGE(PG8_SB(0, 1), b2 + hstepB, voffB);
;             PG8_WAIT_V(6); PG8_BAR; PG8_MMA(1, 1, At, B1); PG8_BAR;
;             PG8_LDB(B0, 1, 0); PG8_SCHED; PG8_LDA(At, 1, 0); PG8_STAGE(PG8_SA(0, 1), a2 + hstepA, voffA);
;             PG8_WAIT_L(8); PG8_BAR; PG8_WAIT_L(0); PG8_MMA(0, 0, At, B0); PG8_BAR; PG8_SCHED;
;             PG8_LDB(B1, 1, 1); PG8_STAGE(PG8_SB(1, 0), b3, voffB);
;             PG8_BAR; PG8_WAIT_L(0); PG8_MMA(0, 1, At, B1); PG8_BAR;
;             PG8_LDA(At, 1, 1); PG8_STAGE(PG8_SA(1, 0), a3, voffA);
;             PG8_BAR; PG8_WAIT_L(0); PG8_MMA(1, 0, At, B0); PG8_BAR; PG8_SCHED;
	s_add_u32 s46, s14, 0x158000
	s_addc_u32 s47, s15, 0
	s_add_i32 s48, s31, s19
	v_lshl_add_u64 v[140:141], s[46:47], 0, v[130:131]
	s_mov_b32 m0, s48
	s_nop 0
	global_load_lds_dwordx4 v[140:141], off
	v_lshl_add_u64 v[140:141], s[46:47], 0, v[128:129]
	s_add_i32 m0, s48, 0x2000
	s_nop 0
	global_load_lds_dwordx4 v[140:141], off
	s_waitcnt vmcnt(6)
	s_barrier
	s_setprio 1
	v_mfma_f32_16x16x32_bf16 v[44:47], v[198:201], v[164:167], v[44:47]
	v_mfma_f32_16x16x32_bf16 v[40:43], v[206:209], v[164:167], v[40:43]
	v_mfma_f32_16x16x32_bf16 v[36:39], v[198:201], v[172:175], v[36:39]
	v_mfma_f32_16x16x32_bf16 v[32:35], v[206:209], v[172:175], v[32:35]
	v_mfma_f32_16x16x32_bf16 v[12:15], v[198:201], v[182:185], v[12:15]
	v_mfma_f32_16x16x32_bf16 v[8:11], v[206:209], v[182:185], v[8:11]
	v_mfma_f32_16x16x32_bf16 v[4:7], v[198:201], v[190:193], v[4:7]
	v_mfma_f32_16x16x32_bf16 v[0:3], v[206:209], v[190:193], v[0:3]
	v_mfma_f32_16x16x32_bf16 v[44:47], v[202:205], v[168:171], v[44:47]
	v_mfma_f32_16x16x32_bf16 v[40:43], v[210:213], v[168:171], v[40:43]
	v_mfma_f32_16x16x32_bf16 v[36:39], v[202:205], v[178:181], v[36:39]
	v_mfma_f32_16x16x32_bf16 v[32:35], v[210:213], v[178:181], v[32:35]
	v_mfma_f32_16x16x32_bf16 v[12:15], v[202:205], v[186:189], v[12:15]
	v_mfma_f32_16x16x32_bf16 v[8:11], v[210:213], v[186:189], v[8:11]
	v_mfma_f32_16x16x32_bf16 v[4:7], v[202:205], v[194:197], v[4:7]
	v_mfma_f32_16x16x32_bf16 v[0:3], v[210:213], v[194:197], v[0:3]
	s_setprio 0
	s_add_i32 s46, 0, 0x18000
	v_add_u32_e32 v160, s46, v147
	s_barrier
	ds_read_b128 v[140:143], v160
	ds_read_b128 v[152:155], v160 offset:1024
	ds_read_b128 v[156:159], v160 offset:2048
	ds_read_b128 v[160:163], v160 offset:3072
	s_add_u32 s16, s16, 0x158000
	s_addc_u32 s17, s17, 0
	s_mov_b32 m0, s24
	v_lshl_add_u64 v[198:199], s[16:17], 0, v[130:131]
	ds_read_b128 v[164:167], v150 offset:32768
	ds_read_b128 v[168:171], v150 offset:33792
	ds_read_b128 v[172:175], v150 offset:34816
	ds_read_b128 v[178:181], v150 offset:35840
	ds_read_b128 v[182:185], v150 offset:36864
	ds_read_b128 v[186:189], v150 offset:37888
	ds_read_b128 v[190:193], v150 offset:38912
	ds_read_b128 v[194:197], v150 offset:39936
	global_load_lds_dwordx4 v[198:199], off
	v_lshl_add_u64 v[198:199], s[16:17], 0, v[128:129]
	s_mov_b32 m0, s25
	s_nop 0
	global_load_lds_dwordx4 v[198:199], off
	s_waitcnt lgkmcnt(8)
	s_barrier
	s_waitcnt lgkmcnt(0)
	s_setprio 1
	s_waitcnt lgkmcnt(0)
	v_mfma_f32_16x16x32_bf16 v[124:127], v[140:143], v[164:167], v[124:127]
	v_mfma_f32_16x16x32_bf16 v[120:123], v[156:159], v[164:167], v[120:123]
	v_mfma_f32_16x16x32_bf16 v[116:119], v[140:143], v[172:175], v[116:119]
	v_mfma_f32_16x16x32_bf16 v[112:115], v[156:159], v[172:175], v[112:115]
	v_mfma_f32_16x16x32_bf16 v[92:95], v[140:143], v[182:185], v[92:95]
	v_mfma_f32_16x16x32_bf16 v[88:91], v[156:159], v[182:185], v[88:91]
	v_mfma_f32_16x16x32_bf16 v[84:87], v[140:143], v[190:193], v[84:87]
	v_mfma_f32_16x16x32_bf16 v[80:83], v[156:159], v[190:193], v[80:83]
	v_mfma_f32_16x16x32_bf16 v[124:127], v[152:155], v[168:171], v[124:127]
	v_mfma_f32_16x16x32_bf16 v[120:123], v[160:163], v[168:171], v[120:123]
	v_mfma_f32_16x16x32_bf16 v[116:119], v[152:155], v[178:181], v[116:119]
	v_mfma_f32_16x16x32_bf16 v[112:115], v[160:163], v[178:181], v[112:115]
	v_mfma_f32_16x16x32_bf16 v[92:95], v[152:155], v[186:189], v[92:95]
	v_mfma_f32_16x16x32_bf16 v[88:91], v[160:163], v[186:189], v[88:91]
	v_mfma_f32_16x16x32_bf16 v[84:87], v[152:155], v[194:197], v[84:87]
	v_mfma_f32_16x16x32_bf16 v[80:83], v[160:163], v[194:197], v[80:83]
	s_setprio 0
	s_barrier
	s_add_i32 s16, 0, 0x1c000
	s_add_i32 s17, s46, s19
	v_add_u32_e32 v177, s16, v147
	v_lshl_add_u64 v[144:145], v[144:145], 0, s[8:9]
	s_mov_b32 m0, s17
	ds_read_b128 v[198:201], v177
	ds_read_b128 v[202:205], v177 offset:1024
	ds_read_b128 v[206:209], v177 offset:2048
	ds_read_b128 v[210:213], v177 offset:3072
	global_load_lds_dwordx4 v[144:145], off
	v_lshl_add_u64 v[144:145], v[214:215], 0, s[8:9]
	s_add_i32 m0, s17, 0x2000
	s_nop 0
	global_load_lds_dwordx4 v[144:145], off
	s_barrier
	s_waitcnt lgkmcnt(0)
	s_setprio 1
	s_waitcnt lgkmcnt(0)
	v_mfma_f32_16x16x32_bf16 v[108:111], v[198:201], v[164:167], v[108:111]
	v_mfma_f32_16x16x32_bf16 v[104:107], v[206:209], v[164:167], v[104:107]
	v_mfma_f32_16x16x32_bf16 v[100:103], v[198:201], v[172:175], v[100:103]
	v_mfma_f32_16x16x32_bf16 v[96:99], v[206:209], v[172:175], v[96:99]
	v_mfma_f32_16x16x32_bf16 v[76:79], v[198:201], v[182:185], v[76:79]
	v_mfma_f32_16x16x32_bf16 v[72:75], v[206:209], v[182:185], v[72:75]
	v_mfma_f32_16x16x32_bf16 v[68:71], v[198:201], v[190:193], v[68:71]
	v_mfma_f32_16x16x32_bf16 v[64:67], v[206:209], v[190:193], v[64:67]
	v_mfma_f32_16x16x32_bf16 v[108:111], v[202:205], v[168:171], v[108:111]
	v_mfma_f32_16x16x32_bf16 v[104:107], v[210:213], v[168:171], v[104:107]
	v_mfma_f32_16x16x32_bf16 v[100:103], v[202:205], v[178:181], v[100:103]
	v_mfma_f32_16x16x32_bf16 v[96:99], v[210:213], v[178:181], v[96:99]
	v_mfma_f32_16x16x32_bf16 v[76:79], v[202:205], v[186:189], v[76:79]
	v_mfma_f32_16x16x32_bf16 v[72:75], v[210:213], v[186:189], v[72:75]
	v_mfma_f32_16x16x32_bf16 v[68:71], v[202:205], v[194:197], v[68:71]
	v_mfma_f32_16x16x32_bf16 v[64:67], v[210:213], v[194:197], v[64:67]
	s_setprio 0
	s_mov_b32 m0, s27
	v_lshl_add_u64 v[144:145], v[216:217], 0, s[8:9]
	s_barrier
	ds_read_b128 v[164:167], v150 offset:49152
	ds_read_b128 v[168:171], v150 offset:50176
	ds_read_b128 v[172:175], v150 offset:51200
	ds_read_b128 v[178:181], v150 offset:52224
	ds_read_b128 v[182:185], v150 offset:53248
	ds_read_b128 v[186:189], v150 offset:54272
	ds_read_b128 v[190:193], v150 offset:55296
	ds_read_b128 v[194:197], v150 offset:56320
	global_load_lds_dwordx4 v[144:145], off
	v_lshl_add_u64 v[144:145], v[218:219], 0, s[8:9]
	s_mov_b32 m0, s28
	s_nop 0
	global_load_lds_dwordx4 v[144:145], off
	s_barrier
; #define PG8_STAGE(bufoff, gbase, voff) do { _Pragma("unroll") for (int _i = 0; _i < 2; ++_i) \
;         __builtin_amdgcn_global_load_lds((const unsigned*)((const char*)(gbase) + (voff)[_i]), (LAS unsigned*)(lds + (bufoff) + ldsw + _i * 8192), 16, 0, 0); } while (0)
; #define PG8_LDA(dst, b, h) do { _Pragma("unroll") for (int m = 0; m < 4; ++m) _Pragma("unroll") for (int k = 0; k < 2; ++k) dst[m][k] = *(const LAS bf16x8*)(lds + PG8_SA(b, h) + aoff + m * 2048 + k * 1024); } while (0)
; #define PG8_BAR __builtin_amdgcn_s_barrier()
;     __device__ __forceinline__ void operator()(const f32x4 (&acc)[2][2][4][2], const Unit& u, int wr, int wc, int fr, int fq) const {
;         const int row0 = u.pm * BM + wr * 64 + fr, col0 = u.pn * BM + wc * 32 + 4 * fq;
;         const float* base = ((u.pm < MP / BM) ? base_lo : base_hi - (size_t)MP * DM) + (size_t)row0 * DM + col0;
;         f32x4 b[2][2], nb[2][2];
; #pragma unroll
;         for (int bj = 0; bj < 2; ++bj)
; #pragma unroll
;             for (int n = 0; n < 2; ++n) b[bj][n] = *(const f32x4*)(base + bj * HALF + n * 16);
; #pragma unroll
;         for (int g = 0; g < 8; ++g) {
;             const int ai = g >> 2, m = g & 3;
;             const int r = row0 + ai * HALF + m * 16; const size_t off = (size_t)r * DM + col0; float s = 0.f;
;             if (g < 7) { const float* nrow = base + (size_t)(((g + 1) >> 2) * HALF + ((g + 1) & 3) * 16) * DM;
; #pragma unroll
;                 for (int bj = 0; bj < 2; ++bj)
; #pragma unroll
;                     for (int n = 0; n < 2; ++n) nb[bj][n] = *(const f32x4*)(nrow + bj * HALF + n * 16); }
; #pragma unroll
;             for (int bj = 0; bj < 2; ++bj)
; #pragma unroll
;                 for (int n = 0; n < 2; ++n) {
;                     const f32x4 o = b[bj][n] + acc[ai][bj][m][n] * alpha;
;                     *(f32x4*)(out + off + bj * HALF + n * 16) = o;
; template <class Epi, class Sched>
; __device__ __forceinline__ void gemm_phase(LAS unsigned char* lds, const Gemm g, const Sched& S, const Epi& E) {
;     ...
;             PG8_BAR; PG8_WAIT_L(0); PG8_MMA(0, 1, At, B1); PG8_BAR;
;             PG8_LDA(At, 1, 1); PG8_STAGE(PG8_SA(1, 0), a3, voffA);
;             PG8_BAR; PG8_WAIT_L(0); PG8_MMA(1, 0, At, B0); PG8_BAR; PG8_SCHED;
;             PG8_STAGE(PG8_SB(1, 1), b3 + hstepB, voffB);
;             PG8_WAIT_V(6); PG8_BAR; PG8_MMA(1, 1, At, B1); PG8_BAR;
	s_waitcnt lgkmcnt(0)
	s_setprio 1
	s_waitcnt lgkmcnt(0)
	v_mfma_f32_16x16x32_bf16 v[60:63], v[140:143], v[164:167], v[60:63]
	v_mfma_f32_16x16x32_bf16 v[56:59], v[156:159], v[164:167], v[56:59]
	v_mfma_f32_16x16x32_bf16 v[52:55], v[140:143], v[172:175], v[52:55]
	v_mfma_f32_16x16x32_bf16 v[48:51], v[156:159], v[172:175], v[48:51]
	v_mfma_f32_16x16x32_bf16 v[28:31], v[140:143], v[182:185], v[28:31]
	v_mfma_f32_16x16x32_bf16 v[24:27], v[156:159], v[182:185], v[24:27]
	v_mfma_f32_16x16x32_bf16 v[20:23], v[140:143], v[190:193], v[20:23]
	v_mfma_f32_16x16x32_bf16 v[16:19], v[156:159], v[190:193], v[16:19]
	v_mfma_f32_16x16x32_bf16 v[60:63], v[152:155], v[168:171], v[60:63]
	v_mfma_f32_16x16x32_bf16 v[56:59], v[160:163], v[168:171], v[56:59]
	v_mfma_f32_16x16x32_bf16 v[52:55], v[152:155], v[178:181], v[52:55]
	v_mfma_f32_16x16x32_bf16 v[48:51], v[160:163], v[178:181], v[48:51]
	v_mfma_f32_16x16x32_bf16 v[28:31], v[152:155], v[186:189], v[28:31]
	v_mfma_f32_16x16x32_bf16 v[24:27], v[160:163], v[186:189], v[24:27]
	v_mfma_f32_16x16x32_bf16 v[20:23], v[152:155], v[194:197], v[20:23]
	v_mfma_f32_16x16x32_bf16 v[16:19], v[160:163], v[194:197], v[16:19]
	s_setprio 0
	s_barrier
	s_add_u32 s14, s14, 0x158080
	s_addc_u32 s15, s15, 0
	s_add_i32 s16, s16, s19
	v_lshl_add_u64 v[140:141], s[14:15], 0, v[130:131]
	s_mov_b32 m0, s16
	s_nop 0
	global_load_lds_dwordx4 v[140:141], off
	v_lshl_add_u64 v[140:141], s[14:15], 0, v[128:129]
	s_add_i32 m0, s16, 0x2000
	s_nop 0
	global_load_lds_dwordx4 v[140:141], off
	s_waitcnt vmcnt(6)
	s_barrier
	s_setprio 1
	v_mfma_f32_16x16x32_bf16 v[44:47], v[198:201], v[164:167], v[44:47]
	v_mfma_f32_16x16x32_bf16 v[40:43], v[206:209], v[164:167], v[40:43]
	v_mfma_f32_16x16x32_bf16 v[36:39], v[198:201], v[172:175], v[36:39]
	v_mfma_f32_16x16x32_bf16 v[32:35], v[206:209], v[172:175], v[32:35]
	v_mfma_f32_16x16x32_bf16 v[12:15], v[198:201], v[182:185], v[12:15]
	v_mfma_f32_16x16x32_bf16 v[8:11], v[206:209], v[182:185], v[8:11]
	v_mfma_f32_16x16x32_bf16 v[4:7], v[198:201], v[190:193], v[4:7]
	v_mfma_f32_16x16x32_bf16 v[0:3], v[206:209], v[190:193], v[0:3]
	v_mfma_f32_16x16x32_bf16 v[44:47], v[202:205], v[168:171], v[44:47]
	v_mfma_f32_16x16x32_bf16 v[40:43], v[210:213], v[168:171], v[40:43]
	v_mfma_f32_16x16x32_bf16 v[36:39], v[202:205], v[178:181], v[36:39]
	v_mfma_f32_16x16x32_bf16 v[32:35], v[210:213], v[178:181], v[32:35]
	v_mfma_f32_16x16x32_bf16 v[12:15], v[202:205], v[186:189], v[12:15]
	v_mfma_f32_16x16x32_bf16 v[8:11], v[210:213], v[186:189], v[8:11]
	v_mfma_f32_16x16x32_bf16 v[4:7], v[202:205], v[194:197], v[4:7]
	v_mfma_f32_16x16x32_bf16 v[0:3], v[210:213], v[194:197], v[0:3]
	s_setprio 0
	s_add_i32 s45, s45, 2
	s_add_u32 s12, s12, 0x100
	s_addc_u32 s13, s13, 0
	s_add_u32 s43, s43, 0x100
	s_addc_u32 s44, s44, 0
	s_cmpk_gt_u32 s45, 0x53
	s_barrier
	s_cbranch_scc0 .LBB0_936
	v_lshl_add_u32 v140, s41, 8, v146
	v_lshl_or_b32 v142, s42, 8, v148
	v_ashrrev_i32_e32 v141, 31, v140
	v_lshlrev_b64 v[144:145], 13, v[140:141]
	v_ashrrev_i32_e32 v143, 31, v142
	v_lshl_add_u64 v[144:145], s[68:69], 0, v[144:145]
	v_lshlrev_b64 v[142:143], 2, v[142:143]
	v_lshl_add_u64 v[144:145], v[144:145], 0, v[142:143]
	v_mov_b32_e32 v232, 0x20000
	v_mov_b32_e32 v233, 0
	v_lshl_add_u64 v[218:219], v[144:145], 0, v[232:233]
	v_mov_b32_e32 v232, 0x40000
	v_lshl_add_u64 v[220:221], v[144:145], 0, v[232:233]
	v_mov_b32_e32 v232, 0x60000
	v_lshl_add_u64 v[222:223], v[144:145], 0, v[232:233]
	v_mov_b32_e32 v232, 0x100000
	v_lshl_add_u64 v[224:225], v[144:145], 0, v[232:233]
	v_mov_b32_e32 v232, 0x120000
	v_lshl_add_u64 v[226:227], v[144:145], 0, v[232:233]
	v_mov_b32_e32 v232, 0x140000
	v_lshl_add_u64 v[228:229], v[144:145], 0, v[232:233]
	v_mov_b32_e32 v232, 0x160000
	v_lshl_add_u64 v[230:231], v[144:145], 0, v[232:233]
	global_load_dwordx4 v[152:155], v[144:145], off
	global_load_dwordx4 v[156:159], v[144:145], off offset:64
	global_load_dwordx4 v[160:163], v[144:145], off offset:512
	global_load_dwordx4 v[164:167], v[144:145], off offset:576
	global_load_dwordx4 v[168:171], v[218:219], off
	global_load_dwordx4 v[172:175], v[218:219], off offset:64
	global_load_dwordx4 v[178:181], v[218:219], off offset:512
	global_load_dwordx4 v[182:185], v[218:219], off offset:576
	global_load_dwordx4 v[186:189], v[220:221], off
	global_load_dwordx4 v[190:193], v[220:221], off offset:64
	global_load_dwordx4 v[194:197], v[220:221], off offset:512
	global_load_dwordx4 v[198:201], v[220:221], off offset:576
	global_load_dwordx4 v[202:205], v[222:223], off
	global_load_dwordx4 v[206:209], v[222:223], off offset:64
	global_load_dwordx4 v[210:213], v[222:223], off offset:512
	global_load_dwordx4 v[214:217], v[222:223], off offset:576
	s_mov_b32 s42, s39
	s_mov_b32 s41, s40
	s_mov_b64 s[14:15], s[6:7]
	s_mov_b64 s[12:13], s[4:5]
	s_waitcnt vmcnt(12)
	v_pk_fma_f32 v[124:125], v[124:125], 0.5, v[152:153] op_sel_hi:[1,0,1]
	v_pk_fma_f32 v[126:127], v[126:127], 0.5, v[154:155] op_sel_hi:[1,0,1]
	v_pk_fma_f32 v[120:121], v[120:121], 0.5, v[156:157] op_sel_hi:[1,0,1]
	v_pk_fma_f32 v[122:123], v[122:123], 0.5, v[158:159] op_sel_hi:[1,0,1]
	v_pk_fma_f32 v[108:109], v[108:109], 0.5, v[160:161] op_sel_hi:[1,0,1]
	v_pk_fma_f32 v[110:111], v[110:111], 0.5, v[162:163] op_sel_hi:[1,0,1]
	v_pk_fma_f32 v[104:105], v[104:105], 0.5, v[164:165] op_sel_hi:[1,0,1]
	v_pk_fma_f32 v[106:107], v[106:107], 0.5, v[166:167] op_sel_hi:[1,0,1]
	global_store_dwordx4 v[144:145], v[124:127], off sc0 sc1
	global_store_dwordx4 v[144:145], v[120:123], off offset:64 sc0 sc1
	global_store_dwordx4 v[144:145], v[108:111], off offset:512 sc0 sc1
	global_store_dwordx4 v[144:145], v[104:107], off offset:576 sc0 sc1
	global_load_dwordx4 v[152:155], v[224:225], off
	global_load_dwordx4 v[156:159], v[224:225], off offset:64
	global_load_dwordx4 v[160:163], v[224:225], off offset:512
	global_load_dwordx4 v[164:167], v[224:225], off offset:576
	s_waitcnt vmcnt(16)
; __device__ __forceinline__ unsigned cvt_pk_bf16(float lo, float hi) { unsigned r; asm volatile("v_cvt_pk_bf16_f32 %0, %1, %2" : "=v"(r) : "v"(lo), "v"(hi)); return r; }
;     __device__ __forceinline__ void operator()(const f32x4 (&acc)[2][2][4][2], const Unit& u, int wr, int wc, int fr, int fq) const {
;     ...
;         for (int g = 0; g < 8; ++g) {
;             const int ai = g >> 2, m = g & 3;
;             const int r = row0 + ai * HALF + m * 16; const size_t off = (size_t)r * DM + col0; float s = 0.f;
;             if (g < 7) { const float* nrow = base + (size_t)(((g + 1) >> 2) * HALF + ((g + 1) & 3) * 16) * DM;
; #pragma unroll
;                 for (int bj = 0; bj < 2; ++bj)
; #pragma unroll
;                     for (int n = 0; n < 2; ++n) nb[bj][n] = *(const f32x4*)(nrow + bj * HALF + n * 16); }
; #pragma unroll
;             for (int bj = 0; bj < 2; ++bj)
; #pragma unroll
;                 for (int n = 0; n < 2; ++n) {
;                     const f32x4 o = b[bj][n] + acc[ai][bj][m][n] * alpha;
;                     *(f32x4*)(out + off + bj * HALF + n * 16) = o;
;                     if (WITH_SSQ) s += (o[0] * o[0] + o[1] * o[1]) + (o[2] * o[2] + o[3] * o[3]);
;                     if (WITH_HB) { u32x2 w; w.x = cvt_pk_bf16(o[0], o[1]); w.y = cvt_pk_bf16(o[2], o[3]); *(u32x2*)(hb + off + bj * HALF + n * 16) = w; }
;                 }
;             if (WITH_SSQ) { s += __shfl_xor(s, 16); s += __shfl_xor(s, 32); if (fq == 0) atomicAdd(ssq + r, s); }
;             asm volatile("" ::: "memory");
; #pragma unroll
;             for (int bj = 0; bj < 2; ++bj)
; #pragma unroll
;                 for (int n = 0; n < 2; ++n) b[bj][n] = nb[bj][n];
;         }
	v_pk_fma_f32 v[116:117], v[116:117], 0.5, v[168:169] op_sel_hi:[1,0,1]
	v_pk_fma_f32 v[118:119], v[118:119], 0.5, v[170:171] op_sel_hi:[1,0,1]
	v_pk_fma_f32 v[112:113], v[112:113], 0.5, v[172:173] op_sel_hi:[1,0,1]
	v_pk_fma_f32 v[114:115], v[114:115], 0.5, v[174:175] op_sel_hi:[1,0,1]
	v_pk_fma_f32 v[100:101], v[100:101], 0.5, v[178:179] op_sel_hi:[1,0,1]
	v_pk_fma_f32 v[102:103], v[102:103], 0.5, v[180:181] op_sel_hi:[1,0,1]
	v_pk_fma_f32 v[96:97], v[96:97], 0.5, v[182:183] op_sel_hi:[1,0,1]
	v_pk_fma_f32 v[98:99], v[98:99], 0.5, v[184:185] op_sel_hi:[1,0,1]
	global_store_dwordx4 v[218:219], v[116:119], off sc0 sc1
	global_store_dwordx4 v[218:219], v[112:115], off offset:64 sc0 sc1
	global_store_dwordx4 v[218:219], v[100:103], off offset:512 sc0 sc1
	global_store_dwordx4 v[218:219], v[96:99], off offset:576 sc0 sc1
	global_load_dwordx4 v[168:171], v[226:227], off
	global_load_dwordx4 v[172:175], v[226:227], off offset:64
	global_load_dwordx4 v[178:181], v[226:227], off offset:512
	global_load_dwordx4 v[182:185], v[226:227], off offset:576
	s_waitcnt vmcnt(20)
	v_pk_fma_f32 v[92:93], v[92:93], 0.5, v[186:187] op_sel_hi:[1,0,1]
	v_pk_fma_f32 v[94:95], v[94:95], 0.5, v[188:189] op_sel_hi:[1,0,1]
	v_pk_fma_f32 v[88:89], v[88:89], 0.5, v[190:191] op_sel_hi:[1,0,1]
	v_pk_fma_f32 v[90:91], v[90:91], 0.5, v[192:193] op_sel_hi:[1,0,1]
	v_pk_fma_f32 v[76:77], v[76:77], 0.5, v[194:195] op_sel_hi:[1,0,1]
	v_pk_fma_f32 v[78:79], v[78:79], 0.5, v[196:197] op_sel_hi:[1,0,1]
	v_pk_fma_f32 v[72:73], v[72:73], 0.5, v[198:199] op_sel_hi:[1,0,1]
	v_pk_fma_f32 v[74:75], v[74:75], 0.5, v[200:201] op_sel_hi:[1,0,1]
	global_store_dwordx4 v[220:221], v[92:95], off sc0 sc1
	global_store_dwordx4 v[220:221], v[88:91], off offset:64 sc0 sc1
	global_store_dwordx4 v[220:221], v[76:79], off offset:512 sc0 sc1
	global_store_dwordx4 v[220:221], v[72:75], off offset:576 sc0 sc1
	global_load_dwordx4 v[186:189], v[228:229], off
	global_load_dwordx4 v[190:193], v[228:229], off offset:64
	global_load_dwordx4 v[194:197], v[228:229], off offset:512
	global_load_dwordx4 v[198:201], v[228:229], off offset:576
	s_waitcnt vmcnt(24)
	v_pk_fma_f32 v[84:85], v[84:85], 0.5, v[202:203] op_sel_hi:[1,0,1]
	v_pk_fma_f32 v[86:87], v[86:87], 0.5, v[204:205] op_sel_hi:[1,0,1]
	v_pk_fma_f32 v[80:81], v[80:81], 0.5, v[206:207] op_sel_hi:[1,0,1]
	v_pk_fma_f32 v[82:83], v[82:83], 0.5, v[208:209] op_sel_hi:[1,0,1]
	v_pk_fma_f32 v[68:69], v[68:69], 0.5, v[210:211] op_sel_hi:[1,0,1]
	v_pk_fma_f32 v[70:71], v[70:71], 0.5, v[212:213] op_sel_hi:[1,0,1]
	v_pk_fma_f32 v[64:65], v[64:65], 0.5, v[214:215] op_sel_hi:[1,0,1]
	v_pk_fma_f32 v[66:67], v[66:67], 0.5, v[216:217] op_sel_hi:[1,0,1]
	global_store_dwordx4 v[222:223], v[84:87], off sc0 sc1
	global_store_dwordx4 v[222:223], v[80:83], off offset:64 sc0 sc1
	global_store_dwordx4 v[222:223], v[68:71], off offset:512 sc0 sc1
	global_store_dwordx4 v[222:223], v[64:67], off offset:576 sc0 sc1
	global_load_dwordx4 v[202:205], v[230:231], off
	global_load_dwordx4 v[206:209], v[230:231], off offset:64
	global_load_dwordx4 v[210:213], v[230:231], off offset:512
	global_load_dwordx4 v[214:217], v[230:231], off offset:576
	s_waitcnt vmcnt(24)
	v_pk_fma_f32 v[60:61], v[60:61], 0.5, v[152:153] op_sel_hi:[1,0,1]
	v_pk_fma_f32 v[62:63], v[62:63], 0.5, v[154:155] op_sel_hi:[1,0,1]
	v_pk_fma_f32 v[56:57], v[56:57], 0.5, v[156:157] op_sel_hi:[1,0,1]
	v_pk_fma_f32 v[58:59], v[58:59], 0.5, v[158:159] op_sel_hi:[1,0,1]
	v_pk_fma_f32 v[44:45], v[44:45], 0.5, v[160:161] op_sel_hi:[1,0,1]
	v_pk_fma_f32 v[46:47], v[46:47], 0.5, v[162:163] op_sel_hi:[1,0,1]
	v_pk_fma_f32 v[40:41], v[40:41], 0.5, v[164:165] op_sel_hi:[1,0,1]
	v_pk_fma_f32 v[42:43], v[42:43], 0.5, v[166:167] op_sel_hi:[1,0,1]
	global_store_dwordx4 v[224:225], v[60:63], off sc0 sc1
	global_store_dwordx4 v[224:225], v[56:59], off offset:64 sc0 sc1
	global_store_dwordx4 v[224:225], v[44:47], off offset:512 sc0 sc1
	global_store_dwordx4 v[224:225], v[40:43], off offset:576 sc0 sc1
	s_waitcnt vmcnt(20)
	v_pk_fma_f32 v[52:53], v[52:53], 0.5, v[168:169] op_sel_hi:[1,0,1]
	v_pk_fma_f32 v[54:55], v[54:55], 0.5, v[170:171] op_sel_hi:[1,0,1]
	v_pk_fma_f32 v[48:49], v[48:49], 0.5, v[172:173] op_sel_hi:[1,0,1]
	v_pk_fma_f32 v[50:51], v[50:51], 0.5, v[174:175] op_sel_hi:[1,0,1]
	v_pk_fma_f32 v[36:37], v[36:37], 0.5, v[178:179] op_sel_hi:[1,0,1]
	v_pk_fma_f32 v[38:39], v[38:39], 0.5, v[180:181] op_sel_hi:[1,0,1]
	v_pk_fma_f32 v[32:33], v[32:33], 0.5, v[182:183] op_sel_hi:[1,0,1]
	v_pk_fma_f32 v[34:35], v[34:35], 0.5, v[184:185] op_sel_hi:[1,0,1]
	global_store_dwordx4 v[226:227], v[52:55], off sc0 sc1
	global_store_dwordx4 v[226:227], v[48:51], off offset:64 sc0 sc1
	global_store_dwordx4 v[226:227], v[36:39], off offset:512 sc0 sc1
	global_store_dwordx4 v[226:227], v[32:35], off offset:576 sc0 sc1
	s_waitcnt vmcnt(16)
	v_pk_fma_f32 v[28:29], v[28:29], 0.5, v[186:187] op_sel_hi:[1,0,1]
	v_pk_fma_f32 v[30:31], v[30:31], 0.5, v[188:189] op_sel_hi:[1,0,1]
	v_pk_fma_f32 v[24:25], v[24:25], 0.5, v[190:191] op_sel_hi:[1,0,1]
	v_pk_fma_f32 v[26:27], v[26:27], 0.5, v[192:193] op_sel_hi:[1,0,1]
	v_pk_fma_f32 v[12:13], v[12:13], 0.5, v[194:195] op_sel_hi:[1,0,1]
	v_pk_fma_f32 v[14:15], v[14:15], 0.5, v[196:197] op_sel_hi:[1,0,1]
	v_pk_fma_f32 v[8:9], v[8:9], 0.5, v[198:199] op_sel_hi:[1,0,1]
	v_pk_fma_f32 v[10:11], v[10:11], 0.5, v[200:201] op_sel_hi:[1,0,1]
	global_store_dwordx4 v[228:229], v[28:31], off sc0 sc1
	global_store_dwordx4 v[228:229], v[24:27], off offset:64 sc0 sc1
	global_store_dwordx4 v[228:229], v[12:15], off offset:512 sc0 sc1
	global_store_dwordx4 v[228:229], v[8:11], off offset:576 sc0 sc1
	s_waitcnt vmcnt(12)
	v_pk_fma_f32 v[20:21], v[20:21], 0.5, v[202:203] op_sel_hi:[1,0,1]
	v_pk_fma_f32 v[22:23], v[22:23], 0.5, v[204:205] op_sel_hi:[1,0,1]
	v_pk_fma_f32 v[16:17], v[16:17], 0.5, v[206:207] op_sel_hi:[1,0,1]
	v_pk_fma_f32 v[18:19], v[18:19], 0.5, v[208:209] op_sel_hi:[1,0,1]
	v_pk_fma_f32 v[4:5], v[4:5], 0.5, v[210:211] op_sel_hi:[1,0,1]
	v_pk_fma_f32 v[6:7], v[6:7], 0.5, v[212:213] op_sel_hi:[1,0,1]
	v_pk_fma_f32 v[0:1], v[0:1], 0.5, v[214:215] op_sel_hi:[1,0,1]
	v_pk_fma_f32 v[2:3], v[2:3], 0.5, v[216:217] op_sel_hi:[1,0,1]
	global_store_dwordx4 v[230:231], v[20:23], off sc0 sc1
	global_store_dwordx4 v[230:231], v[16:19], off offset:64 sc0 sc1
	global_store_dwordx4 v[230:231], v[4:7], off offset:512 sc0 sc1
	global_store_dwordx4 v[230:231], v[0:3], off offset:576 sc0 sc1
	s_and_b64 vcc, exec, s[0:1]
	s_cbranch_vccz .LBB0_929
	s_waitcnt vmcnt(0)
	s_cmpk_gt_u32 s18, 0xff
	s_cbranch_scc1 .LBB0_940
	s_barrier
